# RG-LRU softplus(-lambda) table computed once per launch (hipcc log1pf sequence reused) instead of 32 log1pf per item; conformer LN wave sums via DPP
# speedup vs baseline: 1.2076x; 1.0323x over previous
.LBB0_116:
	s_or_b64 exec, exec, s[0:1]
	v_readlane_b32 s6, v253, 9
	v_readlane_b32 s1, v253, 0
	s_lshl_b32 s2, s1, 2
	s_lshl_b32 s4, s6, 2
	v_readlane_b32 s7, v253, 10
	v_writelane_b32 v253, s2, 47
	s_add_u32 s2, s30, 0x10000
	s_addc_u32 s3, s31, 0
	s_add_u32 s20, s30, 0x2d94000
	v_writelane_b32 v253, s2, 48
	s_addc_u32 s21, s31, 0
	s_mul_i32 s0, s7, s6
	v_writelane_b32 v253, s3, 49
	s_add_u32 s2, s30, 0x2594000
	s_addc_u32 s3, s31, 0
	s_add_u32 s24, s30, 0x7194000
	v_writelane_b32 v253, s2, 50
	s_addc_u32 s25, s31, 0
	s_mul_i32 s36, s0, s33
	v_writelane_b32 v253, s3, 51
	s_add_u32 s2, s30, 0x1200
	s_addc_u32 s3, s31, 0
	s_add_u32 s54, s30, 0x1400
	s_addc_u32 s55, s31, 0
	s_add_u32 s60, s30, 0x1500
	s_addc_u32 s61, s31, 0
	s_add_u32 s64, s30, 0x1600
	v_writelane_b32 v253, s2, 52
	s_addc_u32 s65, s31, 0
	s_mov_b32 s23, 0
	v_writelane_b32 v253, s3, 53
	s_add_u32 s2, s30, 0x1700
	s_addc_u32 s3, s31, 0
	v_writelane_b32 v253, s2, 54
	v_mov_b32_e32 v3, 0
	v_mov_b32_e32 v223, 0x358637bd
	v_writelane_b32 v253, s3, 55
	s_add_u32 s2, s30, 0x1800
	s_addc_u32 s3, s31, 0
	s_add_u32 s44, s30, 0x1900
	s_addc_u32 s45, s31, 0
	s_add_u32 s82, s30, 0x1a00
	s_addc_u32 s83, s31, 0
	s_add_u32 s86, s30, 0x1b00
	s_addc_u32 s87, s31, 0
	s_add_u32 s88, s30, 0x1c00
	s_addc_u32 s89, s31, 0
	s_add_u32 s90, s30, 0x1d00
	s_addc_u32 s91, s31, 0
	s_add_u32 s92, s30, 0x1e00
	s_addc_u32 s93, s31, 0
	s_add_u32 s94, s30, 0x1f00
	s_addc_u32 s95, s31, 0
	s_add_u32 s96, s30, 0x2000
	s_addc_u32 s97, s31, 0
	s_add_u32 s26, s30, 0x2100
	s_addc_u32 s27, s31, 0
	s_add_u32 s46, s30, 0x2200
	s_addc_u32 s47, s31, 0
	s_add_u32 s70, s30, 0x2300
	v_writelane_b32 v253, s2, 56
	s_addc_u32 s71, s31, 0
	v_mov_b32_e32 v224, 0x1000
	v_writelane_b32 v253, s3, 57
	s_add_u32 s2, s30, 0x4400
	s_addc_u32 s3, s31, 0
	v_writelane_b32 v253, s2, 58
	v_mov_b32_e32 v225, 0x2000
	v_mov_b32_e32 v226, 1
	v_writelane_b32 v253, s3, 59
	s_add_u32 s2, s30, 0x4500
	s_addc_u32 s3, s31, 0
	v_writelane_b32 v253, s2, 60
	s_add_u32 s0, s30, 0x114000
	v_mov_b32_e32 v227, 0x3727c5ac
	v_writelane_b32 v253, s3, 61
	v_writelane_b32 v253, s0, 62
	s_addc_u32 s0, s31, 0
	v_writelane_b32 v253, s0, 63
	s_lshr_b32 s0, s6, 3
	s_cmpk_lt_u32 s1, 0x1dc0
	v_writelane_b32 v252, s0, 0
	s_cselect_b64 s[2:3], -1, 0
	v_writelane_b32 v252, s2, 1
	s_lshr_b32 s0, s1, 3
	v_mov_b32_e32 v228, 0x3ecc95a3
	v_writelane_b32 v252, s3, 2
	v_writelane_b32 v252, s0, 3
	s_and_b32 s0, s1, 7
	s_add_u32 s2, s30, 0xd0000
	s_addc_u32 s3, s31, 0
	v_writelane_b32 v252, s2, 4
	s_mul_i32 s0, s0, 34
	v_bfrev_b32_e32 v229, 0.5
	v_writelane_b32 v252, s3, 5
	s_add_u32 s2, s30, 0x90000
	s_addc_u32 s3, s31, 0
	v_writelane_b32 v252, s2, 6
	v_mov_b32_e32 v230, 0x41b17218
	v_mov_b32_e32 v231, 0x3e8293ee
	v_writelane_b32 v252, s3, 7
	v_writelane_b32 v252, s0, 8
	s_add_u32 s0, s30, 0x1a394000
	v_writelane_b32 v252, s0, 9
	s_addc_u32 s0, s31, 0
	s_add_u32 s2, s30, 0x15f94000
	s_addc_u32 s3, s31, 0
	s_add_u32 s84, s30, 0x2514000
	s_addc_u32 s85, s31, 0
	v_writelane_b32 v252, s0, 10
	s_add_u32 s0, s30, 0x1a4a4000
	v_writelane_b32 v252, s0, 11
	s_addc_u32 s0, s31, 0
	v_writelane_b32 v252, s0, 12
	s_add_u32 s0, s30, 0x112000
	v_writelane_b32 v252, s0, 13
	s_addc_u32 s0, s31, 0
	s_cmpk_lt_i32 s1, 0x200
	v_writelane_b32 v252, s0, 14
	s_cselect_b64 s[6:7], -1, 0
	v_writelane_b32 v252, s6, 15
	v_mov_b32_e32 v232, 0xfffff000
	v_mov_b32_e32 v233, 0x1c00
	v_writelane_b32 v252, s7, 16
	s_add_u32 s6, s30, 0x7194200
	s_addc_u32 s7, s31, 0
	v_writelane_b32 v252, s6, 17
	s_add_u32 s0, s30, 0x1d14000
	v_mov_b32_e32 v218, 0x3f317218
	v_writelane_b32 v252, s7, 18
	v_writelane_b32 v252, s0, 19
	s_addc_u32 s0, s31, 0
	s_cmpk_lt_u32 s1, 0x880
	v_writelane_b32 v252, s0, 20
	s_cselect_b64 s[0:1], -1, 0
	v_writelane_b32 v252, s0, 21
	s_ashr_i32 s5, s4, 31
	v_mov_b32_e32 v234, 0x7f800000
	v_writelane_b32 v252, s1, 22
	s_mov_b32 s0, s4
	v_writelane_b32 v252, s0, 23
	v_mov_b32_e32 v235, 0x7fc00000
	v_mov_b32_e32 v236, 0xff800000
	v_writelane_b32 v252, s1, 24
	s_lshl_b64 s[0:1], s[4:5], 11
	v_writelane_b32 v252, s0, 25
	v_mov_b32_e32 v237, 0x1dc0000
	v_mov_b32_e32 v238, 0x1100
	v_writelane_b32 v252, s1, 26
	s_add_u32 s0, s30, 0x1a4ab800
	v_writelane_b32 v252, s0, 27
	s_addc_u32 s0, s31, 0
	v_writelane_b32 v252, s0, 28
	s_add_u32 s0, s30, 0x1a4e7800
	v_writelane_b32 v252, s0, 29
	s_addc_u32 s0, s31, 0
	v_writelane_b32 v252, s0, 30
	s_add_u32 s0, s30, 0x1a4c0000
	v_writelane_b32 v252, s0, 31
	s_addc_u32 s0, s31, 0
	v_writelane_b32 v252, s0, 32
	v_writelane_b32 v252, s36, 33
	v_writelane_b32 v252, s54, 34
	s_mov_b32 s52, 0x78787879
	s_movk_i32 s53, 0xff
	v_writelane_b32 v252, s55, 35
	v_writelane_b32 v252, s60, 36
	s_movk_i32 s18, 0x80
	s_movk_i32 s17, 0xc00
	v_writelane_b32 v252, s61, 37
	s_mov_b32 s19, 0x800000
	s_mov_b32 s37, 0x7f800000
	s_movk_i32 s48, 0x1c00
	s_mov_b32 s51, 0x3f2aaaab
	s_mov_b32 s49, 0x3f317218
	s_mov_b32 s41, 0x33800000
	s_mov_b32 s50, 0x41000000
	s_mov_b32 s40, 0x42a00000
	s_mov_b32 s16, s23
	v_writelane_b32 v252, s64, 38
	s_waitcnt lgkmcnt(0)
	s_barrier
	v_writelane_b32 v252, s65, 39
	v_readlane_b32 s98, v253, 0
	s_cmp_lt_u32 s98, 8
	s_cbranch_scc0 .Lsp_skip
	s_lshl_b32 s98, s98, 10
	v_lshlrev_b32_e32 v4, 2, v222
	v_add_u32_e32 v4, s98, v4
	global_load_dword v68, v4, s[68:69]
	s_waitcnt vmcnt(0)
	v_mul_f32_e32 v1, 0xbfb8aa3b, v68
	v_exp_f32_e32 v1, v1
	s_nop 0
	v_add_f32_e32 v68, 1.0, v1
	v_add_f32_e32 v73, -1.0, v68
	v_sub_f32_e32 v83, v73, v68
	v_add_f32_e32 v83, 1.0, v83
	v_sub_f32_e32 v73, v1, v73
	v_add_f32_e32 v73, v73, v83
	v_frexp_mant_f32_e32 v83, v68
	v_cvt_f64_f32_e32 v[84:85], v68
	v_cmp_gt_f32_e32 vcc, s51, v83
	v_frexp_exp_i32_f64_e32 v83, v[84:85]
	s_nop 0
	v_subbrev_co_u32_e32 v83, vcc, 0, v83, vcc
	v_sub_u32_e32 v84, 0, v83
	v_ldexp_f32 v68, v68, v84
	v_ldexp_f32 v73, v73, v84
	v_add_f32_e32 v84, -1.0, v68
	v_add_f32_e32 v85, 1.0, v84
	v_sub_f32_e32 v85, v68, v85
	v_add_f32_e32 v86, v73, v85
	v_add_f32_e32 v85, 1.0, v68
	v_add_f32_e32 v87, -1.0, v85
	v_sub_f32_e32 v68, v68, v87
	v_add_f32_e32 v68, v73, v68
	v_add_f32_e32 v73, v85, v68
	v_rcp_f32_e32 v92, v73
	v_sub_f32_e32 v85, v73, v85
	v_sub_f32_e32 v68, v68, v85
	v_add_f32_e32 v85, v84, v86
	v_sub_f32_e32 v84, v85, v84
	v_mul_f32_e32 v94, v85, v92
	v_sub_f32_e32 v93, v86, v84
	v_mul_f32_e32 v86, v73, v94
	v_fma_f32 v88, v94, v73, -v86
	v_fmac_f32_e32 v88, v94, v68
	v_add_f32_e32 v84, v86, v88
	v_sub_f32_e32 v87, v85, v84
	v_pk_add_f32 v[90:91], v[84:85], v[86:87] neg_lo:[0,1] neg_hi:[0,1]
	v_mov_b32_e32 v89, v84
	v_pk_add_f32 v[84:85], v[90:91], v[88:89] neg_lo:[0,1] neg_hi:[0,1]
	v_cmp_neq_f32_e32 vcc, s37, v1
	v_add_f32_e32 v85, v93, v85
	v_add_f32_e32 v84, v84, v85
	v_add_f32_e32 v85, v87, v84
	v_mul_f32_e32 v93, v92, v85
	v_mul_f32_e32 v86, v73, v93
	v_fma_f32 v88, v93, v73, -v86
	v_fmac_f32_e32 v88, v93, v68
	v_sub_f32_e32 v68, v87, v85
	v_add_f32_e32 v68, v84, v68
	v_add_f32_e32 v84, v86, v88
	v_sub_f32_e32 v87, v85, v84
	v_pk_add_f32 v[90:91], v[84:85], v[86:87] neg_lo:[0,1] neg_hi:[0,1]
	v_mov_b32_e32 v89, v84
	v_pk_add_f32 v[84:85], v[90:91], v[88:89] neg_lo:[0,1] neg_hi:[0,1]
	v_add_f32_e32 v73, v94, v93
	v_add_f32_e32 v68, v68, v85
	v_add_f32_e32 v68, v84, v68
	v_add_f32_e32 v68, v87, v68
	v_sub_f32_e32 v84, v73, v94
	v_mul_f32_e32 v68, v92, v68
	v_sub_f32_e32 v84, v93, v84
	v_add_f32_e32 v68, v84, v68
	v_add_f32_e32 v85, v73, v68
	v_mul_f32_e32 v86, v85, v85
	v_fmamk_f32 v84, v86, 0x3e9b6dac, v228
	v_fmaak_f32 v219, v86, v84, 0x3f2aaada
	v_cvt_f32_i32_e32 v84, v83
	v_sub_f32_e32 v73, v85, v73
	v_ldexp_f32 v87, v85, 1
	v_mul_f32_e32 v85, v85, v86
	v_pk_mul_f32 v[88:89], v[84:85], v[218:219]
	v_sub_f32_e32 v68, v68, v73
	v_fma_f32 v86, v84, s49, -v88
	v_fmac_f32_e32 v86, 0xb102e308, v84
	v_pk_add_f32 v[84:85], v[88:89], v[86:87]
	v_ldexp_f32 v68, v68, 1
	v_sub_f32_e32 v73, v85, v87
	v_sub_f32_e32 v73, v89, v73
	v_add_f32_e32 v91, v68, v73
	v_mov_b32_e32 v90, v88
	v_pk_add_f32 v[88:89], v[84:85], v[88:89] neg_lo:[0,1] neg_hi:[0,1]
	v_pk_add_f32 v[92:93], v[84:85], v[90:91]
	v_mov_b32_e32 v87, v84
	v_mov_b32_e32 v89, v93
	v_pk_add_f32 v[94:95], v[86:87], v[88:89] neg_lo:[0,1] neg_hi:[0,1]
	v_pk_add_f32 v[86:87], v[86:87], v[88:89]
	v_mov_b32_e32 v90, v91
	v_pk_add_f32 v[88:89], v[86:87], v[84:85] op_sel:[1,0] op_sel_hi:[0,1] neg_lo:[0,1] neg_hi:[0,1]
	v_pk_add_f32 v[96:97], v[92:93], v[88:89] op_sel_hi:[1,0] neg_lo:[0,1] neg_hi:[0,1]
	v_mov_b32_e32 v92, v93
	v_mov_b32_e32 v93, v87
	v_pk_mov_b32 v[88:89], v[84:85], v[88:89] op_sel:[1,0]
	v_mov_b32_e32 v91, v84
	v_pk_add_f32 v[88:89], v[92:93], v[88:89] neg_lo:[0,1] neg_hi:[0,1]
	v_mov_b32_e32 v96, v94
	v_pk_add_f32 v[84:85], v[90:91], v[88:89] neg_lo:[0,1] neg_hi:[0,1]
	v_mov_b32_e32 v95, v87
	v_pk_add_f32 v[88:89], v[96:97], v[84:85]
	s_nop 0
	v_pk_add_f32 v[90:91], v[88:89], v[88:89] op_sel:[0,1] op_sel_hi:[1,0]
	s_nop 0
	v_pk_add_f32 v[86:87], v[86:87], v[90:91] op_sel:[1,0] op_sel_hi:[0,1]
	v_mov_b32_e32 v89, v86
	v_pk_add_f32 v[92:93], v[88:89], v[94:95] neg_lo:[0,1] neg_hi:[0,1]
	v_mov_b32_e32 v85, v90
	v_sub_f32_e32 v68, v88, v92
	v_pk_add_f32 v[84:85], v[84:85], v[92:93] neg_lo:[0,1] neg_hi:[0,1]
	v_sub_f32_e32 v68, v94, v68
	v_add_f32_e32 v68, v84, v68
	v_add_f32_e32 v68, v68, v85
	v_add_f32_e32 v68, v86, v68
	v_cndmask_b32_e32 v68, v234, v68, vcc
	v_cmp_ngt_f32_e32 vcc, -1.0, v1
	s_nop 1
	v_cndmask_b32_e32 v68, v235, v68, vcc
	v_cmp_neq_f32_e32 vcc, -1.0, v1
	s_nop 1
	v_cndmask_b32_e32 v68, v236, v68, vcc
	v_cmp_lt_f32_e64 vcc, |v1|, s41
	s_nop 1
	v_cndmask_b32_e32 v1, v68, v1, vcc
	s_add_u32 s98, s30, 0x8000
	s_addc_u32 s99, s31, 0
	global_store_dword v4, v1, s[98:99]
.Lsp_skip:
	s_branch .LBB0_119
.LBB0_117:
	s_or_b64 exec, exec, s[8:9]
	s_waitcnt vmcnt(0)

.LBB0_717:
	v_ashrrev_i32_e32 v44, 2, v0
	s_add_i32 s0, s0, s1
	v_and_b32_e32 v14, -16, v44
	v_lshlrev_b32_e32 v1, 2, v0
	s_and_b32 s22, s0, 0xffff
	v_ashrrev_i32_e32 v15, 31, v14
	v_and_b32_e32 v2, 0xfc, v1
	v_lshl_add_u64 v[42:43], v[14:15], 0, s[22:23]
	v_mov_b64_e32 v[0:1], s[24:25]
	v_lshlrev_b32_e32 v45, 2, v2
	v_mad_i64_i32 v[0:1], s[0:1], v42, s48, v[0:1]
	v_lshlrev_b32_e32 v2, 1, v2
	v_lshl_add_u64 v[0:1], v[0:1], 0, v[2:3]
	s_movk_i32 s0, 0x1000
	v_add_co_u32_e32 v12, vcc, s0, v0
	s_movk_i32 s0, 0x2000
	s_nop 0
	v_addc_co_u32_e32 v13, vcc, 0, v1, vcc
	v_add_co_u32_e32 v16, vcc, s0, v0
	s_movk_i32 s0, 0x4000
	s_nop 0
	v_addc_co_u32_e32 v17, vcc, 0, v1, vcc
	v_readlane_b32 s4, v252, 42
	v_add_co_u32_e32 v18, vcc, s0, v0
	v_readlane_b32 s5, v252, 43
	s_nop 0
	v_addc_co_u32_e32 v19, vcc, 0, v1, vcc
	s_movk_i32 s0, 0x6000
	s_waitcnt lgkmcnt(0)
	s_barrier
	global_load_dwordx4 v[8:11], v45, s[4:5]
	v_readlane_b32 s4, v252, 44
	v_add_co_u32_e32 v20, vcc, s0, v0
	v_readlane_b32 s5, v252, 45
	s_nop 0
	v_addc_co_u32_e32 v21, vcc, 0, v1, vcc
	s_mov_b32 s0, 0x8000
	v_add_u32_e32 v15, 32, v45
	v_lshlrev_b64 v[42:43], 11, v[42:43]
	global_load_dwordx4 v[4:7], v45, s[4:5]
	global_load_dwordx2 v[50:51], v[12:13], off offset:512
	global_load_dwordx2 v[40:41], v[16:17], off offset:3584
	global_load_dwordx2 v[38:39], v[18:19], off offset:2560
	global_load_dwordx2 v[36:37], v[20:21], off offset:1536
	v_add_co_u32_e32 v12, vcc, s0, v0
	s_mov_b32 s0, 0x9000
	s_nop 0
	v_addc_co_u32_e32 v13, vcc, 0, v1, vcc
	v_add_co_u32_e32 v16, vcc, s0, v0
	s_mov_b32 s0, 0xb000
	s_nop 0
	v_addc_co_u32_e32 v17, vcc, 0, v1, vcc
	v_add_co_u32_e32 v18, vcc, s0, v0
	s_mov_b32 s0, 0xd000
	s_nop 0
	v_addc_co_u32_e32 v19, vcc, 0, v1, vcc
	v_add_co_u32_e32 v20, vcc, s0, v0
	s_mov_b32 s0, 0xf000
	s_nop 0
	v_addc_co_u32_e32 v21, vcc, 0, v1, vcc
	global_load_dwordx2 v[34:35], v[12:13], off offset:512
	global_load_dwordx2 v[32:33], v[16:17], off offset:3584
	global_load_dwordx2 v[30:31], v[18:19], off offset:2560
	global_load_dwordx2 v[28:29], v[20:21], off offset:1536
	v_add_co_u32_e32 v12, vcc, s0, v0
	s_mov_b32 s0, 0x10000
	s_nop 0
	v_addc_co_u32_e32 v13, vcc, 0, v1, vcc
	v_add_co_u32_e32 v16, vcc, s0, v0
	s_mov_b32 s0, 0x12000
	s_nop 0
	v_addc_co_u32_e32 v17, vcc, 0, v1, vcc
	v_add_co_u32_e32 v18, vcc, s0, v0
	s_mov_b32 s0, 0x14000
	s_nop 0
	v_addc_co_u32_e32 v19, vcc, 0, v1, vcc
	v_add_co_u32_e32 v20, vcc, s0, v0
	s_mov_b32 s0, 0x16000
	s_nop 0
	v_addc_co_u32_e32 v21, vcc, 0, v1, vcc
	global_load_dwordx2 v[26:27], v[12:13], off offset:512
	global_load_dwordx2 v[24:25], v[16:17], off offset:3584
	global_load_dwordx2 v[22:23], v[18:19], off offset:2560
	s_nop 0
	global_load_dwordx2 v[20:21], v[20:21], off offset:1536
	v_add_co_u32_e32 v12, vcc, s0, v0
	s_mov_b32 s0, 0x17000
	s_nop 0
	v_addc_co_u32_e32 v13, vcc, 0, v1, vcc
	v_add_co_u32_e32 v16, vcc, s0, v0
	s_mov_b32 s0, 0x19000
	s_nop 0
	v_addc_co_u32_e32 v17, vcc, 0, v1, vcc
	v_lshl_add_u32 v18, v14, 10, v15
	v_add_co_u32_e32 v52, vcc, s0, v0
	s_waitcnt vmcnt(15)
	ds_read_b128 v[46:49], v18
	v_addc_co_u32_e32 v53, vcc, 0, v1, vcc
	s_mov_b32 s0, 0x1b000
	v_add_co_u32_e32 v0, vcc, s0, v0
	s_waitcnt lgkmcnt(0)
	v_add_f32_e32 v45, v46, v47
	v_addc_co_u32_e32 v1, vcc, 0, v1, vcc
	global_load_dwordx2 v[18:19], v[12:13], off offset:512
	s_nop 0
	global_load_dwordx2 v[16:17], v[16:17], off offset:3584
	s_nop 0
	global_load_dwordx2 v[12:13], v[52:53], off offset:2560
	s_nop 0
	global_load_dwordx2 v[0:1], v[0:1], off offset:1536
	v_mov_b32_e32 v52, v222
	v_add_f32_e32 v45, v45, v48
	v_lshlrev_b32_e32 v52, 2, v52
	v_add_f32_e32 v45, v45, v49
	v_bitop3_b32 v52, v52, s18, v229 bitop3:0x6c
	s_nop 1
	v_add_f32_dpp v45, v45, v45 quad_perm:[1,0,3,2] row_mask:0xf bank_mask:0xf
	s_nop 1
	v_add_f32_dpp v45, v45, v45 quad_perm:[2,3,0,1] row_mask:0xf bank_mask:0xf
	s_nop 1
	v_add_f32_dpp v45, v45, v45 row_half_mirror row_mask:0xf bank_mask:0xf
	s_nop 1
	v_add_f32_dpp v45, v45, v45 row_mirror row_mask:0xf bank_mask:0xf
	s_nop 1
	v_add_f32_dpp v45, v45, v45 row_bcast:15 row_mask:0xa bank_mask:0xf
	s_nop 1
	v_add_f32_dpp v45, v45, v45 row_bcast:31 row_mask:0xc bank_mask:0xf
	s_nop 1
	v_readlane_b32 s98, v45, 63
	s_nop 1
	v_mov_b32_e32 v45, s98
	v_lshl_add_u64 v[42:43], s[30:31], 0, v[42:43]
	v_lshl_add_u64 v[42:43], v[42:43], 0, v[2:3]
	s_mov_b32 s0, 0x2d94000
	s_waitcnt lgkmcnt(0)
	v_mov_b32_e32 v52, v222
	s_nop 0
	v_lshlrev_b32_e32 v52, 2, v52
	v_bitop3_b32 v52, v52, 64, v229 bitop3:0x6c
	s_waitcnt lgkmcnt(0)
	v_mov_b32_e32 v52, v222
	s_nop 0
	v_lshlrev_b32_e32 v52, 2, v52
	v_bitop3_b32 v52, v52, 32, v229 bitop3:0x6c
	s_waitcnt lgkmcnt(0)
	v_mov_b32_e32 v52, v222
	s_nop 0
	v_lshlrev_b32_e32 v52, 2, v52
	v_bitop3_b32 v52, v52, 16, v229 bitop3:0x6c
	s_waitcnt lgkmcnt(0)
	v_mov_b32_e32 v52, v222
	s_nop 0
	v_lshlrev_b32_e32 v52, 2, v52
	v_bitop3_b32 v52, v52, 8, v229 bitop3:0x6c
	s_waitcnt lgkmcnt(0)
	v_mov_b32_e32 v52, v222
	s_nop 0
	v_lshlrev_b32_e32 v52, 2, v52
	v_bitop3_b32 v52, v52, 4, v229 bitop3:0x6c
	s_waitcnt lgkmcnt(0)
	v_mul_f32_e32 v52, 0x3b800000, v45
	v_pk_add_f32 v[46:47], v[46:47], v[52:53] op_sel_hi:[1,0] neg_lo:[0,1] neg_hi:[0,1]
	v_pk_add_f32 v[48:49], v[48:49], v[52:53] op_sel_hi:[1,0] neg_lo:[0,1] neg_hi:[0,1]
	v_pk_mul_f32 v[52:53], v[46:47], v[46:47]
	v_pk_mul_f32 v[54:55], v[48:49], v[48:49]
	v_add_f32_e32 v45, v52, v53
	v_mov_b32_e32 v52, v222
	v_add_f32_e32 v45, v54, v45
	v_lshlrev_b32_e32 v52, 2, v52
	v_add_f32_e32 v45, v55, v45
	v_bitop3_b32 v52, v52, s18, v229 bitop3:0x6c
	s_nop 1
	v_add_f32_dpp v45, v45, v45 quad_perm:[1,0,3,2] row_mask:0xf bank_mask:0xf
	s_nop 1
	v_add_f32_dpp v45, v45, v45 quad_perm:[2,3,0,1] row_mask:0xf bank_mask:0xf
	s_nop 1
	v_add_f32_dpp v45, v45, v45 row_half_mirror row_mask:0xf bank_mask:0xf
	s_nop 1
	v_add_f32_dpp v45, v45, v45 row_mirror row_mask:0xf bank_mask:0xf
	s_nop 1
	v_add_f32_dpp v45, v45, v45 row_bcast:15 row_mask:0xa bank_mask:0xf
	s_nop 1
	v_add_f32_dpp v45, v45, v45 row_bcast:31 row_mask:0xc bank_mask:0xf
	s_nop 1
	v_readlane_b32 s98, v45, 63
	s_nop 1
	v_mov_b32_e32 v45, s98
	s_waitcnt lgkmcnt(0)
	v_mov_b32_e32 v52, v222
	s_nop 0
	v_lshlrev_b32_e32 v52, 2, v52
	v_bitop3_b32 v52, v52, 64, v229 bitop3:0x6c
	s_waitcnt lgkmcnt(0)
	v_mov_b32_e32 v52, v222
	s_nop 0
	v_lshlrev_b32_e32 v52, 2, v52
	v_bitop3_b32 v52, v52, 32, v229 bitop3:0x6c
	s_waitcnt lgkmcnt(0)
	v_mov_b32_e32 v52, v222
	s_nop 0
	v_lshlrev_b32_e32 v52, 2, v52
	v_bitop3_b32 v52, v52, 16, v229 bitop3:0x6c
	s_waitcnt lgkmcnt(0)
	v_mov_b32_e32 v52, v222
	s_nop 0
	v_lshlrev_b32_e32 v52, 2, v52
	v_bitop3_b32 v52, v52, 8, v229 bitop3:0x6c
	s_waitcnt lgkmcnt(0)
	v_mov_b32_e32 v52, v222
	s_nop 0
	v_lshlrev_b32_e32 v52, 2, v52
	v_bitop3_b32 v52, v52, 4, v229 bitop3:0x6c
	s_waitcnt lgkmcnt(0)
	v_fmamk_f32 v45, v45, 0x3b800000, v227
	v_mul_f32_e32 v52, 0x4b800000, v45
	v_cmp_gt_f32_e32 vcc, s19, v45
	s_nop 1
	v_cndmask_b32_e32 v45, v45, v52, vcc
	v_rsq_f32_e32 v45, v45
	s_nop 0
	v_mul_f32_e32 v52, 0x45800000, v45
	v_cndmask_b32_e32 v45, v45, v52, vcc
	v_mul_f32_e32 v46, v46, v45
	s_waitcnt vmcnt(16)
	v_fma_f32 v46, v8, v46, v4
	v_mul_f32_e32 v52, 0xbfb8aa3b, v46
	v_exp_f32_e32 v52, v52
	v_mul_f32_e32 v47, v47, v45
	v_fma_f32 v47, v9, v47, v5
	v_mul_f32_e32 v48, v48, v45
	v_add_f32_e32 v52, 1.0, v52
	v_rcp_f32_e32 v52, v52
	v_mul_f32_e32 v45, v49, v45
	v_mul_f32_e32 v53, 0xbfb8aa3b, v47
	v_fma_f32 v48, v10, v48, v6
	v_mul_f32_e32 v46, v46, v52
	s_waitcnt vmcnt(15)
	v_lshlrev_b32_e32 v52, 16, v50
	v_fma_f32 v45, v11, v45, v7
	v_exp_f32_e32 v53, v53
	v_mul_f32_e32 v46, v46, v52
	v_mul_f32_e32 v52, 0xbfb8aa3b, v48
	v_mul_f32_e32 v49, 0xbfb8aa3b, v45
	v_exp_f32_e32 v52, v52
	v_exp_f32_e32 v49, v49
	v_add_f32_e32 v53, 1.0, v53
	v_rcp_f32_e32 v53, v53
	v_add_f32_e32 v52, 1.0, v52
	v_add_f32_e32 v49, 1.0, v49
	v_rcp_f32_e32 v52, v52
	v_rcp_f32_e32 v49, v49
	v_mul_f32_e32 v47, v47, v53
	v_and_b32_e32 v50, 0xffff0000, v50
	v_mul_f32_e32 v47, v47, v50
	v_mul_f32_e32 v48, v48, v52
	v_lshlrev_b32_e32 v50, 16, v51
	v_mul_f32_e32 v45, v45, v49
	v_and_b32_e32 v49, 0xffff0000, v51
	v_mul_f32_e32 v48, v48, v50
	v_mul_f32_e32 v45, v45, v49
	v_or_b32_e32 v52, 1, v14
	v_cvt_pk_bf16_f32 v51, v48, v45
	v_lshl_add_u32 v45, v52, 10, v15
	v_cvt_pk_bf16_f32 v50, v46, v47
	ds_read_b128 v[46:49], v45
	v_add_co_u32_e32 v42, vcc, s0, v42
	v_ashrrev_i32_e32 v53, 31, v52
	s_nop 0
	v_addc_co_u32_e32 v43, vcc, 0, v43, vcc
	global_store_dwordx2 v[42:43], v[50:51], off offset:1024
	v_mov_b32_e32 v43, v222
	s_waitcnt lgkmcnt(0)
	v_add_f32_e32 v42, v46, v47
	v_add_f32_e32 v42, v42, v48
	v_lshlrev_b32_e32 v43, 2, v43
	v_add_f32_e32 v42, v42, v49
	v_bitop3_b32 v43, v43, s18, v229 bitop3:0x6c
	s_nop 1
	v_add_f32_dpp v42, v42, v42 quad_perm:[1,0,3,2] row_mask:0xf bank_mask:0xf
	s_nop 1
	v_add_f32_dpp v42, v42, v42 quad_perm:[2,3,0,1] row_mask:0xf bank_mask:0xf
	s_nop 1
	v_add_f32_dpp v42, v42, v42 row_half_mirror row_mask:0xf bank_mask:0xf
	s_nop 1
	v_add_f32_dpp v42, v42, v42 row_mirror row_mask:0xf bank_mask:0xf
	s_nop 1
	v_add_f32_dpp v42, v42, v42 row_bcast:15 row_mask:0xa bank_mask:0xf
	s_nop 1
	v_add_f32_dpp v42, v42, v42 row_bcast:31 row_mask:0xc bank_mask:0xf
	s_nop 1
	v_readlane_b32 s98, v42, 63
	s_nop 1
	v_mov_b32_e32 v42, s98
	s_waitcnt lgkmcnt(0)
	v_mov_b32_e32 v43, v222
	s_nop 0
	v_lshlrev_b32_e32 v43, 2, v43
	v_bitop3_b32 v43, v43, 64, v229 bitop3:0x6c
	s_waitcnt lgkmcnt(0)
	v_mov_b32_e32 v43, v222
	s_nop 0
	v_lshlrev_b32_e32 v43, 2, v43
	v_bitop3_b32 v43, v43, 32, v229 bitop3:0x6c
	s_waitcnt lgkmcnt(0)
	v_mov_b32_e32 v43, v222
	s_nop 0
	v_lshlrev_b32_e32 v43, 2, v43
	v_bitop3_b32 v43, v43, 16, v229 bitop3:0x6c
	s_waitcnt lgkmcnt(0)
	v_mov_b32_e32 v43, v222
	s_nop 0
	v_lshlrev_b32_e32 v43, 2, v43
	v_bitop3_b32 v43, v43, 8, v229 bitop3:0x6c
	s_waitcnt lgkmcnt(0)
	v_mov_b32_e32 v43, v222
	s_nop 0
	v_lshlrev_b32_e32 v43, 2, v43
	v_bitop3_b32 v43, v43, 4, v229 bitop3:0x6c
	s_waitcnt lgkmcnt(0)
	v_mul_f32_e32 v42, 0x3b800000, v42
	v_pk_add_f32 v[46:47], v[46:47], v[42:43] op_sel_hi:[1,0] neg_lo:[0,1] neg_hi:[0,1]
	v_pk_add_f32 v[42:43], v[48:49], v[42:43] op_sel_hi:[1,0] neg_lo:[0,1] neg_hi:[0,1]
	v_pk_mul_f32 v[48:49], v[46:47], v[46:47]
	v_pk_mul_f32 v[50:51], v[42:43], v[42:43]
	v_add_f32_e32 v45, v48, v49
	v_mov_b32_e32 v48, v222
	v_add_f32_e32 v45, v50, v45
	v_lshlrev_b32_e32 v48, 2, v48
	v_add_f32_e32 v45, v51, v45
	v_bitop3_b32 v48, v48, s18, v229 bitop3:0x6c
	s_nop 1
	v_add_f32_dpp v45, v45, v45 quad_perm:[1,0,3,2] row_mask:0xf bank_mask:0xf
	s_nop 1
	v_add_f32_dpp v45, v45, v45 quad_perm:[2,3,0,1] row_mask:0xf bank_mask:0xf
	s_nop 1
	v_add_f32_dpp v45, v45, v45 row_half_mirror row_mask:0xf bank_mask:0xf
	s_nop 1
	v_add_f32_dpp v45, v45, v45 row_mirror row_mask:0xf bank_mask:0xf
	s_nop 1
	v_add_f32_dpp v45, v45, v45 row_bcast:15 row_mask:0xa bank_mask:0xf
	s_nop 1
	v_add_f32_dpp v45, v45, v45 row_bcast:31 row_mask:0xc bank_mask:0xf
	s_nop 1
	v_readlane_b32 s98, v45, 63
	s_nop 1
	v_mov_b32_e32 v45, s98
	v_or_b32_e32 v50, 2, v14
	v_ashrrev_i32_e32 v51, 31, v50
	s_waitcnt lgkmcnt(0)
	v_mov_b32_e32 v48, v222
	s_nop 0
	v_lshlrev_b32_e32 v48, 2, v48
	v_bitop3_b32 v48, v48, 64, v229 bitop3:0x6c
	s_waitcnt lgkmcnt(0)
	v_mov_b32_e32 v48, v222
	s_nop 0
	v_lshlrev_b32_e32 v48, 2, v48
	v_bitop3_b32 v48, v48, 32, v229 bitop3:0x6c
	s_waitcnt lgkmcnt(0)
	v_mov_b32_e32 v48, v222
	s_nop 0
	v_lshlrev_b32_e32 v48, 2, v48
	v_bitop3_b32 v48, v48, 16, v229 bitop3:0x6c
	s_waitcnt lgkmcnt(0)
	v_mov_b32_e32 v48, v222
	s_nop 0
	v_lshlrev_b32_e32 v48, 2, v48
	v_bitop3_b32 v48, v48, 8, v229 bitop3:0x6c
	s_waitcnt lgkmcnt(0)
	v_mov_b32_e32 v48, v222
	s_nop 0
	v_lshlrev_b32_e32 v48, 2, v48
	v_bitop3_b32 v48, v48, 4, v229 bitop3:0x6c
	s_waitcnt lgkmcnt(0)
	v_fmamk_f32 v45, v45, 0x3b800000, v227
	v_mul_f32_e32 v48, 0x4b800000, v45
	v_cmp_gt_f32_e32 vcc, s19, v45
	s_nop 1
	v_cndmask_b32_e32 v45, v45, v48, vcc
	v_rsq_f32_e32 v45, v45
	s_nop 0
	v_mul_f32_e32 v48, 0x45800000, v45
	v_cndmask_b32_e32 v45, v45, v48, vcc
	v_mul_f32_e32 v46, v46, v45
	v_fma_f32 v46, v8, v46, v4
	v_mul_f32_e32 v48, 0xbfb8aa3b, v46
	v_exp_f32_e32 v48, v48
	v_mul_f32_e32 v47, v47, v45
	v_fma_f32 v47, v9, v47, v5
	v_mul_f32_e32 v42, v42, v45
	v_add_f32_e32 v48, 1.0, v48
	v_rcp_f32_e32 v48, v48
	v_mul_f32_e32 v43, v43, v45
	v_mul_f32_e32 v49, 0xbfb8aa3b, v47
	v_fma_f32 v42, v10, v42, v6
	v_mul_f32_e32 v46, v46, v48
	s_waitcnt vmcnt(15)
	v_lshlrev_b32_e32 v48, 16, v40
	v_fma_f32 v43, v11, v43, v7
	v_exp_f32_e32 v49, v49
	v_mul_f32_e32 v46, v46, v48
	v_mul_f32_e32 v48, 0xbfb8aa3b, v42
	v_mul_f32_e32 v45, 0xbfb8aa3b, v43
	v_exp_f32_e32 v48, v48
	v_exp_f32_e32 v45, v45
	v_add_f32_e32 v49, 1.0, v49
	v_rcp_f32_e32 v49, v49
	v_add_f32_e32 v48, 1.0, v48
	v_add_f32_e32 v45, 1.0, v45
	v_rcp_f32_e32 v48, v48
	v_rcp_f32_e32 v45, v45
	v_mul_f32_e32 v47, v47, v49
	v_and_b32_e32 v40, 0xffff0000, v40
	v_mul_f32_e32 v40, v47, v40
	v_mul_f32_e32 v42, v42, v48
	v_lshlrev_b32_e32 v47, 16, v41
	v_mul_f32_e32 v43, v43, v45
	v_and_b32_e32 v41, 0xffff0000, v41
	v_mul_f32_e32 v42, v42, v47
	v_mul_f32_e32 v41, v43, v41
	v_cvt_pk_bf16_f32 v46, v46, v40
	v_cvt_pk_bf16_f32 v47, v42, v41
	v_lshl_add_u64 v[40:41], v[52:53], 0, s[22:23]
	v_lshlrev_b64 v[40:41], 11, v[40:41]
	v_lshl_add_u64 v[40:41], s[30:31], 0, v[40:41]
	v_lshl_add_u64 v[48:49], v[40:41], 0, v[2:3]
	v_lshl_add_u32 v40, v50, 10, v15
	ds_read_b128 v[40:43], v40
	v_add_co_u32_e32 v48, vcc, s0, v48
	s_waitcnt lgkmcnt(0)
	v_add_f32_e32 v45, v40, v41
	v_addc_co_u32_e32 v49, vcc, 0, v49, vcc
	global_store_dwordx2 v[48:49], v[46:47], off offset:1024
	v_mov_b32_e32 v46, v222
	v_add_f32_e32 v45, v45, v42
	v_lshlrev_b32_e32 v46, 2, v46
	v_add_f32_e32 v45, v45, v43
	v_bitop3_b32 v46, v46, s18, v229 bitop3:0x6c
	s_nop 1
	v_add_f32_dpp v45, v45, v45 quad_perm:[1,0,3,2] row_mask:0xf bank_mask:0xf
	s_nop 1
	v_add_f32_dpp v45, v45, v45 quad_perm:[2,3,0,1] row_mask:0xf bank_mask:0xf
	s_nop 1
	v_add_f32_dpp v45, v45, v45 row_half_mirror row_mask:0xf bank_mask:0xf
	s_nop 1
	v_add_f32_dpp v45, v45, v45 row_mirror row_mask:0xf bank_mask:0xf
	s_nop 1
	v_add_f32_dpp v45, v45, v45 row_bcast:15 row_mask:0xa bank_mask:0xf
	s_nop 1
	v_add_f32_dpp v45, v45, v45 row_bcast:31 row_mask:0xc bank_mask:0xf
	s_nop 1
	v_readlane_b32 s98, v45, 63
	s_nop 1
	v_mov_b32_e32 v45, s98
	s_waitcnt lgkmcnt(0)
	v_mov_b32_e32 v46, v222
	s_nop 0
	v_lshlrev_b32_e32 v46, 2, v46
	v_bitop3_b32 v46, v46, 64, v229 bitop3:0x6c
	s_waitcnt lgkmcnt(0)
	v_mov_b32_e32 v46, v222
	s_nop 0
	v_lshlrev_b32_e32 v46, 2, v46
	v_bitop3_b32 v46, v46, 32, v229 bitop3:0x6c
	s_waitcnt lgkmcnt(0)
	v_mov_b32_e32 v46, v222
	s_nop 0
	v_lshlrev_b32_e32 v46, 2, v46
	v_bitop3_b32 v46, v46, 16, v229 bitop3:0x6c
	s_waitcnt lgkmcnt(0)
	v_mov_b32_e32 v46, v222
	s_nop 0
	v_lshlrev_b32_e32 v46, 2, v46
	v_bitop3_b32 v46, v46, 8, v229 bitop3:0x6c
	s_waitcnt lgkmcnt(0)
	v_mov_b32_e32 v46, v222
	s_nop 0
	v_lshlrev_b32_e32 v46, 2, v46
	v_bitop3_b32 v46, v46, 4, v229 bitop3:0x6c
	s_waitcnt lgkmcnt(0)
	v_mul_f32_e32 v46, 0x3b800000, v45
	v_pk_add_f32 v[40:41], v[40:41], v[46:47] op_sel_hi:[1,0] neg_lo:[0,1] neg_hi:[0,1]
	v_pk_add_f32 v[42:43], v[42:43], v[46:47] op_sel_hi:[1,0] neg_lo:[0,1] neg_hi:[0,1]
	v_pk_mul_f32 v[46:47], v[40:41], v[40:41]
	v_pk_mul_f32 v[48:49], v[42:43], v[42:43]
	v_add_f32_e32 v45, v46, v47
	v_mov_b32_e32 v46, v222
	v_add_f32_e32 v45, v48, v45
	v_lshlrev_b32_e32 v46, 2, v46
	v_add_f32_e32 v45, v49, v45
	v_bitop3_b32 v46, v46, s18, v229 bitop3:0x6c
	s_nop 1
	v_add_f32_dpp v45, v45, v45 quad_perm:[1,0,3,2] row_mask:0xf bank_mask:0xf
	s_nop 1
	v_add_f32_dpp v45, v45, v45 quad_perm:[2,3,0,1] row_mask:0xf bank_mask:0xf
	s_nop 1
	v_add_f32_dpp v45, v45, v45 row_half_mirror row_mask:0xf bank_mask:0xf
	s_nop 1
	v_add_f32_dpp v45, v45, v45 row_mirror row_mask:0xf bank_mask:0xf
	s_nop 1
	v_add_f32_dpp v45, v45, v45 row_bcast:15 row_mask:0xa bank_mask:0xf
	s_nop 1
	v_add_f32_dpp v45, v45, v45 row_bcast:31 row_mask:0xc bank_mask:0xf
	s_nop 1
	v_readlane_b32 s98, v45, 63
	s_nop 1
	v_mov_b32_e32 v45, s98
	v_or_b32_e32 v48, 3, v14
	v_ashrrev_i32_e32 v49, 31, v48
	s_waitcnt lgkmcnt(0)
	v_mov_b32_e32 v46, v222
	s_nop 0
	v_lshlrev_b32_e32 v46, 2, v46
	v_bitop3_b32 v46, v46, 64, v229 bitop3:0x6c
	s_waitcnt lgkmcnt(0)
	v_mov_b32_e32 v46, v222
	s_nop 0
	v_lshlrev_b32_e32 v46, 2, v46
	v_bitop3_b32 v46, v46, 32, v229 bitop3:0x6c
	s_waitcnt lgkmcnt(0)
	v_mov_b32_e32 v46, v222
	s_nop 0
	v_lshlrev_b32_e32 v46, 2, v46
	v_bitop3_b32 v46, v46, 16, v229 bitop3:0x6c
	s_waitcnt lgkmcnt(0)
	v_mov_b32_e32 v46, v222
	s_nop 0
	v_lshlrev_b32_e32 v46, 2, v46
	v_bitop3_b32 v46, v46, 8, v229 bitop3:0x6c
	s_waitcnt lgkmcnt(0)
	v_mov_b32_e32 v46, v222
	s_nop 0
	v_lshlrev_b32_e32 v46, 2, v46
	v_bitop3_b32 v46, v46, 4, v229 bitop3:0x6c
	s_waitcnt lgkmcnt(0)
	v_fmamk_f32 v45, v45, 0x3b800000, v227
	v_mul_f32_e32 v46, 0x4b800000, v45
	v_cmp_gt_f32_e32 vcc, s19, v45
	s_nop 1
	v_cndmask_b32_e32 v45, v45, v46, vcc
	v_rsq_f32_e32 v45, v45
	s_nop 0
	v_mul_f32_e32 v46, 0x45800000, v45
	v_cndmask_b32_e32 v45, v45, v46, vcc
	v_mul_f32_e32 v40, v40, v45
	v_fma_f32 v40, v8, v40, v4
	v_mul_f32_e32 v46, 0xbfb8aa3b, v40
	v_exp_f32_e32 v46, v46
	v_mul_f32_e32 v41, v41, v45
	v_fma_f32 v41, v9, v41, v5
	v_mul_f32_e32 v47, 0xbfb8aa3b, v41
	v_add_f32_e32 v46, 1.0, v46
	v_exp_f32_e32 v47, v47
	v_rcp_f32_e32 v46, v46
	v_mul_f32_e32 v42, v42, v45
	v_mul_f32_e32 v43, v43, v45
	v_add_f32_e32 v47, 1.0, v47
	v_mul_f32_e32 v40, v40, v46
	s_waitcnt vmcnt(15)
	v_lshlrev_b32_e32 v46, 16, v38
	v_fma_f32 v42, v10, v42, v6
	v_fma_f32 v43, v11, v43, v7
	v_rcp_f32_e32 v47, v47
	v_mul_f32_e32 v40, v40, v46
	v_mul_f32_e32 v46, 0xbfb8aa3b, v42
	v_mul_f32_e32 v45, 0xbfb8aa3b, v43
	v_exp_f32_e32 v46, v46
	v_exp_f32_e32 v45, v45
	v_mul_f32_e32 v41, v41, v47
	v_and_b32_e32 v38, 0xffff0000, v38
	v_add_f32_e32 v46, 1.0, v46
	v_mul_f32_e32 v38, v41, v38
	v_add_f32_e32 v41, 1.0, v45
	v_rcp_f32_e32 v46, v46
	v_rcp_f32_e32 v41, v41
	v_lshlrev_b32_e32 v45, 16, v39
	v_and_b32_e32 v39, 0xffff0000, v39
	v_mul_f32_e32 v42, v42, v46
	v_mul_f32_e32 v41, v43, v41
	v_mul_f32_e32 v45, v42, v45
	v_mul_f32_e32 v39, v41, v39
	v_cvt_pk_bf16_f32 v42, v40, v38
	v_cvt_pk_bf16_f32 v43, v45, v39
	v_lshl_add_u64 v[38:39], v[50:51], 0, s[22:23]
	v_lshlrev_b64 v[38:39], 11, v[38:39]
	v_lshl_add_u64 v[38:39], s[30:31], 0, v[38:39]
	v_lshl_add_u64 v[46:47], v[38:39], 0, v[2:3]
	v_lshl_add_u32 v38, v48, 10, v15
	ds_read_b128 v[38:41], v38
	v_add_co_u32_e32 v46, vcc, s0, v46
	s_nop 1
	v_addc_co_u32_e32 v47, vcc, 0, v47, vcc
	global_store_dwordx2 v[46:47], v[42:43], off offset:1024
	v_mov_b32_e32 v43, v222
	s_waitcnt lgkmcnt(0)
	v_add_f32_e32 v42, v38, v39
	v_add_f32_e32 v42, v42, v40
	v_lshlrev_b32_e32 v43, 2, v43
	v_add_f32_e32 v42, v42, v41
	v_bitop3_b32 v43, v43, s18, v229 bitop3:0x6c
	s_nop 1
	v_add_f32_dpp v42, v42, v42 quad_perm:[1,0,3,2] row_mask:0xf bank_mask:0xf
	s_nop 1
	v_add_f32_dpp v42, v42, v42 quad_perm:[2,3,0,1] row_mask:0xf bank_mask:0xf
	s_nop 1
	v_add_f32_dpp v42, v42, v42 row_half_mirror row_mask:0xf bank_mask:0xf
	s_nop 1
	v_add_f32_dpp v42, v42, v42 row_mirror row_mask:0xf bank_mask:0xf
	s_nop 1
	v_add_f32_dpp v42, v42, v42 row_bcast:15 row_mask:0xa bank_mask:0xf
	s_nop 1
	v_add_f32_dpp v42, v42, v42 row_bcast:31 row_mask:0xc bank_mask:0xf
	s_nop 1
	v_readlane_b32 s98, v42, 63
	s_nop 1
	v_mov_b32_e32 v42, s98
	s_waitcnt lgkmcnt(0)
	v_mov_b32_e32 v43, v222
	s_nop 0
	v_lshlrev_b32_e32 v43, 2, v43
	v_bitop3_b32 v43, v43, 64, v229 bitop3:0x6c
	s_waitcnt lgkmcnt(0)
	v_mov_b32_e32 v43, v222
	s_nop 0
	v_lshlrev_b32_e32 v43, 2, v43
	v_bitop3_b32 v43, v43, 32, v229 bitop3:0x6c
	s_waitcnt lgkmcnt(0)
	v_mov_b32_e32 v43, v222
	s_nop 0
	v_lshlrev_b32_e32 v43, 2, v43
	v_bitop3_b32 v43, v43, 16, v229 bitop3:0x6c
	s_waitcnt lgkmcnt(0)
	v_mov_b32_e32 v43, v222
	s_nop 0
	v_lshlrev_b32_e32 v43, 2, v43
	v_bitop3_b32 v43, v43, 8, v229 bitop3:0x6c
	s_waitcnt lgkmcnt(0)
	v_mov_b32_e32 v43, v222
	s_nop 0
	v_lshlrev_b32_e32 v43, 2, v43
	v_bitop3_b32 v43, v43, 4, v229 bitop3:0x6c
	s_waitcnt lgkmcnt(0)
	v_mul_f32_e32 v42, 0x3b800000, v42
	v_pk_add_f32 v[38:39], v[38:39], v[42:43] op_sel_hi:[1,0] neg_lo:[0,1] neg_hi:[0,1]
	v_pk_add_f32 v[40:41], v[40:41], v[42:43] op_sel_hi:[1,0] neg_lo:[0,1] neg_hi:[0,1]
	v_pk_mul_f32 v[42:43], v[38:39], v[38:39]
	v_pk_mul_f32 v[46:47], v[40:41], v[40:41]
	v_add_f32_e32 v42, v42, v43
	v_mov_b32_e32 v43, v222
	v_add_f32_e32 v42, v46, v42
	v_lshlrev_b32_e32 v43, 2, v43
	v_add_f32_e32 v42, v47, v42
	v_bitop3_b32 v43, v43, s18, v229 bitop3:0x6c
	s_nop 1
	v_add_f32_dpp v42, v42, v42 quad_perm:[1,0,3,2] row_mask:0xf bank_mask:0xf
	s_nop 1
	v_add_f32_dpp v42, v42, v42 quad_perm:[2,3,0,1] row_mask:0xf bank_mask:0xf
	s_nop 1
	v_add_f32_dpp v42, v42, v42 row_half_mirror row_mask:0xf bank_mask:0xf
	s_nop 1
	v_add_f32_dpp v42, v42, v42 row_mirror row_mask:0xf bank_mask:0xf
	s_nop 1
	v_add_f32_dpp v42, v42, v42 row_bcast:15 row_mask:0xa bank_mask:0xf
	s_nop 1
	v_add_f32_dpp v42, v42, v42 row_bcast:31 row_mask:0xc bank_mask:0xf
	s_nop 1
	v_readlane_b32 s98, v42, 63
	s_nop 1
	v_mov_b32_e32 v42, s98
	v_or_b32_e32 v46, 4, v14
	v_ashrrev_i32_e32 v47, 31, v46
	s_waitcnt lgkmcnt(0)
	v_mov_b32_e32 v43, v222
	s_nop 0
	v_lshlrev_b32_e32 v43, 2, v43
	v_bitop3_b32 v43, v43, 64, v229 bitop3:0x6c
	s_waitcnt lgkmcnt(0)
	v_mov_b32_e32 v43, v222
	s_nop 0
	v_lshlrev_b32_e32 v43, 2, v43
	v_bitop3_b32 v43, v43, 32, v229 bitop3:0x6c
	s_waitcnt lgkmcnt(0)
	v_mov_b32_e32 v43, v222
	s_nop 0
	v_lshlrev_b32_e32 v43, 2, v43
	v_bitop3_b32 v43, v43, 16, v229 bitop3:0x6c
	s_waitcnt lgkmcnt(0)
	v_mov_b32_e32 v43, v222
	s_nop 0
	v_lshlrev_b32_e32 v43, 2, v43
	v_bitop3_b32 v43, v43, 8, v229 bitop3:0x6c
	s_waitcnt lgkmcnt(0)
	v_mov_b32_e32 v43, v222
	s_nop 0
	v_lshlrev_b32_e32 v43, 2, v43
	v_bitop3_b32 v43, v43, 4, v229 bitop3:0x6c
	s_waitcnt lgkmcnt(0)
	v_fmamk_f32 v42, v42, 0x3b800000, v227
	v_mul_f32_e32 v43, 0x4b800000, v42
	v_cmp_gt_f32_e32 vcc, s19, v42
	s_nop 1
	v_cndmask_b32_e32 v42, v42, v43, vcc
	v_rsq_f32_e32 v42, v42
	s_nop 0
	v_mul_f32_e32 v43, 0x45800000, v42
	v_cndmask_b32_e32 v42, v42, v43, vcc
	v_mul_f32_e32 v38, v38, v42
	v_fma_f32 v38, v8, v38, v4
	v_mul_f32_e32 v43, 0xbfb8aa3b, v38
	v_exp_f32_e32 v43, v43
	v_mul_f32_e32 v39, v39, v42
	v_fma_f32 v39, v9, v39, v5
	v_mul_f32_e32 v45, 0xbfb8aa3b, v39
	v_add_f32_e32 v43, 1.0, v43
	v_exp_f32_e32 v45, v45
	v_rcp_f32_e32 v43, v43
	v_mul_f32_e32 v40, v40, v42
	v_mul_f32_e32 v41, v41, v42
	v_add_f32_e32 v45, 1.0, v45
	v_mul_f32_e32 v38, v38, v43
	s_waitcnt vmcnt(15)
	v_lshlrev_b32_e32 v43, 16, v36
	v_fma_f32 v40, v10, v40, v6
	v_fma_f32 v41, v11, v41, v7
	v_rcp_f32_e32 v45, v45
	v_mul_f32_e32 v38, v38, v43
	v_mul_f32_e32 v43, 0xbfb8aa3b, v40
	v_mul_f32_e32 v42, 0xbfb8aa3b, v41
	v_exp_f32_e32 v43, v43
	v_exp_f32_e32 v42, v42
	v_mul_f32_e32 v39, v39, v45
	v_and_b32_e32 v36, 0xffff0000, v36
	v_add_f32_e32 v43, 1.0, v43
	v_mul_f32_e32 v36, v39, v36
	v_add_f32_e32 v39, 1.0, v42
	v_rcp_f32_e32 v43, v43
	v_rcp_f32_e32 v39, v39
	v_lshlrev_b32_e32 v42, 16, v37
	v_and_b32_e32 v37, 0xffff0000, v37
	v_mul_f32_e32 v40, v40, v43
	v_mul_f32_e32 v39, v41, v39
	v_mul_f32_e32 v42, v40, v42
	v_mul_f32_e32 v37, v39, v37
	v_cvt_pk_bf16_f32 v40, v38, v36
	v_cvt_pk_bf16_f32 v41, v42, v37
	v_lshl_add_u64 v[36:37], v[48:49], 0, s[22:23]
	v_lshlrev_b64 v[36:37], 11, v[36:37]
	v_lshl_add_u64 v[36:37], s[30:31], 0, v[36:37]
	v_lshl_add_u64 v[42:43], v[36:37], 0, v[2:3]
	v_lshl_add_u32 v36, v46, 10, v15
	ds_read_b128 v[36:39], v36
	v_add_co_u32_e32 v42, vcc, s0, v42
	s_nop 1
	v_addc_co_u32_e32 v43, vcc, 0, v43, vcc
	global_store_dwordx2 v[42:43], v[40:41], off offset:1024
	v_mov_b32_e32 v41, v222
	s_waitcnt lgkmcnt(0)
	v_add_f32_e32 v40, v36, v37
	v_add_f32_e32 v40, v40, v38
	v_lshlrev_b32_e32 v41, 2, v41
	v_add_f32_e32 v40, v40, v39
	v_bitop3_b32 v41, v41, s18, v229 bitop3:0x6c
	s_nop 1
	v_add_f32_dpp v40, v40, v40 quad_perm:[1,0,3,2] row_mask:0xf bank_mask:0xf
	s_nop 1
	v_add_f32_dpp v40, v40, v40 quad_perm:[2,3,0,1] row_mask:0xf bank_mask:0xf
	s_nop 1
	v_add_f32_dpp v40, v40, v40 row_half_mirror row_mask:0xf bank_mask:0xf
	s_nop 1
	v_add_f32_dpp v40, v40, v40 row_mirror row_mask:0xf bank_mask:0xf
	s_nop 1
	v_add_f32_dpp v40, v40, v40 row_bcast:15 row_mask:0xa bank_mask:0xf
	s_nop 1
	v_add_f32_dpp v40, v40, v40 row_bcast:31 row_mask:0xc bank_mask:0xf
	s_nop 1
	v_readlane_b32 s98, v40, 63
	s_nop 1
	v_mov_b32_e32 v40, s98
	s_waitcnt lgkmcnt(0)
	v_mov_b32_e32 v41, v222
	s_nop 0
	v_lshlrev_b32_e32 v41, 2, v41
	v_bitop3_b32 v41, v41, 64, v229 bitop3:0x6c
	s_waitcnt lgkmcnt(0)
	v_mov_b32_e32 v41, v222
	s_nop 0
	v_lshlrev_b32_e32 v41, 2, v41
	v_bitop3_b32 v41, v41, 32, v229 bitop3:0x6c
	s_waitcnt lgkmcnt(0)
	v_mov_b32_e32 v41, v222
	s_nop 0
	v_lshlrev_b32_e32 v41, 2, v41
	v_bitop3_b32 v41, v41, 16, v229 bitop3:0x6c
	s_waitcnt lgkmcnt(0)
	v_mov_b32_e32 v41, v222
	s_nop 0
	v_lshlrev_b32_e32 v41, 2, v41
	v_bitop3_b32 v41, v41, 8, v229 bitop3:0x6c
	s_waitcnt lgkmcnt(0)
	v_mov_b32_e32 v41, v222
	s_nop 0
	v_lshlrev_b32_e32 v41, 2, v41
	v_bitop3_b32 v41, v41, 4, v229 bitop3:0x6c
	s_waitcnt lgkmcnt(0)
	v_mul_f32_e32 v40, 0x3b800000, v40
	v_pk_add_f32 v[36:37], v[36:37], v[40:41] op_sel_hi:[1,0] neg_lo:[0,1] neg_hi:[0,1]
	v_pk_add_f32 v[38:39], v[38:39], v[40:41] op_sel_hi:[1,0] neg_lo:[0,1] neg_hi:[0,1]
	v_pk_mul_f32 v[40:41], v[36:37], v[36:37]
	v_pk_mul_f32 v[42:43], v[38:39], v[38:39]
	v_add_f32_e32 v40, v40, v41
	v_mov_b32_e32 v41, v222
	v_add_f32_e32 v40, v42, v40
	v_lshlrev_b32_e32 v41, 2, v41
	v_add_f32_e32 v40, v43, v40
	v_bitop3_b32 v41, v41, s18, v229 bitop3:0x6c
	s_nop 1
	v_add_f32_dpp v40, v40, v40 quad_perm:[1,0,3,2] row_mask:0xf bank_mask:0xf
	s_nop 1
	v_add_f32_dpp v40, v40, v40 quad_perm:[2,3,0,1] row_mask:0xf bank_mask:0xf
	s_nop 1
	v_add_f32_dpp v40, v40, v40 row_half_mirror row_mask:0xf bank_mask:0xf
	s_nop 1
	v_add_f32_dpp v40, v40, v40 row_mirror row_mask:0xf bank_mask:0xf
	s_nop 1
	v_add_f32_dpp v40, v40, v40 row_bcast:15 row_mask:0xa bank_mask:0xf
	s_nop 1
	v_add_f32_dpp v40, v40, v40 row_bcast:31 row_mask:0xc bank_mask:0xf
	s_nop 1
	v_readlane_b32 s98, v40, 63
	s_nop 1
	v_mov_b32_e32 v40, s98
	s_waitcnt lgkmcnt(0)
	v_mov_b32_e32 v41, v222
	s_nop 0
	v_lshlrev_b32_e32 v41, 2, v41
	v_bitop3_b32 v41, v41, 64, v229 bitop3:0x6c
	s_waitcnt lgkmcnt(0)
	v_mov_b32_e32 v41, v222
	s_nop 0
	v_lshlrev_b32_e32 v41, 2, v41
	v_bitop3_b32 v41, v41, 32, v229 bitop3:0x6c
	s_waitcnt lgkmcnt(0)
	v_mov_b32_e32 v41, v222
	s_nop 0
	v_lshlrev_b32_e32 v41, 2, v41
	v_bitop3_b32 v41, v41, 16, v229 bitop3:0x6c
	s_waitcnt lgkmcnt(0)
	v_mov_b32_e32 v41, v222
	s_nop 0
	v_lshlrev_b32_e32 v41, 2, v41
	v_bitop3_b32 v41, v41, 8, v229 bitop3:0x6c
	s_waitcnt lgkmcnt(0)
	v_mov_b32_e32 v41, v222
	s_nop 0
	v_lshlrev_b32_e32 v41, 2, v41
	v_bitop3_b32 v41, v41, 4, v229 bitop3:0x6c
	s_waitcnt lgkmcnt(0)
	v_fmamk_f32 v40, v40, 0x3b800000, v227
	v_mul_f32_e32 v41, 0x4b800000, v40
	v_cmp_gt_f32_e32 vcc, s19, v40
	s_nop 1
	v_cndmask_b32_e32 v40, v40, v41, vcc
	v_rsq_f32_e32 v40, v40
	s_nop 0
	v_mul_f32_e32 v41, 0x45800000, v40
	v_cndmask_b32_e32 v40, v40, v41, vcc
	v_mul_f32_e32 v36, v36, v40
	v_fma_f32 v36, v8, v36, v4
	v_mul_f32_e32 v41, 0xbfb8aa3b, v36
	v_exp_f32_e32 v41, v41
	v_mul_f32_e32 v37, v37, v40
	v_fma_f32 v37, v9, v37, v5
	v_mul_f32_e32 v42, 0xbfb8aa3b, v37
	v_add_f32_e32 v41, 1.0, v41
	v_exp_f32_e32 v42, v42
	v_rcp_f32_e32 v41, v41
	v_mul_f32_e32 v38, v38, v40
	v_mul_f32_e32 v39, v39, v40
	v_add_f32_e32 v42, 1.0, v42
	v_mul_f32_e32 v36, v36, v41
	s_waitcnt vmcnt(15)
	v_lshlrev_b32_e32 v41, 16, v34
	v_fma_f32 v38, v10, v38, v6
	v_fma_f32 v39, v11, v39, v7
	v_rcp_f32_e32 v42, v42
	v_mul_f32_e32 v36, v36, v41
	v_mul_f32_e32 v41, 0xbfb8aa3b, v38
	v_mul_f32_e32 v40, 0xbfb8aa3b, v39
	v_exp_f32_e32 v41, v41
	v_exp_f32_e32 v40, v40
	v_mul_f32_e32 v37, v37, v42
	v_and_b32_e32 v34, 0xffff0000, v34
	v_add_f32_e32 v41, 1.0, v41
	v_mul_f32_e32 v34, v37, v34
	v_add_f32_e32 v37, 1.0, v40
	v_rcp_f32_e32 v41, v41
	v_rcp_f32_e32 v37, v37
	v_lshlrev_b32_e32 v40, 16, v35
	v_and_b32_e32 v35, 0xffff0000, v35
	v_mul_f32_e32 v38, v38, v41
	v_mul_f32_e32 v37, v39, v37
	v_mul_f32_e32 v40, v38, v40
	v_mul_f32_e32 v35, v37, v35
	v_cvt_pk_bf16_f32 v38, v36, v34
	v_cvt_pk_bf16_f32 v39, v40, v35
	v_lshl_add_u64 v[34:35], v[46:47], 0, s[22:23]
	v_lshlrev_b64 v[34:35], 11, v[34:35]
	v_lshl_add_u64 v[34:35], s[30:31], 0, v[34:35]
	v_or_b32_e32 v42, 5, v14
	v_lshl_add_u64 v[40:41], v[34:35], 0, v[2:3]
	v_lshl_add_u32 v34, v42, 10, v15
	ds_read_b128 v[34:37], v34
	v_add_co_u32_e32 v40, vcc, s0, v40
	v_ashrrev_i32_e32 v43, 31, v42
	s_nop 0
	v_addc_co_u32_e32 v41, vcc, 0, v41, vcc
	global_store_dwordx2 v[40:41], v[38:39], off offset:1024
	v_mov_b32_e32 v39, v222
	s_waitcnt lgkmcnt(0)
	v_add_f32_e32 v38, v34, v35
	v_add_f32_e32 v38, v38, v36
	v_lshlrev_b32_e32 v39, 2, v39
	v_add_f32_e32 v38, v38, v37
	v_bitop3_b32 v39, v39, s18, v229 bitop3:0x6c
	s_nop 1
	v_add_f32_dpp v38, v38, v38 quad_perm:[1,0,3,2] row_mask:0xf bank_mask:0xf
	s_nop 1
	v_add_f32_dpp v38, v38, v38 quad_perm:[2,3,0,1] row_mask:0xf bank_mask:0xf
	s_nop 1
	v_add_f32_dpp v38, v38, v38 row_half_mirror row_mask:0xf bank_mask:0xf
	s_nop 1
	v_add_f32_dpp v38, v38, v38 row_mirror row_mask:0xf bank_mask:0xf
	s_nop 1
	v_add_f32_dpp v38, v38, v38 row_bcast:15 row_mask:0xa bank_mask:0xf
	s_nop 1
	v_add_f32_dpp v38, v38, v38 row_bcast:31 row_mask:0xc bank_mask:0xf
	s_nop 1
	v_readlane_b32 s98, v38, 63
	s_nop 1
	v_mov_b32_e32 v38, s98
	s_waitcnt lgkmcnt(0)
	v_mov_b32_e32 v39, v222
	s_nop 0
	v_lshlrev_b32_e32 v39, 2, v39
	v_bitop3_b32 v39, v39, 64, v229 bitop3:0x6c
	s_waitcnt lgkmcnt(0)
	v_mov_b32_e32 v39, v222
	s_nop 0
	v_lshlrev_b32_e32 v39, 2, v39
	v_bitop3_b32 v39, v39, 32, v229 bitop3:0x6c
	s_waitcnt lgkmcnt(0)
	v_mov_b32_e32 v39, v222
	s_nop 0
	v_lshlrev_b32_e32 v39, 2, v39
	v_bitop3_b32 v39, v39, 16, v229 bitop3:0x6c
	s_waitcnt lgkmcnt(0)
	v_mov_b32_e32 v39, v222
	s_nop 0
	v_lshlrev_b32_e32 v39, 2, v39
	v_bitop3_b32 v39, v39, 8, v229 bitop3:0x6c
	s_waitcnt lgkmcnt(0)
	v_mov_b32_e32 v39, v222
	s_nop 0
	v_lshlrev_b32_e32 v39, 2, v39
	v_bitop3_b32 v39, v39, 4, v229 bitop3:0x6c
	s_waitcnt lgkmcnt(0)
	v_mul_f32_e32 v38, 0x3b800000, v38
	v_pk_add_f32 v[34:35], v[34:35], v[38:39] op_sel_hi:[1,0] neg_lo:[0,1] neg_hi:[0,1]
	v_pk_add_f32 v[36:37], v[36:37], v[38:39] op_sel_hi:[1,0] neg_lo:[0,1] neg_hi:[0,1]
	v_pk_mul_f32 v[38:39], v[34:35], v[34:35]
	v_pk_mul_f32 v[40:41], v[36:37], v[36:37]
	v_add_f32_e32 v38, v38, v39
	v_mov_b32_e32 v39, v222
	v_add_f32_e32 v38, v40, v38
	v_lshlrev_b32_e32 v39, 2, v39
	v_add_f32_e32 v38, v41, v38
	v_bitop3_b32 v39, v39, s18, v229 bitop3:0x6c
	s_nop 1
	v_add_f32_dpp v38, v38, v38 quad_perm:[1,0,3,2] row_mask:0xf bank_mask:0xf
	s_nop 1
	v_add_f32_dpp v38, v38, v38 quad_perm:[2,3,0,1] row_mask:0xf bank_mask:0xf
	s_nop 1
	v_add_f32_dpp v38, v38, v38 row_half_mirror row_mask:0xf bank_mask:0xf
	s_nop 1
	v_add_f32_dpp v38, v38, v38 row_mirror row_mask:0xf bank_mask:0xf
	s_nop 1
	v_add_f32_dpp v38, v38, v38 row_bcast:15 row_mask:0xa bank_mask:0xf
	s_nop 1
	v_add_f32_dpp v38, v38, v38 row_bcast:31 row_mask:0xc bank_mask:0xf
	s_nop 1
	v_readlane_b32 s98, v38, 63
	s_nop 1
	v_mov_b32_e32 v38, s98
	s_waitcnt lgkmcnt(0)
	v_mov_b32_e32 v39, v222
	s_nop 0
	v_lshlrev_b32_e32 v39, 2, v39
	v_bitop3_b32 v39, v39, 64, v229 bitop3:0x6c
	s_waitcnt lgkmcnt(0)
	v_mov_b32_e32 v39, v222
	s_nop 0
	v_lshlrev_b32_e32 v39, 2, v39
	v_bitop3_b32 v39, v39, 32, v229 bitop3:0x6c
	s_waitcnt lgkmcnt(0)
	v_mov_b32_e32 v39, v222
	s_nop 0
	v_lshlrev_b32_e32 v39, 2, v39
	v_bitop3_b32 v39, v39, 16, v229 bitop3:0x6c
	s_waitcnt lgkmcnt(0)
	v_mov_b32_e32 v39, v222
	s_nop 0
	v_lshlrev_b32_e32 v39, 2, v39
	v_bitop3_b32 v39, v39, 8, v229 bitop3:0x6c
	s_waitcnt lgkmcnt(0)
	v_mov_b32_e32 v39, v222
	s_nop 0
	v_lshlrev_b32_e32 v39, 2, v39
	v_bitop3_b32 v39, v39, 4, v229 bitop3:0x6c
	s_waitcnt lgkmcnt(0)
	v_fmamk_f32 v38, v38, 0x3b800000, v227
	v_mul_f32_e32 v39, 0x4b800000, v38
	v_cmp_gt_f32_e32 vcc, s19, v38
	s_nop 1
	v_cndmask_b32_e32 v38, v38, v39, vcc
	v_rsq_f32_e32 v38, v38
	s_nop 0
	v_mul_f32_e32 v39, 0x45800000, v38
	v_cndmask_b32_e32 v38, v38, v39, vcc
	v_mul_f32_e32 v34, v34, v38
	v_fma_f32 v34, v8, v34, v4
	v_mul_f32_e32 v39, 0xbfb8aa3b, v34
	v_exp_f32_e32 v39, v39
	v_mul_f32_e32 v35, v35, v38
	v_fma_f32 v35, v9, v35, v5
	v_mul_f32_e32 v40, 0xbfb8aa3b, v35
	v_add_f32_e32 v39, 1.0, v39
	v_exp_f32_e32 v40, v40
	v_rcp_f32_e32 v39, v39
	v_mul_f32_e32 v36, v36, v38
	v_mul_f32_e32 v37, v37, v38
	v_add_f32_e32 v40, 1.0, v40
	v_mul_f32_e32 v34, v34, v39
	s_waitcnt vmcnt(15)
	v_lshlrev_b32_e32 v39, 16, v32
	v_fma_f32 v36, v10, v36, v6
	v_fma_f32 v37, v11, v37, v7
	v_rcp_f32_e32 v40, v40
	v_mul_f32_e32 v34, v34, v39
	v_mul_f32_e32 v39, 0xbfb8aa3b, v36
	v_mul_f32_e32 v38, 0xbfb8aa3b, v37
	v_exp_f32_e32 v39, v39
	v_exp_f32_e32 v38, v38
	v_mul_f32_e32 v35, v35, v40
	v_and_b32_e32 v32, 0xffff0000, v32
	v_add_f32_e32 v39, 1.0, v39
	v_mul_f32_e32 v32, v35, v32
	v_add_f32_e32 v35, 1.0, v38
	v_rcp_f32_e32 v39, v39
	v_rcp_f32_e32 v35, v35
	v_lshlrev_b32_e32 v38, 16, v33
	v_and_b32_e32 v33, 0xffff0000, v33
	v_mul_f32_e32 v36, v36, v39
	v_mul_f32_e32 v35, v37, v35
	v_mul_f32_e32 v38, v36, v38
	v_mul_f32_e32 v33, v35, v33
	v_cvt_pk_bf16_f32 v36, v34, v32
	v_cvt_pk_bf16_f32 v37, v38, v33
	v_lshl_add_u64 v[32:33], v[42:43], 0, s[22:23]
	v_lshlrev_b64 v[32:33], 11, v[32:33]
	v_lshl_add_u64 v[32:33], s[30:31], 0, v[32:33]
	v_or_b32_e32 v40, 6, v14
	v_lshl_add_u64 v[38:39], v[32:33], 0, v[2:3]
	v_lshl_add_u32 v32, v40, 10, v15
	ds_read_b128 v[32:35], v32
	v_add_co_u32_e32 v38, vcc, s0, v38
	v_ashrrev_i32_e32 v41, 31, v40
	s_nop 0
	v_addc_co_u32_e32 v39, vcc, 0, v39, vcc
	global_store_dwordx2 v[38:39], v[36:37], off offset:1024
	v_mov_b32_e32 v37, v222
	s_waitcnt lgkmcnt(0)
	v_add_f32_e32 v36, v32, v33
	v_add_f32_e32 v36, v36, v34
	v_lshlrev_b32_e32 v37, 2, v37
	v_add_f32_e32 v36, v36, v35
	v_bitop3_b32 v37, v37, s18, v229 bitop3:0x6c
	s_nop 1
	v_add_f32_dpp v36, v36, v36 quad_perm:[1,0,3,2] row_mask:0xf bank_mask:0xf
	s_nop 1
	v_add_f32_dpp v36, v36, v36 quad_perm:[2,3,0,1] row_mask:0xf bank_mask:0xf
	s_nop 1
	v_add_f32_dpp v36, v36, v36 row_half_mirror row_mask:0xf bank_mask:0xf
	s_nop 1
	v_add_f32_dpp v36, v36, v36 row_mirror row_mask:0xf bank_mask:0xf
	s_nop 1
	v_add_f32_dpp v36, v36, v36 row_bcast:15 row_mask:0xa bank_mask:0xf
	s_nop 1
	v_add_f32_dpp v36, v36, v36 row_bcast:31 row_mask:0xc bank_mask:0xf
	s_nop 1
	v_readlane_b32 s98, v36, 63
	s_nop 1
	v_mov_b32_e32 v36, s98
	s_waitcnt lgkmcnt(0)
	v_mov_b32_e32 v37, v222
	s_nop 0
	v_lshlrev_b32_e32 v37, 2, v37
	v_bitop3_b32 v37, v37, 64, v229 bitop3:0x6c
	s_waitcnt lgkmcnt(0)
	v_mov_b32_e32 v37, v222
	s_nop 0
	v_lshlrev_b32_e32 v37, 2, v37
	v_bitop3_b32 v37, v37, 32, v229 bitop3:0x6c
	s_waitcnt lgkmcnt(0)
	v_mov_b32_e32 v37, v222
	s_nop 0
	v_lshlrev_b32_e32 v37, 2, v37
	v_bitop3_b32 v37, v37, 16, v229 bitop3:0x6c
	s_waitcnt lgkmcnt(0)
	v_mov_b32_e32 v37, v222
	s_nop 0
	v_lshlrev_b32_e32 v37, 2, v37
	v_bitop3_b32 v37, v37, 8, v229 bitop3:0x6c
	s_waitcnt lgkmcnt(0)
	v_mov_b32_e32 v37, v222
	s_nop 0
	v_lshlrev_b32_e32 v37, 2, v37
	v_bitop3_b32 v37, v37, 4, v229 bitop3:0x6c
	s_waitcnt lgkmcnt(0)
	v_mul_f32_e32 v36, 0x3b800000, v36
	v_pk_add_f32 v[32:33], v[32:33], v[36:37] op_sel_hi:[1,0] neg_lo:[0,1] neg_hi:[0,1]
	v_pk_add_f32 v[34:35], v[34:35], v[36:37] op_sel_hi:[1,0] neg_lo:[0,1] neg_hi:[0,1]
	v_pk_mul_f32 v[36:37], v[32:33], v[32:33]
	v_pk_mul_f32 v[38:39], v[34:35], v[34:35]
	v_add_f32_e32 v36, v36, v37
	v_mov_b32_e32 v37, v222
	v_add_f32_e32 v36, v38, v36
	v_lshlrev_b32_e32 v37, 2, v37
	v_add_f32_e32 v36, v39, v36
	v_bitop3_b32 v37, v37, s18, v229 bitop3:0x6c
	s_nop 1
	v_add_f32_dpp v36, v36, v36 quad_perm:[1,0,3,2] row_mask:0xf bank_mask:0xf
	s_nop 1
	v_add_f32_dpp v36, v36, v36 quad_perm:[2,3,0,1] row_mask:0xf bank_mask:0xf
	s_nop 1
	v_add_f32_dpp v36, v36, v36 row_half_mirror row_mask:0xf bank_mask:0xf
	s_nop 1
	v_add_f32_dpp v36, v36, v36 row_mirror row_mask:0xf bank_mask:0xf
	s_nop 1
	v_add_f32_dpp v36, v36, v36 row_bcast:15 row_mask:0xa bank_mask:0xf
	s_nop 1
	v_add_f32_dpp v36, v36, v36 row_bcast:31 row_mask:0xc bank_mask:0xf
	s_nop 1
	v_readlane_b32 s98, v36, 63
	s_nop 1
	v_mov_b32_e32 v36, s98
	s_waitcnt lgkmcnt(0)
	v_mov_b32_e32 v37, v222
	s_nop 0
	v_lshlrev_b32_e32 v37, 2, v37
	v_bitop3_b32 v37, v37, 64, v229 bitop3:0x6c
	s_waitcnt lgkmcnt(0)
	v_mov_b32_e32 v37, v222
	s_nop 0
	v_lshlrev_b32_e32 v37, 2, v37
	v_bitop3_b32 v37, v37, 32, v229 bitop3:0x6c
	s_waitcnt lgkmcnt(0)
	v_mov_b32_e32 v37, v222
	s_nop 0
	v_lshlrev_b32_e32 v37, 2, v37
	v_bitop3_b32 v37, v37, 16, v229 bitop3:0x6c
	s_waitcnt lgkmcnt(0)
	v_mov_b32_e32 v37, v222
	s_nop 0
	v_lshlrev_b32_e32 v37, 2, v37
	v_bitop3_b32 v37, v37, 8, v229 bitop3:0x6c
	s_waitcnt lgkmcnt(0)
	v_mov_b32_e32 v37, v222
	s_nop 0
	v_lshlrev_b32_e32 v37, 2, v37
	v_bitop3_b32 v37, v37, 4, v229 bitop3:0x6c
	s_waitcnt lgkmcnt(0)
	v_fmamk_f32 v36, v36, 0x3b800000, v227
	v_mul_f32_e32 v37, 0x4b800000, v36
	v_cmp_gt_f32_e32 vcc, s19, v36
	s_nop 1
	v_cndmask_b32_e32 v36, v36, v37, vcc
	v_rsq_f32_e32 v36, v36
	s_nop 0
	v_mul_f32_e32 v37, 0x45800000, v36
	v_cndmask_b32_e32 v36, v36, v37, vcc
	v_mul_f32_e32 v32, v32, v36
	v_fma_f32 v32, v8, v32, v4
	v_mul_f32_e32 v37, 0xbfb8aa3b, v32
	v_exp_f32_e32 v37, v37
	v_mul_f32_e32 v33, v33, v36
	v_fma_f32 v33, v9, v33, v5
	v_mul_f32_e32 v38, 0xbfb8aa3b, v33
	v_add_f32_e32 v37, 1.0, v37
	v_exp_f32_e32 v38, v38
	v_rcp_f32_e32 v37, v37
	v_mul_f32_e32 v34, v34, v36
	v_mul_f32_e32 v35, v35, v36
	v_add_f32_e32 v38, 1.0, v38
	v_mul_f32_e32 v32, v32, v37
	s_waitcnt vmcnt(15)
	v_lshlrev_b32_e32 v37, 16, v30
	v_fma_f32 v34, v10, v34, v6
	v_fma_f32 v35, v11, v35, v7
	v_rcp_f32_e32 v38, v38
	v_mul_f32_e32 v32, v32, v37
	v_mul_f32_e32 v37, 0xbfb8aa3b, v34
	v_mul_f32_e32 v36, 0xbfb8aa3b, v35
	v_exp_f32_e32 v37, v37
	v_exp_f32_e32 v36, v36
	v_mul_f32_e32 v33, v33, v38
	v_and_b32_e32 v30, 0xffff0000, v30
	v_add_f32_e32 v37, 1.0, v37
	v_mul_f32_e32 v30, v33, v30
	v_add_f32_e32 v33, 1.0, v36
	v_rcp_f32_e32 v37, v37
	v_rcp_f32_e32 v33, v33
	v_lshlrev_b32_e32 v36, 16, v31
	v_and_b32_e32 v31, 0xffff0000, v31
	v_mul_f32_e32 v34, v34, v37
	v_mul_f32_e32 v33, v35, v33
	v_mul_f32_e32 v36, v34, v36
	v_mul_f32_e32 v31, v33, v31
	v_cvt_pk_bf16_f32 v34, v32, v30
	v_cvt_pk_bf16_f32 v35, v36, v31
	v_lshl_add_u64 v[30:31], v[40:41], 0, s[22:23]
	v_lshlrev_b64 v[30:31], 11, v[30:31]
	v_lshl_add_u64 v[30:31], s[30:31], 0, v[30:31]
	v_or_b32_e32 v38, 7, v14
	v_lshl_add_u64 v[36:37], v[30:31], 0, v[2:3]
	v_lshl_add_u32 v30, v38, 10, v15
	ds_read_b128 v[30:33], v30
	v_add_co_u32_e32 v36, vcc, s0, v36
	v_ashrrev_i32_e32 v39, 31, v38
	s_nop 0
	v_addc_co_u32_e32 v37, vcc, 0, v37, vcc
	global_store_dwordx2 v[36:37], v[34:35], off offset:1024
	v_mov_b32_e32 v35, v222
	s_waitcnt lgkmcnt(0)
	v_add_f32_e32 v34, v30, v31
	v_add_f32_e32 v34, v34, v32
	v_lshlrev_b32_e32 v35, 2, v35
	v_add_f32_e32 v34, v34, v33
	v_bitop3_b32 v35, v35, s18, v229 bitop3:0x6c
	s_nop 1
	v_add_f32_dpp v34, v34, v34 quad_perm:[1,0,3,2] row_mask:0xf bank_mask:0xf
	s_nop 1
	v_add_f32_dpp v34, v34, v34 quad_perm:[2,3,0,1] row_mask:0xf bank_mask:0xf
	s_nop 1
	v_add_f32_dpp v34, v34, v34 row_half_mirror row_mask:0xf bank_mask:0xf
	s_nop 1
	v_add_f32_dpp v34, v34, v34 row_mirror row_mask:0xf bank_mask:0xf
	s_nop 1
	v_add_f32_dpp v34, v34, v34 row_bcast:15 row_mask:0xa bank_mask:0xf
	s_nop 1
	v_add_f32_dpp v34, v34, v34 row_bcast:31 row_mask:0xc bank_mask:0xf
	s_nop 1
	v_readlane_b32 s98, v34, 63
	s_nop 1
	v_mov_b32_e32 v34, s98
	s_waitcnt lgkmcnt(0)
	v_mov_b32_e32 v35, v222
	s_nop 0
	v_lshlrev_b32_e32 v35, 2, v35
	v_bitop3_b32 v35, v35, 64, v229 bitop3:0x6c
	s_waitcnt lgkmcnt(0)
	v_mov_b32_e32 v35, v222
	s_nop 0
	v_lshlrev_b32_e32 v35, 2, v35
	v_bitop3_b32 v35, v35, 32, v229 bitop3:0x6c
	s_waitcnt lgkmcnt(0)
	v_mov_b32_e32 v35, v222
	s_nop 0
	v_lshlrev_b32_e32 v35, 2, v35
	v_bitop3_b32 v35, v35, 16, v229 bitop3:0x6c
	s_waitcnt lgkmcnt(0)
	v_mov_b32_e32 v35, v222
	s_nop 0
	v_lshlrev_b32_e32 v35, 2, v35
	v_bitop3_b32 v35, v35, 8, v229 bitop3:0x6c
	s_waitcnt lgkmcnt(0)
	v_mov_b32_e32 v35, v222
	s_nop 0
	v_lshlrev_b32_e32 v35, 2, v35
	v_bitop3_b32 v35, v35, 4, v229 bitop3:0x6c
	s_waitcnt lgkmcnt(0)
	v_mul_f32_e32 v34, 0x3b800000, v34
	v_pk_add_f32 v[30:31], v[30:31], v[34:35] op_sel_hi:[1,0] neg_lo:[0,1] neg_hi:[0,1]
	v_pk_add_f32 v[32:33], v[32:33], v[34:35] op_sel_hi:[1,0] neg_lo:[0,1] neg_hi:[0,1]
	v_pk_mul_f32 v[34:35], v[30:31], v[30:31]
	v_pk_mul_f32 v[36:37], v[32:33], v[32:33]
	v_add_f32_e32 v34, v34, v35
	v_mov_b32_e32 v35, v222
	v_add_f32_e32 v34, v36, v34
	v_lshlrev_b32_e32 v35, 2, v35
	v_add_f32_e32 v34, v37, v34
	v_bitop3_b32 v35, v35, s18, v229 bitop3:0x6c
	s_nop 1
	v_add_f32_dpp v34, v34, v34 quad_perm:[1,0,3,2] row_mask:0xf bank_mask:0xf
	s_nop 1
	v_add_f32_dpp v34, v34, v34 quad_perm:[2,3,0,1] row_mask:0xf bank_mask:0xf
	s_nop 1
	v_add_f32_dpp v34, v34, v34 row_half_mirror row_mask:0xf bank_mask:0xf
	s_nop 1
	v_add_f32_dpp v34, v34, v34 row_mirror row_mask:0xf bank_mask:0xf
	s_nop 1
	v_add_f32_dpp v34, v34, v34 row_bcast:15 row_mask:0xa bank_mask:0xf
	s_nop 1
	v_add_f32_dpp v34, v34, v34 row_bcast:31 row_mask:0xc bank_mask:0xf
	s_nop 1
	v_readlane_b32 s98, v34, 63
	s_nop 1
	v_mov_b32_e32 v34, s98
	s_waitcnt lgkmcnt(0)
	v_mov_b32_e32 v35, v222
	s_nop 0
	v_lshlrev_b32_e32 v35, 2, v35
	v_bitop3_b32 v35, v35, 64, v229 bitop3:0x6c
	s_waitcnt lgkmcnt(0)
	v_mov_b32_e32 v35, v222
	s_nop 0
	v_lshlrev_b32_e32 v35, 2, v35
	v_bitop3_b32 v35, v35, 32, v229 bitop3:0x6c
	s_waitcnt lgkmcnt(0)
	v_mov_b32_e32 v35, v222
	s_nop 0
	v_lshlrev_b32_e32 v35, 2, v35
	v_bitop3_b32 v35, v35, 16, v229 bitop3:0x6c
	s_waitcnt lgkmcnt(0)
	v_mov_b32_e32 v35, v222
	s_nop 0
	v_lshlrev_b32_e32 v35, 2, v35
	v_bitop3_b32 v35, v35, 8, v229 bitop3:0x6c
	s_waitcnt lgkmcnt(0)
	v_mov_b32_e32 v35, v222
	s_nop 0
	v_lshlrev_b32_e32 v35, 2, v35
	v_bitop3_b32 v35, v35, 4, v229 bitop3:0x6c
	s_waitcnt lgkmcnt(0)
	v_fmamk_f32 v34, v34, 0x3b800000, v227
	v_mul_f32_e32 v35, 0x4b800000, v34
	v_cmp_gt_f32_e32 vcc, s19, v34
	s_nop 1
	v_cndmask_b32_e32 v34, v34, v35, vcc
	v_rsq_f32_e32 v34, v34
	s_nop 0
	v_mul_f32_e32 v35, 0x45800000, v34
	v_cndmask_b32_e32 v34, v34, v35, vcc
	v_mul_f32_e32 v30, v30, v34
	v_fma_f32 v30, v8, v30, v4
	v_mul_f32_e32 v35, 0xbfb8aa3b, v30
	v_exp_f32_e32 v35, v35
	v_mul_f32_e32 v31, v31, v34
	v_fma_f32 v31, v9, v31, v5
	v_mul_f32_e32 v36, 0xbfb8aa3b, v31
	v_add_f32_e32 v35, 1.0, v35
	v_exp_f32_e32 v36, v36
	v_rcp_f32_e32 v35, v35
	v_mul_f32_e32 v32, v32, v34
	v_mul_f32_e32 v33, v33, v34
	v_add_f32_e32 v36, 1.0, v36
	v_mul_f32_e32 v30, v30, v35
	s_waitcnt vmcnt(15)
	v_lshlrev_b32_e32 v35, 16, v28
	v_fma_f32 v32, v10, v32, v6
	v_fma_f32 v33, v11, v33, v7
	v_rcp_f32_e32 v36, v36
	v_mul_f32_e32 v30, v30, v35
	v_mul_f32_e32 v35, 0xbfb8aa3b, v32
	v_mul_f32_e32 v34, 0xbfb8aa3b, v33
	v_exp_f32_e32 v35, v35
	v_exp_f32_e32 v34, v34
	v_mul_f32_e32 v31, v31, v36
	v_and_b32_e32 v28, 0xffff0000, v28
	v_add_f32_e32 v35, 1.0, v35
	v_mul_f32_e32 v28, v31, v28
	v_add_f32_e32 v31, 1.0, v34
	v_rcp_f32_e32 v35, v35
	v_rcp_f32_e32 v31, v31
	v_lshlrev_b32_e32 v34, 16, v29
	v_and_b32_e32 v29, 0xffff0000, v29
	v_mul_f32_e32 v32, v32, v35
	v_mul_f32_e32 v31, v33, v31
	v_mul_f32_e32 v34, v32, v34
	v_mul_f32_e32 v29, v31, v29
	v_cvt_pk_bf16_f32 v32, v30, v28
	v_cvt_pk_bf16_f32 v33, v34, v29
	v_lshl_add_u64 v[28:29], v[38:39], 0, s[22:23]
	v_lshlrev_b64 v[28:29], 11, v[28:29]
	v_lshl_add_u64 v[28:29], s[30:31], 0, v[28:29]
	v_or_b32_e32 v36, 8, v14
	v_lshl_add_u64 v[34:35], v[28:29], 0, v[2:3]
	v_lshl_add_u32 v28, v36, 10, v15
	ds_read_b128 v[28:31], v28
	v_add_co_u32_e32 v34, vcc, s0, v34
	v_ashrrev_i32_e32 v37, 31, v36
	s_nop 0
	v_addc_co_u32_e32 v35, vcc, 0, v35, vcc
	global_store_dwordx2 v[34:35], v[32:33], off offset:1024
	v_mov_b32_e32 v33, v222
	s_waitcnt lgkmcnt(0)
	v_add_f32_e32 v32, v28, v29
	v_add_f32_e32 v32, v32, v30
	v_lshlrev_b32_e32 v33, 2, v33
	v_add_f32_e32 v32, v32, v31
	v_bitop3_b32 v33, v33, s18, v229 bitop3:0x6c
	s_nop 1
	v_add_f32_dpp v32, v32, v32 quad_perm:[1,0,3,2] row_mask:0xf bank_mask:0xf
	s_nop 1
	v_add_f32_dpp v32, v32, v32 quad_perm:[2,3,0,1] row_mask:0xf bank_mask:0xf
	s_nop 1
	v_add_f32_dpp v32, v32, v32 row_half_mirror row_mask:0xf bank_mask:0xf
	s_nop 1
	v_add_f32_dpp v32, v32, v32 row_mirror row_mask:0xf bank_mask:0xf
	s_nop 1
	v_add_f32_dpp v32, v32, v32 row_bcast:15 row_mask:0xa bank_mask:0xf
	s_nop 1
	v_add_f32_dpp v32, v32, v32 row_bcast:31 row_mask:0xc bank_mask:0xf
	s_nop 1
	v_readlane_b32 s98, v32, 63
	s_nop 1
	v_mov_b32_e32 v32, s98
	s_waitcnt lgkmcnt(0)
	v_mov_b32_e32 v33, v222
	s_nop 0
	v_lshlrev_b32_e32 v33, 2, v33
	v_bitop3_b32 v33, v33, 64, v229 bitop3:0x6c
	s_waitcnt lgkmcnt(0)
	v_mov_b32_e32 v33, v222
	s_nop 0
	v_lshlrev_b32_e32 v33, 2, v33
	v_bitop3_b32 v33, v33, 32, v229 bitop3:0x6c
	s_waitcnt lgkmcnt(0)
	v_mov_b32_e32 v33, v222
	s_nop 0
	v_lshlrev_b32_e32 v33, 2, v33
	v_bitop3_b32 v33, v33, 16, v229 bitop3:0x6c
	s_waitcnt lgkmcnt(0)
	v_mov_b32_e32 v33, v222
	s_nop 0
	v_lshlrev_b32_e32 v33, 2, v33
	v_bitop3_b32 v33, v33, 8, v229 bitop3:0x6c
	s_waitcnt lgkmcnt(0)
	v_mov_b32_e32 v33, v222
	s_nop 0
	v_lshlrev_b32_e32 v33, 2, v33
	v_bitop3_b32 v33, v33, 4, v229 bitop3:0x6c
	s_waitcnt lgkmcnt(0)
	v_mul_f32_e32 v32, 0x3b800000, v32
	v_pk_add_f32 v[28:29], v[28:29], v[32:33] op_sel_hi:[1,0] neg_lo:[0,1] neg_hi:[0,1]
	v_pk_add_f32 v[30:31], v[30:31], v[32:33] op_sel_hi:[1,0] neg_lo:[0,1] neg_hi:[0,1]
	v_pk_mul_f32 v[32:33], v[28:29], v[28:29]
	v_pk_mul_f32 v[34:35], v[30:31], v[30:31]
	v_add_f32_e32 v32, v32, v33
	v_mov_b32_e32 v33, v222
	v_add_f32_e32 v32, v34, v32
	v_lshlrev_b32_e32 v33, 2, v33
	v_add_f32_e32 v32, v35, v32
	v_bitop3_b32 v33, v33, s18, v229 bitop3:0x6c
	s_nop 1
	v_add_f32_dpp v32, v32, v32 quad_perm:[1,0,3,2] row_mask:0xf bank_mask:0xf
	s_nop 1
	v_add_f32_dpp v32, v32, v32 quad_perm:[2,3,0,1] row_mask:0xf bank_mask:0xf
	s_nop 1
	v_add_f32_dpp v32, v32, v32 row_half_mirror row_mask:0xf bank_mask:0xf
	s_nop 1
	v_add_f32_dpp v32, v32, v32 row_mirror row_mask:0xf bank_mask:0xf
	s_nop 1
	v_add_f32_dpp v32, v32, v32 row_bcast:15 row_mask:0xa bank_mask:0xf
	s_nop 1
	v_add_f32_dpp v32, v32, v32 row_bcast:31 row_mask:0xc bank_mask:0xf
	s_nop 1
	v_readlane_b32 s98, v32, 63
	s_nop 1
	v_mov_b32_e32 v32, s98
	s_waitcnt lgkmcnt(0)
	v_mov_b32_e32 v33, v222
	s_nop 0
	v_lshlrev_b32_e32 v33, 2, v33
	v_bitop3_b32 v33, v33, 64, v229 bitop3:0x6c
	s_waitcnt lgkmcnt(0)
	v_mov_b32_e32 v33, v222
	s_nop 0
	v_lshlrev_b32_e32 v33, 2, v33
	v_bitop3_b32 v33, v33, 32, v229 bitop3:0x6c
	s_waitcnt lgkmcnt(0)
	v_mov_b32_e32 v33, v222
	s_nop 0
	v_lshlrev_b32_e32 v33, 2, v33
	v_bitop3_b32 v33, v33, 16, v229 bitop3:0x6c
	s_waitcnt lgkmcnt(0)
	v_mov_b32_e32 v33, v222
	s_nop 0
	v_lshlrev_b32_e32 v33, 2, v33
	v_bitop3_b32 v33, v33, 8, v229 bitop3:0x6c
	s_waitcnt lgkmcnt(0)
	v_mov_b32_e32 v33, v222
	s_nop 0
	v_lshlrev_b32_e32 v33, 2, v33
	v_bitop3_b32 v33, v33, 4, v229 bitop3:0x6c
	s_waitcnt lgkmcnt(0)
	v_fmamk_f32 v32, v32, 0x3b800000, v227
	v_mul_f32_e32 v33, 0x4b800000, v32
	v_cmp_gt_f32_e32 vcc, s19, v32
	s_nop 1
	v_cndmask_b32_e32 v32, v32, v33, vcc
	v_rsq_f32_e32 v32, v32
	s_nop 0
	v_mul_f32_e32 v33, 0x45800000, v32
	v_cndmask_b32_e32 v32, v32, v33, vcc
	v_mul_f32_e32 v28, v28, v32
	v_fma_f32 v28, v8, v28, v4
	v_mul_f32_e32 v33, 0xbfb8aa3b, v28
	v_exp_f32_e32 v33, v33
	v_mul_f32_e32 v29, v29, v32
	v_fma_f32 v29, v9, v29, v5
	v_mul_f32_e32 v34, 0xbfb8aa3b, v29
	v_add_f32_e32 v33, 1.0, v33
	v_exp_f32_e32 v34, v34
	v_rcp_f32_e32 v33, v33
	v_mul_f32_e32 v30, v30, v32
	v_mul_f32_e32 v31, v31, v32
	v_add_f32_e32 v34, 1.0, v34
	v_mul_f32_e32 v28, v28, v33
	s_waitcnt vmcnt(15)
	v_lshlrev_b32_e32 v33, 16, v26
	v_fma_f32 v30, v10, v30, v6
	v_fma_f32 v31, v11, v31, v7
	v_rcp_f32_e32 v34, v34
	v_mul_f32_e32 v28, v28, v33
	v_mul_f32_e32 v33, 0xbfb8aa3b, v30
	v_mul_f32_e32 v32, 0xbfb8aa3b, v31
	v_exp_f32_e32 v33, v33
	v_exp_f32_e32 v32, v32
	v_mul_f32_e32 v29, v29, v34
	v_and_b32_e32 v26, 0xffff0000, v26
	v_add_f32_e32 v33, 1.0, v33
	v_mul_f32_e32 v26, v29, v26
	v_add_f32_e32 v29, 1.0, v32
	v_rcp_f32_e32 v33, v33
	v_rcp_f32_e32 v29, v29
	v_lshlrev_b32_e32 v32, 16, v27
	v_and_b32_e32 v27, 0xffff0000, v27
	v_mul_f32_e32 v30, v30, v33
	v_mul_f32_e32 v29, v31, v29
	v_mul_f32_e32 v32, v30, v32
	v_mul_f32_e32 v27, v29, v27
	v_cvt_pk_bf16_f32 v30, v28, v26
	v_cvt_pk_bf16_f32 v31, v32, v27
	v_lshl_add_u64 v[26:27], v[36:37], 0, s[22:23]
	v_lshlrev_b64 v[26:27], 11, v[26:27]
	v_lshl_add_u64 v[26:27], s[30:31], 0, v[26:27]
	v_or_b32_e32 v34, 9, v14
	v_lshl_add_u64 v[32:33], v[26:27], 0, v[2:3]
	v_lshl_add_u32 v26, v34, 10, v15
	ds_read_b128 v[26:29], v26
	v_add_co_u32_e32 v32, vcc, s0, v32
	v_ashrrev_i32_e32 v35, 31, v34
	s_nop 0
	v_addc_co_u32_e32 v33, vcc, 0, v33, vcc
	global_store_dwordx2 v[32:33], v[30:31], off offset:1024
	v_mov_b32_e32 v31, v222
	s_waitcnt lgkmcnt(0)
	v_add_f32_e32 v30, v26, v27
	v_add_f32_e32 v30, v30, v28
	v_lshlrev_b32_e32 v31, 2, v31
	v_add_f32_e32 v30, v30, v29
	v_bitop3_b32 v31, v31, s18, v229 bitop3:0x6c
	s_nop 1
	v_add_f32_dpp v30, v30, v30 quad_perm:[1,0,3,2] row_mask:0xf bank_mask:0xf
	s_nop 1
	v_add_f32_dpp v30, v30, v30 quad_perm:[2,3,0,1] row_mask:0xf bank_mask:0xf
	s_nop 1
	v_add_f32_dpp v30, v30, v30 row_half_mirror row_mask:0xf bank_mask:0xf
	s_nop 1
	v_add_f32_dpp v30, v30, v30 row_mirror row_mask:0xf bank_mask:0xf
	s_nop 1
	v_add_f32_dpp v30, v30, v30 row_bcast:15 row_mask:0xa bank_mask:0xf
	s_nop 1
	v_add_f32_dpp v30, v30, v30 row_bcast:31 row_mask:0xc bank_mask:0xf
	s_nop 1
	v_readlane_b32 s98, v30, 63
	s_nop 1
	v_mov_b32_e32 v30, s98
	s_waitcnt lgkmcnt(0)
	v_mov_b32_e32 v31, v222
	s_nop 0
	v_lshlrev_b32_e32 v31, 2, v31
	v_bitop3_b32 v31, v31, 64, v229 bitop3:0x6c
	s_waitcnt lgkmcnt(0)
	v_mov_b32_e32 v31, v222
	s_nop 0
	v_lshlrev_b32_e32 v31, 2, v31
	v_bitop3_b32 v31, v31, 32, v229 bitop3:0x6c
	s_waitcnt lgkmcnt(0)
	v_mov_b32_e32 v31, v222
	s_nop 0
	v_lshlrev_b32_e32 v31, 2, v31
	v_bitop3_b32 v31, v31, 16, v229 bitop3:0x6c
	s_waitcnt lgkmcnt(0)
	v_mov_b32_e32 v31, v222
	s_nop 0
	v_lshlrev_b32_e32 v31, 2, v31
	v_bitop3_b32 v31, v31, 8, v229 bitop3:0x6c
	s_waitcnt lgkmcnt(0)
	v_mov_b32_e32 v31, v222
	s_nop 0
	v_lshlrev_b32_e32 v31, 2, v31
	v_bitop3_b32 v31, v31, 4, v229 bitop3:0x6c
	s_waitcnt lgkmcnt(0)
	v_mul_f32_e32 v30, 0x3b800000, v30
	v_pk_add_f32 v[26:27], v[26:27], v[30:31] op_sel_hi:[1,0] neg_lo:[0,1] neg_hi:[0,1]
	v_pk_add_f32 v[28:29], v[28:29], v[30:31] op_sel_hi:[1,0] neg_lo:[0,1] neg_hi:[0,1]
	v_pk_mul_f32 v[30:31], v[26:27], v[26:27]
	v_pk_mul_f32 v[32:33], v[28:29], v[28:29]
	v_add_f32_e32 v30, v30, v31
	v_mov_b32_e32 v31, v222
	v_add_f32_e32 v30, v32, v30
	v_lshlrev_b32_e32 v31, 2, v31
	v_add_f32_e32 v30, v33, v30
	v_bitop3_b32 v31, v31, s18, v229 bitop3:0x6c
	s_nop 1
	v_add_f32_dpp v30, v30, v30 quad_perm:[1,0,3,2] row_mask:0xf bank_mask:0xf
	s_nop 1
	v_add_f32_dpp v30, v30, v30 quad_perm:[2,3,0,1] row_mask:0xf bank_mask:0xf
	s_nop 1
	v_add_f32_dpp v30, v30, v30 row_half_mirror row_mask:0xf bank_mask:0xf
	s_nop 1
	v_add_f32_dpp v30, v30, v30 row_mirror row_mask:0xf bank_mask:0xf
	s_nop 1
	v_add_f32_dpp v30, v30, v30 row_bcast:15 row_mask:0xa bank_mask:0xf
	s_nop 1
	v_add_f32_dpp v30, v30, v30 row_bcast:31 row_mask:0xc bank_mask:0xf
	s_nop 1
	v_readlane_b32 s98, v30, 63
	s_nop 1
	v_mov_b32_e32 v30, s98
	s_waitcnt lgkmcnt(0)
	v_mov_b32_e32 v31, v222
	s_nop 0
	v_lshlrev_b32_e32 v31, 2, v31
	v_bitop3_b32 v31, v31, 64, v229 bitop3:0x6c
	s_waitcnt lgkmcnt(0)
	v_mov_b32_e32 v31, v222
	s_nop 0
	v_lshlrev_b32_e32 v31, 2, v31
	v_bitop3_b32 v31, v31, 32, v229 bitop3:0x6c
	s_waitcnt lgkmcnt(0)
	v_mov_b32_e32 v31, v222
	s_nop 0
	v_lshlrev_b32_e32 v31, 2, v31
	v_bitop3_b32 v31, v31, 16, v229 bitop3:0x6c
	s_waitcnt lgkmcnt(0)
	v_mov_b32_e32 v31, v222
	s_nop 0
	v_lshlrev_b32_e32 v31, 2, v31
	v_bitop3_b32 v31, v31, 8, v229 bitop3:0x6c
	s_waitcnt lgkmcnt(0)
	v_mov_b32_e32 v31, v222
	s_nop 0
	v_lshlrev_b32_e32 v31, 2, v31
	v_bitop3_b32 v31, v31, 4, v229 bitop3:0x6c
	s_waitcnt lgkmcnt(0)
	v_fmamk_f32 v30, v30, 0x3b800000, v227
	v_mul_f32_e32 v31, 0x4b800000, v30
	v_cmp_gt_f32_e32 vcc, s19, v30
	s_nop 1
	v_cndmask_b32_e32 v30, v30, v31, vcc
	v_rsq_f32_e32 v30, v30
	s_nop 0
	v_mul_f32_e32 v31, 0x45800000, v30
	v_cndmask_b32_e32 v30, v30, v31, vcc
	v_mul_f32_e32 v26, v26, v30
	v_fma_f32 v26, v8, v26, v4
	v_mul_f32_e32 v31, 0xbfb8aa3b, v26
	v_exp_f32_e32 v31, v31
	v_mul_f32_e32 v27, v27, v30
	v_fma_f32 v27, v9, v27, v5
	v_mul_f32_e32 v32, 0xbfb8aa3b, v27
	v_add_f32_e32 v31, 1.0, v31
	v_exp_f32_e32 v32, v32
	v_rcp_f32_e32 v31, v31
	v_mul_f32_e32 v28, v28, v30
	v_mul_f32_e32 v29, v29, v30
	v_add_f32_e32 v32, 1.0, v32
	v_mul_f32_e32 v26, v26, v31
	s_waitcnt vmcnt(15)
	v_lshlrev_b32_e32 v31, 16, v24
	v_fma_f32 v28, v10, v28, v6
	v_fma_f32 v29, v11, v29, v7
	v_rcp_f32_e32 v32, v32
	v_mul_f32_e32 v26, v26, v31
	v_mul_f32_e32 v31, 0xbfb8aa3b, v28
	v_mul_f32_e32 v30, 0xbfb8aa3b, v29
	v_exp_f32_e32 v31, v31
	v_exp_f32_e32 v30, v30
	v_mul_f32_e32 v27, v27, v32
	v_and_b32_e32 v24, 0xffff0000, v24
	v_add_f32_e32 v31, 1.0, v31
	v_mul_f32_e32 v24, v27, v24
	v_add_f32_e32 v27, 1.0, v30
	v_rcp_f32_e32 v31, v31
	v_rcp_f32_e32 v27, v27
	v_lshlrev_b32_e32 v30, 16, v25
	v_and_b32_e32 v25, 0xffff0000, v25
	v_mul_f32_e32 v28, v28, v31
	v_mul_f32_e32 v27, v29, v27
	v_mul_f32_e32 v30, v28, v30
	v_mul_f32_e32 v25, v27, v25
	v_cvt_pk_bf16_f32 v28, v26, v24
	v_cvt_pk_bf16_f32 v29, v30, v25
	v_lshl_add_u64 v[24:25], v[34:35], 0, s[22:23]
	v_lshlrev_b64 v[24:25], 11, v[24:25]
	v_lshl_add_u64 v[24:25], s[30:31], 0, v[24:25]
	v_or_b32_e32 v32, 10, v14
	v_lshl_add_u64 v[30:31], v[24:25], 0, v[2:3]
	v_lshl_add_u32 v24, v32, 10, v15
	ds_read_b128 v[24:27], v24
	v_add_co_u32_e32 v30, vcc, s0, v30
	v_ashrrev_i32_e32 v33, 31, v32
	s_nop 0
	v_addc_co_u32_e32 v31, vcc, 0, v31, vcc
	global_store_dwordx2 v[30:31], v[28:29], off offset:1024
	v_mov_b32_e32 v29, v222
	s_waitcnt lgkmcnt(0)
	v_add_f32_e32 v28, v24, v25
	v_add_f32_e32 v28, v28, v26
	v_lshlrev_b32_e32 v29, 2, v29
	v_add_f32_e32 v28, v28, v27
	v_bitop3_b32 v29, v29, s18, v229 bitop3:0x6c
	s_nop 1
	v_add_f32_dpp v28, v28, v28 quad_perm:[1,0,3,2] row_mask:0xf bank_mask:0xf
	s_nop 1
	v_add_f32_dpp v28, v28, v28 quad_perm:[2,3,0,1] row_mask:0xf bank_mask:0xf
	s_nop 1
	v_add_f32_dpp v28, v28, v28 row_half_mirror row_mask:0xf bank_mask:0xf
	s_nop 1
	v_add_f32_dpp v28, v28, v28 row_mirror row_mask:0xf bank_mask:0xf
	s_nop 1
	v_add_f32_dpp v28, v28, v28 row_bcast:15 row_mask:0xa bank_mask:0xf
	s_nop 1
	v_add_f32_dpp v28, v28, v28 row_bcast:31 row_mask:0xc bank_mask:0xf
	s_nop 1
	v_readlane_b32 s98, v28, 63
	s_nop 1
	v_mov_b32_e32 v28, s98
	s_waitcnt lgkmcnt(0)
	v_mov_b32_e32 v29, v222
	s_nop 0
	v_lshlrev_b32_e32 v29, 2, v29
	v_bitop3_b32 v29, v29, 64, v229 bitop3:0x6c
	s_waitcnt lgkmcnt(0)
	v_mov_b32_e32 v29, v222
	s_nop 0
	v_lshlrev_b32_e32 v29, 2, v29
	v_bitop3_b32 v29, v29, 32, v229 bitop3:0x6c
	s_waitcnt lgkmcnt(0)
	v_mov_b32_e32 v29, v222
	s_nop 0
	v_lshlrev_b32_e32 v29, 2, v29
	v_bitop3_b32 v29, v29, 16, v229 bitop3:0x6c
	s_waitcnt lgkmcnt(0)
	v_mov_b32_e32 v29, v222
	s_nop 0
	v_lshlrev_b32_e32 v29, 2, v29
	v_bitop3_b32 v29, v29, 8, v229 bitop3:0x6c
	s_waitcnt lgkmcnt(0)
	v_mov_b32_e32 v29, v222
	s_nop 0
	v_lshlrev_b32_e32 v29, 2, v29
	v_bitop3_b32 v29, v29, 4, v229 bitop3:0x6c
	s_waitcnt lgkmcnt(0)
	v_mul_f32_e32 v28, 0x3b800000, v28
	v_pk_add_f32 v[24:25], v[24:25], v[28:29] op_sel_hi:[1,0] neg_lo:[0,1] neg_hi:[0,1]
	v_pk_add_f32 v[26:27], v[26:27], v[28:29] op_sel_hi:[1,0] neg_lo:[0,1] neg_hi:[0,1]
	v_pk_mul_f32 v[28:29], v[24:25], v[24:25]
	v_pk_mul_f32 v[30:31], v[26:27], v[26:27]
	v_add_f32_e32 v28, v28, v29
	v_mov_b32_e32 v29, v222
	v_add_f32_e32 v28, v30, v28
	v_lshlrev_b32_e32 v29, 2, v29
	v_add_f32_e32 v28, v31, v28
	v_bitop3_b32 v29, v29, s18, v229 bitop3:0x6c
	s_nop 1
	v_add_f32_dpp v28, v28, v28 quad_perm:[1,0,3,2] row_mask:0xf bank_mask:0xf
	s_nop 1
	v_add_f32_dpp v28, v28, v28 quad_perm:[2,3,0,1] row_mask:0xf bank_mask:0xf
	s_nop 1
	v_add_f32_dpp v28, v28, v28 row_half_mirror row_mask:0xf bank_mask:0xf
	s_nop 1
	v_add_f32_dpp v28, v28, v28 row_mirror row_mask:0xf bank_mask:0xf
	s_nop 1
	v_add_f32_dpp v28, v28, v28 row_bcast:15 row_mask:0xa bank_mask:0xf
	s_nop 1
	v_add_f32_dpp v28, v28, v28 row_bcast:31 row_mask:0xc bank_mask:0xf
	s_nop 1
	v_readlane_b32 s98, v28, 63
	s_nop 1
	v_mov_b32_e32 v28, s98
	s_waitcnt lgkmcnt(0)
	v_mov_b32_e32 v29, v222
	s_nop 0
	v_lshlrev_b32_e32 v29, 2, v29
	v_bitop3_b32 v29, v29, 64, v229 bitop3:0x6c
	s_waitcnt lgkmcnt(0)
	v_mov_b32_e32 v29, v222
	s_nop 0
	v_lshlrev_b32_e32 v29, 2, v29
	v_bitop3_b32 v29, v29, 32, v229 bitop3:0x6c
	s_waitcnt lgkmcnt(0)
	v_mov_b32_e32 v29, v222
	s_nop 0
	v_lshlrev_b32_e32 v29, 2, v29
	v_bitop3_b32 v29, v29, 16, v229 bitop3:0x6c
	s_waitcnt lgkmcnt(0)
	v_mov_b32_e32 v29, v222
	s_nop 0
	v_lshlrev_b32_e32 v29, 2, v29
	v_bitop3_b32 v29, v29, 8, v229 bitop3:0x6c
	s_waitcnt lgkmcnt(0)
	v_mov_b32_e32 v29, v222
	s_nop 0
	v_lshlrev_b32_e32 v29, 2, v29
	v_bitop3_b32 v29, v29, 4, v229 bitop3:0x6c
	s_waitcnt lgkmcnt(0)
	v_fmamk_f32 v28, v28, 0x3b800000, v227
	v_mul_f32_e32 v29, 0x4b800000, v28
	v_cmp_gt_f32_e32 vcc, s19, v28
	s_nop 1
	v_cndmask_b32_e32 v28, v28, v29, vcc
	v_rsq_f32_e32 v28, v28
	s_nop 0
	v_mul_f32_e32 v29, 0x45800000, v28
	v_cndmask_b32_e32 v28, v28, v29, vcc
	v_mul_f32_e32 v24, v24, v28
	v_fma_f32 v24, v8, v24, v4
	v_mul_f32_e32 v29, 0xbfb8aa3b, v24
	v_exp_f32_e32 v29, v29
	v_mul_f32_e32 v25, v25, v28
	v_fma_f32 v25, v9, v25, v5
	v_mul_f32_e32 v30, 0xbfb8aa3b, v25
	v_add_f32_e32 v29, 1.0, v29
	v_exp_f32_e32 v30, v30
	v_rcp_f32_e32 v29, v29
	v_mul_f32_e32 v26, v26, v28
	v_mul_f32_e32 v27, v27, v28
	v_add_f32_e32 v30, 1.0, v30
	v_mul_f32_e32 v24, v24, v29
	s_waitcnt vmcnt(15)
	v_lshlrev_b32_e32 v29, 16, v22
	v_fma_f32 v26, v10, v26, v6
	v_fma_f32 v27, v11, v27, v7
	v_rcp_f32_e32 v30, v30
	v_mul_f32_e32 v24, v24, v29
	v_mul_f32_e32 v29, 0xbfb8aa3b, v26
	v_mul_f32_e32 v28, 0xbfb8aa3b, v27
	v_exp_f32_e32 v29, v29
	v_exp_f32_e32 v28, v28
	v_mul_f32_e32 v25, v25, v30
	v_and_b32_e32 v22, 0xffff0000, v22
	v_add_f32_e32 v29, 1.0, v29
	v_mul_f32_e32 v22, v25, v22
	v_add_f32_e32 v25, 1.0, v28
	v_rcp_f32_e32 v29, v29
	v_rcp_f32_e32 v25, v25
	v_lshlrev_b32_e32 v28, 16, v23
	v_and_b32_e32 v23, 0xffff0000, v23
	v_mul_f32_e32 v26, v26, v29
	v_mul_f32_e32 v25, v27, v25
	v_mul_f32_e32 v28, v26, v28
	v_mul_f32_e32 v23, v25, v23
	v_cvt_pk_bf16_f32 v26, v24, v22
	v_cvt_pk_bf16_f32 v27, v28, v23
	v_lshl_add_u64 v[22:23], v[32:33], 0, s[22:23]
	v_lshlrev_b64 v[22:23], 11, v[22:23]
	v_lshl_add_u64 v[22:23], s[30:31], 0, v[22:23]
	v_or_b32_e32 v30, 11, v14
	v_lshl_add_u64 v[28:29], v[22:23], 0, v[2:3]
	v_lshl_add_u32 v22, v30, 10, v15
	ds_read_b128 v[22:25], v22
	v_add_co_u32_e32 v28, vcc, s0, v28
	v_ashrrev_i32_e32 v31, 31, v30
	s_nop 0
	v_addc_co_u32_e32 v29, vcc, 0, v29, vcc
	global_store_dwordx2 v[28:29], v[26:27], off offset:1024
	v_mov_b32_e32 v27, v222
	s_waitcnt lgkmcnt(0)
	v_add_f32_e32 v26, v22, v23
	v_add_f32_e32 v26, v26, v24
	v_lshlrev_b32_e32 v27, 2, v27
	v_add_f32_e32 v26, v26, v25
	v_bitop3_b32 v27, v27, s18, v229 bitop3:0x6c
	s_nop 1
	v_add_f32_dpp v26, v26, v26 quad_perm:[1,0,3,2] row_mask:0xf bank_mask:0xf
	s_nop 1
	v_add_f32_dpp v26, v26, v26 quad_perm:[2,3,0,1] row_mask:0xf bank_mask:0xf
	s_nop 1
	v_add_f32_dpp v26, v26, v26 row_half_mirror row_mask:0xf bank_mask:0xf
	s_nop 1
	v_add_f32_dpp v26, v26, v26 row_mirror row_mask:0xf bank_mask:0xf
	s_nop 1
	v_add_f32_dpp v26, v26, v26 row_bcast:15 row_mask:0xa bank_mask:0xf
	s_nop 1
	v_add_f32_dpp v26, v26, v26 row_bcast:31 row_mask:0xc bank_mask:0xf
	s_nop 1
	v_readlane_b32 s98, v26, 63
	s_nop 1
	v_mov_b32_e32 v26, s98
	s_waitcnt lgkmcnt(0)
	v_mov_b32_e32 v27, v222
	s_nop 0
	v_lshlrev_b32_e32 v27, 2, v27
	v_bitop3_b32 v27, v27, 64, v229 bitop3:0x6c
	s_waitcnt lgkmcnt(0)
	v_mov_b32_e32 v27, v222
	s_nop 0
	v_lshlrev_b32_e32 v27, 2, v27
	v_bitop3_b32 v27, v27, 32, v229 bitop3:0x6c
	s_waitcnt lgkmcnt(0)
	v_mov_b32_e32 v27, v222
	s_nop 0
	v_lshlrev_b32_e32 v27, 2, v27
	v_bitop3_b32 v27, v27, 16, v229 bitop3:0x6c
	s_waitcnt lgkmcnt(0)
	v_mov_b32_e32 v27, v222
	s_nop 0
	v_lshlrev_b32_e32 v27, 2, v27
	v_bitop3_b32 v27, v27, 8, v229 bitop3:0x6c
	s_waitcnt lgkmcnt(0)
	v_mov_b32_e32 v27, v222
	s_nop 0
	v_lshlrev_b32_e32 v27, 2, v27
	v_bitop3_b32 v27, v27, 4, v229 bitop3:0x6c
	s_waitcnt lgkmcnt(0)
	v_mul_f32_e32 v26, 0x3b800000, v26
	v_pk_add_f32 v[22:23], v[22:23], v[26:27] op_sel_hi:[1,0] neg_lo:[0,1] neg_hi:[0,1]
	v_pk_add_f32 v[24:25], v[24:25], v[26:27] op_sel_hi:[1,0] neg_lo:[0,1] neg_hi:[0,1]
	v_pk_mul_f32 v[26:27], v[22:23], v[22:23]
	v_pk_mul_f32 v[28:29], v[24:25], v[24:25]
	v_add_f32_e32 v26, v26, v27
	v_mov_b32_e32 v27, v222
	v_add_f32_e32 v26, v28, v26
	v_lshlrev_b32_e32 v27, 2, v27
	v_add_f32_e32 v26, v29, v26
	v_bitop3_b32 v27, v27, s18, v229 bitop3:0x6c
	s_nop 1
	v_add_f32_dpp v26, v26, v26 quad_perm:[1,0,3,2] row_mask:0xf bank_mask:0xf
	s_nop 1
	v_add_f32_dpp v26, v26, v26 quad_perm:[2,3,0,1] row_mask:0xf bank_mask:0xf
	s_nop 1
	v_add_f32_dpp v26, v26, v26 row_half_mirror row_mask:0xf bank_mask:0xf
	s_nop 1
	v_add_f32_dpp v26, v26, v26 row_mirror row_mask:0xf bank_mask:0xf
	s_nop 1
	v_add_f32_dpp v26, v26, v26 row_bcast:15 row_mask:0xa bank_mask:0xf
	s_nop 1
	v_add_f32_dpp v26, v26, v26 row_bcast:31 row_mask:0xc bank_mask:0xf
	s_nop 1
	v_readlane_b32 s98, v26, 63
	s_nop 1
	v_mov_b32_e32 v26, s98
	s_waitcnt lgkmcnt(0)
	v_mov_b32_e32 v27, v222
	s_nop 0
	v_lshlrev_b32_e32 v27, 2, v27
	v_bitop3_b32 v27, v27, 64, v229 bitop3:0x6c
	s_waitcnt lgkmcnt(0)
	v_mov_b32_e32 v27, v222
	s_nop 0
	v_lshlrev_b32_e32 v27, 2, v27
	v_bitop3_b32 v27, v27, 32, v229 bitop3:0x6c
	s_waitcnt lgkmcnt(0)
	v_mov_b32_e32 v27, v222
	s_nop 0
	v_lshlrev_b32_e32 v27, 2, v27
	v_bitop3_b32 v27, v27, 16, v229 bitop3:0x6c
	s_waitcnt lgkmcnt(0)
	v_mov_b32_e32 v27, v222
	s_nop 0
	v_lshlrev_b32_e32 v27, 2, v27
	v_bitop3_b32 v27, v27, 8, v229 bitop3:0x6c
	s_waitcnt lgkmcnt(0)
	v_mov_b32_e32 v27, v222
	s_nop 0
	v_lshlrev_b32_e32 v27, 2, v27
	v_bitop3_b32 v27, v27, 4, v229 bitop3:0x6c
	s_waitcnt lgkmcnt(0)
	v_fmamk_f32 v26, v26, 0x3b800000, v227
	v_mul_f32_e32 v27, 0x4b800000, v26
	v_cmp_gt_f32_e32 vcc, s19, v26
	s_nop 1
	v_cndmask_b32_e32 v26, v26, v27, vcc
	v_rsq_f32_e32 v26, v26
	s_nop 0
	v_mul_f32_e32 v27, 0x45800000, v26
	v_cndmask_b32_e32 v26, v26, v27, vcc
	v_mul_f32_e32 v22, v22, v26
	v_fma_f32 v22, v8, v22, v4
	v_mul_f32_e32 v27, 0xbfb8aa3b, v22
	v_exp_f32_e32 v27, v27
	v_mul_f32_e32 v23, v23, v26
	v_fma_f32 v23, v9, v23, v5
	v_mul_f32_e32 v28, 0xbfb8aa3b, v23
	v_add_f32_e32 v27, 1.0, v27
	v_exp_f32_e32 v28, v28
	v_rcp_f32_e32 v27, v27
	v_mul_f32_e32 v24, v24, v26
	v_mul_f32_e32 v25, v25, v26
	v_add_f32_e32 v28, 1.0, v28
	v_mul_f32_e32 v22, v22, v27
	s_waitcnt vmcnt(15)
	v_lshlrev_b32_e32 v27, 16, v20
	v_fma_f32 v24, v10, v24, v6
	v_fma_f32 v25, v11, v25, v7
	v_rcp_f32_e32 v28, v28
	v_mul_f32_e32 v22, v22, v27
	v_mul_f32_e32 v27, 0xbfb8aa3b, v24
	v_mul_f32_e32 v26, 0xbfb8aa3b, v25
	v_exp_f32_e32 v27, v27
	v_exp_f32_e32 v26, v26
	v_mul_f32_e32 v23, v23, v28
	v_and_b32_e32 v20, 0xffff0000, v20
	v_add_f32_e32 v27, 1.0, v27
	v_mul_f32_e32 v20, v23, v20
	v_add_f32_e32 v23, 1.0, v26
	v_rcp_f32_e32 v27, v27
	v_rcp_f32_e32 v23, v23
	v_lshlrev_b32_e32 v26, 16, v21
	v_and_b32_e32 v21, 0xffff0000, v21
	v_mul_f32_e32 v24, v24, v27
	v_mul_f32_e32 v23, v25, v23
	v_mul_f32_e32 v26, v24, v26
	v_mul_f32_e32 v21, v23, v21
	v_cvt_pk_bf16_f32 v24, v22, v20
	v_cvt_pk_bf16_f32 v25, v26, v21
	v_lshl_add_u64 v[20:21], v[30:31], 0, s[22:23]
	v_lshlrev_b64 v[20:21], 11, v[20:21]
	v_lshl_add_u64 v[20:21], s[30:31], 0, v[20:21]
	v_or_b32_e32 v28, 12, v14
	v_lshl_add_u64 v[26:27], v[20:21], 0, v[2:3]
	v_lshl_add_u32 v20, v28, 10, v15
	ds_read_b128 v[20:23], v20
	v_add_co_u32_e32 v26, vcc, s0, v26
	v_ashrrev_i32_e32 v29, 31, v28
	s_nop 0
	v_addc_co_u32_e32 v27, vcc, 0, v27, vcc
	global_store_dwordx2 v[26:27], v[24:25], off offset:1024
	v_mov_b32_e32 v25, v222
	s_waitcnt lgkmcnt(0)
	v_add_f32_e32 v24, v20, v21
	v_add_f32_e32 v24, v24, v22
	v_lshlrev_b32_e32 v25, 2, v25
	v_add_f32_e32 v24, v24, v23
	v_bitop3_b32 v25, v25, s18, v229 bitop3:0x6c
	s_nop 1
	v_add_f32_dpp v24, v24, v24 quad_perm:[1,0,3,2] row_mask:0xf bank_mask:0xf
	s_nop 1
	v_add_f32_dpp v24, v24, v24 quad_perm:[2,3,0,1] row_mask:0xf bank_mask:0xf
	s_nop 1
	v_add_f32_dpp v24, v24, v24 row_half_mirror row_mask:0xf bank_mask:0xf
	s_nop 1
	v_add_f32_dpp v24, v24, v24 row_mirror row_mask:0xf bank_mask:0xf
	s_nop 1
	v_add_f32_dpp v24, v24, v24 row_bcast:15 row_mask:0xa bank_mask:0xf
	s_nop 1
	v_add_f32_dpp v24, v24, v24 row_bcast:31 row_mask:0xc bank_mask:0xf
	s_nop 1
	v_readlane_b32 s98, v24, 63
	s_nop 1
	v_mov_b32_e32 v24, s98
	s_waitcnt lgkmcnt(0)
	v_mov_b32_e32 v25, v222
	s_nop 0
	v_lshlrev_b32_e32 v25, 2, v25
	v_bitop3_b32 v25, v25, 64, v229 bitop3:0x6c
	s_waitcnt lgkmcnt(0)
	v_mov_b32_e32 v25, v222
	s_nop 0
	v_lshlrev_b32_e32 v25, 2, v25
	v_bitop3_b32 v25, v25, 32, v229 bitop3:0x6c
	s_waitcnt lgkmcnt(0)
	v_mov_b32_e32 v25, v222
	s_nop 0
	v_lshlrev_b32_e32 v25, 2, v25
	v_bitop3_b32 v25, v25, 16, v229 bitop3:0x6c
	s_waitcnt lgkmcnt(0)
	v_mov_b32_e32 v25, v222
	s_nop 0
	v_lshlrev_b32_e32 v25, 2, v25
	v_bitop3_b32 v25, v25, 8, v229 bitop3:0x6c
	s_waitcnt lgkmcnt(0)
	v_mov_b32_e32 v25, v222
	s_nop 0
	v_lshlrev_b32_e32 v25, 2, v25
	v_bitop3_b32 v25, v25, 4, v229 bitop3:0x6c
	s_waitcnt lgkmcnt(0)
	v_mul_f32_e32 v24, 0x3b800000, v24
	v_pk_add_f32 v[20:21], v[20:21], v[24:25] op_sel_hi:[1,0] neg_lo:[0,1] neg_hi:[0,1]
	v_pk_add_f32 v[22:23], v[22:23], v[24:25] op_sel_hi:[1,0] neg_lo:[0,1] neg_hi:[0,1]
	v_pk_mul_f32 v[24:25], v[20:21], v[20:21]
	v_pk_mul_f32 v[26:27], v[22:23], v[22:23]
	v_add_f32_e32 v24, v24, v25
	v_mov_b32_e32 v25, v222
	v_add_f32_e32 v24, v26, v24
	v_lshlrev_b32_e32 v25, 2, v25
	v_add_f32_e32 v24, v27, v24
	v_bitop3_b32 v25, v25, s18, v229 bitop3:0x6c
	s_nop 1
	v_add_f32_dpp v24, v24, v24 quad_perm:[1,0,3,2] row_mask:0xf bank_mask:0xf
	s_nop 1
	v_add_f32_dpp v24, v24, v24 quad_perm:[2,3,0,1] row_mask:0xf bank_mask:0xf
	s_nop 1
	v_add_f32_dpp v24, v24, v24 row_half_mirror row_mask:0xf bank_mask:0xf
	s_nop 1
	v_add_f32_dpp v24, v24, v24 row_mirror row_mask:0xf bank_mask:0xf
	s_nop 1
	v_add_f32_dpp v24, v24, v24 row_bcast:15 row_mask:0xa bank_mask:0xf
	s_nop 1
	v_add_f32_dpp v24, v24, v24 row_bcast:31 row_mask:0xc bank_mask:0xf
	s_nop 1
	v_readlane_b32 s98, v24, 63
	s_nop 1
	v_mov_b32_e32 v24, s98
	s_waitcnt lgkmcnt(0)
	v_mov_b32_e32 v25, v222
	s_nop 0
	v_lshlrev_b32_e32 v25, 2, v25
	v_bitop3_b32 v25, v25, 64, v229 bitop3:0x6c
	s_waitcnt lgkmcnt(0)
	v_mov_b32_e32 v25, v222
	s_nop 0
	v_lshlrev_b32_e32 v25, 2, v25
	v_bitop3_b32 v25, v25, 32, v229 bitop3:0x6c
	s_waitcnt lgkmcnt(0)
	v_mov_b32_e32 v25, v222
	s_nop 0
	v_lshlrev_b32_e32 v25, 2, v25
	v_bitop3_b32 v25, v25, 16, v229 bitop3:0x6c
	s_waitcnt lgkmcnt(0)
	v_mov_b32_e32 v25, v222
	s_nop 0
	v_lshlrev_b32_e32 v25, 2, v25
	v_bitop3_b32 v25, v25, 8, v229 bitop3:0x6c
	s_waitcnt lgkmcnt(0)
	v_mov_b32_e32 v25, v222
	s_nop 0
	v_lshlrev_b32_e32 v25, 2, v25
	v_bitop3_b32 v25, v25, 4, v229 bitop3:0x6c
	s_waitcnt lgkmcnt(0)
	v_fmamk_f32 v24, v24, 0x3b800000, v227
	v_mul_f32_e32 v25, 0x4b800000, v24
	v_cmp_gt_f32_e32 vcc, s19, v24
	s_nop 1
	v_cndmask_b32_e32 v24, v24, v25, vcc
	v_rsq_f32_e32 v24, v24
	s_nop 0
	v_mul_f32_e32 v25, 0x45800000, v24
	v_cndmask_b32_e32 v24, v24, v25, vcc
	v_mul_f32_e32 v20, v20, v24
	v_fma_f32 v20, v8, v20, v4
	v_mul_f32_e32 v25, 0xbfb8aa3b, v20
	v_exp_f32_e32 v25, v25
	v_mul_f32_e32 v21, v21, v24
	v_fma_f32 v21, v9, v21, v5
	v_mul_f32_e32 v26, 0xbfb8aa3b, v21
	v_add_f32_e32 v25, 1.0, v25
	v_exp_f32_e32 v26, v26
	v_rcp_f32_e32 v25, v25
	v_mul_f32_e32 v22, v22, v24
	v_mul_f32_e32 v23, v23, v24
	v_add_f32_e32 v26, 1.0, v26
	v_mul_f32_e32 v20, v20, v25
	s_waitcnt vmcnt(15)
	v_lshlrev_b32_e32 v25, 16, v18
	v_fma_f32 v22, v10, v22, v6
	v_fma_f32 v23, v11, v23, v7
	v_rcp_f32_e32 v26, v26
	v_mul_f32_e32 v20, v20, v25
	v_mul_f32_e32 v25, 0xbfb8aa3b, v22
	v_mul_f32_e32 v24, 0xbfb8aa3b, v23
	v_exp_f32_e32 v25, v25
	v_exp_f32_e32 v24, v24
	v_mul_f32_e32 v21, v21, v26
	v_and_b32_e32 v18, 0xffff0000, v18
	v_add_f32_e32 v25, 1.0, v25
	v_mul_f32_e32 v18, v21, v18
	v_add_f32_e32 v21, 1.0, v24
	v_rcp_f32_e32 v25, v25
	v_rcp_f32_e32 v21, v21
	v_lshlrev_b32_e32 v24, 16, v19
	v_and_b32_e32 v19, 0xffff0000, v19
	v_mul_f32_e32 v22, v22, v25
	v_mul_f32_e32 v21, v23, v21
	v_mul_f32_e32 v24, v22, v24
	v_mul_f32_e32 v19, v21, v19
	v_cvt_pk_bf16_f32 v22, v20, v18
	v_cvt_pk_bf16_f32 v23, v24, v19
	v_lshl_add_u64 v[18:19], v[28:29], 0, s[22:23]
	v_lshlrev_b64 v[18:19], 11, v[18:19]
	v_lshl_add_u64 v[18:19], s[30:31], 0, v[18:19]
	v_or_b32_e32 v26, 13, v14
	v_lshl_add_u64 v[24:25], v[18:19], 0, v[2:3]
	v_lshl_add_u32 v18, v26, 10, v15
	ds_read_b128 v[18:21], v18
	v_add_co_u32_e32 v24, vcc, s0, v24
	v_ashrrev_i32_e32 v27, 31, v26
	s_nop 0
	v_addc_co_u32_e32 v25, vcc, 0, v25, vcc
	global_store_dwordx2 v[24:25], v[22:23], off offset:1024
	v_mov_b32_e32 v23, v222
	s_waitcnt lgkmcnt(0)
	v_add_f32_e32 v22, v18, v19
	v_add_f32_e32 v22, v22, v20
	v_lshlrev_b32_e32 v23, 2, v23
	v_add_f32_e32 v22, v22, v21
	v_bitop3_b32 v23, v23, s18, v229 bitop3:0x6c
	s_nop 1
	v_add_f32_dpp v22, v22, v22 quad_perm:[1,0,3,2] row_mask:0xf bank_mask:0xf
	s_nop 1
	v_add_f32_dpp v22, v22, v22 quad_perm:[2,3,0,1] row_mask:0xf bank_mask:0xf
	s_nop 1
	v_add_f32_dpp v22, v22, v22 row_half_mirror row_mask:0xf bank_mask:0xf
	s_nop 1
	v_add_f32_dpp v22, v22, v22 row_mirror row_mask:0xf bank_mask:0xf
	s_nop 1
	v_add_f32_dpp v22, v22, v22 row_bcast:15 row_mask:0xa bank_mask:0xf
	s_nop 1
	v_add_f32_dpp v22, v22, v22 row_bcast:31 row_mask:0xc bank_mask:0xf
	s_nop 1
	v_readlane_b32 s98, v22, 63
	s_nop 1
	v_mov_b32_e32 v22, s98
	s_waitcnt lgkmcnt(0)
	v_mov_b32_e32 v23, v222
	s_nop 0
	v_lshlrev_b32_e32 v23, 2, v23
	v_bitop3_b32 v23, v23, 64, v229 bitop3:0x6c
	s_waitcnt lgkmcnt(0)
	v_mov_b32_e32 v23, v222
	s_nop 0
	v_lshlrev_b32_e32 v23, 2, v23
	v_bitop3_b32 v23, v23, 32, v229 bitop3:0x6c
	s_waitcnt lgkmcnt(0)
	v_mov_b32_e32 v23, v222
	s_nop 0
	v_lshlrev_b32_e32 v23, 2, v23
	v_bitop3_b32 v23, v23, 16, v229 bitop3:0x6c
	s_waitcnt lgkmcnt(0)
	v_mov_b32_e32 v23, v222
	s_nop 0
	v_lshlrev_b32_e32 v23, 2, v23
	v_bitop3_b32 v23, v23, 8, v229 bitop3:0x6c
	s_waitcnt lgkmcnt(0)
	v_mov_b32_e32 v23, v222
	s_nop 0
	v_lshlrev_b32_e32 v23, 2, v23
	v_bitop3_b32 v23, v23, 4, v229 bitop3:0x6c
	s_waitcnt lgkmcnt(0)
	v_mul_f32_e32 v22, 0x3b800000, v22
	v_pk_add_f32 v[18:19], v[18:19], v[22:23] op_sel_hi:[1,0] neg_lo:[0,1] neg_hi:[0,1]
	v_pk_add_f32 v[20:21], v[20:21], v[22:23] op_sel_hi:[1,0] neg_lo:[0,1] neg_hi:[0,1]
	v_pk_mul_f32 v[22:23], v[18:19], v[18:19]
	v_pk_mul_f32 v[24:25], v[20:21], v[20:21]
	v_add_f32_e32 v22, v22, v23
	v_mov_b32_e32 v23, v222
	v_add_f32_e32 v22, v24, v22
	v_lshlrev_b32_e32 v23, 2, v23
	v_add_f32_e32 v22, v25, v22
	v_bitop3_b32 v23, v23, s18, v229 bitop3:0x6c
	s_nop 1
	v_add_f32_dpp v22, v22, v22 quad_perm:[1,0,3,2] row_mask:0xf bank_mask:0xf
	s_nop 1
	v_add_f32_dpp v22, v22, v22 quad_perm:[2,3,0,1] row_mask:0xf bank_mask:0xf
	s_nop 1
	v_add_f32_dpp v22, v22, v22 row_half_mirror row_mask:0xf bank_mask:0xf
	s_nop 1
	v_add_f32_dpp v22, v22, v22 row_mirror row_mask:0xf bank_mask:0xf
	s_nop 1
	v_add_f32_dpp v22, v22, v22 row_bcast:15 row_mask:0xa bank_mask:0xf
	s_nop 1
	v_add_f32_dpp v22, v22, v22 row_bcast:31 row_mask:0xc bank_mask:0xf
	s_nop 1
	v_readlane_b32 s98, v22, 63
	s_nop 1
	v_mov_b32_e32 v22, s98
	s_waitcnt lgkmcnt(0)
	v_mov_b32_e32 v23, v222
	s_nop 0
	v_lshlrev_b32_e32 v23, 2, v23
	v_bitop3_b32 v23, v23, 64, v229 bitop3:0x6c
	s_waitcnt lgkmcnt(0)
	v_mov_b32_e32 v23, v222
	s_nop 0
	v_lshlrev_b32_e32 v23, 2, v23
	v_bitop3_b32 v23, v23, 32, v229 bitop3:0x6c
	s_waitcnt lgkmcnt(0)
	v_mov_b32_e32 v23, v222
	s_nop 0
	v_lshlrev_b32_e32 v23, 2, v23
	v_bitop3_b32 v23, v23, 16, v229 bitop3:0x6c
	s_waitcnt lgkmcnt(0)
	v_mov_b32_e32 v23, v222
	s_nop 0
	v_lshlrev_b32_e32 v23, 2, v23
	v_bitop3_b32 v23, v23, 8, v229 bitop3:0x6c
	s_waitcnt lgkmcnt(0)
	v_mov_b32_e32 v23, v222
	s_nop 0
	v_lshlrev_b32_e32 v23, 2, v23
	v_bitop3_b32 v23, v23, 4, v229 bitop3:0x6c
	s_waitcnt lgkmcnt(0)
	v_fmamk_f32 v22, v22, 0x3b800000, v227
	v_mul_f32_e32 v23, 0x4b800000, v22
	v_cmp_gt_f32_e32 vcc, s19, v22
	s_nop 1
	v_cndmask_b32_e32 v22, v22, v23, vcc
	v_rsq_f32_e32 v22, v22
	s_nop 0
	v_mul_f32_e32 v23, 0x45800000, v22
	v_cndmask_b32_e32 v22, v22, v23, vcc
	v_mul_f32_e32 v18, v18, v22
	v_fma_f32 v18, v8, v18, v4
	v_mul_f32_e32 v23, 0xbfb8aa3b, v18
	v_exp_f32_e32 v23, v23
	v_mul_f32_e32 v19, v19, v22
	v_fma_f32 v19, v9, v19, v5
	v_mul_f32_e32 v24, 0xbfb8aa3b, v19
	v_add_f32_e32 v23, 1.0, v23
	v_exp_f32_e32 v24, v24
	v_rcp_f32_e32 v23, v23
	v_mul_f32_e32 v20, v20, v22
	v_mul_f32_e32 v21, v21, v22
	v_add_f32_e32 v24, 1.0, v24
	v_mul_f32_e32 v18, v18, v23
	s_waitcnt vmcnt(15)
	v_lshlrev_b32_e32 v23, 16, v16
	v_fma_f32 v20, v10, v20, v6
	v_fma_f32 v21, v11, v21, v7
	v_rcp_f32_e32 v24, v24
	v_mul_f32_e32 v18, v18, v23
	v_mul_f32_e32 v23, 0xbfb8aa3b, v20
	v_mul_f32_e32 v22, 0xbfb8aa3b, v21
	v_exp_f32_e32 v23, v23
	v_exp_f32_e32 v22, v22
	v_mul_f32_e32 v19, v19, v24
	v_and_b32_e32 v16, 0xffff0000, v16
	v_add_f32_e32 v23, 1.0, v23
	v_mul_f32_e32 v16, v19, v16
	v_add_f32_e32 v19, 1.0, v22
	v_rcp_f32_e32 v23, v23
	v_rcp_f32_e32 v19, v19
	v_lshlrev_b32_e32 v22, 16, v17
	v_and_b32_e32 v17, 0xffff0000, v17
	v_mul_f32_e32 v20, v20, v23
	v_mul_f32_e32 v19, v21, v19
	v_mul_f32_e32 v22, v20, v22
	v_mul_f32_e32 v17, v19, v17
	v_cvt_pk_bf16_f32 v20, v18, v16
	v_cvt_pk_bf16_f32 v21, v22, v17
	v_lshl_add_u64 v[16:17], v[26:27], 0, s[22:23]
	v_lshlrev_b64 v[16:17], 11, v[16:17]
	v_or_b32_e32 v24, 14, v14
	v_lshl_add_u64 v[16:17], s[30:31], 0, v[16:17]
	v_lshl_add_u32 v14, v24, 10, v15
	v_lshl_add_u64 v[22:23], v[16:17], 0, v[2:3]
	ds_read_b128 v[16:19], v14
	v_add_co_u32_e32 v22, vcc, s0, v22
	v_ashrrev_i32_e32 v25, 31, v24
	s_nop 0
	v_addc_co_u32_e32 v23, vcc, 0, v23, vcc
	global_store_dwordx2 v[22:23], v[20:21], off offset:1024
	v_mov_b32_e32 v20, v222
	s_waitcnt lgkmcnt(0)
	v_add_f32_e32 v14, v16, v17
	v_add_f32_e32 v14, v14, v18
	v_lshlrev_b32_e32 v20, 2, v20
	v_add_f32_e32 v14, v14, v19
	v_bitop3_b32 v20, v20, s18, v229 bitop3:0x6c
	s_nop 1
	v_add_f32_dpp v14, v14, v14 quad_perm:[1,0,3,2] row_mask:0xf bank_mask:0xf
	s_nop 1
	v_add_f32_dpp v14, v14, v14 quad_perm:[2,3,0,1] row_mask:0xf bank_mask:0xf
	s_nop 1
	v_add_f32_dpp v14, v14, v14 row_half_mirror row_mask:0xf bank_mask:0xf
	s_nop 1
	v_add_f32_dpp v14, v14, v14 row_mirror row_mask:0xf bank_mask:0xf
	s_nop 1
	v_add_f32_dpp v14, v14, v14 row_bcast:15 row_mask:0xa bank_mask:0xf
	s_nop 1
	v_add_f32_dpp v14, v14, v14 row_bcast:31 row_mask:0xc bank_mask:0xf
	s_nop 1
	v_readlane_b32 s98, v14, 63
	s_nop 1
	v_mov_b32_e32 v14, s98
	s_waitcnt lgkmcnt(0)
	v_mov_b32_e32 v20, v222
	s_nop 0
	v_lshlrev_b32_e32 v20, 2, v20
	v_bitop3_b32 v20, v20, 64, v229 bitop3:0x6c
	s_waitcnt lgkmcnt(0)
	v_mov_b32_e32 v20, v222
	s_nop 0
	v_lshlrev_b32_e32 v20, 2, v20
	v_bitop3_b32 v20, v20, 32, v229 bitop3:0x6c
	s_waitcnt lgkmcnt(0)
	v_mov_b32_e32 v20, v222
	s_nop 0
	v_lshlrev_b32_e32 v20, 2, v20
	v_bitop3_b32 v20, v20, 16, v229 bitop3:0x6c
	s_waitcnt lgkmcnt(0)
	v_mov_b32_e32 v20, v222
	s_nop 0
	v_lshlrev_b32_e32 v20, 2, v20
	v_bitop3_b32 v20, v20, 8, v229 bitop3:0x6c
	s_waitcnt lgkmcnt(0)
	v_mov_b32_e32 v20, v222
	s_nop 0
	v_lshlrev_b32_e32 v20, 2, v20
	v_bitop3_b32 v20, v20, 4, v229 bitop3:0x6c
	s_waitcnt lgkmcnt(0)
	v_mul_f32_e32 v14, 0x3b800000, v14
	v_pk_add_f32 v[16:17], v[16:17], v[14:15] op_sel_hi:[1,0] neg_lo:[0,1] neg_hi:[0,1]
	v_pk_add_f32 v[18:19], v[18:19], v[14:15] op_sel_hi:[1,0] neg_lo:[0,1] neg_hi:[0,1]
	v_pk_mul_f32 v[20:21], v[16:17], v[16:17]
	v_pk_mul_f32 v[22:23], v[18:19], v[18:19]
	v_add_f32_e32 v14, v20, v21
	v_mov_b32_e32 v20, v222
	v_add_f32_e32 v14, v22, v14
	v_lshlrev_b32_e32 v20, 2, v20
	v_add_f32_e32 v14, v23, v14
	v_bitop3_b32 v20, v20, s18, v229 bitop3:0x6c
	s_nop 1
	v_add_f32_dpp v14, v14, v14 quad_perm:[1,0,3,2] row_mask:0xf bank_mask:0xf
	s_nop 1
	v_add_f32_dpp v14, v14, v14 quad_perm:[2,3,0,1] row_mask:0xf bank_mask:0xf
	s_nop 1
	v_add_f32_dpp v14, v14, v14 row_half_mirror row_mask:0xf bank_mask:0xf
	s_nop 1
	v_add_f32_dpp v14, v14, v14 row_mirror row_mask:0xf bank_mask:0xf
	s_nop 1
	v_add_f32_dpp v14, v14, v14 row_bcast:15 row_mask:0xa bank_mask:0xf
	s_nop 1
	v_add_f32_dpp v14, v14, v14 row_bcast:31 row_mask:0xc bank_mask:0xf
	s_nop 1
	v_readlane_b32 s98, v14, 63
	s_nop 1
	v_mov_b32_e32 v14, s98
	s_waitcnt lgkmcnt(0)
	v_mov_b32_e32 v20, v222
	s_nop 0
	v_lshlrev_b32_e32 v20, 2, v20
	v_bitop3_b32 v20, v20, 64, v229 bitop3:0x6c
	s_waitcnt lgkmcnt(0)
	v_mov_b32_e32 v20, v222
	s_nop 0
	v_lshlrev_b32_e32 v20, 2, v20
	v_bitop3_b32 v20, v20, 32, v229 bitop3:0x6c
	s_waitcnt lgkmcnt(0)
	v_mov_b32_e32 v20, v222
	s_nop 0
	v_lshlrev_b32_e32 v20, 2, v20
	v_bitop3_b32 v20, v20, 16, v229 bitop3:0x6c
	s_waitcnt lgkmcnt(0)
	v_mov_b32_e32 v20, v222
	s_nop 0
	v_lshlrev_b32_e32 v20, 2, v20
	v_bitop3_b32 v20, v20, 8, v229 bitop3:0x6c
	s_waitcnt lgkmcnt(0)
	v_mov_b32_e32 v20, v222
	s_nop 0
	v_lshlrev_b32_e32 v20, 2, v20
	v_bitop3_b32 v20, v20, 4, v229 bitop3:0x6c
	s_waitcnt lgkmcnt(0)
	v_fmamk_f32 v14, v14, 0x3b800000, v227
	v_mul_f32_e32 v20, 0x4b800000, v14
	v_cmp_gt_f32_e32 vcc, s19, v14
	s_nop 1
	v_cndmask_b32_e32 v14, v14, v20, vcc
	v_rsq_f32_e32 v14, v14
	s_nop 0
	v_mul_f32_e32 v20, 0x45800000, v14
	v_cndmask_b32_e32 v14, v14, v20, vcc
	v_mul_f32_e32 v16, v16, v14
	v_fma_f32 v16, v8, v16, v4
	v_mul_f32_e32 v20, 0xbfb8aa3b, v16
	v_exp_f32_e32 v20, v20
	v_mul_f32_e32 v17, v17, v14
	v_fma_f32 v17, v9, v17, v5
	v_mul_f32_e32 v21, 0xbfb8aa3b, v17
	v_add_f32_e32 v20, 1.0, v20
	v_exp_f32_e32 v21, v21
	v_rcp_f32_e32 v20, v20
	v_mul_f32_e32 v18, v18, v14
	v_mul_f32_e32 v14, v19, v14
	v_add_f32_e32 v21, 1.0, v21
	v_mul_f32_e32 v16, v16, v20
	s_waitcnt vmcnt(15)
	v_lshlrev_b32_e32 v20, 16, v12
	v_fma_f32 v18, v10, v18, v6
	v_fma_f32 v14, v11, v14, v7
	v_rcp_f32_e32 v21, v21
	v_mul_f32_e32 v16, v16, v20
	v_mul_f32_e32 v20, 0xbfb8aa3b, v18
	v_mul_f32_e32 v19, 0xbfb8aa3b, v14
	v_exp_f32_e32 v20, v20
	v_exp_f32_e32 v19, v19
	v_mul_f32_e32 v17, v17, v21
	v_and_b32_e32 v12, 0xffff0000, v12
	v_add_f32_e32 v20, 1.0, v20
	v_mul_f32_e32 v12, v17, v12
	v_add_f32_e32 v17, 1.0, v19
	v_rcp_f32_e32 v20, v20
	v_rcp_f32_e32 v17, v17
	v_lshlrev_b32_e32 v19, 16, v13
	v_and_b32_e32 v13, 0xffff0000, v13
	v_mul_f32_e32 v18, v18, v20
	v_mul_f32_e32 v14, v14, v17
	v_mul_f32_e32 v18, v18, v19
	v_mul_f32_e32 v13, v14, v13
	v_cvt_pk_bf16_f32 v16, v16, v12
	v_cvt_pk_bf16_f32 v17, v18, v13
	v_lshl_add_u64 v[12:13], v[24:25], 0, s[22:23]
	v_lshlrev_b64 v[12:13], 11, v[12:13]
	v_lshl_add_u64 v[12:13], s[30:31], 0, v[12:13]
	v_or_b32_e32 v20, 15, v44
	v_lshl_add_u64 v[18:19], v[12:13], 0, v[2:3]
	v_lshl_add_u32 v12, v20, 10, v15
	ds_read_b128 v[12:15], v12
	v_add_co_u32_e32 v18, vcc, s0, v18
	v_ashrrev_i32_e32 v21, 31, v20
	s_nop 0
	v_addc_co_u32_e32 v19, vcc, 0, v19, vcc
	global_store_dwordx2 v[18:19], v[16:17], off offset:1024
	v_mov_b32_e32 v17, v222
	s_waitcnt lgkmcnt(0)
	v_add_f32_e32 v16, v12, v13
	v_add_f32_e32 v16, v16, v14
	v_lshlrev_b32_e32 v17, 2, v17
	v_add_f32_e32 v16, v16, v15
	v_bitop3_b32 v17, v17, s18, v229 bitop3:0x6c
	s_nop 1
	v_add_f32_dpp v16, v16, v16 quad_perm:[1,0,3,2] row_mask:0xf bank_mask:0xf
	s_nop 1
	v_add_f32_dpp v16, v16, v16 quad_perm:[2,3,0,1] row_mask:0xf bank_mask:0xf
	s_nop 1
	v_add_f32_dpp v16, v16, v16 row_half_mirror row_mask:0xf bank_mask:0xf
	s_nop 1
	v_add_f32_dpp v16, v16, v16 row_mirror row_mask:0xf bank_mask:0xf
	s_nop 1
	v_add_f32_dpp v16, v16, v16 row_bcast:15 row_mask:0xa bank_mask:0xf
	s_nop 1
	v_add_f32_dpp v16, v16, v16 row_bcast:31 row_mask:0xc bank_mask:0xf
	s_nop 1
	v_readlane_b32 s98, v16, 63
	s_nop 1
	v_mov_b32_e32 v16, s98
	s_waitcnt lgkmcnt(0)
	v_mov_b32_e32 v17, v222
	s_nop 0
	v_lshlrev_b32_e32 v17, 2, v17
	v_bitop3_b32 v17, v17, 64, v229 bitop3:0x6c
	s_waitcnt lgkmcnt(0)
	v_mov_b32_e32 v17, v222
	s_nop 0
	v_lshlrev_b32_e32 v17, 2, v17
	v_bitop3_b32 v17, v17, 32, v229 bitop3:0x6c
	s_waitcnt lgkmcnt(0)
	v_mov_b32_e32 v17, v222
	s_nop 0
	v_lshlrev_b32_e32 v17, 2, v17
	v_bitop3_b32 v17, v17, 16, v229 bitop3:0x6c
	s_waitcnt lgkmcnt(0)
	v_mov_b32_e32 v17, v222
	s_nop 0
	v_lshlrev_b32_e32 v17, 2, v17
	v_bitop3_b32 v17, v17, 8, v229 bitop3:0x6c
	s_waitcnt lgkmcnt(0)
	v_mov_b32_e32 v17, v222
	s_nop 0
	v_lshlrev_b32_e32 v17, 2, v17
	v_bitop3_b32 v17, v17, 4, v229 bitop3:0x6c
	s_waitcnt lgkmcnt(0)
	v_mul_f32_e32 v16, 0x3b800000, v16
	v_pk_add_f32 v[12:13], v[12:13], v[16:17] op_sel_hi:[1,0] neg_lo:[0,1] neg_hi:[0,1]
	v_pk_add_f32 v[14:15], v[14:15], v[16:17] op_sel_hi:[1,0] neg_lo:[0,1] neg_hi:[0,1]
	v_pk_mul_f32 v[16:17], v[12:13], v[12:13]
	v_pk_mul_f32 v[18:19], v[14:15], v[14:15]
	v_add_f32_e32 v16, v16, v17
	v_mov_b32_e32 v17, v222
	v_add_f32_e32 v16, v18, v16
	v_lshlrev_b32_e32 v17, 2, v17
	v_add_f32_e32 v16, v19, v16
	v_bitop3_b32 v17, v17, s18, v229 bitop3:0x6c
	s_nop 1
	v_add_f32_dpp v16, v16, v16 quad_perm:[1,0,3,2] row_mask:0xf bank_mask:0xf
	s_nop 1
	v_add_f32_dpp v16, v16, v16 quad_perm:[2,3,0,1] row_mask:0xf bank_mask:0xf
	s_nop 1
	v_add_f32_dpp v16, v16, v16 row_half_mirror row_mask:0xf bank_mask:0xf
	s_nop 1
	v_add_f32_dpp v16, v16, v16 row_mirror row_mask:0xf bank_mask:0xf
	s_nop 1
	v_add_f32_dpp v16, v16, v16 row_bcast:15 row_mask:0xa bank_mask:0xf
	s_nop 1
	v_add_f32_dpp v16, v16, v16 row_bcast:31 row_mask:0xc bank_mask:0xf
	s_nop 1
	v_readlane_b32 s98, v16, 63
	s_nop 1
	v_mov_b32_e32 v16, s98
	s_waitcnt lgkmcnt(0)
	v_mov_b32_e32 v17, v222
	s_nop 0
	v_lshlrev_b32_e32 v17, 2, v17
	v_bitop3_b32 v17, v17, 64, v229 bitop3:0x6c
	s_waitcnt lgkmcnt(0)
	v_mov_b32_e32 v17, v222
	s_nop 0
	v_lshlrev_b32_e32 v17, 2, v17
	v_bitop3_b32 v17, v17, 32, v229 bitop3:0x6c
	s_waitcnt lgkmcnt(0)
	v_mov_b32_e32 v17, v222
	s_nop 0
	v_lshlrev_b32_e32 v17, 2, v17
	v_bitop3_b32 v17, v17, 16, v229 bitop3:0x6c
	s_waitcnt lgkmcnt(0)
	v_mov_b32_e32 v17, v222
	s_nop 0
	v_lshlrev_b32_e32 v17, 2, v17
	v_bitop3_b32 v17, v17, 8, v229 bitop3:0x6c
	s_waitcnt lgkmcnt(0)
	v_mov_b32_e32 v17, v222
	s_nop 0
	v_lshlrev_b32_e32 v17, 2, v17
	v_bitop3_b32 v17, v17, 4, v229 bitop3:0x6c
	s_waitcnt lgkmcnt(0)
	v_fmamk_f32 v16, v16, 0x3b800000, v227
	v_mul_f32_e32 v17, 0x4b800000, v16
	v_cmp_gt_f32_e32 vcc, s19, v16
	s_nop 1
	v_cndmask_b32_e32 v16, v16, v17, vcc
	v_rsq_f32_e32 v16, v16
	s_nop 0
	v_mul_f32_e32 v17, 0x45800000, v16
	v_cndmask_b32_e32 v16, v16, v17, vcc
	v_mul_f32_e32 v12, v12, v16
	v_fma_f32 v4, v8, v12, v4
	v_mul_f32_e32 v12, v13, v16
	v_mul_f32_e32 v8, 0xbfb8aa3b, v4
	v_fma_f32 v5, v9, v12, v5
	v_exp_f32_e32 v8, v8
	v_mul_f32_e32 v9, 0xbfb8aa3b, v5
	v_exp_f32_e32 v9, v9
	v_add_f32_e32 v8, 1.0, v8
	v_rcp_f32_e32 v8, v8
	v_add_f32_e32 v9, 1.0, v9
	v_rcp_f32_e32 v9, v9
	v_mul_f32_e32 v4, v4, v8
	s_waitcnt vmcnt(15)
	v_lshlrev_b32_e32 v8, 16, v0
	v_mul_f32_e32 v4, v4, v8
	v_mul_f32_e32 v5, v5, v9
	v_mul_f32_e32 v8, v14, v16
	v_mul_f32_e32 v9, v15, v16
	v_fma_f32 v6, v10, v8, v6
	v_fmac_f32_e32 v7, v11, v9
	v_mul_f32_e32 v8, 0xbfb8aa3b, v6
	v_mul_f32_e32 v9, 0xbfb8aa3b, v7
	v_exp_f32_e32 v8, v8
	v_exp_f32_e32 v9, v9
	v_and_b32_e32 v0, 0xffff0000, v0
	v_mul_f32_e32 v0, v5, v0
	v_add_f32_e32 v8, 1.0, v8
	v_add_f32_e32 v5, 1.0, v9
	v_rcp_f32_e32 v8, v8
	v_rcp_f32_e32 v5, v5
	v_cvt_pk_bf16_f32 v0, v4, v0
	v_mul_f32_e32 v6, v6, v8
	v_lshlrev_b32_e32 v8, 16, v1
	v_mul_f32_e32 v5, v7, v5
	v_and_b32_e32 v1, 0xffff0000, v1
	v_mul_f32_e32 v1, v5, v1
	v_lshl_add_u64 v[4:5], v[20:21], 0, s[22:23]
	v_lshlrev_b64 v[4:5], 11, v[4:5]
	v_lshl_add_u64 v[4:5], s[30:31], 0, v[4:5]
	v_lshl_add_u64 v[4:5], v[4:5], 0, v[2:3]
	v_mul_f32_e32 v6, v6, v8
	v_add_co_u32_e32 v4, vcc, 0x2d94000, v4
	v_cvt_pk_bf16_f32 v1, v6, v1
	s_nop 0
	v_addc_co_u32_e32 v5, vcc, 0, v5, vcc
	global_store_dwordx2 v[4:5], v[0:1], off offset:1024

.LBB0_758:
	s_or_b64 exec, exec, s[0:1]
	v_lshl_add_u32 v0, v64, 1, 32
	s_waitcnt vmcnt(0)
	v_lshlrev_b32_e32 v64, 16, v46
	v_and_b32_e32 v65, 0xffff0000, v46
	v_lshlrev_b32_e32 v46, 16, v47
	v_and_b32_e32 v47, 0xffff0000, v47
	v_lshlrev_b32_e32 v68, 16, v37
	v_and_b32_e32 v69, 0xffff0000, v37
	v_pk_fma_f32 v[46:47], v[22:23], v[46:47], v[6:7]
	v_lshlrev_b32_e32 v66, 16, v36
	v_and_b32_e32 v67, 0xffff0000, v36
	v_lshlrev_b32_e32 v70, 16, v60
	v_and_b32_e32 v71, 0xffff0000, v60
	v_lshlrev_b32_e32 v60, 16, v61
	v_and_b32_e32 v61, 0xffff0000, v61
	v_pk_fma_f32 v[36:37], v[20:21], v[64:65], v[4:5]
	v_pk_fma_f32 v[46:47], v[18:19], v[68:69], v[46:47]
	v_lshlrev_b32_e32 v72, 16, v52
	v_and_b32_e32 v73, 0xffff0000, v52
	v_pk_fma_f32 v[36:37], v[16:17], v[66:67], v[36:37]
	v_lshlrev_b32_e32 v52, 16, v53
	v_and_b32_e32 v53, 0xffff0000, v53
	v_pk_fma_f32 v[46:47], v[14:15], v[60:61], v[46:47]
	v_pk_fma_f32 v[66:67], v[20:21], v[66:67], v[4:5]
	v_pk_fma_f32 v[68:69], v[22:23], v[68:69], v[6:7]
	v_pk_fma_f32 v[46:47], v[10:11], v[52:53], v[46:47]
	v_pk_fma_f32 v[66:67], v[16:17], v[70:71], v[66:67]
	v_pk_fma_f32 v[68:69], v[18:19], v[60:61], v[68:69]
	v_pk_fma_f32 v[36:37], v[12:13], v[70:71], v[36:37]
	v_cvt_pk_bf16_f32 v65, v46, v47
	v_lshlrev_b32_e32 v46, 16, v58
	v_and_b32_e32 v47, 0xffff0000, v58
	v_pk_fma_f32 v[66:67], v[12:13], v[72:73], v[66:67]
	v_lshlrev_b32_e32 v58, 16, v59
	v_and_b32_e32 v59, 0xffff0000, v59
	v_pk_fma_f32 v[68:69], v[14:15], v[52:53], v[68:69]
	v_pk_fma_f32 v[36:37], v[8:9], v[72:73], v[36:37]
	s_movk_i32 s9, 0x220
	v_pk_fma_f32 v[66:67], v[8:9], v[46:47], v[66:67]
	v_pk_fma_f32 v[68:69], v[10:11], v[58:59], v[68:69]
	v_cvt_pk_bf16_f32 v64, v36, v37
	v_mad_u64_u32 v[36:37], s[0:1], v63, s9, v[0:1]
	v_cvt_pk_bf16_f32 v66, v66, v67
	v_cvt_pk_bf16_f32 v67, v68, v69
	ds_write2_b64 v36, v[64:65], v[66:67] offset1:68
	v_pk_fma_f32 v[66:67], v[20:21], v[70:71], v[4:5]
	v_pk_fma_f32 v[60:61], v[22:23], v[60:61], v[6:7]
	v_pk_fma_f32 v[66:67], v[16:17], v[72:73], v[66:67]
	v_pk_fma_f32 v[60:61], v[18:19], v[52:53], v[60:61]
	v_lshlrev_b32_e32 v64, 16, v42
	v_and_b32_e32 v65, 0xffff0000, v42
	v_pk_fma_f32 v[66:67], v[12:13], v[46:47], v[66:67]
	v_lshlrev_b32_e32 v42, 16, v43
	v_and_b32_e32 v43, 0xffff0000, v43
	v_pk_fma_f32 v[60:61], v[14:15], v[58:59], v[60:61]
	v_pk_fma_f32 v[68:69], v[20:21], v[72:73], v[4:5]
	v_pk_fma_f32 v[52:53], v[22:23], v[52:53], v[6:7]
	v_pk_fma_f32 v[66:67], v[8:9], v[64:65], v[66:67]
	v_pk_fma_f32 v[60:61], v[10:11], v[42:43], v[60:61]
	v_pk_fma_f32 v[68:69], v[16:17], v[46:47], v[68:69]
	v_pk_fma_f32 v[52:53], v[18:19], v[58:59], v[52:53]
	v_cvt_pk_bf16_f32 v66, v66, v67
	v_cvt_pk_bf16_f32 v67, v60, v61
	v_lshlrev_b32_e32 v60, 16, v56
	v_and_b32_e32 v61, 0xffff0000, v56
	v_pk_fma_f32 v[68:69], v[12:13], v[64:65], v[68:69]
	v_lshlrev_b32_e32 v56, 16, v57
	v_and_b32_e32 v57, 0xffff0000, v57
	v_pk_fma_f32 v[52:53], v[14:15], v[42:43], v[52:53]
	v_pk_fma_f32 v[46:47], v[20:21], v[46:47], v[4:5]
	v_pk_fma_f32 v[58:59], v[22:23], v[58:59], v[6:7]
	v_pk_fma_f32 v[68:69], v[8:9], v[60:61], v[68:69]
	v_pk_fma_f32 v[52:53], v[10:11], v[56:57], v[52:53]
	v_pk_fma_f32 v[46:47], v[16:17], v[64:65], v[46:47]
	v_pk_fma_f32 v[58:59], v[18:19], v[42:43], v[58:59]
	v_cvt_pk_bf16_f32 v68, v68, v69
	v_cvt_pk_bf16_f32 v69, v52, v53
	v_lshlrev_b32_e32 v52, 16, v38
	v_and_b32_e32 v53, 0xffff0000, v38
	v_pk_fma_f32 v[46:47], v[12:13], v[60:61], v[46:47]
	v_lshlrev_b32_e32 v38, 16, v39
	v_and_b32_e32 v39, 0xffff0000, v39
	v_pk_fma_f32 v[58:59], v[14:15], v[56:57], v[58:59]
	v_pk_fma_f32 v[64:65], v[20:21], v[64:65], v[4:5]
	v_pk_fma_f32 v[42:43], v[22:23], v[42:43], v[6:7]
	v_pk_fma_f32 v[46:47], v[8:9], v[52:53], v[46:47]
	v_pk_fma_f32 v[58:59], v[10:11], v[38:39], v[58:59]
	v_pk_fma_f32 v[64:65], v[16:17], v[60:61], v[64:65]
	v_pk_fma_f32 v[42:43], v[18:19], v[56:57], v[42:43]
	v_cvt_pk_bf16_f32 v46, v46, v47
	v_cvt_pk_bf16_f32 v47, v58, v59
	v_lshlrev_b32_e32 v58, 16, v54
	v_and_b32_e32 v59, 0xffff0000, v54
	v_pk_fma_f32 v[64:65], v[12:13], v[52:53], v[64:65]
	v_lshlrev_b32_e32 v54, 16, v55
	v_and_b32_e32 v55, 0xffff0000, v55
	v_pk_fma_f32 v[42:43], v[14:15], v[38:39], v[42:43]
	v_pk_fma_f32 v[64:65], v[8:9], v[58:59], v[64:65]
	v_pk_fma_f32 v[42:43], v[10:11], v[54:55], v[42:43]
	v_cvt_pk_bf16_f32 v64, v64, v65
	v_cvt_pk_bf16_f32 v65, v42, v43
	v_add_u32_e32 v1, 0x800, v36
	ds_write2_b64 v1, v[46:47], v[64:65] offset0:16 offset1:84
	v_pk_fma_f32 v[46:47], v[20:21], v[60:61], v[4:5]
	v_pk_fma_f32 v[56:57], v[22:23], v[56:57], v[6:7]
	v_pk_fma_f32 v[46:47], v[16:17], v[52:53], v[46:47]
	v_pk_fma_f32 v[56:57], v[18:19], v[38:39], v[56:57]
	v_lshlrev_b32_e32 v42, 16, v34
	v_and_b32_e32 v43, 0xffff0000, v34
	v_pk_fma_f32 v[46:47], v[12:13], v[58:59], v[46:47]
	v_lshlrev_b32_e32 v34, 16, v35
	v_and_b32_e32 v35, 0xffff0000, v35
	v_pk_fma_f32 v[56:57], v[14:15], v[54:55], v[56:57]
	v_pk_fma_f32 v[52:53], v[20:21], v[52:53], v[4:5]
	v_pk_fma_f32 v[38:39], v[22:23], v[38:39], v[6:7]
	v_pk_fma_f32 v[46:47], v[8:9], v[42:43], v[46:47]
	v_pk_fma_f32 v[56:57], v[10:11], v[34:35], v[56:57]
	v_pk_fma_f32 v[52:53], v[16:17], v[58:59], v[52:53]
	v_pk_fma_f32 v[38:39], v[18:19], v[54:55], v[38:39]
	v_cvt_pk_bf16_f32 v46, v46, v47
	v_cvt_pk_bf16_f32 v47, v56, v57
	v_lshlrev_b32_e32 v56, 16, v50
	v_and_b32_e32 v57, 0xffff0000, v50
	v_pk_fma_f32 v[52:53], v[12:13], v[42:43], v[52:53]
	v_lshlrev_b32_e32 v50, 16, v51
	v_and_b32_e32 v51, 0xffff0000, v51
	v_pk_fma_f32 v[38:39], v[14:15], v[34:35], v[38:39]
	v_pk_fma_f32 v[52:53], v[8:9], v[56:57], v[52:53]
	v_pk_fma_f32 v[38:39], v[10:11], v[50:51], v[38:39]
	v_cvt_pk_bf16_f32 v52, v52, v53
	v_cvt_pk_bf16_f32 v53, v38, v39
	ds_write2_b64 v1, v[46:47], v[52:53] offset0:152 offset1:220
	v_pk_fma_f32 v[46:47], v[20:21], v[58:59], v[4:5]
	v_pk_fma_f32 v[52:53], v[22:23], v[54:55], v[6:7]
	v_pk_fma_f32 v[46:47], v[16:17], v[42:43], v[46:47]
	v_pk_fma_f32 v[52:53], v[18:19], v[34:35], v[52:53]
	v_lshlrev_b32_e32 v38, 16, v32
	v_and_b32_e32 v39, 0xffff0000, v32
	v_pk_fma_f32 v[46:47], v[12:13], v[56:57], v[46:47]
	v_lshlrev_b32_e32 v32, 16, v33
	v_and_b32_e32 v33, 0xffff0000, v33
	v_pk_fma_f32 v[52:53], v[14:15], v[50:51], v[52:53]
	v_pk_fma_f32 v[42:43], v[20:21], v[42:43], v[4:5]
	v_pk_fma_f32 v[34:35], v[22:23], v[34:35], v[6:7]
	v_pk_fma_f32 v[46:47], v[8:9], v[38:39], v[46:47]
	v_pk_fma_f32 v[52:53], v[10:11], v[32:33], v[52:53]
	v_pk_fma_f32 v[42:43], v[16:17], v[56:57], v[42:43]
	v_pk_fma_f32 v[34:35], v[18:19], v[50:51], v[34:35]
	v_cvt_pk_bf16_f32 v46, v46, v47
	v_cvt_pk_bf16_f32 v47, v52, v53
	v_lshlrev_b32_e32 v52, 16, v48
	v_and_b32_e32 v53, 0xffff0000, v48
	v_pk_fma_f32 v[42:43], v[12:13], v[38:39], v[42:43]
	v_lshlrev_b32_e32 v48, 16, v49
	v_and_b32_e32 v49, 0xffff0000, v49
	v_pk_fma_f32 v[34:35], v[14:15], v[32:33], v[34:35]
	v_pk_fma_f32 v[42:43], v[8:9], v[52:53], v[42:43]
	v_pk_fma_f32 v[34:35], v[10:11], v[48:49], v[34:35]
	v_cvt_pk_bf16_f32 v42, v42, v43
	v_cvt_pk_bf16_f32 v43, v34, v35
	v_add_u32_e32 v1, 0x1000, v36
	ds_write2_b64 v1, v[46:47], v[42:43] offset0:32 offset1:100
	v_pk_fma_f32 v[42:43], v[20:21], v[56:57], v[4:5]
	v_pk_fma_f32 v[46:47], v[22:23], v[50:51], v[6:7]
	v_pk_fma_f32 v[42:43], v[16:17], v[38:39], v[42:43]
	v_pk_fma_f32 v[46:47], v[18:19], v[32:33], v[46:47]
	v_lshlrev_b32_e32 v34, 16, v30
	v_and_b32_e32 v35, 0xffff0000, v30
	v_pk_fma_f32 v[42:43], v[12:13], v[52:53], v[42:43]
	v_lshlrev_b32_e32 v30, 16, v31
	v_and_b32_e32 v31, 0xffff0000, v31
	v_pk_fma_f32 v[46:47], v[14:15], v[48:49], v[46:47]
	v_pk_fma_f32 v[38:39], v[20:21], v[38:39], v[4:5]
	v_pk_fma_f32 v[32:33], v[22:23], v[32:33], v[6:7]
	v_pk_fma_f32 v[42:43], v[8:9], v[34:35], v[42:43]
	v_pk_fma_f32 v[46:47], v[10:11], v[30:31], v[46:47]
	v_pk_fma_f32 v[38:39], v[16:17], v[52:53], v[38:39]
	v_pk_fma_f32 v[32:33], v[18:19], v[48:49], v[32:33]
	v_cvt_pk_bf16_f32 v42, v42, v43
	v_cvt_pk_bf16_f32 v43, v46, v47
	v_lshlrev_b32_e32 v46, 16, v44
	v_and_b32_e32 v47, 0xffff0000, v44
	v_pk_fma_f32 v[38:39], v[12:13], v[34:35], v[38:39]
	v_lshlrev_b32_e32 v44, 16, v45
	v_and_b32_e32 v45, 0xffff0000, v45
	v_pk_fma_f32 v[32:33], v[14:15], v[30:31], v[32:33]
	v_pk_fma_f32 v[38:39], v[8:9], v[46:47], v[38:39]
	v_pk_fma_f32 v[32:33], v[10:11], v[44:45], v[32:33]
	v_cvt_pk_bf16_f32 v38, v38, v39
	v_cvt_pk_bf16_f32 v39, v32, v33
	ds_write2_b64 v1, v[42:43], v[38:39] offset0:168 offset1:236
	v_pk_fma_f32 v[38:39], v[20:21], v[52:53], v[4:5]
	v_pk_fma_f32 v[42:43], v[22:23], v[48:49], v[6:7]
	v_pk_fma_f32 v[38:39], v[16:17], v[34:35], v[38:39]
	v_pk_fma_f32 v[42:43], v[18:19], v[30:31], v[42:43]
	v_lshlrev_b32_e32 v32, 16, v28
	v_and_b32_e32 v33, 0xffff0000, v28
	v_pk_fma_f32 v[38:39], v[12:13], v[46:47], v[38:39]
	v_lshlrev_b32_e32 v28, 16, v29
	v_and_b32_e32 v29, 0xffff0000, v29
	v_pk_fma_f32 v[42:43], v[14:15], v[44:45], v[42:43]
	v_pk_fma_f32 v[34:35], v[20:21], v[34:35], v[4:5]
	v_pk_fma_f32 v[30:31], v[22:23], v[30:31], v[6:7]
	v_pk_fma_f32 v[38:39], v[8:9], v[32:33], v[38:39]
	v_pk_fma_f32 v[42:43], v[10:11], v[28:29], v[42:43]
	v_pk_fma_f32 v[34:35], v[16:17], v[46:47], v[34:35]
	v_pk_fma_f32 v[30:31], v[18:19], v[44:45], v[30:31]
	v_cvt_pk_bf16_f32 v38, v38, v39
	v_cvt_pk_bf16_f32 v39, v42, v43
	v_lshlrev_b32_e32 v42, 16, v40
	v_and_b32_e32 v43, 0xffff0000, v40
	v_pk_fma_f32 v[34:35], v[12:13], v[32:33], v[34:35]
	v_lshlrev_b32_e32 v40, 16, v41
	v_and_b32_e32 v41, 0xffff0000, v41
	v_pk_fma_f32 v[30:31], v[14:15], v[28:29], v[30:31]
	v_pk_fma_f32 v[34:35], v[8:9], v[42:43], v[34:35]
	v_pk_fma_f32 v[30:31], v[10:11], v[40:41], v[30:31]
	v_cvt_pk_bf16_f32 v34, v34, v35
	v_cvt_pk_bf16_f32 v35, v30, v31
	v_add_u32_e32 v1, 0x1800, v36
	ds_write2_b64 v1, v[38:39], v[34:35] offset0:48 offset1:116
	v_pk_fma_f32 v[34:35], v[20:21], v[46:47], v[4:5]
	v_pk_fma_f32 v[38:39], v[22:23], v[44:45], v[6:7]
	v_pk_fma_f32 v[34:35], v[16:17], v[32:33], v[34:35]
	v_pk_fma_f32 v[38:39], v[18:19], v[28:29], v[38:39]
	v_lshlrev_b32_e32 v30, 16, v26
	v_and_b32_e32 v31, 0xffff0000, v26
	v_pk_fma_f32 v[34:35], v[12:13], v[42:43], v[34:35]
	v_lshlrev_b32_e32 v26, 16, v27
	v_and_b32_e32 v27, 0xffff0000, v27
	v_pk_fma_f32 v[38:39], v[14:15], v[40:41], v[38:39]
	v_pk_fma_f32 v[34:35], v[8:9], v[30:31], v[34:35]
	v_pk_fma_f32 v[38:39], v[10:11], v[26:27], v[38:39]
	v_cvt_pk_bf16_f32 v34, v34, v35
	v_cvt_pk_bf16_f32 v35, v38, v39
	ds_write2_b64 v36, v[66:67], v[68:69] offset0:136 offset1:204
	ds_write_b64 v36, v[34:35] offset:7616
	v_mov_b32_e32 v34, v20
	v_mov_b32_e32 v35, v16
	v_mov_b32_e32 v36, v32
	v_mov_b32_e32 v37, v42
	v_mov_b32_e32 v16, v21
	v_mov_b32_e32 v42, v33
	v_mov_b32_e32 v20, v22
	v_mov_b32_e32 v21, v18
	v_mov_b32_e32 v32, v28
	v_mov_b32_e32 v33, v40
	v_mov_b32_e32 v18, v23
	v_mov_b32_e32 v40, v29
	v_lshlrev_b32_e32 v23, 16, v24
	v_mov_b32_e32 v28, v12
	v_mov_b32_e32 v29, v8
	v_mov_b32_e32 v22, v30
	v_pk_mul_f32 v[34:35], v[34:35], v[36:37]
	v_pk_mul_f32 v[16:17], v[16:17], v[42:43]
	v_pk_mul_f32 v[22:23], v[28:29], v[22:23]
	v_and_b32_e32 v29, 0xffff0000, v24
	v_mov_b32_e32 v8, v13
	v_mov_b32_e32 v28, v31
	v_pk_mul_f32 v[8:9], v[8:9], v[28:29]
	v_mov_b32_e32 v28, v14
	v_mov_b32_e32 v29, v10
	v_mov_b32_e32 v10, v15
	v_mov_b32_e32 v14, v34
	v_mov_b32_e32 v15, v16
	v_pk_add_f32 v[4:5], v[4:5], v[14:15]
	v_mov_b32_e32 v16, v35
	v_pk_add_f32 v[4:5], v[4:5], v[16:17]
	v_mov_b32_e32 v14, v22
	v_mov_b32_e32 v15, v8
	v_pk_mul_f32 v[20:21], v[20:21], v[32:33]
	v_pk_mul_f32 v[18:19], v[18:19], v[40:41]
	v_pk_add_f32 v[4:5], v[4:5], v[14:15]
	v_mov_b32_e32 v8, v23
	v_lshlrev_b32_e32 v13, 16, v25
	v_mov_b32_e32 v12, v26
	v_and_b32_e32 v25, 0xffff0000, v25
	v_mov_b32_e32 v24, v27
	v_pk_add_f32 v[4:5], v[4:5], v[8:9]
	v_mov_b32_e32 v8, v20
	v_mov_b32_e32 v9, v18
	v_pk_mul_f32 v[12:13], v[28:29], v[12:13]
	v_pk_mul_f32 v[10:11], v[10:11], v[24:25]
	v_pk_add_f32 v[6:7], v[6:7], v[8:9]
	v_mov_b32_e32 v18, v21
	v_pk_add_f32 v[6:7], v[6:7], v[18:19]
	v_mov_b32_e32 v8, v12
	v_mov_b32_e32 v9, v10
	v_pk_add_f32 v[6:7], v[6:7], v[8:9]
	v_mov_b32_e32 v10, v13
	v_pk_add_f32 v[6:7], v[6:7], v[10:11]
	v_or_b32_e32 v1, 15, v62
	v_cvt_pk_bf16_f32 v4, v4, v5
	v_cvt_pk_bf16_f32 v5, v6, v7
	v_mad_u64_u32 v[0:1], s[0:1], v1, s9, v[0:1]
	ds_write_b64 v0, v[4:5]
	v_mov_b32_e32 v0, v222
	s_waitcnt lgkmcnt(0)
	s_barrier
	v_readlane_b32 s0, v252, 46
	v_ashrrev_i32_e32 v1, 6, v0
	v_bfe_u32 v81, v0, 4, 2
	v_add_u32_e32 v4, s0, v1
	v_readlane_b32 s0, v252, 47
	v_ashrrev_i32_e32 v5, 31, v4
	v_lshlrev_b64 v[4:5], 13, v[4:5]
	v_add_u32_e32 v6, s0, v1
	v_ashrrev_i32_e32 v7, 31, v6
	v_and_b32_e32 v72, 0xffffffc0, v0
	v_and_b32_e32 v80, 15, v0
	v_lshl_add_u64 v[4:5], s[84:85], 0, v[4:5]
	v_lshlrev_b64 v[6:7], 13, v[6:7]
	v_lshlrev_b32_e32 v2, 4, v81
	v_ashrrev_i32_e32 v73, 31, v72
	v_readlane_b32 s0, v252, 48
	v_lshl_add_u64 v[6:7], s[84:85], 0, v[6:7]
	v_lshl_add_u64 v[4:5], v[4:5], 0, v[2:3]
	v_lshlrev_b32_e32 v8, 7, v80
	v_mov_b32_e32 v9, v3
	v_lshlrev_b64 v[74:75], 2, v[72:73]
	v_readlane_b32 s1, v252, 49
	v_lshl_add_u64 v[6:7], v[6:7], 0, v[2:3]
	v_lshl_add_u64 v[10:11], v[4:5], 0, v[8:9]
	v_lshl_add_u64 v[76:77], s[0:1], 0, v[74:75]
	v_readlane_b32 s0, v252, 50
	v_lshl_add_u64 v[12:13], v[6:7], 0, v[8:9]
	global_load_dwordx4 v[56:59], v[10:11], off
	global_load_dwordx4 v[52:55], v[12:13], off
	global_load_dwordx4 v[64:67], v[10:11], off offset:64
	global_load_dwordx4 v[60:63], v[12:13], off offset:64
	global_load_dwordx4 v[40:43], v[10:11], off offset:2048
	global_load_dwordx4 v[36:39], v[12:13], off offset:2048
	global_load_dwordx4 v[48:51], v[10:11], off offset:2112
	global_load_dwordx4 v[44:47], v[12:13], off offset:2112
	v_or_b32_e32 v10, 0x1000, v8
	v_mov_b32_e32 v11, v3
	v_readlane_b32 s1, v252, 51
	v_lshl_add_u64 v[12:13], v[4:5], 0, v[10:11]
	v_or_b32_e32 v8, 0x1800, v8
	v_lshl_add_u64 v[68:69], s[0:1], 0, v[74:75]
	v_lshl_add_u64 v[10:11], v[6:7], 0, v[10:11]
	global_load_dwordx4 v[24:27], v[12:13], off
	global_load_dwordx4 v[20:23], v[10:11], off
	global_load_dwordx4 v[32:35], v[12:13], off offset:64
	global_load_dwordx4 v[28:31], v[10:11], off offset:64
	v_lshl_add_u64 v[12:13], v[4:5], 0, v[8:9]
	v_lshl_add_u64 v[14:15], v[6:7], 0, v[8:9]
	v_lshl_add_u64 v[78:79], v[68:69], 0, v[2:3]
	global_load_dwordx4 v[8:11], v[12:13], off
	global_load_dwordx4 v[4:7], v[14:15], off
	global_load_dwordx4 v[16:19], v[12:13], off offset:64
	s_nop 0
	global_load_dwordx4 v[12:15], v[14:15], off offset:64
	v_readlane_b32 s0, v252, 52
	v_readlane_b32 s1, v252, 53
	s_movk_i32 s10, 0x88
	v_lshl_add_u64 v[152:153], v[76:77], 0, v[2:3]
	v_lshlrev_b32_e32 v82, 3, v81
	v_readlane_b32 s7, v252, 11
	v_readlane_b32 s8, v252, 12
	s_waitcnt vmcnt(0)
	s_lshl_b32 s98, s16, 11
	s_add_u32 s98, s98, 0x8000
	s_add_u32 s98, s30, s98
	s_addc_u32 s99, s31, 0
	v_lshrrev_b32_e32 v172, 4, v222
	v_and_b32_e32 v171, 3, v172
	v_lshrrev_b32_e32 v172, 2, v172
	v_lshlrev_b32_e32 v171, 4, v171
	v_lshl_or_b32 v172, v172, 8, v171
	global_load_dword v1, v172, s[98:99]
	global_load_dword v158, v172, s[98:99] offset:4
	global_load_dword v159, v172, s[98:99] offset:8
	global_load_dword v160, v172, s[98:99] offset:12
	global_load_dword v161, v172, s[98:99] offset:64
	global_load_dword v162, v172, s[98:99] offset:68
	global_load_dword v164, v172, s[98:99] offset:72
	global_load_dword v166, v172, s[98:99] offset:76
	global_load_dword v163, v172, s[98:99] offset:128
	global_load_dword v165, v172, s[98:99] offset:132
	global_load_dword v167, v172, s[98:99] offset:136
	global_load_dword v168, v172, s[98:99] offset:140
	global_load_dword v169, v172, s[98:99] offset:192
	global_load_dword v170, v172, s[98:99] offset:196
	global_load_dword v171, v172, s[98:99] offset:200
	global_load_dword v172, v172, s[98:99] offset:204
	v_lshl_or_b32 v96, v81, 2, v72
	v_lshlrev_b32_e32 v97, 3, v80
	v_lshl_add_u64 v[68:69], s[0:1], 0, v[74:75]
	v_lshl_add_u64 v[154:155], v[68:69], 0, v[2:3]
	v_mul_lo_u32 v69, v0, s10
	v_lshl_add_u32 v68, v72, 1, 32
	v_add_u32_e32 v112, 32, v69
	v_mul_u32_u24_e32 v69, 0x220, v80
	v_add3_u32 v180, v68, v69, v2
	ds_read_b128 v[68:71], v180
	ds_read_b128 v[72:75], v180 offset:64
	global_load_dwordx4 v[84:87], v[154:155], off
	global_load_dwordx4 v[88:91], v[152:153], off
	s_waitcnt lgkmcnt(1)
	v_mfma_f32_16x16x32_bf16 v[76:79], v[56:59], v[68:71], 0
	v_sub_u32_e32 v2, v180, v82
	ds_read_b64 v[92:93], v2
	v_add_u32_e32 v173, 0x8800, v112
	s_waitcnt lgkmcnt(1)
	v_mfma_f32_16x16x32_bf16 v[80:83], v[64:67], v[72:75], v[76:79]
	v_add_u32_e32 v185, 0x8810, v112
	v_add_u32_e32 v184, 0x8820, v112
	s_waitcnt lgkmcnt(0)
	v_lshlrev_b32_e32 v95, 16, v92
	v_mfma_f32_16x16x32_bf16 v[76:79], v[52:55], v[68:71], 0
	v_and_b32_e32 v98, 0xffff0000, v92
	v_lshlrev_b32_e32 v99, 16, v93
	v_and_b32_e32 v93, 0xffff0000, v93
	v_mfma_f32_16x16x32_bf16 v[76:79], v[60:63], v[72:75], v[76:79]
	v_add_u32_e32 v175, 0x8860, v112
	v_add_u32_e32 v179, 0x8830, v112
	v_add_u32_e32 v176, 0x8840, v112
	v_add_u32_e32 v178, 0x8850, v112
	v_add_u32_e32 v177, 0x8870, v112
	s_mul_i32 s0, s4, 0x88
	s_add_i32 s0, s0, s5
	s_lshl_b32 s0, s0, 11
	s_add_u32 s4, s7, s0
	s_addc_u32 s5, s8, 0
	v_readlane_b32 s1, v252, 54
	s_add_i32 s0, s0, 0x22000
	s_add_u32 s0, s7, s0
	s_waitcnt vmcnt(1)
	v_add_f32_e32 v80, v80, v84
	v_mul_f32_e32 v80, 0xbfb8aa3b, v80
	v_exp_f32_e32 v80, v80
	s_waitcnt vmcnt(0)
	v_add_f32_e32 v76, v76, v88
	v_mul_f32_e32 v76, 0xbfb8aa3b, v76
	v_exp_f32_e32 v76, v76
	v_add_f32_e32 v80, 1.0, v80
	v_rcp_f32_e32 v80, v80
	v_add_f32_e32 v77, v77, v89
	v_add_f32_e32 v76, 1.0, v76
	v_rcp_f32_e32 v76, v76
	v_mul_f32_e32 v80, 0xc1000000, v80
	s_waitcnt vmcnt(0)
	v_mul_f32_e32 v80, v80, v1
	v_mul_f32_e32 v80, 0x3fb8aa3b, v80
	v_exp_f32_e32 v94, v80
	v_mul_f32_e32 v77, 0xbfb8aa3b, v77
	v_exp_f32_e32 v77, v77
	v_add_f32_e32 v79, v79, v91
	v_sub_f32_e32 v80, 1.0, v94
	v_add_f32_e32 v84, 1.0, v94
	v_mul_f32_e32 v80, v80, v84
	v_max_f32_e32 v80, 0, v80
	v_sqrt_f32_e32 v80, v80
	v_add_f32_e32 v77, 1.0, v77
	v_rcp_f32_e32 v77, v77
	v_mul_f32_e32 v79, 0xbfb8aa3b, v79
	v_mul_f32_e32 v76, v76, v80
	v_mul_f32_e32 v95, v76, v95
	v_mul_lo_u32 v76, v96, s10
	v_add3_u32 v92, 32, v97, v76
	v_add_f32_e32 v76, v81, v85
	v_mul_f32_e32 v76, 0xbfb8aa3b, v76
	v_exp_f32_e32 v76, v76
	v_add_u32_e32 v181, 0x8800, v92
	v_exp_f32_e32 v79, v79
	v_add_u32_e32 v182, 0x9000, v92
	v_add_f32_e32 v76, 1.0, v76
	v_rcp_f32_e32 v76, v76
	v_add_f32_e32 v79, 1.0, v79
	v_rcp_f32_e32 v79, v79
	v_add_u32_e32 v183, 0x9800, v92
	v_mul_f32_e32 v76, 0xc1000000, v76
	v_mul_f32_e32 v76, v76, v158
	v_mul_f32_e32 v76, 0x3fb8aa3b, v76
	v_exp_f32_e32 v76, v76
	v_add_u32_e32 v174, 0xa000, v92
	v_sub_f32_e32 v80, 1.0, v76
	v_add_f32_e32 v81, 1.0, v76
	v_mul_f32_e32 v80, v80, v81
	v_max_f32_e32 v80, 0, v80
	v_sqrt_f32_e32 v80, v80
	s_nop 0
	v_mul_f32_e32 v77, v77, v80
	v_mul_f32_e32 v77, v77, v98
	ds_write2_b64 v181, v[94:95], v[76:77] offset1:17
	v_add_f32_e32 v76, v82, v86
	v_mul_f32_e32 v76, 0xbfb8aa3b, v76
	v_exp_f32_e32 v76, v76
	v_add_f32_e32 v77, v78, v90
	v_mul_f32_e32 v77, 0xbfb8aa3b, v77
	v_exp_f32_e32 v77, v77
	v_add_f32_e32 v76, 1.0, v76
	v_rcp_f32_e32 v76, v76
	v_add_f32_e32 v77, 1.0, v77
	v_rcp_f32_e32 v77, v77
	v_mul_f32_e32 v76, 0xc1000000, v76
	v_mul_f32_e32 v76, v76, v159
	v_mul_f32_e32 v76, 0x3fb8aa3b, v76
	v_exp_f32_e32 v76, v76
	s_nop 0
	v_sub_f32_e32 v78, 1.0, v76
	v_add_f32_e32 v80, 1.0, v76
	v_mul_f32_e32 v78, v78, v80
	v_max_f32_e32 v78, 0, v78
	v_sqrt_f32_e32 v78, v78
	s_nop 0
	v_mul_f32_e32 v77, v77, v78
	v_add_f32_e32 v78, v83, v87
	v_mul_f32_e32 v78, 0xbfb8aa3b, v78
	v_exp_f32_e32 v78, v78
	v_mul_f32_e32 v77, v77, v99
	v_add_f32_e32 v78, 1.0, v78
	v_rcp_f32_e32 v78, v78
	s_nop 0
	v_mul_f32_e32 v78, 0xc1000000, v78
	v_mul_f32_e32 v78, v78, v160
	v_mul_f32_e32 v78, 0x3fb8aa3b, v78
	v_exp_f32_e32 v78, v78
	s_nop 0
	v_sub_f32_e32 v80, 1.0, v78
	v_add_f32_e32 v81, 1.0, v78
	v_mul_f32_e32 v80, v80, v81
	v_max_f32_e32 v80, 0, v80
	v_sqrt_f32_e32 v80, v80
	s_nop 0
	v_mul_f32_e32 v79, v79, v80
	v_mul_f32_e32 v79, v79, v93
	ds_write2_b64 v181, v[76:77], v[78:79] offset0:34 offset1:51
	global_load_dwordx4 v[84:87], v[154:155], off offset:64
	global_load_dwordx4 v[88:91], v[152:153], off offset:64
	v_mfma_f32_16x16x32_bf16 v[76:79], v[40:43], v[68:71], 0
	ds_read_b64 v[94:95], v2 offset:32
	s_waitcnt lgkmcnt(0)
	v_lshlrev_b32_e32 v93, 16, v94
	v_mfma_f32_16x16x32_bf16 v[80:83], v[48:51], v[72:75], v[76:79]
	v_and_b32_e32 v96, 0xffff0000, v94
	v_lshlrev_b32_e32 v97, 16, v95
	v_and_b32_e32 v98, 0xffff0000, v95
	v_mfma_f32_16x16x32_bf16 v[76:79], v[36:39], v[68:71], 0
	v_mfma_f32_16x16x32_bf16 v[76:79], v[44:47], v[72:75], v[76:79]
	s_waitcnt vmcnt(1)
	s_nop 1
	v_add_f32_e32 v80, v80, v84
	v_mul_f32_e32 v80, 0xbfb8aa3b, v80
	v_exp_f32_e32 v80, v80
	s_waitcnt vmcnt(0)
	s_nop 0
	v_add_f32_e32 v76, v76, v88
	v_mul_f32_e32 v76, 0xbfb8aa3b, v76
	v_exp_f32_e32 v76, v76
	v_add_f32_e32 v80, 1.0, v80
	v_rcp_f32_e32 v80, v80
	v_add_f32_e32 v77, v77, v89
	v_add_f32_e32 v76, 1.0, v76
	v_rcp_f32_e32 v76, v76
	v_mul_f32_e32 v80, 0xc1000000, v80
	v_mul_f32_e32 v80, v80, v161
	v_mul_f32_e32 v80, 0x3fb8aa3b, v80
	v_exp_f32_e32 v94, v80
	v_mul_f32_e32 v77, 0xbfb8aa3b, v77
	v_exp_f32_e32 v77, v77
	v_add_f32_e32 v79, v79, v91
	v_sub_f32_e32 v80, 1.0, v94
	v_add_f32_e32 v84, 1.0, v94
	v_mul_f32_e32 v80, v80, v84
	v_max_f32_e32 v80, 0, v80
	v_sqrt_f32_e32 v80, v80
	v_add_f32_e32 v77, 1.0, v77
	v_rcp_f32_e32 v77, v77
	v_mul_f32_e32 v79, 0xbfb8aa3b, v79
	v_mul_f32_e32 v76, v76, v80
	v_mul_f32_e32 v95, v76, v93
	v_add_f32_e32 v76, v81, v85
	v_mul_f32_e32 v76, 0xbfb8aa3b, v76
	v_exp_f32_e32 v76, v76
	v_exp_f32_e32 v79, v79
	v_add_f32_e32 v76, 1.0, v76
	v_rcp_f32_e32 v76, v76
	v_add_f32_e32 v79, 1.0, v79
	v_rcp_f32_e32 v79, v79
	v_mul_f32_e32 v76, 0xc1000000, v76
	v_mul_f32_e32 v76, v76, v162
	v_mul_f32_e32 v76, 0x3fb8aa3b, v76
	v_exp_f32_e32 v76, v76
	s_nop 0
	v_sub_f32_e32 v80, 1.0, v76
	v_add_f32_e32 v81, 1.0, v76
	v_mul_f32_e32 v80, v80, v81
	v_max_f32_e32 v80, 0, v80
	v_sqrt_f32_e32 v80, v80
	s_nop 0
	v_mul_f32_e32 v77, v77, v80
	v_mul_f32_e32 v77, v77, v96
	ds_write2_b64 v182, v[94:95], v[76:77] offset0:16 offset1:33
	v_add_f32_e32 v76, v82, v86
	v_mul_f32_e32 v76, 0xbfb8aa3b, v76
	v_exp_f32_e32 v76, v76
	v_add_f32_e32 v77, v78, v90
	v_mul_f32_e32 v77, 0xbfb8aa3b, v77
	v_exp_f32_e32 v77, v77
	v_add_f32_e32 v76, 1.0, v76
	v_rcp_f32_e32 v76, v76
	v_add_f32_e32 v77, 1.0, v77
	v_rcp_f32_e32 v77, v77
	v_mul_f32_e32 v76, 0xc1000000, v76
	v_mul_f32_e32 v76, v76, v164
	v_mul_f32_e32 v76, 0x3fb8aa3b, v76
	v_exp_f32_e32 v76, v76
	s_nop 0
	v_sub_f32_e32 v78, 1.0, v76
	v_add_f32_e32 v80, 1.0, v76
	v_mul_f32_e32 v78, v78, v80
	v_max_f32_e32 v78, 0, v78
	v_sqrt_f32_e32 v78, v78
	s_nop 0
	v_mul_f32_e32 v77, v77, v78
	v_add_f32_e32 v78, v83, v87
	v_mul_f32_e32 v78, 0xbfb8aa3b, v78
	v_exp_f32_e32 v78, v78
	v_mul_f32_e32 v77, v77, v97
	v_add_f32_e32 v78, 1.0, v78
	v_rcp_f32_e32 v78, v78
	s_nop 0
	v_mul_f32_e32 v78, 0xc1000000, v78
	v_mul_f32_e32 v78, v78, v166
	v_mul_f32_e32 v78, 0x3fb8aa3b, v78
	v_exp_f32_e32 v78, v78
	s_nop 0
	v_sub_f32_e32 v80, 1.0, v78
	v_add_f32_e32 v81, 1.0, v78
	v_mul_f32_e32 v80, v80, v81
	v_max_f32_e32 v80, 0, v80
	v_sqrt_f32_e32 v80, v80
	s_nop 0
	v_mul_f32_e32 v79, v79, v80
	v_mul_f32_e32 v79, v79, v98
	ds_write2_b64 v182, v[76:77], v[78:79] offset0:50 offset1:67
	global_load_dwordx4 v[84:87], v[154:155], off offset:128
	global_load_dwordx4 v[88:91], v[152:153], off offset:128
	v_mfma_f32_16x16x32_bf16 v[76:79], v[24:27], v[68:71], 0
	ds_read_b64 v[94:95], v2 offset:64
	s_waitcnt lgkmcnt(0)
	v_lshlrev_b32_e32 v93, 16, v94
	v_mfma_f32_16x16x32_bf16 v[80:83], v[32:35], v[72:75], v[76:79]
	v_and_b32_e32 v96, 0xffff0000, v94
	v_lshlrev_b32_e32 v97, 16, v95
	v_and_b32_e32 v98, 0xffff0000, v95
	v_mfma_f32_16x16x32_bf16 v[76:79], v[20:23], v[68:71], 0
	v_mfma_f32_16x16x32_bf16 v[76:79], v[28:31], v[72:75], v[76:79]
	s_waitcnt vmcnt(1)
	s_nop 1
	v_add_f32_e32 v80, v80, v84
	v_mul_f32_e32 v80, 0xbfb8aa3b, v80
	v_exp_f32_e32 v80, v80
	s_waitcnt vmcnt(0)
	s_nop 0
	v_add_f32_e32 v76, v76, v88
	v_mul_f32_e32 v76, 0xbfb8aa3b, v76
	v_exp_f32_e32 v76, v76
	v_add_f32_e32 v80, 1.0, v80
	v_rcp_f32_e32 v80, v80
	v_add_f32_e32 v77, v77, v89
	v_add_f32_e32 v76, 1.0, v76
	v_rcp_f32_e32 v76, v76
	v_mul_f32_e32 v80, 0xc1000000, v80
	v_mul_f32_e32 v80, v80, v163
	v_mul_f32_e32 v80, 0x3fb8aa3b, v80
	v_exp_f32_e32 v94, v80
	v_mul_f32_e32 v77, 0xbfb8aa3b, v77
	v_exp_f32_e32 v77, v77
	v_add_f32_e32 v79, v79, v91
	v_sub_f32_e32 v80, 1.0, v94
	v_add_f32_e32 v84, 1.0, v94
	v_mul_f32_e32 v80, v80, v84
	v_max_f32_e32 v80, 0, v80
	v_sqrt_f32_e32 v80, v80
	v_add_f32_e32 v77, 1.0, v77
	v_rcp_f32_e32 v77, v77
	v_mul_f32_e32 v79, 0xbfb8aa3b, v79
	v_mul_f32_e32 v76, v76, v80
	v_mul_f32_e32 v95, v76, v93
	v_add_f32_e32 v76, v81, v85
	v_mul_f32_e32 v76, 0xbfb8aa3b, v76
	v_exp_f32_e32 v76, v76
	v_exp_f32_e32 v79, v79
	v_add_f32_e32 v76, 1.0, v76
	v_rcp_f32_e32 v76, v76
	v_add_f32_e32 v79, 1.0, v79
	v_rcp_f32_e32 v79, v79
	v_mul_f32_e32 v76, 0xc1000000, v76
	v_mul_f32_e32 v76, v76, v165
	v_mul_f32_e32 v76, 0x3fb8aa3b, v76
	v_exp_f32_e32 v76, v76
	s_nop 0
	v_sub_f32_e32 v80, 1.0, v76
	v_add_f32_e32 v81, 1.0, v76
	v_mul_f32_e32 v80, v80, v81
	v_max_f32_e32 v80, 0, v80
	v_sqrt_f32_e32 v80, v80
	s_nop 0
	v_mul_f32_e32 v77, v77, v80
	v_mul_f32_e32 v77, v77, v96
	ds_write2_b64 v183, v[94:95], v[76:77] offset0:32 offset1:49
	v_add_f32_e32 v76, v82, v86
	v_mul_f32_e32 v76, 0xbfb8aa3b, v76
	v_exp_f32_e32 v76, v76
	v_add_f32_e32 v77, v78, v90
	v_mul_f32_e32 v77, 0xbfb8aa3b, v77
	v_exp_f32_e32 v77, v77
	v_add_f32_e32 v76, 1.0, v76
	v_rcp_f32_e32 v76, v76
	v_add_f32_e32 v77, 1.0, v77
	v_rcp_f32_e32 v77, v77
	v_mul_f32_e32 v76, 0xc1000000, v76
	v_mul_f32_e32 v76, v76, v167
	v_mul_f32_e32 v76, 0x3fb8aa3b, v76
	v_exp_f32_e32 v76, v76
	s_nop 0
	v_sub_f32_e32 v78, 1.0, v76
	v_add_f32_e32 v80, 1.0, v76
	v_mul_f32_e32 v78, v78, v80
	v_max_f32_e32 v78, 0, v78
	v_sqrt_f32_e32 v78, v78
	s_nop 0
	v_mul_f32_e32 v77, v77, v78
	v_add_f32_e32 v78, v83, v87
	v_mul_f32_e32 v78, 0xbfb8aa3b, v78
	v_exp_f32_e32 v78, v78
	v_mul_f32_e32 v77, v77, v97
	v_add_f32_e32 v78, 1.0, v78
	v_rcp_f32_e32 v78, v78
	s_nop 0
	v_mul_f32_e32 v78, 0xc1000000, v78
	v_mul_f32_e32 v78, v78, v168
	v_mul_f32_e32 v78, 0x3fb8aa3b, v78
	v_exp_f32_e32 v78, v78
	s_nop 0
	v_sub_f32_e32 v80, 1.0, v78
	v_add_f32_e32 v81, 1.0, v78
	v_mul_f32_e32 v80, v80, v81
	v_max_f32_e32 v80, 0, v80
	v_sqrt_f32_e32 v80, v80
	s_nop 0
	v_mul_f32_e32 v79, v79, v80
	v_mul_f32_e32 v79, v79, v98
	ds_write2_b64 v183, v[76:77], v[78:79] offset0:66 offset1:83
	v_mfma_f32_16x16x32_bf16 v[76:79], v[8:11], v[68:71], 0
	v_mfma_f32_16x16x32_bf16 v[68:71], v[4:7], v[68:71], 0
	v_mfma_f32_16x16x32_bf16 v[76:79], v[16:19], v[72:75], v[76:79]
	v_mfma_f32_16x16x32_bf16 v[68:71], v[12:15], v[72:75], v[68:71]
	global_load_dwordx4 v[72:75], v[154:155], off offset:192
	global_load_dwordx4 v[80:83], v[152:153], off offset:192
	ds_read_b64 v[84:85], v2 offset:96
	s_waitcnt lgkmcnt(0)
	v_lshlrev_b32_e32 v86, 16, v84
	v_and_b32_e32 v87, 0xffff0000, v84
	v_lshlrev_b32_e32 v88, 16, v85
	v_and_b32_e32 v89, 0xffff0000, v85
	s_waitcnt vmcnt(1)
	v_add_f32_e32 v72, v76, v72
	v_mul_f32_e32 v72, 0xbfb8aa3b, v72
	v_exp_f32_e32 v72, v72
	s_waitcnt vmcnt(0)
	v_add_f32_e32 v68, v68, v80
	v_mul_f32_e32 v68, 0xbfb8aa3b, v68
	v_exp_f32_e32 v68, v68
	v_add_f32_e32 v72, 1.0, v72
	v_rcp_f32_e32 v72, v72
	v_add_f32_e32 v69, v69, v81
	v_add_f32_e32 v68, 1.0, v68
	v_rcp_f32_e32 v68, v68
	v_mul_f32_e32 v72, 0xc1000000, v72
	v_mul_f32_e32 v72, v169, v72
	v_mul_f32_e32 v72, 0x3fb8aa3b, v72
	v_exp_f32_e32 v84, v72
	v_mul_f32_e32 v69, 0xbfb8aa3b, v69
	v_exp_f32_e32 v69, v69
	v_add_f32_e32 v71, v71, v83
	v_sub_f32_e32 v72, 1.0, v84
	v_add_f32_e32 v76, 1.0, v84
	v_mul_f32_e32 v72, v72, v76
	v_max_f32_e32 v72, 0, v72
	v_sqrt_f32_e32 v72, v72
	v_add_f32_e32 v69, 1.0, v69
	v_rcp_f32_e32 v69, v69
	v_mul_f32_e32 v71, 0xbfb8aa3b, v71
	v_mul_f32_e32 v68, v68, v72
	v_mul_f32_e32 v85, v68, v86
	v_add_f32_e32 v68, v77, v73
	v_mul_f32_e32 v68, 0xbfb8aa3b, v68
	v_exp_f32_e32 v68, v68
	v_exp_f32_e32 v71, v71
	v_add_f32_e32 v68, 1.0, v68
	v_rcp_f32_e32 v68, v68
	v_add_f32_e32 v71, 1.0, v71
	v_rcp_f32_e32 v71, v71
	v_mul_f32_e32 v68, 0xc1000000, v68
	v_mul_f32_e32 v68, v170, v68
	v_mul_f32_e32 v68, 0x3fb8aa3b, v68
	v_exp_f32_e32 v68, v68
	s_nop 0
	v_sub_f32_e32 v72, 1.0, v68
	v_add_f32_e32 v73, 1.0, v68
	v_mul_f32_e32 v72, v72, v73
	v_max_f32_e32 v72, 0, v72
	v_sqrt_f32_e32 v72, v72
	s_nop 0
	v_mul_f32_e32 v69, v69, v72
	v_mul_f32_e32 v69, v69, v87
	ds_write2_b64 v174, v[84:85], v[68:69] offset0:48 offset1:65
	v_add_f32_e32 v68, v78, v74
	v_mul_f32_e32 v68, 0xbfb8aa3b, v68
	v_exp_f32_e32 v68, v68
	v_add_f32_e32 v69, v70, v82
	v_mul_f32_e32 v69, 0xbfb8aa3b, v69
	v_exp_f32_e32 v69, v69
	v_add_f32_e32 v68, 1.0, v68
	v_rcp_f32_e32 v68, v68
	v_add_f32_e32 v69, 1.0, v69
	v_rcp_f32_e32 v69, v69
	v_mul_f32_e32 v68, 0xc1000000, v68
	v_mul_f32_e32 v68, v171, v68
	v_mul_f32_e32 v68, 0x3fb8aa3b, v68
	v_exp_f32_e32 v68, v68
	s_nop 0
	v_sub_f32_e32 v70, 1.0, v68
	v_add_f32_e32 v72, 1.0, v68
	v_mul_f32_e32 v70, v70, v72
	v_max_f32_e32 v70, 0, v70
	v_sqrt_f32_e32 v70, v70
	s_nop 0
	v_mul_f32_e32 v69, v69, v70
	v_add_f32_e32 v70, v79, v75
	v_mul_f32_e32 v70, 0xbfb8aa3b, v70
	v_exp_f32_e32 v70, v70
	v_mul_f32_e32 v69, v69, v88
	v_add_f32_e32 v70, 1.0, v70
	v_rcp_f32_e32 v70, v70
	s_nop 0
	v_mul_f32_e32 v70, 0xc1000000, v70
	v_mul_f32_e32 v70, v172, v70
	v_mul_f32_e32 v70, 0x3fb8aa3b, v70
	v_exp_f32_e32 v70, v70
	s_nop 0
	v_sub_f32_e32 v72, 1.0, v70
	v_add_f32_e32 v73, 1.0, v70
	v_mul_f32_e32 v72, v72, v73
	v_max_f32_e32 v72, 0, v72
	v_sqrt_f32_e32 v72, v72
	s_nop 0
	v_mul_f32_e32 v71, v71, v72
	v_mul_f32_e32 v71, v71, v89
	ds_write2_b64 v174, v[68:69], v[70:71] offset0:82 offset1:99
	s_waitcnt lgkmcnt(0)
	s_barrier
	ds_read2_b64 v[68:71], v173 offset1:1
	ds_read2_b64 v[108:111], v175 offset1:1
	ds_read2_b64 v[100:103], v185 offset1:1
	ds_read2_b64 v[88:91], v184 offset1:1
	ds_read2_b64 v[92:95], v179 offset1:1
	ds_read2_b64 v[104:107], v178 offset1:1
	s_waitcnt lgkmcnt(5)
	v_fma_f32 v72, 0, v68, v69
	v_pk_mul_f32 v[156:157], v[68:69], v[70:71]
	v_fmac_f32_e32 v71, v70, v72
	s_waitcnt lgkmcnt(3)
	v_fma_f32 v68, v100, v71, v101
	v_fma_f32 v68, v102, v68, v103
	ds_read2_b64 v[96:99], v176 offset1:1
	ds_read2_b64 v[84:87], v177 offset1:1
	s_waitcnt lgkmcnt(4)
	v_fma_f32 v68, v88, v68, v89
	v_fma_f32 v68, v90, v68, v91
	s_waitcnt lgkmcnt(3)
	v_fma_f32 v68, v92, v68, v93
	v_fma_f32 v68, v94, v68, v95
	s_waitcnt lgkmcnt(1)
	v_fma_f32 v68, v96, v68, v97
	v_fma_f32 v68, v98, v68, v99
	v_fma_f32 v68, v104, v68, v105
	v_fma_f32 v68, v106, v68, v107
	v_fma_f32 v68, v108, v68, v109
	v_fma_f32 v68, v110, v68, v111
	s_waitcnt lgkmcnt(0)
	v_fma_f32 v68, v84, v68, v85
	v_fma_f32 v89, v86, v68, v87
	s_barrier
	ds_read_b128 v[68:71], v180 offset:8704
	ds_read_b128 v[72:75], v180 offset:8768
	global_load_dwordx4 v[112:115], v[154:155], off
	global_load_dwordx4 v[116:119], v[152:153], off
	s_waitcnt lgkmcnt(1)
	v_mfma_f32_16x16x32_bf16 v[76:79], v[56:59], v[68:71], 0
	ds_read_b64 v[120:121], v2 offset:8704
	s_waitcnt lgkmcnt(0)
	v_lshlrev_b32_e32 v97, 16, v120
	v_mfma_f32_16x16x32_bf16 v[76:79], v[64:67], v[72:75], v[76:79]
	v_and_b32_e32 v109, 0xffff0000, v120
	v_lshlrev_b32_e32 v122, 16, v121
	v_and_b32_e32 v123, 0xffff0000, v121
	v_mfma_f32_16x16x32_bf16 v[80:83], v[52:55], v[68:71], 0
	v_mfma_f32_16x16x32_bf16 v[80:83], v[60:63], v[72:75], v[80:83]
	s_waitcnt vmcnt(1)
	s_nop 1
	v_add_f32_e32 v76, v76, v112
	v_mul_f32_e32 v76, 0xbfb8aa3b, v76
	v_exp_f32_e32 v76, v76
	s_waitcnt vmcnt(0)
	s_nop 0
	v_add_f32_e32 v80, v80, v116
	v_mul_f32_e32 v80, 0xbfb8aa3b, v80
	v_exp_f32_e32 v80, v80
	v_add_f32_e32 v76, 1.0, v76
	v_rcp_f32_e32 v76, v76
	v_add_f32_e32 v80, 1.0, v80
	v_rcp_f32_e32 v80, v80
	v_mul_f32_e32 v76, 0xc1000000, v76
	v_mul_f32_e32 v76, v1, v76
	v_mul_f32_e32 v76, 0x3fb8aa3b, v76
	v_exp_f32_e32 v120, v76
	s_nop 0
	v_sub_f32_e32 v76, 1.0, v120
	v_add_f32_e32 v112, 1.0, v120
	v_mul_f32_e32 v76, v76, v112
	v_max_f32_e32 v76, 0, v76
	v_sqrt_f32_e32 v76, v76
	s_nop 0
	v_mul_f32_e32 v76, v80, v76
	v_mul_f32_e32 v121, v76, v97
	v_add_f32_e32 v76, v77, v113
	v_mul_f32_e32 v76, 0xbfb8aa3b, v76
	v_exp_f32_e32 v76, v76
	v_add_f32_e32 v77, v81, v117
	v_mul_f32_e32 v77, 0xbfb8aa3b, v77
	v_exp_f32_e32 v77, v77
	v_add_f32_e32 v76, 1.0, v76
	v_rcp_f32_e32 v76, v76
	v_add_f32_e32 v77, 1.0, v77
	v_rcp_f32_e32 v77, v77
	v_mul_f32_e32 v76, 0xc1000000, v76
	v_mul_f32_e32 v76, v158, v76
	v_mul_f32_e32 v76, 0x3fb8aa3b, v76
	v_exp_f32_e32 v76, v76
	s_nop 0
	v_sub_f32_e32 v80, 1.0, v76
	v_add_f32_e32 v81, 1.0, v76
	v_mul_f32_e32 v80, v80, v81
	v_max_f32_e32 v80, 0, v80
	v_sqrt_f32_e32 v80, v80
	s_nop 0
	v_mul_f32_e32 v77, v77, v80
	v_mul_f32_e32 v77, v77, v109
	ds_write2_b64 v181, v[120:121], v[76:77] offset1:17
	v_add_f32_e32 v76, v78, v114
	v_mul_f32_e32 v76, 0xbfb8aa3b, v76
	v_exp_f32_e32 v76, v76
	v_add_f32_e32 v77, v82, v118
	v_mul_f32_e32 v77, 0xbfb8aa3b, v77
	v_exp_f32_e32 v77, v77
	v_add_f32_e32 v76, 1.0, v76
	v_rcp_f32_e32 v76, v76
	v_add_f32_e32 v77, 1.0, v77
	v_rcp_f32_e32 v77, v77
	v_mul_f32_e32 v76, 0xc1000000, v76
	v_mul_f32_e32 v76, v159, v76
	v_mul_f32_e32 v76, 0x3fb8aa3b, v76
	v_exp_f32_e32 v76, v76
	s_nop 0
	v_sub_f32_e32 v78, 1.0, v76
	v_add_f32_e32 v80, 1.0, v76
	v_mul_f32_e32 v78, v78, v80
	v_max_f32_e32 v78, 0, v78
	v_sqrt_f32_e32 v78, v78
	s_nop 0
	v_mul_f32_e32 v77, v77, v78
	v_add_f32_e32 v78, v79, v115
	v_mul_f32_e32 v78, 0xbfb8aa3b, v78
	v_exp_f32_e32 v78, v78
	v_add_f32_e32 v79, v83, v119
	v_mul_f32_e32 v79, 0xbfb8aa3b, v79
	v_exp_f32_e32 v79, v79
	v_add_f32_e32 v78, 1.0, v78
	v_rcp_f32_e32 v78, v78
	v_mul_f32_e32 v77, v77, v122
	v_add_f32_e32 v79, 1.0, v79
	v_rcp_f32_e32 v79, v79
	v_mul_f32_e32 v78, 0xc1000000, v78
	v_mul_f32_e32 v78, v160, v78
	v_mul_f32_e32 v78, 0x3fb8aa3b, v78
	v_exp_f32_e32 v78, v78
	s_nop 0
	v_sub_f32_e32 v80, 1.0, v78
	v_add_f32_e32 v81, 1.0, v78
	v_mul_f32_e32 v80, v80, v81
	v_max_f32_e32 v80, 0, v80
	v_sqrt_f32_e32 v80, v80
	s_nop 0
	v_mul_f32_e32 v79, v79, v80
	v_mul_f32_e32 v79, v79, v123
	ds_write2_b64 v181, v[76:77], v[78:79] offset0:34 offset1:51
	global_load_dwordx4 v[112:115], v[154:155], off offset:64
	global_load_dwordx4 v[116:119], v[152:153], off offset:64
	v_mfma_f32_16x16x32_bf16 v[76:79], v[40:43], v[68:71], 0
	ds_read_b64 v[120:121], v2 offset:8736
	s_waitcnt lgkmcnt(0)
	v_lshlrev_b32_e32 v97, 16, v120
	v_mfma_f32_16x16x32_bf16 v[80:83], v[48:51], v[72:75], v[76:79]
	v_and_b32_e32 v109, 0xffff0000, v120
	v_lshlrev_b32_e32 v122, 16, v121
	v_and_b32_e32 v123, 0xffff0000, v121
	v_mfma_f32_16x16x32_bf16 v[76:79], v[36:39], v[68:71], 0
	v_mfma_f32_16x16x32_bf16 v[76:79], v[44:47], v[72:75], v[76:79]
	s_waitcnt vmcnt(1)
	s_nop 1
	v_add_f32_e32 v80, v80, v112
	v_mul_f32_e32 v80, 0xbfb8aa3b, v80
	v_exp_f32_e32 v80, v80
	s_waitcnt vmcnt(0)
	s_nop 0
	v_add_f32_e32 v76, v76, v116
	v_mul_f32_e32 v76, 0xbfb8aa3b, v76
	v_exp_f32_e32 v76, v76
	v_add_f32_e32 v80, 1.0, v80
	v_rcp_f32_e32 v80, v80
	v_add_f32_e32 v77, v77, v117
	v_add_f32_e32 v76, 1.0, v76
	v_rcp_f32_e32 v76, v76
	v_mul_f32_e32 v80, 0xc1000000, v80
	v_mul_f32_e32 v80, v161, v80
	v_mul_f32_e32 v80, 0x3fb8aa3b, v80
	v_exp_f32_e32 v120, v80
	v_mul_f32_e32 v77, 0xbfb8aa3b, v77
	v_exp_f32_e32 v77, v77
	v_add_f32_e32 v79, v79, v119
	v_sub_f32_e32 v80, 1.0, v120
	v_add_f32_e32 v112, 1.0, v120
	v_mul_f32_e32 v80, v80, v112
	v_max_f32_e32 v80, 0, v80
	v_sqrt_f32_e32 v80, v80
	v_add_f32_e32 v77, 1.0, v77
	v_rcp_f32_e32 v77, v77
	v_mul_f32_e32 v79, 0xbfb8aa3b, v79
	v_mul_f32_e32 v76, v76, v80
	v_mul_f32_e32 v121, v76, v97
	v_add_f32_e32 v76, v81, v113
	v_mul_f32_e32 v76, 0xbfb8aa3b, v76
	v_exp_f32_e32 v76, v76
	v_exp_f32_e32 v79, v79
	v_add_f32_e32 v76, 1.0, v76
	v_rcp_f32_e32 v76, v76
	v_add_f32_e32 v79, 1.0, v79
	v_rcp_f32_e32 v79, v79
	v_mul_f32_e32 v76, 0xc1000000, v76
	v_mul_f32_e32 v76, v162, v76
	v_mul_f32_e32 v76, 0x3fb8aa3b, v76
	v_exp_f32_e32 v76, v76
	s_nop 0
	v_sub_f32_e32 v80, 1.0, v76
	v_add_f32_e32 v81, 1.0, v76
	v_mul_f32_e32 v80, v80, v81
	v_max_f32_e32 v80, 0, v80
	v_sqrt_f32_e32 v80, v80
	s_nop 0
	v_mul_f32_e32 v77, v77, v80
	v_mul_f32_e32 v77, v77, v109
	ds_write2_b64 v182, v[120:121], v[76:77] offset0:16 offset1:33
	v_add_f32_e32 v76, v82, v114
	v_mul_f32_e32 v76, 0xbfb8aa3b, v76
	v_exp_f32_e32 v76, v76
	v_add_f32_e32 v77, v78, v118
	v_mul_f32_e32 v77, 0xbfb8aa3b, v77
	v_exp_f32_e32 v77, v77
	v_add_f32_e32 v76, 1.0, v76
	v_rcp_f32_e32 v76, v76
	v_add_f32_e32 v77, 1.0, v77
	v_rcp_f32_e32 v77, v77
	v_mul_f32_e32 v76, 0xc1000000, v76
	v_mul_f32_e32 v76, v164, v76
	v_mul_f32_e32 v76, 0x3fb8aa3b, v76
	v_exp_f32_e32 v76, v76
	s_nop 0
	v_sub_f32_e32 v78, 1.0, v76
	v_add_f32_e32 v80, 1.0, v76
	v_mul_f32_e32 v78, v78, v80
	v_max_f32_e32 v78, 0, v78
	v_sqrt_f32_e32 v78, v78
	s_nop 0
	v_mul_f32_e32 v77, v77, v78
	v_add_f32_e32 v78, v83, v115
	v_mul_f32_e32 v78, 0xbfb8aa3b, v78
	v_exp_f32_e32 v78, v78
	v_mul_f32_e32 v77, v77, v122
	v_add_f32_e32 v78, 1.0, v78
	v_rcp_f32_e32 v78, v78
	s_nop 0
	v_mul_f32_e32 v78, 0xc1000000, v78
	v_mul_f32_e32 v78, v166, v78
	v_mul_f32_e32 v78, 0x3fb8aa3b, v78
	v_exp_f32_e32 v78, v78
	s_nop 0
	v_sub_f32_e32 v80, 1.0, v78
	v_add_f32_e32 v81, 1.0, v78
	v_mul_f32_e32 v80, v80, v81
	v_max_f32_e32 v80, 0, v80
	v_sqrt_f32_e32 v80, v80
	s_nop 0
	v_mul_f32_e32 v79, v79, v80
	v_mul_f32_e32 v79, v79, v123
	ds_write2_b64 v182, v[76:77], v[78:79] offset0:50 offset1:67
	global_load_dwordx4 v[112:115], v[154:155], off offset:128
	global_load_dwordx4 v[116:119], v[152:153], off offset:128
	v_mfma_f32_16x16x32_bf16 v[76:79], v[24:27], v[68:71], 0
	ds_read_b64 v[120:121], v2 offset:8768
	s_waitcnt lgkmcnt(0)
	v_lshlrev_b32_e32 v97, 16, v120
	v_mfma_f32_16x16x32_bf16 v[80:83], v[32:35], v[72:75], v[76:79]
	v_and_b32_e32 v109, 0xffff0000, v120
	v_lshlrev_b32_e32 v122, 16, v121
	v_and_b32_e32 v123, 0xffff0000, v121
	v_mfma_f32_16x16x32_bf16 v[76:79], v[20:23], v[68:71], 0
	v_mfma_f32_16x16x32_bf16 v[76:79], v[28:31], v[72:75], v[76:79]
	s_waitcnt vmcnt(1)
	s_nop 1
	v_add_f32_e32 v80, v80, v112
	v_mul_f32_e32 v80, 0xbfb8aa3b, v80
	v_exp_f32_e32 v80, v80
	s_waitcnt vmcnt(0)
	s_nop 0
	v_add_f32_e32 v76, v76, v116
	v_mul_f32_e32 v76, 0xbfb8aa3b, v76
	v_exp_f32_e32 v76, v76
	v_add_f32_e32 v80, 1.0, v80
	v_rcp_f32_e32 v80, v80
	v_add_f32_e32 v77, v77, v117
	v_add_f32_e32 v76, 1.0, v76
	v_rcp_f32_e32 v76, v76
	v_mul_f32_e32 v80, 0xc1000000, v80
	v_mul_f32_e32 v80, v163, v80
	v_mul_f32_e32 v80, 0x3fb8aa3b, v80
	v_exp_f32_e32 v120, v80
	v_mul_f32_e32 v77, 0xbfb8aa3b, v77
	v_exp_f32_e32 v77, v77
	v_add_f32_e32 v79, v79, v119
	v_sub_f32_e32 v80, 1.0, v120
	v_add_f32_e32 v112, 1.0, v120
	v_mul_f32_e32 v80, v80, v112
	v_max_f32_e32 v80, 0, v80
	v_sqrt_f32_e32 v80, v80
	v_add_f32_e32 v77, 1.0, v77
	v_rcp_f32_e32 v77, v77
	v_mul_f32_e32 v79, 0xbfb8aa3b, v79
	v_mul_f32_e32 v76, v76, v80
	v_mul_f32_e32 v121, v76, v97
	v_add_f32_e32 v76, v81, v113
	v_mul_f32_e32 v76, 0xbfb8aa3b, v76
	v_exp_f32_e32 v76, v76
	v_exp_f32_e32 v79, v79
	v_add_f32_e32 v76, 1.0, v76
	v_rcp_f32_e32 v76, v76
	v_add_f32_e32 v79, 1.0, v79
	v_rcp_f32_e32 v79, v79
	v_mul_f32_e32 v76, 0xc1000000, v76
	v_mul_f32_e32 v76, v165, v76
	v_mul_f32_e32 v76, 0x3fb8aa3b, v76
	v_exp_f32_e32 v76, v76
	s_nop 0
	v_sub_f32_e32 v80, 1.0, v76
	v_add_f32_e32 v81, 1.0, v76
	v_mul_f32_e32 v80, v80, v81
	v_max_f32_e32 v80, 0, v80
	v_sqrt_f32_e32 v80, v80
	s_nop 0
	v_mul_f32_e32 v77, v77, v80
	v_mul_f32_e32 v77, v77, v109
	ds_write2_b64 v183, v[120:121], v[76:77] offset0:32 offset1:49
	v_add_f32_e32 v76, v82, v114
	v_mul_f32_e32 v76, 0xbfb8aa3b, v76
	v_exp_f32_e32 v76, v76
	v_add_f32_e32 v77, v78, v118
	v_mul_f32_e32 v77, 0xbfb8aa3b, v77
	v_exp_f32_e32 v77, v77
	v_add_f32_e32 v76, 1.0, v76
	v_rcp_f32_e32 v76, v76
	v_add_f32_e32 v77, 1.0, v77
	v_rcp_f32_e32 v77, v77
	v_mul_f32_e32 v76, 0xc1000000, v76
	v_mul_f32_e32 v76, v167, v76
	v_mul_f32_e32 v76, 0x3fb8aa3b, v76
	v_exp_f32_e32 v76, v76
	s_nop 0
	v_sub_f32_e32 v78, 1.0, v76
	v_add_f32_e32 v80, 1.0, v76
	v_mul_f32_e32 v78, v78, v80
	v_max_f32_e32 v78, 0, v78
	v_sqrt_f32_e32 v78, v78
	s_nop 0
	v_mul_f32_e32 v77, v77, v78
	v_add_f32_e32 v78, v83, v115
	v_mul_f32_e32 v78, 0xbfb8aa3b, v78
	v_exp_f32_e32 v78, v78
	v_mul_f32_e32 v77, v77, v122
	v_add_f32_e32 v78, 1.0, v78
	v_rcp_f32_e32 v78, v78
	s_nop 0
	v_mul_f32_e32 v78, 0xc1000000, v78
	v_mul_f32_e32 v78, v168, v78
	v_mul_f32_e32 v78, 0x3fb8aa3b, v78
	v_exp_f32_e32 v78, v78
	s_nop 0
	v_sub_f32_e32 v80, 1.0, v78
	v_add_f32_e32 v81, 1.0, v78
	v_mul_f32_e32 v80, v80, v81
	v_max_f32_e32 v80, 0, v80
	v_sqrt_f32_e32 v80, v80
	s_nop 0
	v_mul_f32_e32 v79, v79, v80
	v_mul_f32_e32 v79, v79, v123
	ds_write2_b64 v183, v[76:77], v[78:79] offset0:66 offset1:83
	v_mfma_f32_16x16x32_bf16 v[76:79], v[8:11], v[68:71], 0
	v_mfma_f32_16x16x32_bf16 v[68:71], v[4:7], v[68:71], 0
	v_mfma_f32_16x16x32_bf16 v[76:79], v[16:19], v[72:75], v[76:79]
	v_mfma_f32_16x16x32_bf16 v[68:71], v[12:15], v[72:75], v[68:71]
	global_load_dwordx4 v[72:75], v[154:155], off offset:192
	global_load_dwordx4 v[80:83], v[152:153], off offset:192
	ds_read_b64 v[112:113], v2 offset:8800
	s_waitcnt lgkmcnt(0)
	v_lshlrev_b32_e32 v97, 16, v112
	v_and_b32_e32 v109, 0xffff0000, v112
	v_lshlrev_b32_e32 v114, 16, v113
	v_and_b32_e32 v115, 0xffff0000, v113
	s_waitcnt vmcnt(1)
	v_add_f32_e32 v72, v76, v72
	v_mul_f32_e32 v72, 0xbfb8aa3b, v72
	v_exp_f32_e32 v72, v72
	s_waitcnt vmcnt(0)
	v_add_f32_e32 v68, v68, v80
	v_mul_f32_e32 v68, 0xbfb8aa3b, v68
	v_exp_f32_e32 v68, v68
	v_add_f32_e32 v72, 1.0, v72
	v_rcp_f32_e32 v72, v72
	v_add_f32_e32 v69, v69, v81
	v_add_f32_e32 v68, 1.0, v68
	v_rcp_f32_e32 v68, v68
	v_mul_f32_e32 v72, 0xc1000000, v72
	v_mul_f32_e32 v72, v169, v72
	v_mul_f32_e32 v72, 0x3fb8aa3b, v72
	v_exp_f32_e32 v112, v72
	v_mul_f32_e32 v69, 0xbfb8aa3b, v69
	v_exp_f32_e32 v69, v69
	v_add_f32_e32 v71, v71, v83
	v_sub_f32_e32 v72, 1.0, v112
	v_add_f32_e32 v76, 1.0, v112
	v_mul_f32_e32 v72, v72, v76
	v_max_f32_e32 v72, 0, v72
	v_sqrt_f32_e32 v72, v72
	v_add_f32_e32 v69, 1.0, v69
	v_rcp_f32_e32 v69, v69
	v_mul_f32_e32 v71, 0xbfb8aa3b, v71
	v_mul_f32_e32 v68, v68, v72
	v_mul_f32_e32 v113, v68, v97
	v_add_f32_e32 v68, v77, v73
	v_mul_f32_e32 v68, 0xbfb8aa3b, v68
	v_exp_f32_e32 v68, v68
	v_exp_f32_e32 v71, v71
	v_add_f32_e32 v68, 1.0, v68
	v_rcp_f32_e32 v68, v68
	v_add_f32_e32 v71, 1.0, v71
	v_rcp_f32_e32 v71, v71
	v_mul_f32_e32 v68, 0xc1000000, v68
	v_mul_f32_e32 v68, v170, v68
	v_mul_f32_e32 v68, 0x3fb8aa3b, v68
	v_exp_f32_e32 v68, v68
	s_nop 0
	v_sub_f32_e32 v72, 1.0, v68
	v_add_f32_e32 v73, 1.0, v68
	v_mul_f32_e32 v72, v72, v73
	v_max_f32_e32 v72, 0, v72
	v_sqrt_f32_e32 v72, v72
	s_nop 0
	v_mul_f32_e32 v69, v69, v72
	v_mul_f32_e32 v69, v69, v109
	ds_write2_b64 v174, v[112:113], v[68:69] offset0:48 offset1:65
	v_add_f32_e32 v68, v78, v74
	v_mul_f32_e32 v68, 0xbfb8aa3b, v68
	v_exp_f32_e32 v68, v68
	v_add_f32_e32 v69, v70, v82
	v_mul_f32_e32 v69, 0xbfb8aa3b, v69
	v_exp_f32_e32 v69, v69
	v_add_f32_e32 v68, 1.0, v68
	v_rcp_f32_e32 v68, v68
	v_add_f32_e32 v69, 1.0, v69
	v_rcp_f32_e32 v69, v69
	v_mul_f32_e32 v68, 0xc1000000, v68
	v_mul_f32_e32 v68, v171, v68
	v_mul_f32_e32 v68, 0x3fb8aa3b, v68
	v_exp_f32_e32 v68, v68
	s_nop 0
	v_sub_f32_e32 v70, 1.0, v68
	v_add_f32_e32 v72, 1.0, v68
	v_mul_f32_e32 v70, v70, v72
	v_max_f32_e32 v70, 0, v70
	v_sqrt_f32_e32 v70, v70
	s_nop 0
	v_mul_f32_e32 v69, v69, v70
	v_add_f32_e32 v70, v79, v75
	v_mul_f32_e32 v70, 0xbfb8aa3b, v70
	v_exp_f32_e32 v70, v70
	v_mul_f32_e32 v69, v69, v114
	v_add_f32_e32 v70, 1.0, v70
	v_rcp_f32_e32 v70, v70
	s_nop 0
	v_mul_f32_e32 v70, 0xc1000000, v70
	v_mul_f32_e32 v70, v172, v70
	v_mul_f32_e32 v70, 0x3fb8aa3b, v70
	v_exp_f32_e32 v70, v70
	s_nop 0
	v_sub_f32_e32 v72, 1.0, v70
	v_add_f32_e32 v73, 1.0, v70
	v_mul_f32_e32 v72, v72, v73
	v_max_f32_e32 v72, 0, v72
	v_sqrt_f32_e32 v72, v72
	s_nop 0
	v_mul_f32_e32 v71, v71, v72
	v_mul_f32_e32 v71, v71, v115
	ds_write2_b64 v174, v[68:69], v[70:71] offset0:82 offset1:99
	s_waitcnt lgkmcnt(0)
	s_barrier
	ds_read2_b64 v[124:127], v173 offset1:1
	ds_read2_b64 v[76:79], v175 offset1:1
	ds_read2_b64 v[128:131], v185 offset1:1
	ds_read2_b64 v[132:135], v184 offset1:1
	ds_read2_b64 v[136:139], v179 offset1:1
	s_waitcnt lgkmcnt(4)
	v_fma_f32 v68, v89, v124, v125
	v_fma_f32 v68, v126, v68, v127
	s_waitcnt lgkmcnt(2)
	v_fma_f32 v68, v128, v68, v129
	v_fma_f32 v68, v130, v68, v131
	s_waitcnt lgkmcnt(1)
	v_fma_f32 v68, v132, v68, v133
	v_fma_f32 v68, v134, v68, v135
	s_waitcnt lgkmcnt(0)
	v_fma_f32 v68, v136, v68, v137
	v_fma_f32 v72, v138, v68, v139
	ds_read2_b64 v[68:71], v176 offset1:1
	ds_read2_b64 v[80:83], v177 offset1:1
	s_waitcnt lgkmcnt(1)
	v_fma_f32 v69, v68, v72, v69
	ds_read2_b64 v[72:75], v178 offset1:1
	s_waitcnt lgkmcnt(0)
	s_barrier
	ds_read_b128 v[112:115], v180 offset:17408
	ds_read_b128 v[116:119], v180 offset:17472
	global_load_dwordx4 v[144:147], v[154:155], off
	global_load_dwordx4 v[148:151], v[152:153], off
	s_waitcnt lgkmcnt(1)
	v_mfma_f32_16x16x32_bf16 v[120:123], v[56:59], v[112:115], 0
	ds_read_b64 v[186:187], v2 offset:17408
	v_fma_f32 v69, v70, v69, v71
	v_fma_f32 v69, v72, v69, v73
	s_waitcnt lgkmcnt(1)
	v_mfma_f32_16x16x32_bf16 v[120:123], v[64:67], v[116:119], v[120:123]
	v_fma_f32 v69, v74, v69, v75
	v_fma_f32 v69, v76, v69, v77
	s_waitcnt lgkmcnt(0)
	v_lshlrev_b32_e32 v77, 16, v186
	v_mfma_f32_16x16x32_bf16 v[140:143], v[52:55], v[112:115], 0
	v_and_b32_e32 v89, 0xffff0000, v186
	v_lshlrev_b32_e32 v97, 16, v187
	v_and_b32_e32 v109, 0xffff0000, v187
	v_mfma_f32_16x16x32_bf16 v[140:143], v[60:63], v[116:119], v[140:143]
	v_fma_f32 v69, v78, v69, v79
	v_fma_f32 v69, v80, v69, v81
	v_fma_f32 v69, v82, v69, v83
	s_waitcnt vmcnt(1)
	v_add_f32_e32 v120, v120, v144
	v_mul_f32_e32 v120, 0xbfb8aa3b, v120
	v_exp_f32_e32 v120, v120
	s_waitcnt vmcnt(0)
	v_add_f32_e32 v125, v140, v148
	v_mul_f32_e32 v125, 0xbfb8aa3b, v125
	v_exp_f32_e32 v125, v125
	v_add_f32_e32 v120, 1.0, v120
	v_rcp_f32_e32 v120, v120
	v_add_f32_e32 v125, 1.0, v125
	v_rcp_f32_e32 v125, v125
	v_mul_f32_e32 v120, 0xc1000000, v120
	v_mul_f32_e32 v120, v1, v120
	v_mul_f32_e32 v120, 0x3fb8aa3b, v120
	v_exp_f32_e32 v186, v120
	s_nop 0
	v_sub_f32_e32 v120, 1.0, v186
	v_add_f32_e32 v133, 1.0, v186
	v_mul_f32_e32 v120, v120, v133
	v_max_f32_e32 v120, 0, v120
	v_sqrt_f32_e32 v120, v120
	s_nop 0
	v_mul_f32_e32 v120, v125, v120
	v_mul_f32_e32 v187, v120, v77
	v_add_f32_e32 v77, v121, v145
	v_mul_f32_e32 v77, 0xbfb8aa3b, v77
	v_exp_f32_e32 v77, v77
	v_add_f32_e32 v120, v141, v149
	v_mul_f32_e32 v120, 0xbfb8aa3b, v120
	v_exp_f32_e32 v120, v120
	v_add_f32_e32 v77, 1.0, v77
	v_rcp_f32_e32 v77, v77
	v_add_f32_e32 v120, 1.0, v120
	v_rcp_f32_e32 v121, v120
	v_mul_f32_e32 v77, 0xc1000000, v77
	v_mul_f32_e32 v77, v158, v77
	v_mul_f32_e32 v77, 0x3fb8aa3b, v77
	v_exp_f32_e32 v120, v77
	s_nop 0
	v_sub_f32_e32 v77, 1.0, v120
	v_add_f32_e32 v125, 1.0, v120
	v_mul_f32_e32 v77, v77, v125
	v_max_f32_e32 v77, 0, v77
	v_sqrt_f32_e32 v77, v77
	s_nop 0
	v_mul_f32_e32 v77, v121, v77
	v_mul_f32_e32 v121, v77, v89
	v_add_f32_e32 v77, v122, v146
	v_mul_f32_e32 v77, 0xbfb8aa3b, v77
	v_exp_f32_e32 v77, v77
	ds_write2_b64 v181, v[186:187], v[120:121] offset1:17
	v_add_f32_e32 v89, v142, v150
	v_mul_f32_e32 v89, 0xbfb8aa3b, v89
	v_add_f32_e32 v77, 1.0, v77
	v_rcp_f32_e32 v77, v77
	v_exp_f32_e32 v89, v89
	v_mul_f32_e32 v77, 0xc1000000, v77
	v_mul_f32_e32 v77, v159, v77
	v_mul_f32_e32 v77, 0x3fb8aa3b, v77
	v_exp_f32_e32 v120, v77
	v_add_f32_e32 v89, 1.0, v89
	v_rcp_f32_e32 v89, v89
	v_sub_f32_e32 v77, 1.0, v120
	v_add_f32_e32 v121, 1.0, v120
	v_mul_f32_e32 v77, v77, v121
	v_max_f32_e32 v77, 0, v77
	v_sqrt_f32_e32 v77, v77
	s_nop 0
	v_mul_f32_e32 v77, v89, v77
	v_mul_f32_e32 v121, v77, v97
	v_add_f32_e32 v77, v123, v147
	v_mul_f32_e32 v77, 0xbfb8aa3b, v77
	v_exp_f32_e32 v77, v77
	v_add_f32_e32 v89, v143, v151
	v_mul_f32_e32 v89, 0xbfb8aa3b, v89
	v_exp_f32_e32 v89, v89
	v_add_f32_e32 v77, 1.0, v77
	v_rcp_f32_e32 v77, v77
	v_add_f32_e32 v89, 1.0, v89
	v_rcp_f32_e32 v89, v89
	v_mul_f32_e32 v77, 0xc1000000, v77
	v_mul_f32_e32 v77, v160, v77
	v_mul_f32_e32 v77, 0x3fb8aa3b, v77
	v_exp_f32_e32 v122, v77
	s_nop 0
	v_sub_f32_e32 v77, 1.0, v122
	v_add_f32_e32 v97, 1.0, v122
	v_mul_f32_e32 v77, v77, v97
	v_max_f32_e32 v77, 0, v77
	v_sqrt_f32_e32 v77, v77
	s_nop 0
	v_mul_f32_e32 v77, v89, v77
	v_mul_f32_e32 v123, v77, v109
	ds_write2_b64 v181, v[120:121], v[122:123] offset0:34 offset1:51
	global_load_dwordx4 v[144:147], v[154:155], off offset:64
	global_load_dwordx4 v[148:151], v[152:153], off offset:64
	v_mfma_f32_16x16x32_bf16 v[120:123], v[40:43], v[112:115], 0
	ds_read_b64 v[186:187], v2 offset:17440
	s_waitcnt lgkmcnt(0)
	v_lshlrev_b32_e32 v77, 16, v186
	v_mfma_f32_16x16x32_bf16 v[140:143], v[48:51], v[116:119], v[120:123]
	v_and_b32_e32 v89, 0xffff0000, v186
	v_lshlrev_b32_e32 v97, 16, v187
	v_and_b32_e32 v109, 0xffff0000, v187
	v_mfma_f32_16x16x32_bf16 v[120:123], v[36:39], v[112:115], 0
	v_mfma_f32_16x16x32_bf16 v[120:123], v[44:47], v[116:119], v[120:123]
	s_waitcnt vmcnt(1)
	s_nop 1
	v_add_f32_e32 v125, v140, v144
	v_mul_f32_e32 v125, 0xbfb8aa3b, v125
	v_exp_f32_e32 v125, v125
	s_waitcnt vmcnt(0)
	s_nop 0
	v_add_f32_e32 v120, v120, v148
	v_mul_f32_e32 v120, 0xbfb8aa3b, v120
	v_exp_f32_e32 v120, v120
	v_add_f32_e32 v125, 1.0, v125
	v_rcp_f32_e32 v125, v125
	v_add_f32_e32 v120, 1.0, v120
	v_rcp_f32_e32 v120, v120
	v_mul_f32_e32 v125, 0xc1000000, v125
	v_mul_f32_e32 v125, v161, v125
	v_mul_f32_e32 v125, 0x3fb8aa3b, v125
	v_exp_f32_e32 v186, v125
	s_nop 0
	v_sub_f32_e32 v125, 1.0, v186
	v_add_f32_e32 v133, 1.0, v186
	v_mul_f32_e32 v125, v125, v133
	v_max_f32_e32 v125, 0, v125
	v_sqrt_f32_e32 v125, v125
	s_nop 0
	v_mul_f32_e32 v120, v120, v125
	v_mul_f32_e32 v187, v120, v77
	v_add_f32_e32 v77, v141, v145
	v_mul_f32_e32 v77, 0xbfb8aa3b, v77
	v_exp_f32_e32 v77, v77
	v_add_f32_e32 v120, v121, v149
	v_mul_f32_e32 v120, 0xbfb8aa3b, v120
	v_exp_f32_e32 v120, v120
	v_add_f32_e32 v77, 1.0, v77
	v_rcp_f32_e32 v77, v77
	v_add_f32_e32 v120, 1.0, v120
	v_rcp_f32_e32 v121, v120
	v_mul_f32_e32 v77, 0xc1000000, v77
	v_mul_f32_e32 v77, v162, v77
	v_mul_f32_e32 v77, 0x3fb8aa3b, v77
	v_exp_f32_e32 v120, v77
	s_nop 0
	v_sub_f32_e32 v77, 1.0, v120
	v_add_f32_e32 v125, 1.0, v120
	v_mul_f32_e32 v77, v77, v125
	v_max_f32_e32 v77, 0, v77
	v_sqrt_f32_e32 v77, v77
	s_nop 0
	v_mul_f32_e32 v77, v121, v77
	v_mul_f32_e32 v121, v77, v89
	v_add_f32_e32 v77, v142, v146
	v_mul_f32_e32 v77, 0xbfb8aa3b, v77
	v_exp_f32_e32 v77, v77
	ds_write2_b64 v182, v[186:187], v[120:121] offset0:16 offset1:33
	v_add_f32_e32 v89, v122, v150
	v_mul_f32_e32 v89, 0xbfb8aa3b, v89
	v_add_f32_e32 v77, 1.0, v77
	v_rcp_f32_e32 v77, v77
	v_exp_f32_e32 v89, v89
	v_mul_f32_e32 v77, 0xc1000000, v77
	v_mul_f32_e32 v77, v164, v77
	v_mul_f32_e32 v77, 0x3fb8aa3b, v77
	v_exp_f32_e32 v120, v77
	v_add_f32_e32 v89, 1.0, v89
	v_rcp_f32_e32 v89, v89
	v_sub_f32_e32 v77, 1.0, v120
	v_add_f32_e32 v121, 1.0, v120
	v_mul_f32_e32 v77, v77, v121
	v_max_f32_e32 v77, 0, v77
	v_sqrt_f32_e32 v77, v77
	s_nop 0
	v_mul_f32_e32 v77, v89, v77
	v_mul_f32_e32 v121, v77, v97
	v_add_f32_e32 v77, v143, v147
	v_mul_f32_e32 v77, 0xbfb8aa3b, v77
	v_exp_f32_e32 v77, v77
	v_add_f32_e32 v89, v123, v151
	v_mul_f32_e32 v89, 0xbfb8aa3b, v89
	v_exp_f32_e32 v89, v89
	v_add_f32_e32 v77, 1.0, v77
	v_rcp_f32_e32 v77, v77
	v_add_f32_e32 v89, 1.0, v89
	v_rcp_f32_e32 v89, v89
	v_mul_f32_e32 v77, 0xc1000000, v77
	v_mul_f32_e32 v77, v166, v77
	v_mul_f32_e32 v77, 0x3fb8aa3b, v77
	v_exp_f32_e32 v122, v77
	s_nop 0
	v_sub_f32_e32 v77, 1.0, v122
	v_add_f32_e32 v97, 1.0, v122
	v_mul_f32_e32 v77, v77, v97
	v_max_f32_e32 v77, 0, v77
	v_sqrt_f32_e32 v77, v77
	s_nop 0
	v_mul_f32_e32 v77, v89, v77
	v_mul_f32_e32 v123, v77, v109
	ds_write2_b64 v182, v[120:121], v[122:123] offset0:50 offset1:67
	global_load_dwordx4 v[144:147], v[154:155], off offset:128
	global_load_dwordx4 v[148:151], v[152:153], off offset:128
	v_mfma_f32_16x16x32_bf16 v[120:123], v[24:27], v[112:115], 0
	ds_read_b64 v[186:187], v2 offset:17472
	s_waitcnt lgkmcnt(0)
	v_lshlrev_b32_e32 v77, 16, v186
	v_mfma_f32_16x16x32_bf16 v[140:143], v[32:35], v[116:119], v[120:123]
	v_and_b32_e32 v89, 0xffff0000, v186
	v_lshlrev_b32_e32 v97, 16, v187
	v_and_b32_e32 v109, 0xffff0000, v187
	v_mfma_f32_16x16x32_bf16 v[120:123], v[20:23], v[112:115], 0
	v_mfma_f32_16x16x32_bf16 v[120:123], v[28:31], v[116:119], v[120:123]
	s_waitcnt vmcnt(1)
	s_nop 1
	v_add_f32_e32 v125, v140, v144
	v_mul_f32_e32 v125, 0xbfb8aa3b, v125
	v_exp_f32_e32 v125, v125
	s_waitcnt vmcnt(0)
	s_nop 0
	v_add_f32_e32 v120, v120, v148
	v_mul_f32_e32 v120, 0xbfb8aa3b, v120
	v_exp_f32_e32 v120, v120
	v_add_f32_e32 v125, 1.0, v125
	v_rcp_f32_e32 v125, v125
	v_add_f32_e32 v120, 1.0, v120
	v_rcp_f32_e32 v120, v120
	v_mul_f32_e32 v125, 0xc1000000, v125
	v_mul_f32_e32 v125, v163, v125
	v_mul_f32_e32 v125, 0x3fb8aa3b, v125
	v_exp_f32_e32 v186, v125
	s_nop 0
	v_sub_f32_e32 v125, 1.0, v186
	v_add_f32_e32 v133, 1.0, v186
	v_mul_f32_e32 v125, v125, v133
	v_max_f32_e32 v125, 0, v125
	v_sqrt_f32_e32 v125, v125
	s_nop 0
	v_mul_f32_e32 v120, v120, v125
	v_mul_f32_e32 v187, v120, v77
	v_add_f32_e32 v77, v141, v145
	v_mul_f32_e32 v77, 0xbfb8aa3b, v77
	v_exp_f32_e32 v77, v77
	v_add_f32_e32 v120, v121, v149
	v_mul_f32_e32 v120, 0xbfb8aa3b, v120
	v_exp_f32_e32 v120, v120
	v_add_f32_e32 v77, 1.0, v77
	v_rcp_f32_e32 v77, v77
	v_add_f32_e32 v120, 1.0, v120
	v_rcp_f32_e32 v121, v120
	v_mul_f32_e32 v77, 0xc1000000, v77
	v_mul_f32_e32 v77, v165, v77
	v_mul_f32_e32 v77, 0x3fb8aa3b, v77
	v_exp_f32_e32 v120, v77
	s_nop 0
	v_sub_f32_e32 v77, 1.0, v120
	v_add_f32_e32 v125, 1.0, v120
	v_mul_f32_e32 v77, v77, v125
	v_max_f32_e32 v77, 0, v77
	v_sqrt_f32_e32 v77, v77
	s_nop 0
	v_mul_f32_e32 v77, v121, v77
	v_mul_f32_e32 v121, v77, v89
	v_add_f32_e32 v77, v142, v146
	v_mul_f32_e32 v77, 0xbfb8aa3b, v77
	v_exp_f32_e32 v77, v77
	ds_write2_b64 v183, v[186:187], v[120:121] offset0:32 offset1:49
	v_add_f32_e32 v89, v122, v150
	v_mul_f32_e32 v89, 0xbfb8aa3b, v89
	v_add_f32_e32 v77, 1.0, v77
	v_rcp_f32_e32 v77, v77
	v_exp_f32_e32 v89, v89
	v_mul_f32_e32 v77, 0xc1000000, v77
	v_mul_f32_e32 v77, v167, v77
	v_mul_f32_e32 v77, 0x3fb8aa3b, v77
	v_exp_f32_e32 v120, v77
	v_add_f32_e32 v89, 1.0, v89
	v_rcp_f32_e32 v89, v89
	v_sub_f32_e32 v77, 1.0, v120
	v_add_f32_e32 v121, 1.0, v120
	v_mul_f32_e32 v77, v77, v121
	v_max_f32_e32 v77, 0, v77
	v_sqrt_f32_e32 v77, v77
	s_nop 0
	v_mul_f32_e32 v77, v89, v77
	v_mul_f32_e32 v121, v77, v97
	v_add_f32_e32 v77, v143, v147
	v_mul_f32_e32 v77, 0xbfb8aa3b, v77
	v_exp_f32_e32 v77, v77
	v_add_f32_e32 v89, v123, v151
	v_mul_f32_e32 v89, 0xbfb8aa3b, v89
	v_exp_f32_e32 v89, v89
	v_add_f32_e32 v77, 1.0, v77
	v_rcp_f32_e32 v77, v77
	v_add_f32_e32 v89, 1.0, v89
	v_rcp_f32_e32 v89, v89
	v_mul_f32_e32 v77, 0xc1000000, v77
	v_mul_f32_e32 v77, v168, v77
	v_mul_f32_e32 v77, 0x3fb8aa3b, v77
	v_exp_f32_e32 v122, v77
	s_nop 0
	v_sub_f32_e32 v77, 1.0, v122
	v_add_f32_e32 v97, 1.0, v122
	v_mul_f32_e32 v77, v77, v97
	v_max_f32_e32 v77, 0, v77
	v_sqrt_f32_e32 v77, v77
	s_nop 0
	v_mul_f32_e32 v77, v89, v77
	v_mul_f32_e32 v123, v77, v109
	ds_write2_b64 v183, v[120:121], v[122:123] offset0:66 offset1:83
	v_mfma_f32_16x16x32_bf16 v[120:123], v[8:11], v[112:115], 0
	v_mfma_f32_16x16x32_bf16 v[112:115], v[4:7], v[112:115], 0
	v_mfma_f32_16x16x32_bf16 v[120:123], v[16:19], v[116:119], v[120:123]
	v_mfma_f32_16x16x32_bf16 v[112:115], v[12:15], v[116:119], v[112:115]
	global_load_dwordx4 v[116:119], v[154:155], off offset:192
	global_load_dwordx4 v[140:143], v[152:153], off offset:192
	ds_read_b64 v[144:145], v2 offset:17504
	s_waitcnt lgkmcnt(0)
	v_lshlrev_b32_e32 v77, 16, v144
	v_and_b32_e32 v89, 0xffff0000, v144
	v_lshlrev_b32_e32 v97, 16, v145
	v_and_b32_e32 v109, 0xffff0000, v145
	s_waitcnt vmcnt(1)
	v_add_f32_e32 v116, v120, v116
	v_mul_f32_e32 v116, 0xbfb8aa3b, v116
	v_exp_f32_e32 v116, v116
	s_waitcnt vmcnt(0)
	v_add_f32_e32 v112, v112, v140
	v_mul_f32_e32 v112, 0xbfb8aa3b, v112
	v_exp_f32_e32 v112, v112
	v_add_f32_e32 v116, 1.0, v116
	v_rcp_f32_e32 v116, v116
	v_add_f32_e32 v112, 1.0, v112
	v_rcp_f32_e32 v112, v112
	v_mul_f32_e32 v116, 0xc1000000, v116
	v_mul_f32_e32 v116, v169, v116
	v_mul_f32_e32 v116, 0x3fb8aa3b, v116
	v_exp_f32_e32 v144, v116
	s_nop 0
	v_sub_f32_e32 v116, 1.0, v144
	v_add_f32_e32 v120, 1.0, v144
	v_mul_f32_e32 v116, v116, v120
	v_max_f32_e32 v116, 0, v116
	v_sqrt_f32_e32 v116, v116
	s_nop 0
	v_mul_f32_e32 v112, v112, v116
	v_mul_f32_e32 v145, v112, v77
	v_add_f32_e32 v77, v121, v117
	v_mul_f32_e32 v77, 0xbfb8aa3b, v77
	v_exp_f32_e32 v77, v77
	v_add_f32_e32 v112, v113, v141
	v_mul_f32_e32 v112, 0xbfb8aa3b, v112
	v_exp_f32_e32 v112, v112
	v_add_f32_e32 v77, 1.0, v77
	v_rcp_f32_e32 v77, v77
	v_add_f32_e32 v112, 1.0, v112
	v_rcp_f32_e32 v113, v112
	v_mul_f32_e32 v77, 0xc1000000, v77
	v_mul_f32_e32 v77, v170, v77
	v_mul_f32_e32 v77, 0x3fb8aa3b, v77
	v_exp_f32_e32 v112, v77
	s_nop 0
	v_sub_f32_e32 v77, 1.0, v112
	v_add_f32_e32 v116, 1.0, v112
	v_mul_f32_e32 v77, v77, v116
	v_max_f32_e32 v77, 0, v77
	v_sqrt_f32_e32 v77, v77
	s_nop 0
	v_mul_f32_e32 v77, v113, v77
	v_mul_f32_e32 v113, v77, v89
	v_add_f32_e32 v77, v122, v118
	v_mul_f32_e32 v77, 0xbfb8aa3b, v77
	v_exp_f32_e32 v77, v77
	ds_write2_b64 v174, v[144:145], v[112:113] offset0:48 offset1:65
	v_add_f32_e32 v89, v114, v142
	v_mul_f32_e32 v89, 0xbfb8aa3b, v89
	v_add_f32_e32 v77, 1.0, v77
	v_rcp_f32_e32 v77, v77
	v_exp_f32_e32 v89, v89
	v_mul_f32_e32 v77, 0xc1000000, v77
	v_mul_f32_e32 v77, v171, v77
	v_mul_f32_e32 v77, 0x3fb8aa3b, v77
	v_exp_f32_e32 v112, v77
	v_add_f32_e32 v89, 1.0, v89
	v_rcp_f32_e32 v89, v89
	v_sub_f32_e32 v77, 1.0, v112
	v_add_f32_e32 v113, 1.0, v112
	v_mul_f32_e32 v77, v77, v113
	v_max_f32_e32 v77, 0, v77
	v_sqrt_f32_e32 v77, v77
	s_nop 0
	v_mul_f32_e32 v77, v89, v77
	v_mul_f32_e32 v113, v77, v97
	v_add_f32_e32 v77, v123, v119
	v_mul_f32_e32 v77, 0xbfb8aa3b, v77
	v_exp_f32_e32 v77, v77
	v_add_f32_e32 v89, v115, v143
	v_mul_f32_e32 v89, 0xbfb8aa3b, v89
	v_exp_f32_e32 v89, v89
	v_add_f32_e32 v77, 1.0, v77
	v_rcp_f32_e32 v77, v77
	v_add_f32_e32 v89, 1.0, v89
	v_rcp_f32_e32 v89, v89
	v_mul_f32_e32 v77, 0xc1000000, v77
	v_mul_f32_e32 v77, v172, v77
	v_mul_f32_e32 v77, 0x3fb8aa3b, v77
	v_exp_f32_e32 v114, v77
	s_nop 0
	v_sub_f32_e32 v77, 1.0, v114
	v_add_f32_e32 v97, 1.0, v114
	v_mul_f32_e32 v77, v77, v97
	v_max_f32_e32 v77, 0, v77
	v_sqrt_f32_e32 v77, v77
	s_nop 0
	v_mul_f32_e32 v77, v89, v77
	v_mul_f32_e32 v115, v77, v109
	ds_write2_b64 v174, v[112:113], v[114:115] offset0:82 offset1:99
	s_waitcnt lgkmcnt(0)
	s_barrier
	ds_read2_b64 v[116:119], v173 offset1:1
	v_mov_b32_e32 v112, v156
	v_mov_b32_e32 v114, v100
	v_pk_mul_f32 v[100:101], v[156:157], v[100:101]
	s_waitcnt lgkmcnt(0)
	v_fma_f32 v113, v69, v116, v117
	v_mov_b32_e32 v115, v118
	v_pk_mul_f32 v[140:141], v[100:101], v[102:103]
	v_pk_fma_f32 v[100:101], v[112:113], v[114:115], v[118:119]
	s_nop 0
	v_mov_b32_e32 v141, v101
	ds_read2_b64 v[120:123], v185 offset1:1
	ds_read2_b64 v[112:115], v184 offset1:1
	ds_read2_b64 v[100:103], v179 offset1:1
	s_waitcnt lgkmcnt(2)
	v_mov_b32_e32 v89, v120
	v_pk_mul_f32 v[142:143], v[140:141], v[88:89]
	v_pk_fma_f32 v[88:89], v[140:141], v[88:89], v[120:121]
	v_pk_mul_f32 v[90:91], v[142:143], v[90:91]
	v_mov_b32_e32 v140, v92
	v_mov_b32_e32 v88, v90
	v_mov_b32_e32 v141, v122
	v_pk_mul_f32 v[90:91], v[90:91], v[92:93]
	v_pk_fma_f32 v[88:89], v[88:89], v[140:141], v[122:123]
	v_pk_mul_f32 v[90:91], v[90:91], v[94:95]
	s_waitcnt lgkmcnt(1)
	v_mov_b32_e32 v97, v112
	v_mov_b32_e32 v91, v89
	v_pk_mul_f32 v[88:89], v[90:91], v[96:97]
	v_pk_fma_f32 v[90:91], v[90:91], v[96:97], v[112:113]
	v_pk_mul_f32 v[88:89], v[88:89], v[98:99]
	v_mov_b32_e32 v92, v104
	v_mov_b32_e32 v90, v88
	v_mov_b32_e32 v93, v114
	v_pk_mul_f32 v[88:89], v[88:89], v[104:105]
	v_pk_fma_f32 v[90:91], v[90:91], v[92:93], v[114:115]
	v_pk_mul_f32 v[88:89], v[88:89], v[106:107]
	s_waitcnt lgkmcnt(0)
	v_mov_b32_e32 v109, v100
	v_mov_b32_e32 v89, v91
	v_pk_mul_f32 v[90:91], v[88:89], v[108:109]
	v_pk_fma_f32 v[98:99], v[88:89], v[108:109], v[100:101]
	v_pk_mul_f32 v[96:97], v[90:91], v[110:111]
	ds_read2_b64 v[92:95], v176 offset1:1
	ds_read2_b64 v[88:91], v178 offset1:1
	v_mov_b32_e32 v98, v96
	v_mov_b32_e32 v104, v84
	v_mov_b32_e32 v105, v102
	v_pk_mul_f32 v[84:85], v[96:97], v[84:85]
	s_waitcnt lgkmcnt(1)
	v_mov_b32_e32 v125, v92
	v_pk_mul_f32 v[84:85], v[84:85], v[86:87]
	v_pk_fma_f32 v[86:87], v[98:99], v[104:105], v[102:103]
	v_mov_b32_e32 v96, v128
	v_mov_b32_e32 v85, v87
	v_pk_mul_f32 v[86:87], v[84:85], v[124:125]
	v_pk_fma_f32 v[84:85], v[84:85], v[124:125], v[92:93]
	v_pk_mul_f32 v[86:87], v[86:87], v[126:127]
	v_mov_b32_e32 v97, v94
	v_mov_b32_e32 v84, v86
	v_pk_mul_f32 v[86:87], v[86:87], v[128:129]
	v_pk_fma_f32 v[84:85], v[84:85], v[96:97], v[94:95]
	v_pk_mul_f32 v[86:87], v[86:87], v[130:131]
	s_waitcnt lgkmcnt(0)
	v_mov_b32_e32 v133, v88
	v_mov_b32_e32 v87, v85
	v_pk_mul_f32 v[84:85], v[86:87], v[132:133]
	v_pk_fma_f32 v[86:87], v[86:87], v[132:133], v[88:89]
	v_pk_mul_f32 v[84:85], v[84:85], v[134:135]
	v_mov_b32_e32 v96, v136
	v_mov_b32_e32 v86, v84
	v_mov_b32_e32 v97, v90
	v_pk_mul_f32 v[84:85], v[84:85], v[136:137]
	s_nop 0
	v_pk_mul_f32 v[124:125], v[84:85], v[138:139]
	v_pk_fma_f32 v[84:85], v[86:87], v[96:97], v[90:91]
	s_nop 0
	v_mov_b32_e32 v125, v85
	ds_read2_b64 v[96:99], v175 offset1:1
	ds_read2_b64 v[84:87], v177 offset1:1
	s_waitcnt lgkmcnt(0)
	s_barrier
	ds_read_b128 v[104:107], v180 offset:26112
	ds_read_b128 v[108:111], v180 offset:26176
	s_waitcnt lgkmcnt(1)
	v_mfma_f32_16x16x32_bf16 v[56:59], v[56:59], v[104:107], 0
	v_mfma_f32_16x16x32_bf16 v[52:55], v[52:55], v[104:107], 0
	s_waitcnt lgkmcnt(0)
	v_mfma_f32_16x16x32_bf16 v[56:59], v[64:67], v[108:111], v[56:59]
	v_mfma_f32_16x16x32_bf16 v[52:55], v[60:63], v[108:111], v[52:55]
	global_load_dwordx4 v[60:63], v[154:155], off
	global_load_dwordx4 v[64:67], v[152:153], off
	ds_read_b64 v[126:127], v2 offset:26112
	s_waitcnt lgkmcnt(0)
	v_lshlrev_b32_e32 v69, 16, v126
	v_and_b32_e32 v77, 0xffff0000, v126
	v_lshlrev_b32_e32 v93, 16, v127
	v_and_b32_e32 v113, 0xffff0000, v127
	v_mfma_f32_16x16x32_bf16 v[40:43], v[40:43], v[104:107], 0
	s_waitcnt vmcnt(1)
	v_add_f32_e32 v56, v56, v60
	v_mul_f32_e32 v56, 0xbfb8aa3b, v56
	v_exp_f32_e32 v56, v56
	s_waitcnt vmcnt(0)
	v_add_f32_e32 v52, v52, v64
	v_mul_f32_e32 v52, 0xbfb8aa3b, v52
	v_exp_f32_e32 v52, v52
	v_add_f32_e32 v56, 1.0, v56
	v_rcp_f32_e32 v56, v56
	v_mfma_f32_16x16x32_bf16 v[36:39], v[36:39], v[104:107], 0
	v_add_f32_e32 v52, 1.0, v52
	v_rcp_f32_e32 v52, v52
	v_mul_f32_e32 v56, 0xc1000000, v56
	v_mul_f32_e32 v1, v1, v56
	v_mul_f32_e32 v1, 0x3fb8aa3b, v1
	v_exp_f32_e32 v126, v1
	v_mfma_f32_16x16x32_bf16 v[40:43], v[48:51], v[108:111], v[40:43]
	v_sub_f32_e32 v1, 1.0, v126
	v_add_f32_e32 v56, 1.0, v126
	v_mul_f32_e32 v1, v1, v56
	v_max_f32_e32 v1, 0, v1
	v_sqrt_f32_e32 v1, v1
	v_mfma_f32_16x16x32_bf16 v[36:39], v[44:47], v[108:111], v[36:39]
	v_mul_f32_e32 v1, v52, v1
	v_mul_f32_e32 v127, v1, v69
	v_add_f32_e32 v1, v57, v61
	v_mul_f32_e32 v1, 0xbfb8aa3b, v1
	v_exp_f32_e32 v1, v1
	v_add_f32_e32 v52, v53, v65
	v_mul_f32_e32 v52, 0xbfb8aa3b, v52
	v_exp_f32_e32 v52, v52
	v_add_f32_e32 v1, 1.0, v1
	v_rcp_f32_e32 v1, v1
	v_mfma_f32_16x16x32_bf16 v[24:27], v[24:27], v[104:107], 0
	v_add_f32_e32 v52, 1.0, v52
	v_rcp_f32_e32 v53, v52
	v_mul_f32_e32 v1, 0xc1000000, v1
	v_mul_f32_e32 v1, v158, v1
	v_mul_f32_e32 v1, 0x3fb8aa3b, v1
	v_exp_f32_e32 v52, v1
	v_mfma_f32_16x16x32_bf16 v[20:23], v[20:23], v[104:107], 0
	v_mov_b32_e32 v69, v96
	v_sub_f32_e32 v1, 1.0, v52
	v_add_f32_e32 v56, 1.0, v52
	v_mul_f32_e32 v1, v1, v56
	v_max_f32_e32 v1, 0, v1
	v_sqrt_f32_e32 v1, v1
	v_mfma_f32_16x16x32_bf16 v[24:27], v[32:35], v[108:111], v[24:27]
	v_mul_f32_e32 v1, v53, v1
	v_mul_f32_e32 v53, v1, v77
	v_add_f32_e32 v1, v58, v62
	v_mul_f32_e32 v1, 0xbfb8aa3b, v1
	v_exp_f32_e32 v1, v1
	ds_write2_b64 v181, v[126:127], v[52:53] offset1:17
	v_add_f32_e32 v52, v54, v66
	v_mul_f32_e32 v52, 0xbfb8aa3b, v52
	v_add_f32_e32 v1, 1.0, v1
	v_rcp_f32_e32 v1, v1
	v_exp_f32_e32 v52, v52
	v_mfma_f32_16x16x32_bf16 v[20:23], v[28:31], v[108:111], v[20:23]
	v_mov_b32_e32 v77, v84
	v_mul_f32_e32 v1, 0xc1000000, v1
	v_mul_f32_e32 v1, v159, v1
	v_add_f32_e32 v52, 1.0, v52
	v_mul_f32_e32 v1, 0x3fb8aa3b, v1
	v_rcp_f32_e32 v53, v52
	v_exp_f32_e32 v52, v1
	v_mfma_f32_16x16x32_bf16 v[8:11], v[8:11], v[104:107], 0
	v_sub_f32_e32 v1, 1.0, v52
	v_add_f32_e32 v54, 1.0, v52
	v_mul_f32_e32 v1, v1, v54
	v_max_f32_e32 v1, 0, v1
	v_sqrt_f32_e32 v1, v1
	v_add_f32_e32 v54, v55, v67
	v_mul_f32_e32 v54, 0xbfb8aa3b, v54
	v_exp_f32_e32 v54, v54
	v_mul_f32_e32 v1, v53, v1
	v_mul_f32_e32 v53, v1, v93
	v_add_f32_e32 v1, v59, v63
	v_mul_f32_e32 v1, 0xbfb8aa3b, v1
	v_exp_f32_e32 v1, v1
	v_add_f32_e32 v54, 1.0, v54
	v_rcp_f32_e32 v55, v54
	v_mfma_f32_16x16x32_bf16 v[4:7], v[4:7], v[104:107], 0
	v_add_f32_e32 v1, 1.0, v1
	v_rcp_f32_e32 v1, v1
	v_mfma_f32_16x16x32_bf16 v[8:11], v[16:19], v[108:111], v[8:11]
	v_mul_f32_e32 v1, 0xc1000000, v1
	v_mul_f32_e32 v1, v160, v1
	v_mul_f32_e32 v1, 0x3fb8aa3b, v1
	v_exp_f32_e32 v54, v1
	v_mfma_f32_16x16x32_bf16 v[4:7], v[12:15], v[108:111], v[4:7]
	v_sub_f32_e32 v1, 1.0, v54
	v_add_f32_e32 v56, 1.0, v54
	v_mul_f32_e32 v1, v1, v56
	v_max_f32_e32 v1, 0, v1
	v_sqrt_f32_e32 v1, v1
	s_nop 0
	v_mul_f32_e32 v1, v55, v1
	v_mul_f32_e32 v55, v1, v113
	ds_write2_b64 v181, v[52:53], v[54:55] offset0:34 offset1:51
	global_load_dwordx4 v[44:47], v[154:155], off offset:64
	global_load_dwordx4 v[48:51], v[152:153], off offset:64
	ds_read_b64 v[52:53], v2 offset:26144
	s_waitcnt lgkmcnt(0)
	v_lshlrev_b32_e32 v1, 16, v52
	v_and_b32_e32 v54, 0xffff0000, v52
	v_lshlrev_b32_e32 v55, 16, v53
	v_and_b32_e32 v56, 0xffff0000, v53
	s_waitcnt vmcnt(1)
	v_add_f32_e32 v40, v40, v44
	v_mul_f32_e32 v40, 0xbfb8aa3b, v40
	v_exp_f32_e32 v40, v40
	s_waitcnt vmcnt(0)
	v_add_f32_e32 v36, v36, v48
	v_mul_f32_e32 v36, 0xbfb8aa3b, v36
	v_exp_f32_e32 v36, v36
	v_add_f32_e32 v40, 1.0, v40
	v_rcp_f32_e32 v40, v40
	v_add_f32_e32 v36, 1.0, v36
	v_rcp_f32_e32 v36, v36
	v_mul_f32_e32 v40, 0xc1000000, v40
	v_mul_f32_e32 v40, v161, v40
	v_mul_f32_e32 v40, 0x3fb8aa3b, v40
	v_exp_f32_e32 v52, v40
	s_nop 0
	v_sub_f32_e32 v40, 1.0, v52
	v_add_f32_e32 v44, 1.0, v52
	v_mul_f32_e32 v40, v40, v44
	v_max_f32_e32 v40, 0, v40
	v_sqrt_f32_e32 v40, v40
	s_nop 0
	v_mul_f32_e32 v36, v36, v40
	v_mul_f32_e32 v53, v36, v1
	v_add_f32_e32 v1, v41, v45
	v_mul_f32_e32 v1, 0xbfb8aa3b, v1
	v_exp_f32_e32 v1, v1
	v_add_f32_e32 v36, v37, v49
	v_mul_f32_e32 v36, 0xbfb8aa3b, v36
	v_exp_f32_e32 v36, v36
	v_add_f32_e32 v1, 1.0, v1
	v_rcp_f32_e32 v1, v1
	v_add_f32_e32 v36, 1.0, v36
	v_rcp_f32_e32 v37, v36
	v_mul_f32_e32 v1, 0xc1000000, v1
	v_mul_f32_e32 v1, v162, v1
	v_mul_f32_e32 v1, 0x3fb8aa3b, v1
	v_exp_f32_e32 v36, v1
	s_nop 0
	v_sub_f32_e32 v1, 1.0, v36
	v_add_f32_e32 v40, 1.0, v36
	v_mul_f32_e32 v1, v1, v40
	v_max_f32_e32 v1, 0, v1
	v_sqrt_f32_e32 v1, v1
	s_nop 0
	v_mul_f32_e32 v1, v37, v1
	v_mul_f32_e32 v37, v1, v54
	v_add_f32_e32 v1, v42, v46
	v_mul_f32_e32 v1, 0xbfb8aa3b, v1
	v_exp_f32_e32 v1, v1
	ds_write2_b64 v182, v[52:53], v[36:37] offset0:16 offset1:33
	v_add_f32_e32 v36, v38, v50
	v_mul_f32_e32 v36, 0xbfb8aa3b, v36
	v_add_f32_e32 v1, 1.0, v1
	v_rcp_f32_e32 v1, v1
	v_exp_f32_e32 v36, v36
	v_mul_f32_e32 v1, 0xc1000000, v1
	v_mul_f32_e32 v1, v164, v1
	v_add_f32_e32 v36, 1.0, v36
	v_mul_f32_e32 v1, 0x3fb8aa3b, v1
	v_rcp_f32_e32 v37, v36
	v_exp_f32_e32 v36, v1
	s_nop 0
	v_sub_f32_e32 v1, 1.0, v36
	v_add_f32_e32 v38, 1.0, v36
	v_mul_f32_e32 v1, v1, v38
	v_max_f32_e32 v1, 0, v1
	v_sqrt_f32_e32 v1, v1
	v_add_f32_e32 v38, v39, v51
	v_mul_f32_e32 v38, 0xbfb8aa3b, v38
	v_exp_f32_e32 v38, v38
	v_mul_f32_e32 v1, v37, v1
	v_mul_f32_e32 v37, v1, v55
	v_add_f32_e32 v1, v43, v47
	v_mul_f32_e32 v1, 0xbfb8aa3b, v1
	v_exp_f32_e32 v1, v1
	v_add_f32_e32 v38, 1.0, v38
	v_rcp_f32_e32 v39, v38
	v_add_f32_e32 v1, 1.0, v1
	v_rcp_f32_e32 v1, v1
	s_nop 0
	v_mul_f32_e32 v1, 0xc1000000, v1
	v_mul_f32_e32 v1, v166, v1
	v_mul_f32_e32 v1, 0x3fb8aa3b, v1
	v_exp_f32_e32 v38, v1
	s_nop 0
	v_sub_f32_e32 v1, 1.0, v38
	v_add_f32_e32 v40, 1.0, v38
	v_mul_f32_e32 v1, v1, v40
	v_max_f32_e32 v1, 0, v1
	v_sqrt_f32_e32 v1, v1
	s_nop 0
	v_mul_f32_e32 v1, v39, v1
	v_mul_f32_e32 v39, v1, v56
	ds_write2_b64 v182, v[36:37], v[38:39] offset0:50 offset1:67
	global_load_dwordx4 v[28:31], v[154:155], off offset:128
	global_load_dwordx4 v[32:35], v[152:153], off offset:128
	ds_read_b64 v[36:37], v2 offset:26176
	s_waitcnt lgkmcnt(0)
	v_lshlrev_b32_e32 v1, 16, v36
	v_and_b32_e32 v38, 0xffff0000, v36
	v_lshlrev_b32_e32 v39, 16, v37
	v_and_b32_e32 v40, 0xffff0000, v37
	s_waitcnt vmcnt(1)
	v_add_f32_e32 v24, v24, v28
	v_mul_f32_e32 v24, 0xbfb8aa3b, v24
	v_exp_f32_e32 v24, v24
	s_waitcnt vmcnt(0)
	v_add_f32_e32 v20, v20, v32
	v_mul_f32_e32 v20, 0xbfb8aa3b, v20
	v_exp_f32_e32 v20, v20
	v_add_f32_e32 v24, 1.0, v24
	v_rcp_f32_e32 v24, v24
	v_mov_b32_e32 v32, v84
	v_add_f32_e32 v20, 1.0, v20
	v_rcp_f32_e32 v20, v20
	v_mul_f32_e32 v24, 0xc1000000, v24
	v_mul_f32_e32 v24, v163, v24
	v_mul_f32_e32 v24, 0x3fb8aa3b, v24
	v_exp_f32_e32 v36, v24
	s_nop 0
	v_sub_f32_e32 v24, 1.0, v36
	v_add_f32_e32 v28, 1.0, v36
	v_mul_f32_e32 v24, v24, v28
	v_max_f32_e32 v24, 0, v24
	v_sqrt_f32_e32 v24, v24
	s_nop 0
	v_mul_f32_e32 v20, v20, v24
	v_mul_f32_e32 v37, v20, v1
	v_add_f32_e32 v1, v25, v29
	v_mul_f32_e32 v1, 0xbfb8aa3b, v1
	v_exp_f32_e32 v1, v1
	v_add_f32_e32 v20, v21, v33
	v_mul_f32_e32 v20, 0xbfb8aa3b, v20
	v_exp_f32_e32 v20, v20
	v_add_f32_e32 v1, 1.0, v1
	v_rcp_f32_e32 v1, v1
	v_add_f32_e32 v20, 1.0, v20
	v_rcp_f32_e32 v21, v20
	v_mul_f32_e32 v1, 0xc1000000, v1
	v_mul_f32_e32 v1, v165, v1
	v_mul_f32_e32 v1, 0x3fb8aa3b, v1
	v_exp_f32_e32 v20, v1
	s_nop 0
	v_sub_f32_e32 v1, 1.0, v20
	v_add_f32_e32 v24, 1.0, v20
	v_mul_f32_e32 v1, v1, v24
	v_max_f32_e32 v1, 0, v1
	v_sqrt_f32_e32 v1, v1
	s_nop 0
	v_mul_f32_e32 v1, v21, v1
	v_mul_f32_e32 v21, v1, v38
	v_add_f32_e32 v1, v26, v30
	v_mul_f32_e32 v1, 0xbfb8aa3b, v1
	v_exp_f32_e32 v1, v1
	ds_write2_b64 v183, v[36:37], v[20:21] offset0:32 offset1:49
	v_add_f32_e32 v20, v22, v34
	v_mul_f32_e32 v20, 0xbfb8aa3b, v20
	v_add_f32_e32 v1, 1.0, v1
	v_rcp_f32_e32 v1, v1
	v_exp_f32_e32 v20, v20
	v_mul_f32_e32 v1, 0xc1000000, v1
	v_mul_f32_e32 v1, v167, v1
	v_add_f32_e32 v20, 1.0, v20
	v_mul_f32_e32 v1, 0x3fb8aa3b, v1
	v_rcp_f32_e32 v21, v20
	v_exp_f32_e32 v20, v1
	s_nop 0
	v_sub_f32_e32 v1, 1.0, v20
	v_add_f32_e32 v22, 1.0, v20
	v_mul_f32_e32 v1, v1, v22
	v_max_f32_e32 v1, 0, v1
	v_sqrt_f32_e32 v1, v1
	v_add_f32_e32 v22, v23, v35
	v_mul_f32_e32 v22, 0xbfb8aa3b, v22
	v_exp_f32_e32 v22, v22
	v_mul_f32_e32 v1, v21, v1
	v_mul_f32_e32 v21, v1, v39
	v_add_f32_e32 v1, v27, v31
	v_mul_f32_e32 v1, 0xbfb8aa3b, v1
	v_exp_f32_e32 v1, v1
	v_add_f32_e32 v22, 1.0, v22
	v_rcp_f32_e32 v23, v22
	v_add_f32_e32 v1, 1.0, v1
	v_rcp_f32_e32 v1, v1
	s_nop 0
	v_mul_f32_e32 v1, 0xc1000000, v1
	v_mul_f32_e32 v1, v168, v1
	v_mul_f32_e32 v1, 0x3fb8aa3b, v1
	v_exp_f32_e32 v22, v1
	s_nop 0
	v_sub_f32_e32 v1, 1.0, v22
	v_add_f32_e32 v24, 1.0, v22
	v_mul_f32_e32 v1, v1, v24
	v_max_f32_e32 v1, 0, v1
	v_sqrt_f32_e32 v1, v1
	s_nop 0
	v_mul_f32_e32 v1, v23, v1
	v_mul_f32_e32 v23, v1, v40
	ds_write2_b64 v183, v[20:21], v[22:23] offset0:66 offset1:83
	global_load_dwordx4 v[12:15], v[154:155], off offset:192
	global_load_dwordx4 v[16:19], v[152:153], off offset:192
	ds_read_b64 v[20:21], v2 offset:26208
	s_waitcnt lgkmcnt(0)
	v_lshlrev_b32_e32 v1, 16, v20
	v_and_b32_e32 v2, 0xffff0000, v20
	v_lshlrev_b32_e32 v22, 16, v21
	v_and_b32_e32 v23, 0xffff0000, v21
	s_waitcnt vmcnt(1)
	v_add_f32_e32 v8, v8, v12
	v_mul_f32_e32 v8, 0xbfb8aa3b, v8
	v_exp_f32_e32 v8, v8
	s_waitcnt vmcnt(0)
	v_add_f32_e32 v4, v4, v16
	v_mul_f32_e32 v4, 0xbfb8aa3b, v4
	v_exp_f32_e32 v4, v4
	v_add_f32_e32 v8, 1.0, v8
	v_rcp_f32_e32 v8, v8
	v_add_f32_e32 v4, 1.0, v4
	v_rcp_f32_e32 v4, v4
	v_mul_f32_e32 v8, 0xc1000000, v8
	v_mul_f32_e32 v8, v169, v8
	v_mul_f32_e32 v8, 0x3fb8aa3b, v8
	v_exp_f32_e32 v20, v8
	s_nop 0
	v_sub_f32_e32 v8, 1.0, v20
	v_add_f32_e32 v12, 1.0, v20
	v_mul_f32_e32 v8, v8, v12
	v_max_f32_e32 v8, 0, v8
	v_sqrt_f32_e32 v8, v8
	v_mov_b32_e32 v12, v72
	v_mul_f32_e32 v4, v4, v8
	v_mul_f32_e32 v21, v4, v1
	v_add_f32_e32 v1, v9, v13
	v_mul_f32_e32 v1, 0xbfb8aa3b, v1
	v_exp_f32_e32 v1, v1
	v_add_f32_e32 v4, v5, v17
	v_mul_f32_e32 v4, 0xbfb8aa3b, v4
	v_exp_f32_e32 v4, v4
	v_add_f32_e32 v1, 1.0, v1
	v_rcp_f32_e32 v1, v1
	v_mov_b32_e32 v13, v98
	v_add_f32_e32 v4, 1.0, v4
	v_rcp_f32_e32 v5, v4
	v_mul_f32_e32 v1, 0xc1000000, v1
	v_mul_f32_e32 v1, v170, v1
	v_mul_f32_e32 v1, 0x3fb8aa3b, v1
	v_exp_f32_e32 v4, v1
	s_nop 0
	v_sub_f32_e32 v1, 1.0, v4
	v_add_f32_e32 v8, 1.0, v4
	v_mul_f32_e32 v1, v1, v8
	v_max_f32_e32 v1, 0, v1
	v_sqrt_f32_e32 v1, v1
	v_pk_mul_f32 v[8:9], v[124:125], v[68:69]
	v_mul_f32_e32 v1, v5, v1
	v_mul_f32_e32 v5, v1, v2
	v_add_f32_e32 v1, v10, v14
	v_mul_f32_e32 v1, 0xbfb8aa3b, v1
	v_exp_f32_e32 v1, v1
	ds_write2_b64 v174, v[20:21], v[4:5] offset0:48 offset1:65
	v_add_f32_e32 v2, v6, v18
	v_mul_f32_e32 v2, 0xbfb8aa3b, v2
	v_add_f32_e32 v1, 1.0, v1
	v_rcp_f32_e32 v1, v1
	v_exp_f32_e32 v2, v2
	v_pk_mul_f32 v[8:9], v[8:9], v[70:71]
	v_mov_b32_e32 v20, v120
	v_mul_f32_e32 v1, 0xc1000000, v1
	v_mul_f32_e32 v1, v171, v1
	v_mul_f32_e32 v1, 0x3fb8aa3b, v1
	v_exp_f32_e32 v4, v1
	v_add_f32_e32 v2, 1.0, v2
	v_rcp_f32_e32 v2, v2
	v_sub_f32_e32 v1, 1.0, v4
	v_add_f32_e32 v5, 1.0, v4
	v_mul_f32_e32 v1, v1, v5
	v_max_f32_e32 v1, 0, v1
	v_sqrt_f32_e32 v1, v1
	s_nop 0
	v_mul_f32_e32 v1, v2, v1
	v_mul_f32_e32 v5, v1, v22
	v_add_f32_e32 v1, v11, v15
	v_mul_f32_e32 v1, 0xbfb8aa3b, v1
	v_exp_f32_e32 v1, v1
	v_add_f32_e32 v2, v7, v19
	v_mul_f32_e32 v2, 0xbfb8aa3b, v2
	v_exp_f32_e32 v2, v2
	v_add_f32_e32 v1, 1.0, v1
	v_rcp_f32_e32 v1, v1
	v_pk_fma_f32 v[10:11], v[124:125], v[68:69], v[96:97]
	v_add_f32_e32 v2, 1.0, v2
	v_rcp_f32_e32 v2, v2
	v_mul_f32_e32 v1, 0xc1000000, v1
	v_mul_f32_e32 v1, v172, v1
	v_mul_f32_e32 v1, 0x3fb8aa3b, v1
	v_exp_f32_e32 v6, v1
	v_mov_b32_e32 v10, v8
	v_pk_mul_f32 v[8:9], v[8:9], v[72:73]
	v_pk_fma_f32 v[10:11], v[10:11], v[12:13], v[98:99]
	v_sub_f32_e32 v1, 1.0, v6
	v_add_f32_e32 v7, 1.0, v6
	v_mul_f32_e32 v1, v1, v7
	v_max_f32_e32 v1, 0, v1
	v_sqrt_f32_e32 v1, v1
	v_pk_mul_f32 v[8:9], v[8:9], v[74:75]
	v_mov_b32_e32 v12, v80
	v_mov_b32_e32 v9, v11
	v_mul_f32_e32 v1, v2, v1
	v_mul_f32_e32 v7, v1, v23
	ds_write2_b64 v174, v[4:5], v[6:7] offset0:82 offset1:99
	s_waitcnt lgkmcnt(0)
	s_barrier
	ds_read2_b64 v[4:7], v173 offset1:1
	v_pk_mul_f32 v[10:11], v[8:9], v[76:77]
	v_pk_fma_f32 v[8:9], v[8:9], v[76:77], v[84:85]
	v_pk_mul_f32 v[10:11], v[10:11], v[78:79]
	v_mov_b32_e32 v13, v86
	v_mov_b32_e32 v8, v10
	v_pk_mul_f32 v[10:11], v[10:11], v[80:81]
	v_pk_fma_f32 v[8:9], v[8:9], v[12:13], v[86:87]
	v_pk_mul_f32 v[10:11], v[10:11], v[82:83]
	s_waitcnt lgkmcnt(0)
	v_mov_b32_e32 v117, v4
	v_mov_b32_e32 v11, v9
	v_pk_mul_f32 v[8:9], v[10:11], v[116:117]
	v_pk_fma_f32 v[18:19], v[10:11], v[116:117], v[4:5]
	v_pk_mul_f32 v[16:17], v[8:9], v[118:119]
	ds_read2_b64 v[8:11], v185 offset1:1
	ds_read2_b64 v[12:15], v184 offset1:1
	v_mov_b32_e32 v18, v16
	v_mov_b32_e32 v21, v6
	v_pk_mul_f32 v[16:17], v[16:17], v[120:121]
	v_pk_fma_f32 v[18:19], v[18:19], v[20:21], v[6:7]
	v_pk_mul_f32 v[16:17], v[16:17], v[122:123]
	s_waitcnt lgkmcnt(1)
	v_mov_b32_e32 v113, v8
	v_mov_b32_e32 v17, v19
	v_pk_mul_f32 v[18:19], v[16:17], v[112:113]
	v_pk_fma_f32 v[16:17], v[16:17], v[112:113], v[8:9]
	v_pk_mul_f32 v[18:19], v[18:19], v[114:115]
	v_mov_b32_e32 v20, v100
	v_mov_b32_e32 v16, v18
	v_mov_b32_e32 v21, v10
	v_pk_mul_f32 v[18:19], v[18:19], v[100:101]
	v_pk_fma_f32 v[16:17], v[16:17], v[20:21], v[10:11]
	v_pk_mul_f32 v[18:19], v[18:19], v[102:103]
	s_waitcnt lgkmcnt(0)
	v_mov_b32_e32 v93, v12
	v_mov_b32_e32 v19, v17
	v_pk_mul_f32 v[16:17], v[18:19], v[92:93]
	v_pk_fma_f32 v[18:19], v[18:19], v[92:93], v[12:13]
	v_pk_mul_f32 v[16:17], v[16:17], v[94:95]
	v_mov_b32_e32 v20, v88
	v_mov_b32_e32 v18, v16
	v_mov_b32_e32 v21, v14
	v_pk_mul_f32 v[16:17], v[16:17], v[88:89]
	v_ashrrev_i32_e32 v1, 31, v0
	v_pk_mul_f32 v[28:29], v[16:17], v[90:91]
	v_pk_fma_f32 v[16:17], v[18:19], v[20:21], v[14:15]
	v_lshl_add_u64 v[0:1], v[0:1], 3, s[4:5]
	v_mov_b32_e32 v29, v17
	ds_read2_b64 v[16:19], v179 offset1:1
	ds_read2_b64 v[20:23], v176 offset1:1
	ds_read2_b64 v[24:27], v178 offset1:1
	v_readlane_b32 s4, v252, 56
	v_readlane_b32 s5, v252, 57
	s_waitcnt lgkmcnt(2)
	v_mov_b32_e32 v97, v16
	v_pk_mul_f32 v[30:31], v[28:29], v[96:97]
	v_pk_fma_f32 v[28:29], v[28:29], v[96:97], v[16:17]
	v_pk_mul_f32 v[30:31], v[30:31], v[98:99]
	v_mov_b32_e32 v33, v18
	v_mov_b32_e32 v28, v30
	v_pk_mul_f32 v[30:31], v[30:31], v[84:85]
	v_pk_fma_f32 v[28:29], v[28:29], v[32:33], v[18:19]
	v_pk_mul_f32 v[30:31], v[30:31], v[86:87]
	s_waitcnt lgkmcnt(1)
	v_mov_b32_e32 v5, v20
	v_mov_b32_e32 v31, v29
	v_pk_mul_f32 v[28:29], v[30:31], v[4:5]
	v_pk_fma_f32 v[4:5], v[30:31], v[4:5], v[20:21]
	v_pk_mul_f32 v[6:7], v[28:29], v[6:7]
	v_mov_b32_e32 v28, v8
	v_mov_b32_e32 v4, v6
	v_mov_b32_e32 v29, v22
	v_pk_mul_f32 v[6:7], v[6:7], v[8:9]
	v_pk_fma_f32 v[4:5], v[4:5], v[28:29], v[22:23]
	v_pk_mul_f32 v[6:7], v[6:7], v[10:11]
	s_waitcnt lgkmcnt(0)
	v_mov_b32_e32 v13, v24
	v_mov_b32_e32 v7, v5
	v_pk_mul_f32 v[4:5], v[6:7], v[12:13]
	v_pk_fma_f32 v[12:13], v[6:7], v[12:13], v[24:25]
	v_pk_mul_f32 v[14:15], v[4:5], v[14:15]
	ds_read2_b64 v[4:7], v175 offset1:1
	ds_read2_b64 v[8:11], v177 offset1:1
	v_mov_b32_e32 v12, v14
	v_mov_b32_e32 v28, v16
	v_mov_b32_e32 v29, v26
	v_pk_mul_f32 v[14:15], v[14:15], v[16:17]
	v_pk_fma_f32 v[12:13], v[12:13], v[28:29], v[26:27]
	v_pk_mul_f32 v[14:15], v[14:15], v[18:19]
	s_waitcnt lgkmcnt(1)
	v_mov_b32_e32 v21, v4
	v_mov_b32_e32 v15, v13
	v_pk_mul_f32 v[12:13], v[14:15], v[20:21]
	v_pk_fma_f32 v[14:15], v[14:15], v[20:21], v[4:5]
	v_pk_mul_f32 v[12:13], v[12:13], v[22:23]
	v_mov_b32_e32 v16, v24
	v_mov_b32_e32 v14, v12
	v_mov_b32_e32 v17, v6
	v_pk_mul_f32 v[12:13], v[12:13], v[24:25]
	v_pk_fma_f32 v[14:15], v[14:15], v[16:17], v[6:7]
	v_pk_mul_f32 v[12:13], v[12:13], v[26:27]
	s_waitcnt lgkmcnt(0)
	v_mov_b32_e32 v5, v8
	v_mov_b32_e32 v13, v15
	v_pk_mul_f32 v[14:15], v[12:13], v[4:5]
	v_pk_fma_f32 v[4:5], v[12:13], v[4:5], v[8:9]
	v_pk_mul_f32 v[6:7], v[14:15], v[6:7]
	v_mov_b32_e32 v12, v8
	v_mov_b32_e32 v4, v6
	v_mov_b32_e32 v13, v10
	v_pk_mul_f32 v[6:7], v[6:7], v[8:9]
	v_pk_fma_f32 v[4:5], v[4:5], v[12:13], v[10:11]
	v_pk_mul_f32 v[6:7], v[6:7], v[10:11]
	s_nop 0
	v_mov_b32_e32 v7, v5
	s_barrier
	global_store_dwordx2 v[0:1], v[6:7], off
	v_mov_b32_e32 v0, v222
	v_mov_b32_e32 v9, v3
	v_ashrrev_i32_e32 v1, 6, v0
	v_add_u32_e32 v4, s1, v1
	v_readlane_b32 s1, v252, 55
	v_ashrrev_i32_e32 v5, 31, v4
	v_bfe_u32 v81, v0, 4, 2
	v_add_u32_e32 v6, s1, v1
	v_lshlrev_b64 v[4:5], 13, v[4:5]
	v_ashrrev_i32_e32 v7, 31, v6
	v_and_b32_e32 v72, 0xffffffc0, v0
	v_and_b32_e32 v80, 15, v0
	v_lshl_add_u64 v[4:5], s[84:85], 0, v[4:5]
	v_lshlrev_b64 v[6:7], 13, v[6:7]
	v_lshlrev_b32_e32 v2, 4, v81
	v_ashrrev_i32_e32 v73, 31, v72
	v_lshl_add_u64 v[6:7], s[84:85], 0, v[6:7]
	v_lshl_add_u64 v[4:5], v[4:5], 0, v[2:3]
	v_lshlrev_b32_e32 v8, 7, v80
	v_lshlrev_b64 v[74:75], 2, v[72:73]
	v_lshl_add_u64 v[6:7], v[6:7], 0, v[2:3]
	v_lshl_add_u64 v[10:11], v[4:5], 0, v[8:9]
	v_lshl_add_u64 v[76:77], s[4:5], 0, v[74:75]
	v_readlane_b32 s4, v252, 58
	v_lshl_add_u64 v[12:13], v[6:7], 0, v[8:9]
	global_load_dwordx4 v[56:59], v[10:11], off
	global_load_dwordx4 v[52:55], v[12:13], off
	global_load_dwordx4 v[64:67], v[10:11], off offset:64
	global_load_dwordx4 v[60:63], v[12:13], off offset:64
	global_load_dwordx4 v[40:43], v[10:11], off offset:2048
	global_load_dwordx4 v[36:39], v[12:13], off offset:2048
	global_load_dwordx4 v[48:51], v[10:11], off offset:2112
	global_load_dwordx4 v[44:47], v[12:13], off offset:2112
	v_or_b32_e32 v10, 0x1000, v8
	v_mov_b32_e32 v11, v3
	v_readlane_b32 s5, v252, 59
	v_lshl_add_u64 v[12:13], v[4:5], 0, v[10:11]
	v_or_b32_e32 v8, 0x1800, v8
	v_lshl_add_u64 v[68:69], s[4:5], 0, v[74:75]
	v_lshl_add_u64 v[10:11], v[6:7], 0, v[10:11]
	global_load_dwordx4 v[24:27], v[12:13], off
	global_load_dwordx4 v[20:23], v[10:11], off
	global_load_dwordx4 v[32:35], v[12:13], off offset:64
	global_load_dwordx4 v[28:31], v[10:11], off offset:64
	v_lshl_add_u64 v[12:13], v[4:5], 0, v[8:9]
	v_lshl_add_u64 v[14:15], v[6:7], 0, v[8:9]
	v_lshl_add_u64 v[78:79], v[68:69], 0, v[2:3]
	global_load_dwordx4 v[8:11], v[12:13], off
	global_load_dwordx4 v[4:7], v[14:15], off
	global_load_dwordx4 v[16:19], v[12:13], off offset:64
	s_nop 0
	global_load_dwordx4 v[12:15], v[14:15], off offset:64
	v_readlane_b32 s4, v252, 60
	v_readlane_b32 s5, v252, 61
	s_movk_i32 s1, 0x218
	v_lshlrev_b32_e32 v113, 1, v72
	v_lshl_add_u64 v[152:153], v[76:77], 0, v[2:3]
	v_lshlrev_b32_e32 v112, 3, v81
	s_waitcnt vmcnt(0)
	s_lshl_b32 s98, s16, 11
	s_add_u32 s98, s98, 0x8400
	s_add_u32 s98, s30, s98
	s_addc_u32 s99, s31, 0
	v_lshrrev_b32_e32 v173, 4, v222
	v_and_b32_e32 v172, 3, v173
	v_lshrrev_b32_e32 v173, 2, v173
	v_lshlrev_b32_e32 v172, 4, v172
	v_lshl_or_b32 v173, v173, 8, v172
	global_load_dword v1, v173, s[98:99]
	global_load_dword v158, v173, s[98:99] offset:4
	global_load_dword v159, v173, s[98:99] offset:8
	global_load_dword v160, v173, s[98:99] offset:12
	global_load_dword v161, v173, s[98:99] offset:64
	global_load_dword v162, v173, s[98:99] offset:68
	global_load_dword v164, v173, s[98:99] offset:72
	global_load_dword v166, v173, s[98:99] offset:76
	global_load_dword v163, v173, s[98:99] offset:128
	global_load_dword v165, v173, s[98:99] offset:132
	global_load_dword v167, v173, s[98:99] offset:136
	global_load_dword v168, v173, s[98:99] offset:140
	global_load_dword v169, v173, s[98:99] offset:192
	global_load_dword v170, v173, s[98:99] offset:196
	global_load_dword v172, v173, s[98:99] offset:200
	global_load_dword v173, v173, s[98:99] offset:204
	v_lshl_add_u32 v92, v80, 3, 32
	v_lshl_or_b32 v93, v81, 2, v72
	v_lshl_add_u64 v[68:69], s[4:5], 0, v[74:75]
	v_lshl_add_u64 v[154:155], v[68:69], 0, v[2:3]
	v_mul_lo_u32 v68, v0, s10
	v_add_u32_e32 v108, 32, v68
	v_mad_u32_u24 v68, v80, s1, v92
	v_add3_u32 v176, v68, v113, v2
	ds_read_b128 v[68:71], v176 offset:26112
	ds_read_b128 v[72:75], v176 offset:26176
	global_load_dwordx4 v[84:87], v[154:155], off
	global_load_dwordx4 v[88:91], v[152:153], off
	s_waitcnt lgkmcnt(1)
	v_mfma_f32_16x16x32_bf16 v[76:79], v[56:59], v[68:71], 0
	v_sub_u32_e32 v174, v176, v112
	ds_read_b64 v[94:95], v174 offset:26112
	v_mad_u64_u32 v[92:93], s[4:5], v93, s10, v[92:93]
	s_waitcnt lgkmcnt(1)
	v_mfma_f32_16x16x32_bf16 v[80:83], v[64:67], v[72:75], v[76:79]
	v_add_u32_e32 v177, 0x8800, v92
	s_waitcnt lgkmcnt(0)
	v_lshlrev_b32_e32 v96, 16, v94
	v_and_b32_e32 v97, 0xffff0000, v94
	v_mfma_f32_16x16x32_bf16 v[76:79], v[52:55], v[68:71], 0
	v_lshlrev_b32_e32 v98, 16, v95
	v_and_b32_e32 v99, 0xffff0000, v95
	v_add_u32_e32 v178, 0x9000, v92
	v_mfma_f32_16x16x32_bf16 v[76:79], v[60:63], v[72:75], v[76:79]
	v_add_u32_e32 v179, 0x9800, v92
	v_add_u32_e32 v175, 0xa000, v92
	v_add_u32_e32 v183, 0x8870, v108
	v_add_u32_e32 v180, 0x8860, v108
	v_add_u32_e32 v182, 0x8850, v108
	v_add_u32_e32 v184, 0x8830, v108
	v_add_u32_e32 v181, 0x8840, v108
	v_add_u32_e32 v171, 0x8800, v108
	v_add_u32_e32 v186, 0x8820, v108
	v_add_u32_e32 v185, 0x8810, v108
	s_addc_u32 s1, s8, 0
	s_waitcnt vmcnt(1)
	v_add_f32_e32 v80, v80, v84
	v_mul_f32_e32 v80, 0xbfb8aa3b, v80
	v_exp_f32_e32 v80, v80
	s_waitcnt vmcnt(0)
	v_add_f32_e32 v76, v76, v88
	v_mul_f32_e32 v76, 0xbfb8aa3b, v76
	v_exp_f32_e32 v76, v76
	v_add_f32_e32 v80, 1.0, v80
	v_rcp_f32_e32 v80, v80
	v_add_f32_e32 v77, v77, v89
	v_add_f32_e32 v76, 1.0, v76
	v_rcp_f32_e32 v76, v76
	v_mul_f32_e32 v80, 0xc1000000, v80
	s_waitcnt vmcnt(0)
	v_mul_f32_e32 v80, v80, v1
	v_mul_f32_e32 v80, 0x3fb8aa3b, v80
	v_exp_f32_e32 v94, v80
	v_mul_f32_e32 v77, 0xbfb8aa3b, v77
	v_exp_f32_e32 v77, v77
	v_add_f32_e32 v79, v79, v91
	v_sub_f32_e32 v80, 1.0, v94
	v_add_f32_e32 v84, 1.0, v94
	v_mul_f32_e32 v80, v80, v84
	v_max_f32_e32 v80, 0, v80
	v_sqrt_f32_e32 v80, v80
	v_add_f32_e32 v77, 1.0, v77
	v_rcp_f32_e32 v77, v77
	v_mul_f32_e32 v79, 0xbfb8aa3b, v79
	v_mul_f32_e32 v76, v76, v80
	v_mul_f32_e32 v95, v76, v96
	v_add_f32_e32 v76, v81, v85
	v_mul_f32_e32 v76, 0xbfb8aa3b, v76
	v_exp_f32_e32 v76, v76
	v_exp_f32_e32 v79, v79
	v_add_f32_e32 v76, 1.0, v76
	v_rcp_f32_e32 v76, v76
	v_add_f32_e32 v79, 1.0, v79
	v_rcp_f32_e32 v79, v79
	v_mul_f32_e32 v76, 0xc1000000, v76
	v_mul_f32_e32 v76, v76, v158
	v_mul_f32_e32 v76, 0x3fb8aa3b, v76
	v_exp_f32_e32 v76, v76
	s_nop 0
	v_sub_f32_e32 v80, 1.0, v76
	v_add_f32_e32 v81, 1.0, v76
	v_mul_f32_e32 v80, v80, v81
	v_max_f32_e32 v80, 0, v80
	v_sqrt_f32_e32 v80, v80
	s_nop 0
	v_mul_f32_e32 v77, v77, v80
	v_mul_f32_e32 v77, v77, v97
	ds_write2_b64 v177, v[94:95], v[76:77] offset1:17
	v_add_f32_e32 v76, v82, v86
	v_mul_f32_e32 v76, 0xbfb8aa3b, v76
	v_exp_f32_e32 v76, v76
	v_add_f32_e32 v77, v78, v90
	v_mul_f32_e32 v77, 0xbfb8aa3b, v77
	v_exp_f32_e32 v77, v77
	v_add_f32_e32 v76, 1.0, v76
	v_rcp_f32_e32 v76, v76
	v_add_f32_e32 v77, 1.0, v77
	v_rcp_f32_e32 v77, v77
	v_mul_f32_e32 v76, 0xc1000000, v76
	v_mul_f32_e32 v76, v76, v159
	v_mul_f32_e32 v76, 0x3fb8aa3b, v76
	v_exp_f32_e32 v76, v76
	s_nop 0
	v_sub_f32_e32 v78, 1.0, v76
	v_add_f32_e32 v80, 1.0, v76
	v_mul_f32_e32 v78, v78, v80
	v_max_f32_e32 v78, 0, v78
	v_sqrt_f32_e32 v78, v78
	s_nop 0
	v_mul_f32_e32 v77, v77, v78
	v_add_f32_e32 v78, v83, v87
	v_mul_f32_e32 v78, 0xbfb8aa3b, v78
	v_exp_f32_e32 v78, v78
	v_mul_f32_e32 v77, v77, v98
	v_add_f32_e32 v78, 1.0, v78
	v_rcp_f32_e32 v78, v78
	s_nop 0
	v_mul_f32_e32 v78, 0xc1000000, v78
	v_mul_f32_e32 v78, v78, v160
	v_mul_f32_e32 v78, 0x3fb8aa3b, v78
	v_exp_f32_e32 v78, v78
	s_nop 0
	v_sub_f32_e32 v80, 1.0, v78
	v_add_f32_e32 v81, 1.0, v78
	v_mul_f32_e32 v80, v80, v81
	v_max_f32_e32 v80, 0, v80
	v_sqrt_f32_e32 v80, v80
	s_nop 0
	v_mul_f32_e32 v79, v79, v80
	v_mul_f32_e32 v79, v79, v99
	ds_write2_b64 v177, v[76:77], v[78:79] offset0:34 offset1:51
	global_load_dwordx4 v[84:87], v[154:155], off offset:64
	global_load_dwordx4 v[88:91], v[152:153], off offset:64
	v_mfma_f32_16x16x32_bf16 v[76:79], v[40:43], v[68:71], 0
	ds_read_b64 v[94:95], v174 offset:26144
	s_waitcnt lgkmcnt(0)
	v_lshlrev_b32_e32 v93, 16, v94
	v_mfma_f32_16x16x32_bf16 v[80:83], v[48:51], v[72:75], v[76:79]
	v_and_b32_e32 v96, 0xffff0000, v94
	v_lshlrev_b32_e32 v97, 16, v95
	v_and_b32_e32 v98, 0xffff0000, v95
	v_mfma_f32_16x16x32_bf16 v[76:79], v[36:39], v[68:71], 0
	v_mfma_f32_16x16x32_bf16 v[76:79], v[44:47], v[72:75], v[76:79]
	s_waitcnt vmcnt(1)
	s_nop 1
	v_add_f32_e32 v80, v80, v84
	v_mul_f32_e32 v80, 0xbfb8aa3b, v80
	v_exp_f32_e32 v80, v80
	s_waitcnt vmcnt(0)
	s_nop 0
	v_add_f32_e32 v76, v76, v88
	v_mul_f32_e32 v76, 0xbfb8aa3b, v76
	v_exp_f32_e32 v76, v76
	v_add_f32_e32 v80, 1.0, v80
	v_rcp_f32_e32 v80, v80
	v_add_f32_e32 v77, v77, v89
	v_add_f32_e32 v76, 1.0, v76
	v_rcp_f32_e32 v76, v76
	v_mul_f32_e32 v80, 0xc1000000, v80
	v_mul_f32_e32 v80, v80, v161
	v_mul_f32_e32 v80, 0x3fb8aa3b, v80
	v_exp_f32_e32 v94, v80
	v_mul_f32_e32 v77, 0xbfb8aa3b, v77
	v_exp_f32_e32 v77, v77
	v_add_f32_e32 v79, v79, v91
	v_sub_f32_e32 v80, 1.0, v94
	v_add_f32_e32 v84, 1.0, v94
	v_mul_f32_e32 v80, v80, v84
	v_max_f32_e32 v80, 0, v80
	v_sqrt_f32_e32 v80, v80
	v_add_f32_e32 v77, 1.0, v77
	v_rcp_f32_e32 v77, v77
	v_mul_f32_e32 v79, 0xbfb8aa3b, v79
	v_mul_f32_e32 v76, v76, v80
	v_mul_f32_e32 v95, v76, v93
	v_add_f32_e32 v76, v81, v85
	v_mul_f32_e32 v76, 0xbfb8aa3b, v76
	v_exp_f32_e32 v76, v76
	v_exp_f32_e32 v79, v79
	v_add_f32_e32 v76, 1.0, v76
	v_rcp_f32_e32 v76, v76
	v_add_f32_e32 v79, 1.0, v79
	v_rcp_f32_e32 v79, v79
	v_mul_f32_e32 v76, 0xc1000000, v76
	v_mul_f32_e32 v76, v76, v162
	v_mul_f32_e32 v76, 0x3fb8aa3b, v76
	v_exp_f32_e32 v76, v76
	s_nop 0
	v_sub_f32_e32 v80, 1.0, v76
	v_add_f32_e32 v81, 1.0, v76
	v_mul_f32_e32 v80, v80, v81
	v_max_f32_e32 v80, 0, v80
	v_sqrt_f32_e32 v80, v80
	s_nop 0
	v_mul_f32_e32 v77, v77, v80
	v_mul_f32_e32 v77, v77, v96
	ds_write2_b64 v178, v[94:95], v[76:77] offset0:16 offset1:33
	v_add_f32_e32 v76, v82, v86
	v_mul_f32_e32 v76, 0xbfb8aa3b, v76
	v_exp_f32_e32 v76, v76
	v_add_f32_e32 v77, v78, v90
	v_mul_f32_e32 v77, 0xbfb8aa3b, v77
	v_exp_f32_e32 v77, v77
	v_add_f32_e32 v76, 1.0, v76
	v_rcp_f32_e32 v76, v76
	v_add_f32_e32 v77, 1.0, v77
	v_rcp_f32_e32 v77, v77
	v_mul_f32_e32 v76, 0xc1000000, v76
	v_mul_f32_e32 v76, v76, v164
	v_mul_f32_e32 v76, 0x3fb8aa3b, v76
	v_exp_f32_e32 v76, v76
	s_nop 0
	v_sub_f32_e32 v78, 1.0, v76
	v_add_f32_e32 v80, 1.0, v76
	v_mul_f32_e32 v78, v78, v80
	v_max_f32_e32 v78, 0, v78
	v_sqrt_f32_e32 v78, v78
	s_nop 0
	v_mul_f32_e32 v77, v77, v78
	v_add_f32_e32 v78, v83, v87
	v_mul_f32_e32 v78, 0xbfb8aa3b, v78
	v_exp_f32_e32 v78, v78
	v_mul_f32_e32 v77, v77, v97
	v_add_f32_e32 v78, 1.0, v78
	v_rcp_f32_e32 v78, v78
	s_nop 0
	v_mul_f32_e32 v78, 0xc1000000, v78
	v_mul_f32_e32 v78, v78, v166
	v_mul_f32_e32 v78, 0x3fb8aa3b, v78
	v_exp_f32_e32 v78, v78
	s_nop 0
	v_sub_f32_e32 v80, 1.0, v78
	v_add_f32_e32 v81, 1.0, v78
	v_mul_f32_e32 v80, v80, v81
	v_max_f32_e32 v80, 0, v80
	v_sqrt_f32_e32 v80, v80
	s_nop 0
	v_mul_f32_e32 v79, v79, v80
	v_mul_f32_e32 v79, v79, v98
	ds_write2_b64 v178, v[76:77], v[78:79] offset0:50 offset1:67
	global_load_dwordx4 v[84:87], v[154:155], off offset:128
	global_load_dwordx4 v[88:91], v[152:153], off offset:128
	v_mfma_f32_16x16x32_bf16 v[76:79], v[24:27], v[68:71], 0
	ds_read_b64 v[94:95], v174 offset:26176
	s_waitcnt lgkmcnt(0)
	v_lshlrev_b32_e32 v93, 16, v94
	v_mfma_f32_16x16x32_bf16 v[80:83], v[32:35], v[72:75], v[76:79]
	v_and_b32_e32 v96, 0xffff0000, v94
	v_lshlrev_b32_e32 v97, 16, v95
	v_and_b32_e32 v98, 0xffff0000, v95
	v_mfma_f32_16x16x32_bf16 v[76:79], v[20:23], v[68:71], 0
	v_mfma_f32_16x16x32_bf16 v[76:79], v[28:31], v[72:75], v[76:79]
	s_waitcnt vmcnt(1)
	s_nop 1
	v_add_f32_e32 v80, v80, v84
	v_mul_f32_e32 v80, 0xbfb8aa3b, v80
	v_exp_f32_e32 v80, v80
	s_waitcnt vmcnt(0)
	s_nop 0
	v_add_f32_e32 v76, v76, v88
	v_mul_f32_e32 v76, 0xbfb8aa3b, v76
	v_exp_f32_e32 v76, v76
	v_add_f32_e32 v80, 1.0, v80
	v_rcp_f32_e32 v80, v80
	v_add_f32_e32 v77, v77, v89
	v_add_f32_e32 v76, 1.0, v76
	v_rcp_f32_e32 v76, v76
	v_mul_f32_e32 v80, 0xc1000000, v80
	v_mul_f32_e32 v80, v80, v163
	v_mul_f32_e32 v80, 0x3fb8aa3b, v80
	v_exp_f32_e32 v94, v80
	v_mul_f32_e32 v77, 0xbfb8aa3b, v77
	v_exp_f32_e32 v77, v77
	v_add_f32_e32 v79, v79, v91
	v_sub_f32_e32 v80, 1.0, v94
	v_add_f32_e32 v84, 1.0, v94
	v_mul_f32_e32 v80, v80, v84
	v_max_f32_e32 v80, 0, v80
	v_sqrt_f32_e32 v80, v80
	v_add_f32_e32 v77, 1.0, v77
	v_rcp_f32_e32 v77, v77
	v_mul_f32_e32 v79, 0xbfb8aa3b, v79
	v_mul_f32_e32 v76, v76, v80
	v_mul_f32_e32 v95, v76, v93
	v_add_f32_e32 v76, v81, v85
	v_mul_f32_e32 v76, 0xbfb8aa3b, v76
	v_exp_f32_e32 v76, v76
	v_exp_f32_e32 v79, v79
	v_add_f32_e32 v76, 1.0, v76
	v_rcp_f32_e32 v76, v76
	v_add_f32_e32 v79, 1.0, v79
	v_rcp_f32_e32 v79, v79
	v_mul_f32_e32 v76, 0xc1000000, v76
	v_mul_f32_e32 v76, v76, v165
	v_mul_f32_e32 v76, 0x3fb8aa3b, v76
	v_exp_f32_e32 v76, v76
	s_nop 0
	v_sub_f32_e32 v80, 1.0, v76
	v_add_f32_e32 v81, 1.0, v76
	v_mul_f32_e32 v80, v80, v81
	v_max_f32_e32 v80, 0, v80
	v_sqrt_f32_e32 v80, v80
	s_nop 0
	v_mul_f32_e32 v77, v77, v80
	v_mul_f32_e32 v77, v77, v96
	ds_write2_b64 v179, v[94:95], v[76:77] offset0:32 offset1:49
	v_add_f32_e32 v76, v82, v86
	v_mul_f32_e32 v76, 0xbfb8aa3b, v76
	v_exp_f32_e32 v76, v76
	v_add_f32_e32 v77, v78, v90
	v_mul_f32_e32 v77, 0xbfb8aa3b, v77
	v_exp_f32_e32 v77, v77
	v_add_f32_e32 v76, 1.0, v76
	v_rcp_f32_e32 v76, v76
	v_add_f32_e32 v77, 1.0, v77
	v_rcp_f32_e32 v77, v77
	v_mul_f32_e32 v76, 0xc1000000, v76
	v_mul_f32_e32 v76, v76, v167
	v_mul_f32_e32 v76, 0x3fb8aa3b, v76
	v_exp_f32_e32 v76, v76
	s_nop 0
	v_sub_f32_e32 v78, 1.0, v76
	v_add_f32_e32 v80, 1.0, v76
	v_mul_f32_e32 v78, v78, v80
	v_max_f32_e32 v78, 0, v78
	v_sqrt_f32_e32 v78, v78
	s_nop 0
	v_mul_f32_e32 v77, v77, v78
	v_add_f32_e32 v78, v83, v87
	v_mul_f32_e32 v78, 0xbfb8aa3b, v78
	v_exp_f32_e32 v78, v78
	v_mul_f32_e32 v77, v77, v97
	v_add_f32_e32 v78, 1.0, v78
	v_rcp_f32_e32 v78, v78
	s_nop 0
	v_mul_f32_e32 v78, 0xc1000000, v78
	v_mul_f32_e32 v78, v78, v168
	v_mul_f32_e32 v78, 0x3fb8aa3b, v78
	v_exp_f32_e32 v78, v78
	s_nop 0
	v_sub_f32_e32 v80, 1.0, v78
	v_add_f32_e32 v81, 1.0, v78
	v_mul_f32_e32 v80, v80, v81
	v_max_f32_e32 v80, 0, v80
	v_sqrt_f32_e32 v80, v80
	s_nop 0
	v_mul_f32_e32 v79, v79, v80
	v_mul_f32_e32 v79, v79, v98
	ds_write2_b64 v179, v[76:77], v[78:79] offset0:66 offset1:83
	v_mfma_f32_16x16x32_bf16 v[76:79], v[8:11], v[68:71], 0
	v_mfma_f32_16x16x32_bf16 v[68:71], v[4:7], v[68:71], 0
	v_mfma_f32_16x16x32_bf16 v[76:79], v[16:19], v[72:75], v[76:79]
	v_mfma_f32_16x16x32_bf16 v[68:71], v[12:15], v[72:75], v[68:71]
	global_load_dwordx4 v[72:75], v[154:155], off offset:192
	global_load_dwordx4 v[80:83], v[152:153], off offset:192
	ds_read_b64 v[84:85], v174 offset:26208
	s_waitcnt lgkmcnt(0)
	v_lshlrev_b32_e32 v86, 16, v84
	v_and_b32_e32 v87, 0xffff0000, v84
	v_lshlrev_b32_e32 v88, 16, v85
	v_and_b32_e32 v89, 0xffff0000, v85
	s_waitcnt vmcnt(1)
	v_add_f32_e32 v72, v76, v72
	v_mul_f32_e32 v72, 0xbfb8aa3b, v72
	v_exp_f32_e32 v72, v72
	s_waitcnt vmcnt(0)
	v_add_f32_e32 v68, v68, v80
	v_mul_f32_e32 v68, 0xbfb8aa3b, v68
	v_exp_f32_e32 v68, v68
	v_add_f32_e32 v72, 1.0, v72
	v_rcp_f32_e32 v72, v72
	v_add_f32_e32 v69, v69, v81
	v_add_f32_e32 v68, 1.0, v68
	v_rcp_f32_e32 v68, v68
	v_mul_f32_e32 v72, 0xc1000000, v72
	v_mul_f32_e32 v72, v169, v72
	v_mul_f32_e32 v72, 0x3fb8aa3b, v72
	v_exp_f32_e32 v84, v72
	v_mul_f32_e32 v69, 0xbfb8aa3b, v69
	v_exp_f32_e32 v69, v69
	v_add_f32_e32 v71, v71, v83
	v_sub_f32_e32 v72, 1.0, v84
	v_add_f32_e32 v76, 1.0, v84
	v_mul_f32_e32 v72, v72, v76
	v_max_f32_e32 v72, 0, v72
	v_sqrt_f32_e32 v72, v72
	v_add_f32_e32 v69, 1.0, v69
	v_rcp_f32_e32 v69, v69
	v_mul_f32_e32 v71, 0xbfb8aa3b, v71
	v_mul_f32_e32 v68, v68, v72
	v_mul_f32_e32 v85, v68, v86
	v_add_f32_e32 v68, v77, v73
	v_mul_f32_e32 v68, 0xbfb8aa3b, v68
	v_exp_f32_e32 v68, v68
	v_exp_f32_e32 v71, v71
	v_add_f32_e32 v68, 1.0, v68
	v_rcp_f32_e32 v68, v68
	v_add_f32_e32 v71, 1.0, v71
	v_rcp_f32_e32 v71, v71
	v_mul_f32_e32 v68, 0xc1000000, v68
	v_mul_f32_e32 v68, v170, v68
	v_mul_f32_e32 v68, 0x3fb8aa3b, v68
	v_exp_f32_e32 v68, v68
	s_nop 0
	v_sub_f32_e32 v72, 1.0, v68
	v_add_f32_e32 v73, 1.0, v68
	v_mul_f32_e32 v72, v72, v73
	v_max_f32_e32 v72, 0, v72
	v_sqrt_f32_e32 v72, v72
	s_nop 0
	v_mul_f32_e32 v69, v69, v72
	v_mul_f32_e32 v69, v69, v87
	ds_write2_b64 v175, v[84:85], v[68:69] offset0:48 offset1:65
	v_add_f32_e32 v68, v78, v74
	v_mul_f32_e32 v68, 0xbfb8aa3b, v68
	v_exp_f32_e32 v68, v68
	v_add_f32_e32 v69, v70, v82
	v_mul_f32_e32 v69, 0xbfb8aa3b, v69
	v_exp_f32_e32 v69, v69
	v_add_f32_e32 v68, 1.0, v68
	v_rcp_f32_e32 v68, v68
	v_add_f32_e32 v69, 1.0, v69
	v_rcp_f32_e32 v69, v69
	v_mul_f32_e32 v68, 0xc1000000, v68
	v_mul_f32_e32 v68, v172, v68
	v_mul_f32_e32 v68, 0x3fb8aa3b, v68
	v_exp_f32_e32 v68, v68
	s_nop 0
	v_sub_f32_e32 v70, 1.0, v68
	v_add_f32_e32 v72, 1.0, v68
	v_mul_f32_e32 v70, v70, v72
	v_max_f32_e32 v70, 0, v70
	v_sqrt_f32_e32 v70, v70
	s_nop 0
	v_mul_f32_e32 v69, v69, v70
	v_add_f32_e32 v70, v79, v75
	v_mul_f32_e32 v70, 0xbfb8aa3b, v70
	v_exp_f32_e32 v70, v70
	v_mul_f32_e32 v69, v69, v88
	v_add_f32_e32 v70, 1.0, v70
	v_rcp_f32_e32 v70, v70
	s_nop 0
	v_mul_f32_e32 v70, 0xc1000000, v70
	v_mul_f32_e32 v70, v173, v70
	v_mul_f32_e32 v70, 0x3fb8aa3b, v70
	v_exp_f32_e32 v70, v70
	s_nop 0
	v_sub_f32_e32 v72, 1.0, v70
	v_add_f32_e32 v73, 1.0, v70
	v_mul_f32_e32 v72, v72, v73
	v_max_f32_e32 v72, 0, v72
	v_sqrt_f32_e32 v72, v72
	s_nop 0
	v_mul_f32_e32 v71, v71, v72
	v_mul_f32_e32 v71, v71, v89
	ds_write2_b64 v175, v[68:69], v[70:71] offset0:82 offset1:99
	s_waitcnt lgkmcnt(0)
	s_barrier
	ds_read2_b64 v[68:71], v183 offset1:1
	ds_read2_b64 v[96:99], v184 offset1:1
	ds_read2_b64 v[104:107], v180 offset1:1
	ds_read2_b64 v[84:87], v171 offset1:1
	ds_read2_b64 v[88:91], v182 offset1:1
	ds_read2_b64 v[92:95], v181 offset1:1
	s_waitcnt lgkmcnt(5)
	v_fma_f32 v72, 0, v70, v71
	v_pk_mul_f32 v[156:157], v[70:71], v[68:69]
	v_fmac_f32_e32 v69, v68, v72
	s_waitcnt lgkmcnt(3)
	v_fma_f32 v68, v106, v69, v107
	v_fma_f32 v68, v104, v68, v105
	s_waitcnt lgkmcnt(1)
	v_fma_f32 v68, v90, v68, v91
	v_fma_f32 v68, v88, v68, v89
	ds_read2_b64 v[100:103], v186 offset1:1
	ds_read2_b64 v[108:111], v185 offset1:1
	s_waitcnt lgkmcnt(2)
	v_fma_f32 v68, v94, v68, v95
	v_fma_f32 v68, v92, v68, v93
	v_fma_f32 v68, v98, v68, v99
	v_fma_f32 v68, v96, v68, v97
	s_waitcnt lgkmcnt(1)
	v_fma_f32 v68, v102, v68, v103
	v_fma_f32 v68, v100, v68, v101
	s_waitcnt lgkmcnt(0)
	v_fma_f32 v68, v110, v68, v111
	v_fma_f32 v68, v108, v68, v109
	v_fma_f32 v68, v86, v68, v87
	v_fma_f32 v91, v84, v68, v85
	v_or_b32_e32 v68, 0xfffff0, v0
	v_mad_i32_i24 v68, v68, s9, 32
	v_add3_u32 v2, v68, v113, v2
	s_barrier
	ds_read_b128 v[68:71], v2 offset:26112
	ds_read_b128 v[72:75], v2 offset:26176
	v_sub_u32_e32 v2, v2, v112
	global_load_dwordx4 v[112:115], v[154:155], off
	global_load_dwordx4 v[116:119], v[152:153], off
	s_waitcnt lgkmcnt(1)
	v_mfma_f32_16x16x32_bf16 v[76:79], v[56:59], v[68:71], 0
	ds_read_b64 v[120:121], v2 offset:26112
	s_waitcnt lgkmcnt(0)
	v_lshlrev_b32_e32 v99, 16, v120
	v_mfma_f32_16x16x32_bf16 v[76:79], v[64:67], v[72:75], v[76:79]
	v_and_b32_e32 v111, 0xffff0000, v120
	v_lshlrev_b32_e32 v122, 16, v121
	v_and_b32_e32 v123, 0xffff0000, v121
	v_mfma_f32_16x16x32_bf16 v[80:83], v[52:55], v[68:71], 0
	v_mfma_f32_16x16x32_bf16 v[80:83], v[60:63], v[72:75], v[80:83]
	s_waitcnt vmcnt(1)
	s_nop 1
	v_add_f32_e32 v76, v76, v112
	v_mul_f32_e32 v76, 0xbfb8aa3b, v76
	v_exp_f32_e32 v76, v76
	s_waitcnt vmcnt(0)
	s_nop 0
	v_add_f32_e32 v80, v80, v116
	v_mul_f32_e32 v80, 0xbfb8aa3b, v80
	v_exp_f32_e32 v80, v80
	v_add_f32_e32 v76, 1.0, v76
	v_rcp_f32_e32 v76, v76
	v_add_f32_e32 v80, 1.0, v80
	v_rcp_f32_e32 v80, v80
	v_mul_f32_e32 v76, 0xc1000000, v76
	v_mul_f32_e32 v76, v1, v76
	v_mul_f32_e32 v76, 0x3fb8aa3b, v76
	v_exp_f32_e32 v120, v76
	s_nop 0
	v_sub_f32_e32 v76, 1.0, v120
	v_add_f32_e32 v112, 1.0, v120
	v_mul_f32_e32 v76, v76, v112
	v_max_f32_e32 v76, 0, v76
	v_sqrt_f32_e32 v76, v76
	s_nop 0
	v_mul_f32_e32 v76, v80, v76
	v_mul_f32_e32 v121, v76, v99
	v_add_f32_e32 v76, v77, v113
	v_mul_f32_e32 v76, 0xbfb8aa3b, v76
	v_exp_f32_e32 v76, v76
	v_add_f32_e32 v77, v81, v117
	v_mul_f32_e32 v77, 0xbfb8aa3b, v77
	v_exp_f32_e32 v77, v77
	v_add_f32_e32 v76, 1.0, v76
	v_rcp_f32_e32 v76, v76
	v_add_f32_e32 v77, 1.0, v77
	v_rcp_f32_e32 v77, v77
	v_mul_f32_e32 v76, 0xc1000000, v76
	v_mul_f32_e32 v76, v158, v76
	v_mul_f32_e32 v76, 0x3fb8aa3b, v76
	v_exp_f32_e32 v76, v76
	s_nop 0
	v_sub_f32_e32 v80, 1.0, v76
	v_add_f32_e32 v81, 1.0, v76
	v_mul_f32_e32 v80, v80, v81
	v_max_f32_e32 v80, 0, v80
	v_sqrt_f32_e32 v80, v80
	s_nop 0
	v_mul_f32_e32 v77, v77, v80
	v_mul_f32_e32 v77, v77, v111
	ds_write2_b64 v177, v[120:121], v[76:77] offset1:17
	v_add_f32_e32 v76, v78, v114
	v_mul_f32_e32 v76, 0xbfb8aa3b, v76
	v_exp_f32_e32 v76, v76
	v_add_f32_e32 v77, v82, v118
	v_mul_f32_e32 v77, 0xbfb8aa3b, v77
	v_exp_f32_e32 v77, v77
	v_add_f32_e32 v76, 1.0, v76
	v_rcp_f32_e32 v76, v76
	v_add_f32_e32 v77, 1.0, v77
	v_rcp_f32_e32 v77, v77
	v_mul_f32_e32 v76, 0xc1000000, v76
	v_mul_f32_e32 v76, v159, v76
	v_mul_f32_e32 v76, 0x3fb8aa3b, v76
	v_exp_f32_e32 v76, v76
	s_nop 0
	v_sub_f32_e32 v78, 1.0, v76
	v_add_f32_e32 v80, 1.0, v76
	v_mul_f32_e32 v78, v78, v80
	v_max_f32_e32 v78, 0, v78
	v_sqrt_f32_e32 v78, v78
	s_nop 0
	v_mul_f32_e32 v77, v77, v78
	v_add_f32_e32 v78, v79, v115
	v_mul_f32_e32 v78, 0xbfb8aa3b, v78
	v_exp_f32_e32 v78, v78
	v_add_f32_e32 v79, v83, v119
	v_mul_f32_e32 v79, 0xbfb8aa3b, v79
	v_exp_f32_e32 v79, v79
	v_add_f32_e32 v78, 1.0, v78
	v_rcp_f32_e32 v78, v78
	v_mul_f32_e32 v77, v77, v122
	v_add_f32_e32 v79, 1.0, v79
	v_rcp_f32_e32 v79, v79
	v_mul_f32_e32 v78, 0xc1000000, v78
	v_mul_f32_e32 v78, v160, v78
	v_mul_f32_e32 v78, 0x3fb8aa3b, v78
	v_exp_f32_e32 v78, v78
	s_nop 0
	v_sub_f32_e32 v80, 1.0, v78
	v_add_f32_e32 v81, 1.0, v78
	v_mul_f32_e32 v80, v80, v81
	v_max_f32_e32 v80, 0, v80
	v_sqrt_f32_e32 v80, v80
	s_nop 0
	v_mul_f32_e32 v79, v79, v80
	v_mul_f32_e32 v79, v79, v123
	ds_write2_b64 v177, v[76:77], v[78:79] offset0:34 offset1:51
	global_load_dwordx4 v[112:115], v[154:155], off offset:64
	global_load_dwordx4 v[116:119], v[152:153], off offset:64
	v_mfma_f32_16x16x32_bf16 v[76:79], v[40:43], v[68:71], 0
	ds_read_b64 v[120:121], v2 offset:26144
	s_waitcnt lgkmcnt(0)
	v_lshlrev_b32_e32 v99, 16, v120
	v_mfma_f32_16x16x32_bf16 v[80:83], v[48:51], v[72:75], v[76:79]
	v_and_b32_e32 v111, 0xffff0000, v120
	v_lshlrev_b32_e32 v122, 16, v121
	v_and_b32_e32 v123, 0xffff0000, v121
	v_mfma_f32_16x16x32_bf16 v[76:79], v[36:39], v[68:71], 0
	v_mfma_f32_16x16x32_bf16 v[76:79], v[44:47], v[72:75], v[76:79]
	s_waitcnt vmcnt(1)
	s_nop 1
	v_add_f32_e32 v80, v80, v112
	v_mul_f32_e32 v80, 0xbfb8aa3b, v80
	v_exp_f32_e32 v80, v80
	s_waitcnt vmcnt(0)
	s_nop 0
	v_add_f32_e32 v76, v76, v116
	v_mul_f32_e32 v76, 0xbfb8aa3b, v76
	v_exp_f32_e32 v76, v76
	v_add_f32_e32 v80, 1.0, v80
	v_rcp_f32_e32 v80, v80
	v_add_f32_e32 v77, v77, v117
	v_add_f32_e32 v76, 1.0, v76
	v_rcp_f32_e32 v76, v76
	v_mul_f32_e32 v80, 0xc1000000, v80
	v_mul_f32_e32 v80, v161, v80
	v_mul_f32_e32 v80, 0x3fb8aa3b, v80
	v_exp_f32_e32 v120, v80
	v_mul_f32_e32 v77, 0xbfb8aa3b, v77
	v_exp_f32_e32 v77, v77
	v_add_f32_e32 v79, v79, v119
	v_sub_f32_e32 v80, 1.0, v120
	v_add_f32_e32 v112, 1.0, v120
	v_mul_f32_e32 v80, v80, v112
	v_max_f32_e32 v80, 0, v80
	v_sqrt_f32_e32 v80, v80
	v_add_f32_e32 v77, 1.0, v77
	v_rcp_f32_e32 v77, v77
	v_mul_f32_e32 v79, 0xbfb8aa3b, v79
	v_mul_f32_e32 v76, v76, v80
	v_mul_f32_e32 v121, v76, v99
	v_add_f32_e32 v76, v81, v113
	v_mul_f32_e32 v76, 0xbfb8aa3b, v76
	v_exp_f32_e32 v76, v76
	v_exp_f32_e32 v79, v79
	v_add_f32_e32 v76, 1.0, v76
	v_rcp_f32_e32 v76, v76
	v_add_f32_e32 v79, 1.0, v79
	v_rcp_f32_e32 v79, v79
	v_mul_f32_e32 v76, 0xc1000000, v76
	v_mul_f32_e32 v76, v162, v76
	v_mul_f32_e32 v76, 0x3fb8aa3b, v76
	v_exp_f32_e32 v76, v76
	s_nop 0
	v_sub_f32_e32 v80, 1.0, v76
	v_add_f32_e32 v81, 1.0, v76
	v_mul_f32_e32 v80, v80, v81
	v_max_f32_e32 v80, 0, v80
	v_sqrt_f32_e32 v80, v80
	s_nop 0
	v_mul_f32_e32 v77, v77, v80
	v_mul_f32_e32 v77, v77, v111
	ds_write2_b64 v178, v[120:121], v[76:77] offset0:16 offset1:33
	v_add_f32_e32 v76, v82, v114
	v_mul_f32_e32 v76, 0xbfb8aa3b, v76
	v_exp_f32_e32 v76, v76
	v_add_f32_e32 v77, v78, v118
	v_mul_f32_e32 v77, 0xbfb8aa3b, v77
	v_exp_f32_e32 v77, v77
	v_add_f32_e32 v76, 1.0, v76
	v_rcp_f32_e32 v76, v76
	v_add_f32_e32 v77, 1.0, v77
	v_rcp_f32_e32 v77, v77
	v_mul_f32_e32 v76, 0xc1000000, v76
	v_mul_f32_e32 v76, v164, v76
	v_mul_f32_e32 v76, 0x3fb8aa3b, v76
	v_exp_f32_e32 v76, v76
	s_nop 0
	v_sub_f32_e32 v78, 1.0, v76
	v_add_f32_e32 v80, 1.0, v76
	v_mul_f32_e32 v78, v78, v80
	v_max_f32_e32 v78, 0, v78
	v_sqrt_f32_e32 v78, v78
	s_nop 0
	v_mul_f32_e32 v77, v77, v78
	v_add_f32_e32 v78, v83, v115
	v_mul_f32_e32 v78, 0xbfb8aa3b, v78
	v_exp_f32_e32 v78, v78
	v_mul_f32_e32 v77, v77, v122
	v_add_f32_e32 v78, 1.0, v78
	v_rcp_f32_e32 v78, v78
	s_nop 0
	v_mul_f32_e32 v78, 0xc1000000, v78
	v_mul_f32_e32 v78, v166, v78
	v_mul_f32_e32 v78, 0x3fb8aa3b, v78
	v_exp_f32_e32 v78, v78
	s_nop 0
	v_sub_f32_e32 v80, 1.0, v78
	v_add_f32_e32 v81, 1.0, v78
	v_mul_f32_e32 v80, v80, v81
	v_max_f32_e32 v80, 0, v80
	v_sqrt_f32_e32 v80, v80
	s_nop 0
	v_mul_f32_e32 v79, v79, v80
	v_mul_f32_e32 v79, v79, v123
	ds_write2_b64 v178, v[76:77], v[78:79] offset0:50 offset1:67
	global_load_dwordx4 v[112:115], v[154:155], off offset:128
	global_load_dwordx4 v[116:119], v[152:153], off offset:128
	v_mfma_f32_16x16x32_bf16 v[76:79], v[24:27], v[68:71], 0
	ds_read_b64 v[120:121], v2 offset:26176
	s_waitcnt lgkmcnt(0)
	v_lshlrev_b32_e32 v99, 16, v120
	v_mfma_f32_16x16x32_bf16 v[80:83], v[32:35], v[72:75], v[76:79]
	v_and_b32_e32 v111, 0xffff0000, v120
	v_lshlrev_b32_e32 v122, 16, v121
	v_and_b32_e32 v123, 0xffff0000, v121
	v_mfma_f32_16x16x32_bf16 v[76:79], v[20:23], v[68:71], 0
	v_mfma_f32_16x16x32_bf16 v[76:79], v[28:31], v[72:75], v[76:79]
	s_waitcnt vmcnt(1)
	s_nop 1
	v_add_f32_e32 v80, v80, v112
	v_mul_f32_e32 v80, 0xbfb8aa3b, v80
	v_exp_f32_e32 v80, v80
	s_waitcnt vmcnt(0)
	s_nop 0
	v_add_f32_e32 v76, v76, v116
	v_mul_f32_e32 v76, 0xbfb8aa3b, v76
	v_exp_f32_e32 v76, v76
	v_add_f32_e32 v80, 1.0, v80
	v_rcp_f32_e32 v80, v80
	v_add_f32_e32 v77, v77, v117
	v_add_f32_e32 v76, 1.0, v76
	v_rcp_f32_e32 v76, v76
	v_mul_f32_e32 v80, 0xc1000000, v80
	v_mul_f32_e32 v80, v163, v80
	v_mul_f32_e32 v80, 0x3fb8aa3b, v80
	v_exp_f32_e32 v120, v80
	v_mul_f32_e32 v77, 0xbfb8aa3b, v77
	v_exp_f32_e32 v77, v77
	v_add_f32_e32 v79, v79, v119
	v_sub_f32_e32 v80, 1.0, v120
	v_add_f32_e32 v112, 1.0, v120
	v_mul_f32_e32 v80, v80, v112
	v_max_f32_e32 v80, 0, v80
	v_sqrt_f32_e32 v80, v80
	v_add_f32_e32 v77, 1.0, v77
	v_rcp_f32_e32 v77, v77
	v_mul_f32_e32 v79, 0xbfb8aa3b, v79
	v_mul_f32_e32 v76, v76, v80
	v_mul_f32_e32 v121, v76, v99
	v_add_f32_e32 v76, v81, v113
	v_mul_f32_e32 v76, 0xbfb8aa3b, v76
	v_exp_f32_e32 v76, v76
	v_exp_f32_e32 v79, v79
	v_add_f32_e32 v76, 1.0, v76
	v_rcp_f32_e32 v76, v76
	v_add_f32_e32 v79, 1.0, v79
	v_rcp_f32_e32 v79, v79
	v_mul_f32_e32 v76, 0xc1000000, v76
	v_mul_f32_e32 v76, v165, v76
	v_mul_f32_e32 v76, 0x3fb8aa3b, v76
	v_exp_f32_e32 v76, v76
	s_nop 0
	v_sub_f32_e32 v80, 1.0, v76
	v_add_f32_e32 v81, 1.0, v76
	v_mul_f32_e32 v80, v80, v81
	v_max_f32_e32 v80, 0, v80
	v_sqrt_f32_e32 v80, v80
	s_nop 0
	v_mul_f32_e32 v77, v77, v80
	v_mul_f32_e32 v77, v77, v111
	ds_write2_b64 v179, v[120:121], v[76:77] offset0:32 offset1:49
	v_add_f32_e32 v76, v82, v114
	v_mul_f32_e32 v76, 0xbfb8aa3b, v76
	v_exp_f32_e32 v76, v76
	v_add_f32_e32 v77, v78, v118
	v_mul_f32_e32 v77, 0xbfb8aa3b, v77
	v_exp_f32_e32 v77, v77
	v_add_f32_e32 v76, 1.0, v76
	v_rcp_f32_e32 v76, v76
	v_add_f32_e32 v77, 1.0, v77
	v_rcp_f32_e32 v77, v77
	v_mul_f32_e32 v76, 0xc1000000, v76
	v_mul_f32_e32 v76, v167, v76
	v_mul_f32_e32 v76, 0x3fb8aa3b, v76
	v_exp_f32_e32 v76, v76
	s_nop 0
	v_sub_f32_e32 v78, 1.0, v76
	v_add_f32_e32 v80, 1.0, v76
	v_mul_f32_e32 v78, v78, v80
	v_max_f32_e32 v78, 0, v78
	v_sqrt_f32_e32 v78, v78
	s_nop 0
	v_mul_f32_e32 v77, v77, v78
	v_add_f32_e32 v78, v83, v115
	v_mul_f32_e32 v78, 0xbfb8aa3b, v78
	v_exp_f32_e32 v78, v78
	v_mul_f32_e32 v77, v77, v122
	v_add_f32_e32 v78, 1.0, v78
	v_rcp_f32_e32 v78, v78
	s_nop 0
	v_mul_f32_e32 v78, 0xc1000000, v78
	v_mul_f32_e32 v78, v168, v78
	v_mul_f32_e32 v78, 0x3fb8aa3b, v78
	v_exp_f32_e32 v78, v78
	s_nop 0
	v_sub_f32_e32 v80, 1.0, v78
	v_add_f32_e32 v81, 1.0, v78
	v_mul_f32_e32 v80, v80, v81
	v_max_f32_e32 v80, 0, v80
	v_sqrt_f32_e32 v80, v80
	s_nop 0
	v_mul_f32_e32 v79, v79, v80
	v_mul_f32_e32 v79, v79, v123
	ds_write2_b64 v179, v[76:77], v[78:79] offset0:66 offset1:83
	v_mfma_f32_16x16x32_bf16 v[76:79], v[8:11], v[68:71], 0
	v_mfma_f32_16x16x32_bf16 v[68:71], v[4:7], v[68:71], 0
	v_mfma_f32_16x16x32_bf16 v[76:79], v[16:19], v[72:75], v[76:79]
	v_mfma_f32_16x16x32_bf16 v[68:71], v[12:15], v[72:75], v[68:71]
	global_load_dwordx4 v[72:75], v[154:155], off offset:192
	global_load_dwordx4 v[80:83], v[152:153], off offset:192
	ds_read_b64 v[112:113], v2 offset:26208
	s_waitcnt lgkmcnt(0)
	v_lshlrev_b32_e32 v2, 16, v112
	v_and_b32_e32 v99, 0xffff0000, v112
	v_lshlrev_b32_e32 v111, 16, v113
	v_and_b32_e32 v114, 0xffff0000, v113
	s_waitcnt vmcnt(1)
	v_add_f32_e32 v72, v76, v72
	v_mul_f32_e32 v72, 0xbfb8aa3b, v72
	v_exp_f32_e32 v72, v72
	s_waitcnt vmcnt(0)
	v_add_f32_e32 v68, v68, v80
	v_mul_f32_e32 v68, 0xbfb8aa3b, v68
	v_exp_f32_e32 v68, v68
	v_add_f32_e32 v72, 1.0, v72
	v_rcp_f32_e32 v72, v72
	v_add_f32_e32 v68, 1.0, v68
	v_rcp_f32_e32 v68, v68
	v_mul_f32_e32 v72, 0xc1000000, v72
	v_mul_f32_e32 v72, v169, v72
	v_mul_f32_e32 v72, 0x3fb8aa3b, v72
	v_exp_f32_e32 v112, v72
	s_nop 0
	v_sub_f32_e32 v72, 1.0, v112
	v_add_f32_e32 v76, 1.0, v112
	v_mul_f32_e32 v72, v72, v76
	v_max_f32_e32 v72, 0, v72
	v_sqrt_f32_e32 v72, v72
	s_nop 0
	v_mul_f32_e32 v68, v68, v72
	v_mul_f32_e32 v113, v68, v2
	v_add_f32_e32 v2, v77, v73
	v_mul_f32_e32 v2, 0xbfb8aa3b, v2
	v_exp_f32_e32 v2, v2
	v_add_f32_e32 v68, v69, v81
	v_mul_f32_e32 v68, 0xbfb8aa3b, v68
	v_exp_f32_e32 v68, v68
	v_add_f32_e32 v2, 1.0, v2
	v_rcp_f32_e32 v2, v2
	v_add_f32_e32 v68, 1.0, v68
	v_rcp_f32_e32 v69, v68
	v_mul_f32_e32 v2, 0xc1000000, v2
	v_mul_f32_e32 v2, v170, v2
	v_mul_f32_e32 v2, 0x3fb8aa3b, v2
	v_exp_f32_e32 v68, v2
	s_nop 0
	v_sub_f32_e32 v2, 1.0, v68
	v_add_f32_e32 v72, 1.0, v68
	v_mul_f32_e32 v2, v2, v72
	v_max_f32_e32 v2, 0, v2
	v_sqrt_f32_e32 v2, v2
	s_nop 0
	v_mul_f32_e32 v2, v69, v2
	v_mul_f32_e32 v69, v2, v99
	v_add_f32_e32 v2, v78, v74
	v_mul_f32_e32 v2, 0xbfb8aa3b, v2
	v_exp_f32_e32 v2, v2
	ds_write2_b64 v175, v[112:113], v[68:69] offset0:48 offset1:65
	v_add_f32_e32 v68, v70, v82
	v_mul_f32_e32 v68, 0xbfb8aa3b, v68
	v_add_f32_e32 v2, 1.0, v2
	v_rcp_f32_e32 v2, v2
	v_exp_f32_e32 v68, v68
	v_mul_f32_e32 v2, 0xc1000000, v2
	v_mul_f32_e32 v2, v172, v2
	v_add_f32_e32 v68, 1.0, v68
	v_mul_f32_e32 v2, 0x3fb8aa3b, v2
	v_rcp_f32_e32 v69, v68
	v_exp_f32_e32 v68, v2
	s_nop 0
	v_sub_f32_e32 v2, 1.0, v68
	v_add_f32_e32 v70, 1.0, v68
	v_mul_f32_e32 v2, v2, v70
	v_max_f32_e32 v2, 0, v2
	v_sqrt_f32_e32 v2, v2
	v_add_f32_e32 v70, v71, v83
	v_mul_f32_e32 v70, 0xbfb8aa3b, v70
	v_exp_f32_e32 v70, v70
	v_mul_f32_e32 v2, v69, v2
	v_mul_f32_e32 v69, v2, v111
	v_add_f32_e32 v2, v79, v75
	v_mul_f32_e32 v2, 0xbfb8aa3b, v2
	v_exp_f32_e32 v2, v2
	v_add_f32_e32 v70, 1.0, v70
	v_rcp_f32_e32 v71, v70
	v_add_f32_e32 v2, 1.0, v2
	v_rcp_f32_e32 v2, v2
	s_nop 0
	v_mul_f32_e32 v2, 0xc1000000, v2
	v_mul_f32_e32 v2, v173, v2
	v_mul_f32_e32 v2, 0x3fb8aa3b, v2
	v_exp_f32_e32 v70, v2
	s_nop 0
	v_sub_f32_e32 v2, 1.0, v70
	v_add_f32_e32 v72, 1.0, v70
	v_mul_f32_e32 v2, v2, v72
	v_max_f32_e32 v2, 0, v2
	v_sqrt_f32_e32 v2, v2
	s_nop 0
	v_mul_f32_e32 v2, v71, v2
	v_mul_f32_e32 v71, v2, v114
	ds_write2_b64 v175, v[68:69], v[70:71] offset0:82 offset1:99
	s_waitcnt lgkmcnt(0)
	s_barrier
	ds_read2_b64 v[124:127], v183 offset1:1
	ds_read2_b64 v[68:71], v184 offset1:1
	ds_read2_b64 v[128:131], v180 offset1:1
	ds_read2_b64 v[80:83], v171 offset1:1
	ds_read2_b64 v[132:135], v182 offset1:1
	ds_read2_b64 v[136:139], v181 offset1:1
	ds_read2_b64 v[72:75], v186 offset1:1
	ds_read2_b64 v[76:79], v185 offset1:1
	s_waitcnt lgkmcnt(0)
	s_barrier
	ds_read_b128 v[112:115], v176 offset:8704
	ds_read_b128 v[116:119], v176 offset:8768
	global_load_dwordx4 v[144:147], v[154:155], off
	global_load_dwordx4 v[148:151], v[152:153], off
	s_waitcnt lgkmcnt(1)
	v_mfma_f32_16x16x32_bf16 v[120:123], v[56:59], v[112:115], 0
	v_fma_f32 v2, v91, v126, v127
	v_fma_f32 v2, v124, v2, v125
	v_fma_f32 v2, v130, v2, v131
	s_waitcnt lgkmcnt(0)
	v_mfma_f32_16x16x32_bf16 v[120:123], v[64:67], v[116:119], v[120:123]
	v_fma_f32 v2, v128, v2, v129
	v_fma_f32 v2, v134, v2, v135
	v_fma_f32 v2, v132, v2, v133
	v_mfma_f32_16x16x32_bf16 v[140:143], v[52:55], v[112:115], 0
	v_fma_f32 v2, v138, v2, v139
	v_fma_f32 v2, v136, v2, v137
	ds_read_b64 v[188:189], v174 offset:8704
	v_fma_f32 v2, v70, v2, v71
	v_mfma_f32_16x16x32_bf16 v[140:143], v[60:63], v[116:119], v[140:143]
	v_fma_f32 v2, v68, v2, v69
	v_fma_f32 v2, v74, v2, v75
	v_fma_f32 v2, v72, v2, v73
	v_fma_f32 v2, v78, v2, v79
	s_waitcnt lgkmcnt(0)
	v_lshlrev_b32_e32 v71, 16, v188
	v_and_b32_e32 v79, 0xffff0000, v188
	v_lshlrev_b32_e32 v91, 16, v189
	v_and_b32_e32 v99, 0xffff0000, v189
	v_fma_f32 v2, v76, v2, v77
	v_fma_f32 v2, v82, v2, v83
	v_fma_f32 v2, v80, v2, v81
	s_waitcnt vmcnt(1)
	v_add_f32_e32 v111, v120, v144
	v_mul_f32_e32 v111, 0xbfb8aa3b, v111
	v_exp_f32_e32 v111, v111
	s_waitcnt vmcnt(0)
	v_add_f32_e32 v120, v140, v148
	v_mul_f32_e32 v120, 0xbfb8aa3b, v120
	v_exp_f32_e32 v120, v120
	v_add_f32_e32 v111, 1.0, v111
	v_rcp_f32_e32 v111, v111
	v_add_f32_e32 v120, 1.0, v120
	v_rcp_f32_e32 v120, v120
	v_mul_f32_e32 v111, 0xc1000000, v111
	v_mul_f32_e32 v111, v1, v111
	v_mul_f32_e32 v111, 0x3fb8aa3b, v111
	v_exp_f32_e32 v188, v111
	s_nop 0
	v_sub_f32_e32 v111, 1.0, v188
	v_add_f32_e32 v127, 1.0, v188
	v_mul_f32_e32 v111, v111, v127
	v_max_f32_e32 v111, 0, v111
	v_sqrt_f32_e32 v111, v111
	s_nop 0
	v_mul_f32_e32 v111, v120, v111
	v_mul_f32_e32 v189, v111, v71
	v_add_f32_e32 v71, v121, v145
	v_mul_f32_e32 v71, 0xbfb8aa3b, v71
	v_exp_f32_e32 v71, v71
	v_add_f32_e32 v111, v141, v149
	v_mul_f32_e32 v111, 0xbfb8aa3b, v111
	v_exp_f32_e32 v111, v111
	v_add_f32_e32 v71, 1.0, v71
	v_rcp_f32_e32 v71, v71
	v_add_f32_e32 v111, 1.0, v111
	v_rcp_f32_e32 v111, v111
	v_mul_f32_e32 v71, 0xc1000000, v71
	v_mul_f32_e32 v71, v158, v71
	v_mul_f32_e32 v71, 0x3fb8aa3b, v71
	v_exp_f32_e32 v120, v71
	s_nop 0
	v_sub_f32_e32 v71, 1.0, v120
	v_add_f32_e32 v121, 1.0, v120
	v_mul_f32_e32 v71, v71, v121
	v_max_f32_e32 v71, 0, v71
	v_sqrt_f32_e32 v71, v71
	s_nop 0
	v_mul_f32_e32 v71, v111, v71
	v_mul_f32_e32 v121, v71, v79
	v_add_f32_e32 v71, v122, v146
	v_mul_f32_e32 v71, 0xbfb8aa3b, v71
	v_exp_f32_e32 v71, v71
	ds_write2_b64 v177, v[188:189], v[120:121] offset1:17
	v_add_f32_e32 v79, v142, v150
	v_mul_f32_e32 v79, 0xbfb8aa3b, v79
	v_add_f32_e32 v71, 1.0, v71
	v_rcp_f32_e32 v71, v71
	v_exp_f32_e32 v79, v79
	v_mul_f32_e32 v71, 0xc1000000, v71
	v_mul_f32_e32 v71, v159, v71
	v_mul_f32_e32 v71, 0x3fb8aa3b, v71
	v_exp_f32_e32 v120, v71
	v_add_f32_e32 v79, 1.0, v79
	v_rcp_f32_e32 v79, v79
	v_sub_f32_e32 v71, 1.0, v120
	v_add_f32_e32 v111, 1.0, v120
	v_mul_f32_e32 v71, v71, v111
	v_max_f32_e32 v71, 0, v71
	v_sqrt_f32_e32 v71, v71
	s_nop 0
	v_mul_f32_e32 v71, v79, v71
	v_mul_f32_e32 v121, v71, v91
	v_add_f32_e32 v71, v123, v147
	v_mul_f32_e32 v71, 0xbfb8aa3b, v71
	v_exp_f32_e32 v71, v71
	v_add_f32_e32 v79, v143, v151
	v_mul_f32_e32 v79, 0xbfb8aa3b, v79
	v_exp_f32_e32 v79, v79
	v_add_f32_e32 v71, 1.0, v71
	v_rcp_f32_e32 v71, v71
	v_add_f32_e32 v79, 1.0, v79
	v_rcp_f32_e32 v79, v79
	v_mul_f32_e32 v71, 0xc1000000, v71
	v_mul_f32_e32 v71, v160, v71
	v_mul_f32_e32 v71, 0x3fb8aa3b, v71
	v_exp_f32_e32 v122, v71
	s_nop 0
	v_sub_f32_e32 v71, 1.0, v122
	v_add_f32_e32 v91, 1.0, v122
	v_mul_f32_e32 v71, v71, v91
	v_max_f32_e32 v71, 0, v71
	v_sqrt_f32_e32 v71, v71
	s_nop 0
	v_mul_f32_e32 v71, v79, v71
	v_mul_f32_e32 v123, v71, v99
	ds_write2_b64 v177, v[120:121], v[122:123] offset0:34 offset1:51
	global_load_dwordx4 v[144:147], v[154:155], off offset:64
	global_load_dwordx4 v[148:151], v[152:153], off offset:64
	v_mfma_f32_16x16x32_bf16 v[120:123], v[40:43], v[112:115], 0
	ds_read_b64 v[188:189], v174 offset:8736
	s_waitcnt lgkmcnt(0)
	v_lshlrev_b32_e32 v71, 16, v188
	v_mfma_f32_16x16x32_bf16 v[140:143], v[48:51], v[116:119], v[120:123]
	v_and_b32_e32 v79, 0xffff0000, v188
	v_lshlrev_b32_e32 v91, 16, v189
	v_and_b32_e32 v99, 0xffff0000, v189
	v_mfma_f32_16x16x32_bf16 v[120:123], v[36:39], v[112:115], 0
	v_mfma_f32_16x16x32_bf16 v[120:123], v[44:47], v[116:119], v[120:123]
	s_waitcnt vmcnt(1)
	s_nop 1
	v_add_f32_e32 v111, v140, v144
	v_mul_f32_e32 v111, 0xbfb8aa3b, v111
	v_exp_f32_e32 v111, v111
	s_waitcnt vmcnt(0)
	s_nop 0
	v_add_f32_e32 v120, v120, v148
	v_mul_f32_e32 v120, 0xbfb8aa3b, v120
	v_exp_f32_e32 v120, v120
	v_add_f32_e32 v111, 1.0, v111
	v_rcp_f32_e32 v111, v111
	v_add_f32_e32 v120, 1.0, v120
	v_rcp_f32_e32 v120, v120
	v_mul_f32_e32 v111, 0xc1000000, v111
	v_mul_f32_e32 v111, v161, v111
	v_mul_f32_e32 v111, 0x3fb8aa3b, v111
	v_exp_f32_e32 v188, v111
	s_nop 0
	v_sub_f32_e32 v111, 1.0, v188
	v_add_f32_e32 v127, 1.0, v188
	v_mul_f32_e32 v111, v111, v127
	v_max_f32_e32 v111, 0, v111
	v_sqrt_f32_e32 v111, v111
	s_nop 0
	v_mul_f32_e32 v111, v120, v111
	v_mul_f32_e32 v189, v111, v71
	v_add_f32_e32 v71, v141, v145
	v_mul_f32_e32 v71, 0xbfb8aa3b, v71
	v_exp_f32_e32 v71, v71
	v_add_f32_e32 v111, v121, v149
	v_mul_f32_e32 v111, 0xbfb8aa3b, v111
	v_exp_f32_e32 v111, v111
	v_add_f32_e32 v71, 1.0, v71
	v_rcp_f32_e32 v71, v71
	v_add_f32_e32 v111, 1.0, v111
	v_rcp_f32_e32 v111, v111
	v_mul_f32_e32 v71, 0xc1000000, v71
	v_mul_f32_e32 v71, v162, v71
	v_mul_f32_e32 v71, 0x3fb8aa3b, v71
	v_exp_f32_e32 v120, v71
	s_nop 0
	v_sub_f32_e32 v71, 1.0, v120
	v_add_f32_e32 v121, 1.0, v120
	v_mul_f32_e32 v71, v71, v121
	v_max_f32_e32 v71, 0, v71
	v_sqrt_f32_e32 v71, v71
	s_nop 0
	v_mul_f32_e32 v71, v111, v71
	v_mul_f32_e32 v121, v71, v79
	v_add_f32_e32 v71, v142, v146
	v_mul_f32_e32 v71, 0xbfb8aa3b, v71
	v_exp_f32_e32 v71, v71
	ds_write2_b64 v178, v[188:189], v[120:121] offset0:16 offset1:33
	v_add_f32_e32 v79, v122, v150
	v_mul_f32_e32 v79, 0xbfb8aa3b, v79
	v_add_f32_e32 v71, 1.0, v71
	v_rcp_f32_e32 v71, v71
	v_exp_f32_e32 v79, v79
	v_mul_f32_e32 v71, 0xc1000000, v71
	v_mul_f32_e32 v71, v164, v71
	v_mul_f32_e32 v71, 0x3fb8aa3b, v71
	v_exp_f32_e32 v120, v71
	v_add_f32_e32 v79, 1.0, v79
	v_rcp_f32_e32 v79, v79
	v_sub_f32_e32 v71, 1.0, v120
	v_add_f32_e32 v111, 1.0, v120
	v_mul_f32_e32 v71, v71, v111
	v_max_f32_e32 v71, 0, v71
	v_sqrt_f32_e32 v71, v71
	s_nop 0
	v_mul_f32_e32 v71, v79, v71
	v_mul_f32_e32 v121, v71, v91
	v_add_f32_e32 v71, v143, v147
	v_mul_f32_e32 v71, 0xbfb8aa3b, v71
	v_exp_f32_e32 v71, v71
	v_add_f32_e32 v79, v123, v151
	v_mul_f32_e32 v79, 0xbfb8aa3b, v79
	v_exp_f32_e32 v79, v79
	v_add_f32_e32 v71, 1.0, v71
	v_rcp_f32_e32 v71, v71
	v_add_f32_e32 v79, 1.0, v79
	v_rcp_f32_e32 v79, v79
	v_mul_f32_e32 v71, 0xc1000000, v71
	v_mul_f32_e32 v71, v166, v71
	v_mul_f32_e32 v71, 0x3fb8aa3b, v71
	v_exp_f32_e32 v122, v71
	s_nop 0
	v_sub_f32_e32 v71, 1.0, v122
	v_add_f32_e32 v91, 1.0, v122
	v_mul_f32_e32 v71, v71, v91
	v_max_f32_e32 v71, 0, v71
	v_sqrt_f32_e32 v71, v71
	s_nop 0
	v_mul_f32_e32 v71, v79, v71
	v_mul_f32_e32 v123, v71, v99
	ds_write2_b64 v178, v[120:121], v[122:123] offset0:50 offset1:67
	global_load_dwordx4 v[144:147], v[154:155], off offset:128
	global_load_dwordx4 v[148:151], v[152:153], off offset:128
	v_mfma_f32_16x16x32_bf16 v[120:123], v[24:27], v[112:115], 0
	ds_read_b64 v[188:189], v174 offset:8768
	s_waitcnt lgkmcnt(0)
	v_lshlrev_b32_e32 v71, 16, v188
	v_mfma_f32_16x16x32_bf16 v[140:143], v[32:35], v[116:119], v[120:123]
	v_and_b32_e32 v79, 0xffff0000, v188
	v_lshlrev_b32_e32 v91, 16, v189
	v_and_b32_e32 v99, 0xffff0000, v189
	v_mfma_f32_16x16x32_bf16 v[120:123], v[20:23], v[112:115], 0
	v_mfma_f32_16x16x32_bf16 v[120:123], v[28:31], v[116:119], v[120:123]
	s_waitcnt vmcnt(1)
	s_nop 1
	v_add_f32_e32 v111, v140, v144
	v_mul_f32_e32 v111, 0xbfb8aa3b, v111
	v_exp_f32_e32 v111, v111
	s_waitcnt vmcnt(0)
	s_nop 0
	v_add_f32_e32 v120, v120, v148
	v_mul_f32_e32 v120, 0xbfb8aa3b, v120
	v_exp_f32_e32 v120, v120
	v_add_f32_e32 v111, 1.0, v111
	v_rcp_f32_e32 v111, v111
	v_add_f32_e32 v120, 1.0, v120
	v_rcp_f32_e32 v120, v120
	v_mul_f32_e32 v111, 0xc1000000, v111
	v_mul_f32_e32 v111, v163, v111
	v_mul_f32_e32 v111, 0x3fb8aa3b, v111
	v_exp_f32_e32 v188, v111
	s_nop 0
	v_sub_f32_e32 v111, 1.0, v188
	v_add_f32_e32 v127, 1.0, v188
	v_mul_f32_e32 v111, v111, v127
	v_max_f32_e32 v111, 0, v111
	v_sqrt_f32_e32 v111, v111
	s_nop 0
	v_mul_f32_e32 v111, v120, v111
	v_mul_f32_e32 v189, v111, v71
	v_add_f32_e32 v71, v141, v145
	v_mul_f32_e32 v71, 0xbfb8aa3b, v71
	v_exp_f32_e32 v71, v71
	v_add_f32_e32 v111, v121, v149
	v_mul_f32_e32 v111, 0xbfb8aa3b, v111
	v_exp_f32_e32 v111, v111
	v_add_f32_e32 v71, 1.0, v71
	v_rcp_f32_e32 v71, v71
	v_add_f32_e32 v111, 1.0, v111
	v_rcp_f32_e32 v111, v111
	v_mul_f32_e32 v71, 0xc1000000, v71
	v_mul_f32_e32 v71, v165, v71
	v_mul_f32_e32 v71, 0x3fb8aa3b, v71
	v_exp_f32_e32 v120, v71
	s_nop 0
	v_sub_f32_e32 v71, 1.0, v120
	v_add_f32_e32 v121, 1.0, v120
	v_mul_f32_e32 v71, v71, v121
	v_max_f32_e32 v71, 0, v71
	v_sqrt_f32_e32 v71, v71
	s_nop 0
	v_mul_f32_e32 v71, v111, v71
	v_mul_f32_e32 v121, v71, v79
	v_add_f32_e32 v71, v142, v146
	v_mul_f32_e32 v71, 0xbfb8aa3b, v71
	v_exp_f32_e32 v71, v71
	ds_write2_b64 v179, v[188:189], v[120:121] offset0:32 offset1:49
	v_add_f32_e32 v79, v122, v150
	v_mul_f32_e32 v79, 0xbfb8aa3b, v79
	v_add_f32_e32 v71, 1.0, v71
	v_rcp_f32_e32 v71, v71
	v_exp_f32_e32 v79, v79
	v_mul_f32_e32 v71, 0xc1000000, v71
	v_mul_f32_e32 v71, v167, v71
	v_mul_f32_e32 v71, 0x3fb8aa3b, v71
	v_exp_f32_e32 v120, v71
	v_add_f32_e32 v79, 1.0, v79
	v_rcp_f32_e32 v79, v79
	v_sub_f32_e32 v71, 1.0, v120
	v_add_f32_e32 v111, 1.0, v120
	v_mul_f32_e32 v71, v71, v111
	v_max_f32_e32 v71, 0, v71
	v_sqrt_f32_e32 v71, v71
	s_nop 0
	v_mul_f32_e32 v71, v79, v71
	v_mul_f32_e32 v121, v71, v91
	v_add_f32_e32 v71, v143, v147
	v_mul_f32_e32 v71, 0xbfb8aa3b, v71
	v_exp_f32_e32 v71, v71
	v_add_f32_e32 v79, v123, v151
	v_mul_f32_e32 v79, 0xbfb8aa3b, v79
	v_exp_f32_e32 v79, v79
	v_add_f32_e32 v71, 1.0, v71
	v_rcp_f32_e32 v71, v71
	v_add_f32_e32 v79, 1.0, v79
	v_rcp_f32_e32 v79, v79
	v_mul_f32_e32 v71, 0xc1000000, v71
	v_mul_f32_e32 v71, v168, v71
	v_mul_f32_e32 v71, 0x3fb8aa3b, v71
	v_exp_f32_e32 v122, v71
	s_nop 0
	v_sub_f32_e32 v71, 1.0, v122
	v_add_f32_e32 v91, 1.0, v122
	v_mul_f32_e32 v71, v71, v91
	v_max_f32_e32 v71, 0, v71
	v_sqrt_f32_e32 v71, v71
	s_nop 0
	v_mul_f32_e32 v71, v79, v71
	v_mul_f32_e32 v123, v71, v99
	ds_write2_b64 v179, v[120:121], v[122:123] offset0:66 offset1:83
	v_mfma_f32_16x16x32_bf16 v[120:123], v[8:11], v[112:115], 0
	v_mfma_f32_16x16x32_bf16 v[112:115], v[4:7], v[112:115], 0
	v_mfma_f32_16x16x32_bf16 v[120:123], v[16:19], v[116:119], v[120:123]
	v_mfma_f32_16x16x32_bf16 v[112:115], v[12:15], v[116:119], v[112:115]
	global_load_dwordx4 v[116:119], v[154:155], off offset:192
	global_load_dwordx4 v[140:143], v[152:153], off offset:192
	ds_read_b64 v[144:145], v174 offset:8800
	s_waitcnt lgkmcnt(0)
	v_lshlrev_b32_e32 v71, 16, v144
	v_and_b32_e32 v79, 0xffff0000, v144
	v_lshlrev_b32_e32 v91, 16, v145
	v_and_b32_e32 v99, 0xffff0000, v145
	s_waitcnt vmcnt(1)
	v_add_f32_e32 v111, v120, v116
	v_mul_f32_e32 v111, 0xbfb8aa3b, v111
	v_exp_f32_e32 v111, v111
	s_waitcnt vmcnt(0)
	v_add_f32_e32 v112, v112, v140
	v_mul_f32_e32 v112, 0xbfb8aa3b, v112
	v_exp_f32_e32 v112, v112
	v_add_f32_e32 v111, 1.0, v111
	v_rcp_f32_e32 v111, v111
	v_add_f32_e32 v112, 1.0, v112
	v_rcp_f32_e32 v112, v112
	v_mul_f32_e32 v111, 0xc1000000, v111
	v_mul_f32_e32 v111, v169, v111
	v_mul_f32_e32 v111, 0x3fb8aa3b, v111
	v_exp_f32_e32 v144, v111
	s_nop 0
	v_sub_f32_e32 v111, 1.0, v144
	v_add_f32_e32 v116, 1.0, v144
	v_mul_f32_e32 v111, v111, v116
	v_max_f32_e32 v111, 0, v111
	v_sqrt_f32_e32 v111, v111
	v_mov_b32_e32 v116, v156
	v_mul_f32_e32 v111, v112, v111
	v_mul_f32_e32 v145, v111, v71
	v_add_f32_e32 v71, v121, v117
	v_mul_f32_e32 v71, 0xbfb8aa3b, v71
	v_exp_f32_e32 v71, v71
	v_add_f32_e32 v111, v113, v141
	v_mul_f32_e32 v111, 0xbfb8aa3b, v111
	v_exp_f32_e32 v111, v111
	v_add_f32_e32 v71, 1.0, v71
	v_rcp_f32_e32 v71, v71
	v_add_f32_e32 v111, 1.0, v111
	v_rcp_f32_e32 v111, v111
	v_mul_f32_e32 v71, 0xc1000000, v71
	v_mul_f32_e32 v71, v170, v71
	v_mul_f32_e32 v71, 0x3fb8aa3b, v71
	v_exp_f32_e32 v112, v71
	s_nop 0
	v_sub_f32_e32 v71, 1.0, v112
	v_add_f32_e32 v113, 1.0, v112
	v_mul_f32_e32 v71, v71, v113
	v_max_f32_e32 v71, 0, v71
	v_sqrt_f32_e32 v71, v71
	s_nop 0
	v_mul_f32_e32 v71, v111, v71
	v_mul_f32_e32 v113, v71, v79
	v_add_f32_e32 v71, v122, v118
	v_mul_f32_e32 v71, 0xbfb8aa3b, v71
	v_exp_f32_e32 v71, v71
	ds_write2_b64 v175, v[144:145], v[112:113] offset0:48 offset1:65
	v_add_f32_e32 v79, v114, v142
	v_mul_f32_e32 v79, 0xbfb8aa3b, v79
	v_add_f32_e32 v71, 1.0, v71
	v_rcp_f32_e32 v71, v71
	v_exp_f32_e32 v79, v79
	v_mov_b32_e32 v118, v106
	v_pk_mul_f32 v[106:107], v[156:157], v[106:107]
	v_mul_f32_e32 v71, 0xc1000000, v71
	v_mul_f32_e32 v71, v172, v71
	v_mul_f32_e32 v71, 0x3fb8aa3b, v71
	v_exp_f32_e32 v112, v71
	v_add_f32_e32 v79, 1.0, v79
	v_rcp_f32_e32 v79, v79
	v_pk_mul_f32 v[140:141], v[106:107], v[104:105]
	v_sub_f32_e32 v71, 1.0, v112
	v_add_f32_e32 v111, 1.0, v112
	v_mul_f32_e32 v71, v71, v111
	v_max_f32_e32 v71, 0, v71
	v_sqrt_f32_e32 v71, v71
	s_nop 0
	v_mul_f32_e32 v71, v79, v71
	v_mul_f32_e32 v113, v71, v91
	v_add_f32_e32 v71, v123, v119
	v_mul_f32_e32 v71, 0xbfb8aa3b, v71
	v_exp_f32_e32 v71, v71
	v_add_f32_e32 v79, v115, v143
	v_mul_f32_e32 v79, 0xbfb8aa3b, v79
	v_exp_f32_e32 v79, v79
	v_add_f32_e32 v71, 1.0, v71
	v_rcp_f32_e32 v71, v71
	v_add_f32_e32 v79, 1.0, v79
	v_rcp_f32_e32 v79, v79
	v_mul_f32_e32 v71, 0xc1000000, v71
	v_mul_f32_e32 v71, v173, v71
	v_mul_f32_e32 v71, 0x3fb8aa3b, v71
	v_exp_f32_e32 v114, v71
	s_nop 0
	v_sub_f32_e32 v71, 1.0, v114
	v_add_f32_e32 v91, 1.0, v114
	v_mul_f32_e32 v71, v71, v91
	v_max_f32_e32 v71, 0, v71
	v_sqrt_f32_e32 v71, v71
	s_nop 0
	v_mul_f32_e32 v71, v79, v71
	v_mul_f32_e32 v115, v71, v99
	ds_write2_b64 v175, v[112:113], v[114:115] offset0:82 offset1:99
	s_waitcnt lgkmcnt(0)
	s_barrier
	ds_read2_b64 v[112:115], v183 offset1:1
	s_waitcnt lgkmcnt(0)
	v_fma_f32 v117, v2, v114, v115
	v_mov_b32_e32 v119, v112
	v_pk_fma_f32 v[104:105], v[116:117], v[118:119], v[112:113]
	s_nop 0
	v_mov_b32_e32 v141, v105
	ds_read2_b64 v[120:123], v180 offset1:1
	ds_read2_b64 v[116:119], v182 offset1:1
	ds_read2_b64 v[104:107], v181 offset1:1
	s_waitcnt lgkmcnt(2)
	v_mov_b32_e32 v91, v122
	v_pk_mul_f32 v[142:143], v[140:141], v[90:91]
	v_pk_fma_f32 v[90:91], v[140:141], v[90:91], v[122:123]
	v_pk_mul_f32 v[88:89], v[142:143], v[88:89]
	v_mov_b32_e32 v140, v94
	v_mov_b32_e32 v90, v88
	v_mov_b32_e32 v141, v120
	v_pk_mul_f32 v[88:89], v[88:89], v[94:95]
	v_pk_fma_f32 v[90:91], v[90:91], v[140:141], v[120:121]
	v_pk_mul_f32 v[88:89], v[88:89], v[92:93]
	s_waitcnt lgkmcnt(1)
	v_mov_b32_e32 v99, v118
	v_mov_b32_e32 v89, v91
	v_pk_mul_f32 v[90:91], v[88:89], v[98:99]
	v_pk_fma_f32 v[88:89], v[88:89], v[98:99], v[118:119]
	v_pk_mul_f32 v[90:91], v[90:91], v[96:97]
	v_mov_b32_e32 v92, v102
	v_mov_b32_e32 v88, v90
	v_mov_b32_e32 v93, v116
	v_pk_mul_f32 v[90:91], v[90:91], v[102:103]
	v_pk_fma_f32 v[88:89], v[88:89], v[92:93], v[116:117]
	v_pk_mul_f32 v[90:91], v[90:91], v[100:101]
	s_waitcnt lgkmcnt(0)
	v_mov_b32_e32 v111, v106
	v_mov_b32_e32 v91, v89
	v_pk_mul_f32 v[88:89], v[90:91], v[110:111]
	v_pk_fma_f32 v[98:99], v[90:91], v[110:111], v[106:107]
	v_pk_mul_f32 v[96:97], v[88:89], v[108:109]
	ds_read2_b64 v[92:95], v184 offset1:1
	ds_read2_b64 v[88:91], v186 offset1:1
	v_mov_b32_e32 v98, v96
	v_mov_b32_e32 v100, v86
	v_mov_b32_e32 v101, v104
	v_pk_mul_f32 v[86:87], v[96:97], v[86:87]
	s_waitcnt lgkmcnt(1)
	v_mov_b32_e32 v127, v94
	v_pk_mul_f32 v[84:85], v[86:87], v[84:85]
	v_pk_fma_f32 v[86:87], v[98:99], v[100:101], v[104:105]
	v_mov_b32_e32 v96, v130
	v_mov_b32_e32 v85, v87
	v_pk_mul_f32 v[86:87], v[84:85], v[126:127]
	v_pk_fma_f32 v[84:85], v[84:85], v[126:127], v[94:95]
	v_pk_mul_f32 v[86:87], v[86:87], v[124:125]
	v_mov_b32_e32 v97, v92
	v_mov_b32_e32 v84, v86
	v_pk_mul_f32 v[86:87], v[86:87], v[130:131]
	v_pk_fma_f32 v[84:85], v[84:85], v[96:97], v[92:93]
	v_pk_mul_f32 v[86:87], v[86:87], v[128:129]
	s_waitcnt lgkmcnt(0)
	v_mov_b32_e32 v135, v90
	v_mov_b32_e32 v87, v85
	v_pk_mul_f32 v[84:85], v[86:87], v[134:135]
	v_pk_fma_f32 v[86:87], v[86:87], v[134:135], v[90:91]
	v_pk_mul_f32 v[84:85], v[84:85], v[132:133]
	v_mov_b32_e32 v96, v138
	v_mov_b32_e32 v86, v84
	v_mov_b32_e32 v97, v88
	v_pk_mul_f32 v[84:85], v[84:85], v[138:139]
	s_nop 0
	v_pk_mul_f32 v[124:125], v[84:85], v[136:137]
	v_pk_fma_f32 v[84:85], v[86:87], v[96:97], v[88:89]
	s_nop 0
	v_mov_b32_e32 v125, v85
	ds_read2_b64 v[84:87], v185 offset1:1
	ds_read2_b64 v[96:99], v171 offset1:1
	s_waitcnt lgkmcnt(0)
	s_barrier
	ds_read_b128 v[100:103], v176
	ds_read_b128 v[108:111], v176 offset:64
	s_waitcnt lgkmcnt(1)
	v_mfma_f32_16x16x32_bf16 v[56:59], v[56:59], v[100:103], 0
	v_mfma_f32_16x16x32_bf16 v[52:55], v[52:55], v[100:103], 0
	s_waitcnt lgkmcnt(0)
	v_mfma_f32_16x16x32_bf16 v[56:59], v[64:67], v[108:111], v[56:59]
	v_mfma_f32_16x16x32_bf16 v[52:55], v[60:63], v[108:111], v[52:55]
	global_load_dwordx4 v[60:63], v[154:155], off
	global_load_dwordx4 v[64:67], v[152:153], off
	ds_read_b64 v[126:127], v174
	s_waitcnt lgkmcnt(0)
	v_lshlrev_b32_e32 v2, 16, v126
	v_and_b32_e32 v71, 0xffff0000, v126
	v_lshlrev_b32_e32 v79, 16, v127
	v_and_b32_e32 v95, 0xffff0000, v127
	v_mfma_f32_16x16x32_bf16 v[40:43], v[40:43], v[100:103], 0
	s_waitcnt vmcnt(1)
	v_add_f32_e32 v56, v56, v60
	v_mul_f32_e32 v56, 0xbfb8aa3b, v56
	v_exp_f32_e32 v56, v56
	s_waitcnt vmcnt(0)
	v_add_f32_e32 v52, v52, v64
	v_mul_f32_e32 v52, 0xbfb8aa3b, v52
	v_exp_f32_e32 v52, v52
	v_add_f32_e32 v56, 1.0, v56
	v_rcp_f32_e32 v56, v56
	v_mfma_f32_16x16x32_bf16 v[36:39], v[36:39], v[100:103], 0
	v_add_f32_e32 v52, 1.0, v52
	v_rcp_f32_e32 v52, v52
	v_mul_f32_e32 v56, 0xc1000000, v56
	v_mul_f32_e32 v1, v1, v56
	v_mul_f32_e32 v1, 0x3fb8aa3b, v1
	v_exp_f32_e32 v126, v1
	v_mfma_f32_16x16x32_bf16 v[40:43], v[48:51], v[108:111], v[40:43]
	v_sub_f32_e32 v1, 1.0, v126
	v_add_f32_e32 v56, 1.0, v126
	v_mul_f32_e32 v1, v1, v56
	v_max_f32_e32 v1, 0, v1
	v_sqrt_f32_e32 v1, v1
	v_mfma_f32_16x16x32_bf16 v[36:39], v[44:47], v[108:111], v[36:39]
	v_mul_f32_e32 v1, v52, v1
	v_mul_f32_e32 v127, v1, v2
	v_add_f32_e32 v1, v57, v61
	v_mul_f32_e32 v1, 0xbfb8aa3b, v1
	v_exp_f32_e32 v1, v1
	v_add_f32_e32 v2, v53, v65
	v_mul_f32_e32 v2, 0xbfb8aa3b, v2
	v_exp_f32_e32 v2, v2
	v_add_f32_e32 v1, 1.0, v1
	v_rcp_f32_e32 v1, v1
	v_mfma_f32_16x16x32_bf16 v[24:27], v[24:27], v[100:103], 0
	v_add_f32_e32 v2, 1.0, v2
	v_rcp_f32_e32 v2, v2
	v_mul_f32_e32 v1, 0xc1000000, v1
	v_mul_f32_e32 v1, v158, v1
	v_mul_f32_e32 v1, 0x3fb8aa3b, v1
	v_exp_f32_e32 v52, v1
	v_mfma_f32_16x16x32_bf16 v[20:23], v[20:23], v[100:103], 0
	v_sub_f32_e32 v1, 1.0, v52
	v_add_f32_e32 v53, 1.0, v52
	v_mul_f32_e32 v1, v1, v53
	v_max_f32_e32 v1, 0, v1
	v_sqrt_f32_e32 v1, v1
	v_mfma_f32_16x16x32_bf16 v[24:27], v[32:35], v[108:111], v[24:27]
	v_mul_f32_e32 v1, v2, v1
	v_mul_f32_e32 v53, v1, v71
	v_add_f32_e32 v1, v58, v62
	v_mul_f32_e32 v1, 0xbfb8aa3b, v1
	v_exp_f32_e32 v1, v1
	ds_write2_b64 v177, v[126:127], v[52:53] offset1:17
	v_add_f32_e32 v2, v54, v66
	v_mul_f32_e32 v2, 0xbfb8aa3b, v2
	v_add_f32_e32 v1, 1.0, v1
	v_rcp_f32_e32 v1, v1
	v_exp_f32_e32 v2, v2
	v_mfma_f32_16x16x32_bf16 v[20:23], v[28:31], v[108:111], v[20:23]
	v_mov_b32_e32 v71, v86
	v_mul_f32_e32 v1, 0xc1000000, v1
	v_mul_f32_e32 v1, v159, v1
	v_mul_f32_e32 v1, 0x3fb8aa3b, v1
	v_exp_f32_e32 v52, v1
	v_add_f32_e32 v2, 1.0, v2
	v_rcp_f32_e32 v2, v2
	v_mfma_f32_16x16x32_bf16 v[8:11], v[8:11], v[100:103], 0
	v_sub_f32_e32 v1, 1.0, v52
	v_add_f32_e32 v53, 1.0, v52
	v_mul_f32_e32 v1, v1, v53
	v_max_f32_e32 v1, 0, v1
	v_sqrt_f32_e32 v1, v1
	v_mfma_f32_16x16x32_bf16 v[4:7], v[4:7], v[100:103], 0
	v_mul_f32_e32 v1, v2, v1
	v_mul_f32_e32 v53, v1, v79
	v_add_f32_e32 v1, v59, v63
	v_mul_f32_e32 v1, 0xbfb8aa3b, v1
	v_exp_f32_e32 v1, v1
	v_add_f32_e32 v2, v55, v67
	v_mul_f32_e32 v2, 0xbfb8aa3b, v2
	v_exp_f32_e32 v2, v2
	v_add_f32_e32 v1, 1.0, v1
	v_rcp_f32_e32 v1, v1
	v_mfma_f32_16x16x32_bf16 v[8:11], v[16:19], v[108:111], v[8:11]
	v_add_f32_e32 v2, 1.0, v2
	v_rcp_f32_e32 v2, v2
	v_mul_f32_e32 v1, 0xc1000000, v1
	v_mul_f32_e32 v1, v160, v1
	v_mul_f32_e32 v1, 0x3fb8aa3b, v1
	v_exp_f32_e32 v54, v1
	v_mfma_f32_16x16x32_bf16 v[4:7], v[12:15], v[108:111], v[4:7]
	v_mov_b32_e32 v79, v98
	v_sub_f32_e32 v1, 1.0, v54
	v_add_f32_e32 v55, 1.0, v54
	v_mul_f32_e32 v1, v1, v55
	v_max_f32_e32 v1, 0, v1
	v_sqrt_f32_e32 v1, v1
	s_nop 0
	v_mul_f32_e32 v1, v2, v1
	v_mul_f32_e32 v55, v1, v95
	ds_write2_b64 v177, v[52:53], v[54:55] offset0:34 offset1:51
	global_load_dwordx4 v[44:47], v[154:155], off offset:64
	global_load_dwordx4 v[48:51], v[152:153], off offset:64
	ds_read_b64 v[52:53], v174 offset:32
	s_waitcnt lgkmcnt(0)
	v_lshlrev_b32_e32 v1, 16, v52
	v_and_b32_e32 v2, 0xffff0000, v52
	v_lshlrev_b32_e32 v54, 16, v53
	v_and_b32_e32 v55, 0xffff0000, v53
	s_waitcnt vmcnt(1)
	v_add_f32_e32 v40, v40, v44
	v_mul_f32_e32 v40, 0xbfb8aa3b, v40
	v_exp_f32_e32 v40, v40
	s_waitcnt vmcnt(0)
	v_add_f32_e32 v36, v36, v48
	v_mul_f32_e32 v36, 0xbfb8aa3b, v36
	v_exp_f32_e32 v36, v36
	v_add_f32_e32 v40, 1.0, v40
	v_rcp_f32_e32 v40, v40
	v_add_f32_e32 v36, 1.0, v36
	v_rcp_f32_e32 v36, v36
	v_mul_f32_e32 v40, 0xc1000000, v40
	v_mul_f32_e32 v40, v161, v40
	v_mul_f32_e32 v40, 0x3fb8aa3b, v40
	v_exp_f32_e32 v52, v40
	s_nop 0
	v_sub_f32_e32 v40, 1.0, v52
	v_add_f32_e32 v44, 1.0, v52
	v_mul_f32_e32 v40, v40, v44
	v_max_f32_e32 v40, 0, v40
	v_sqrt_f32_e32 v40, v40
	s_nop 0
	v_mul_f32_e32 v36, v36, v40
	v_mul_f32_e32 v53, v36, v1
	v_add_f32_e32 v1, v41, v45
	v_mul_f32_e32 v1, 0xbfb8aa3b, v1
	v_exp_f32_e32 v1, v1
	v_add_f32_e32 v36, v37, v49
	v_mul_f32_e32 v36, 0xbfb8aa3b, v36
	v_exp_f32_e32 v36, v36
	v_add_f32_e32 v1, 1.0, v1
	v_rcp_f32_e32 v1, v1
	v_add_f32_e32 v36, 1.0, v36
	v_rcp_f32_e32 v37, v36
	v_mul_f32_e32 v1, 0xc1000000, v1
	v_mul_f32_e32 v1, v162, v1
	v_mul_f32_e32 v1, 0x3fb8aa3b, v1
	v_exp_f32_e32 v36, v1
	s_nop 0
	v_sub_f32_e32 v1, 1.0, v36
	v_add_f32_e32 v40, 1.0, v36
	v_mul_f32_e32 v1, v1, v40
	v_max_f32_e32 v1, 0, v1
	v_sqrt_f32_e32 v1, v1
	s_nop 0
	v_mul_f32_e32 v1, v37, v1
	v_mul_f32_e32 v37, v1, v2
	v_add_f32_e32 v1, v42, v46
	v_mul_f32_e32 v1, 0xbfb8aa3b, v1
	v_exp_f32_e32 v1, v1
	ds_write2_b64 v178, v[52:53], v[36:37] offset0:16 offset1:33
	v_add_f32_e32 v2, v38, v50
	v_mul_f32_e32 v2, 0xbfb8aa3b, v2
	v_add_f32_e32 v1, 1.0, v1
	v_rcp_f32_e32 v1, v1
	v_exp_f32_e32 v2, v2
	v_mul_f32_e32 v1, 0xc1000000, v1
	v_mul_f32_e32 v1, v164, v1
	v_mul_f32_e32 v1, 0x3fb8aa3b, v1
	v_exp_f32_e32 v36, v1
	v_add_f32_e32 v2, 1.0, v2
	v_rcp_f32_e32 v2, v2
	v_sub_f32_e32 v1, 1.0, v36
	v_add_f32_e32 v37, 1.0, v36
	v_mul_f32_e32 v1, v1, v37
	v_max_f32_e32 v1, 0, v1
	v_sqrt_f32_e32 v1, v1
	s_nop 0
	v_mul_f32_e32 v1, v2, v1
	v_mul_f32_e32 v37, v1, v54
	v_add_f32_e32 v1, v43, v47
	v_mul_f32_e32 v1, 0xbfb8aa3b, v1
	v_exp_f32_e32 v1, v1
	v_add_f32_e32 v2, v39, v51
	v_mul_f32_e32 v2, 0xbfb8aa3b, v2
	v_exp_f32_e32 v2, v2
	v_add_f32_e32 v1, 1.0, v1
	v_rcp_f32_e32 v1, v1
	v_add_f32_e32 v2, 1.0, v2
	v_rcp_f32_e32 v2, v2
	v_mul_f32_e32 v1, 0xc1000000, v1
	v_mul_f32_e32 v1, v166, v1
	v_mul_f32_e32 v1, 0x3fb8aa3b, v1
	v_exp_f32_e32 v38, v1
	s_nop 0
	v_sub_f32_e32 v1, 1.0, v38
	v_add_f32_e32 v39, 1.0, v38
	v_mul_f32_e32 v1, v1, v39
	v_max_f32_e32 v1, 0, v1
	v_sqrt_f32_e32 v1, v1
	s_nop 0
	v_mul_f32_e32 v1, v2, v1
	v_mul_f32_e32 v39, v1, v55
	ds_write2_b64 v178, v[36:37], v[38:39] offset0:50 offset1:67
	global_load_dwordx4 v[28:31], v[154:155], off offset:128
	global_load_dwordx4 v[32:35], v[152:153], off offset:128
	ds_read_b64 v[36:37], v174 offset:64
	s_waitcnt lgkmcnt(0)
	v_lshlrev_b32_e32 v1, 16, v36
	v_and_b32_e32 v2, 0xffff0000, v36
	v_lshlrev_b32_e32 v38, 16, v37
	v_and_b32_e32 v39, 0xffff0000, v37
	s_waitcnt vmcnt(1)
	v_add_f32_e32 v24, v24, v28
	v_mul_f32_e32 v24, 0xbfb8aa3b, v24
	v_exp_f32_e32 v24, v24
	s_waitcnt vmcnt(0)
	v_add_f32_e32 v20, v20, v32
	v_mul_f32_e32 v20, 0xbfb8aa3b, v20
	v_exp_f32_e32 v20, v20
	v_add_f32_e32 v24, 1.0, v24
	v_rcp_f32_e32 v24, v24
	v_mov_b32_e32 v32, v98
	v_add_f32_e32 v20, 1.0, v20
	v_rcp_f32_e32 v20, v20
	v_mul_f32_e32 v24, 0xc1000000, v24
	v_mul_f32_e32 v24, v163, v24
	v_mul_f32_e32 v24, 0x3fb8aa3b, v24
	v_exp_f32_e32 v36, v24
	s_nop 0
	v_sub_f32_e32 v24, 1.0, v36
	v_add_f32_e32 v28, 1.0, v36
	v_mul_f32_e32 v24, v24, v28
	v_max_f32_e32 v24, 0, v24
	v_sqrt_f32_e32 v24, v24
	s_nop 0
	v_mul_f32_e32 v20, v20, v24
	v_mul_f32_e32 v37, v20, v1
	v_add_f32_e32 v1, v25, v29
	v_mul_f32_e32 v1, 0xbfb8aa3b, v1
	v_exp_f32_e32 v1, v1
	v_add_f32_e32 v20, v21, v33
	v_mul_f32_e32 v20, 0xbfb8aa3b, v20
	v_exp_f32_e32 v20, v20
	v_add_f32_e32 v1, 1.0, v1
	v_rcp_f32_e32 v1, v1
	v_add_f32_e32 v20, 1.0, v20
	v_rcp_f32_e32 v21, v20
	v_mul_f32_e32 v1, 0xc1000000, v1
	v_mul_f32_e32 v1, v165, v1
	v_mul_f32_e32 v1, 0x3fb8aa3b, v1
	v_exp_f32_e32 v20, v1
	s_nop 0
	v_sub_f32_e32 v1, 1.0, v20
	v_add_f32_e32 v24, 1.0, v20
	v_mul_f32_e32 v1, v1, v24
	v_max_f32_e32 v1, 0, v1
	v_sqrt_f32_e32 v1, v1
	s_nop 0
	v_mul_f32_e32 v1, v21, v1
	v_mul_f32_e32 v21, v1, v2
	v_add_f32_e32 v1, v26, v30
	v_mul_f32_e32 v1, 0xbfb8aa3b, v1
	v_exp_f32_e32 v1, v1
	ds_write2_b64 v179, v[36:37], v[20:21] offset0:32 offset1:49
	v_add_f32_e32 v2, v22, v34
	v_mul_f32_e32 v2, 0xbfb8aa3b, v2
	v_add_f32_e32 v1, 1.0, v1
	v_rcp_f32_e32 v1, v1
	v_exp_f32_e32 v2, v2
	v_mul_f32_e32 v1, 0xc1000000, v1
	v_mul_f32_e32 v1, v167, v1
	v_mul_f32_e32 v1, 0x3fb8aa3b, v1
	v_exp_f32_e32 v20, v1
	v_add_f32_e32 v2, 1.0, v2
	v_rcp_f32_e32 v2, v2
	v_sub_f32_e32 v1, 1.0, v20
	v_add_f32_e32 v21, 1.0, v20
	v_mul_f32_e32 v1, v1, v21
	v_max_f32_e32 v1, 0, v1
	v_sqrt_f32_e32 v1, v1
	s_nop 0
	v_mul_f32_e32 v1, v2, v1
	v_mul_f32_e32 v21, v1, v38
	v_add_f32_e32 v1, v27, v31
	v_mul_f32_e32 v1, 0xbfb8aa3b, v1
	v_exp_f32_e32 v1, v1
	v_add_f32_e32 v2, v23, v35
	v_mul_f32_e32 v2, 0xbfb8aa3b, v2
	v_exp_f32_e32 v2, v2
	v_add_f32_e32 v1, 1.0, v1
	v_rcp_f32_e32 v1, v1
	v_add_f32_e32 v2, 1.0, v2
	v_rcp_f32_e32 v2, v2
	v_mul_f32_e32 v1, 0xc1000000, v1
	v_mul_f32_e32 v1, v168, v1
	v_mul_f32_e32 v1, 0x3fb8aa3b, v1
	v_exp_f32_e32 v22, v1
	s_nop 0
	v_sub_f32_e32 v1, 1.0, v22
	v_add_f32_e32 v23, 1.0, v22
	v_mul_f32_e32 v1, v1, v23
	v_max_f32_e32 v1, 0, v1
	v_sqrt_f32_e32 v1, v1
	s_nop 0
	v_mul_f32_e32 v1, v2, v1
	v_mul_f32_e32 v23, v1, v39
	ds_write2_b64 v179, v[20:21], v[22:23] offset0:66 offset1:83
	global_load_dwordx4 v[12:15], v[154:155], off offset:192
	global_load_dwordx4 v[16:19], v[152:153], off offset:192
	ds_read_b64 v[20:21], v174 offset:96
	s_waitcnt lgkmcnt(0)
	v_lshlrev_b32_e32 v1, 16, v20
	v_and_b32_e32 v2, 0xffff0000, v20
	v_lshlrev_b32_e32 v22, 16, v21
	v_and_b32_e32 v23, 0xffff0000, v21
	s_waitcnt vmcnt(1)
	v_add_f32_e32 v8, v8, v12
	v_mul_f32_e32 v8, 0xbfb8aa3b, v8
	v_exp_f32_e32 v8, v8
	s_waitcnt vmcnt(0)
	v_add_f32_e32 v4, v4, v16
	v_mul_f32_e32 v4, 0xbfb8aa3b, v4
	v_exp_f32_e32 v4, v4
	v_add_f32_e32 v8, 1.0, v8
	v_rcp_f32_e32 v8, v8
	v_add_f32_e32 v4, 1.0, v4
	v_rcp_f32_e32 v4, v4
	v_mul_f32_e32 v8, 0xc1000000, v8
	v_mul_f32_e32 v8, v169, v8
	v_mul_f32_e32 v8, 0x3fb8aa3b, v8
	v_exp_f32_e32 v20, v8
	s_nop 0
	v_sub_f32_e32 v8, 1.0, v20
	v_add_f32_e32 v12, 1.0, v20
	v_mul_f32_e32 v8, v8, v12
	v_max_f32_e32 v8, 0, v8
	v_sqrt_f32_e32 v8, v8
	s_nop 0
	v_mul_f32_e32 v4, v4, v8
	v_mul_f32_e32 v21, v4, v1
	v_add_f32_e32 v1, v9, v13
	v_mul_f32_e32 v1, 0xbfb8aa3b, v1
	v_exp_f32_e32 v1, v1
	v_add_f32_e32 v4, v5, v17
	v_mul_f32_e32 v4, 0xbfb8aa3b, v4
	v_exp_f32_e32 v4, v4
	v_add_f32_e32 v1, 1.0, v1
	v_rcp_f32_e32 v1, v1
	v_mov_b32_e32 v9, v84
	v_add_f32_e32 v4, 1.0, v4
	v_rcp_f32_e32 v5, v4
	v_mul_f32_e32 v1, 0xc1000000, v1
	v_mul_f32_e32 v1, v170, v1
	v_mul_f32_e32 v1, 0x3fb8aa3b, v1
	v_exp_f32_e32 v4, v1
	s_nop 0
	v_sub_f32_e32 v1, 1.0, v4
	v_add_f32_e32 v8, 1.0, v4
	v_mul_f32_e32 v1, v1, v8
	v_max_f32_e32 v1, 0, v1
	v_sqrt_f32_e32 v1, v1
	v_mov_b32_e32 v8, v74
	v_mul_f32_e32 v1, v5, v1
	v_mul_f32_e32 v5, v1, v2
	v_add_f32_e32 v1, v10, v14
	v_mul_f32_e32 v1, 0xbfb8aa3b, v1
	v_exp_f32_e32 v1, v1
	ds_write2_b64 v175, v[20:21], v[4:5] offset0:48 offset1:65
	v_add_f32_e32 v2, v6, v18
	v_mul_f32_e32 v2, 0xbfb8aa3b, v2
	v_add_f32_e32 v1, 1.0, v1
	v_rcp_f32_e32 v1, v1
	v_exp_f32_e32 v2, v2
	v_mul_f32_e32 v1, 0xc1000000, v1
	v_mul_f32_e32 v1, v172, v1
	v_mul_f32_e32 v1, 0x3fb8aa3b, v1
	v_exp_f32_e32 v4, v1
	v_add_f32_e32 v2, 1.0, v2
	v_rcp_f32_e32 v2, v2
	v_sub_f32_e32 v1, 1.0, v4
	v_add_f32_e32 v5, 1.0, v4
	v_mul_f32_e32 v1, v1, v5
	v_max_f32_e32 v1, 0, v1
	v_sqrt_f32_e32 v1, v1
	s_nop 0
	v_mul_f32_e32 v1, v2, v1
	v_mul_f32_e32 v5, v1, v22
	v_add_f32_e32 v1, v11, v15
	v_mul_f32_e32 v1, 0xbfb8aa3b, v1
	v_exp_f32_e32 v1, v1
	v_add_f32_e32 v2, v7, v19
	v_mul_f32_e32 v2, 0xbfb8aa3b, v2
	v_exp_f32_e32 v2, v2
	v_add_f32_e32 v1, 1.0, v1
	v_rcp_f32_e32 v1, v1
	v_add_f32_e32 v2, 1.0, v2
	v_rcp_f32_e32 v2, v2
	v_mul_f32_e32 v1, 0xc1000000, v1
	v_mul_f32_e32 v1, v173, v1
	v_mul_f32_e32 v1, 0x3fb8aa3b, v1
	v_exp_f32_e32 v6, v1
	s_nop 0
	v_sub_f32_e32 v1, 1.0, v6
	v_add_f32_e32 v7, 1.0, v6
	v_mul_f32_e32 v1, v1, v7
	v_max_f32_e32 v1, 0, v1
	v_sqrt_f32_e32 v1, v1
	s_nop 0
	v_mul_f32_e32 v1, v2, v1
	v_mul_f32_e32 v7, v1, v23
	ds_write2_b64 v175, v[4:5], v[6:7] offset0:82 offset1:99
	v_pk_mul_f32 v[4:5], v[124:125], v[70:71]
	v_pk_fma_f32 v[6:7], v[124:125], v[70:71], v[86:87]
	v_pk_mul_f32 v[4:5], v[4:5], v[68:69]
	s_waitcnt lgkmcnt(0)
	v_mov_b32_e32 v6, v4
	v_pk_mul_f32 v[4:5], v[4:5], v[74:75]
	v_pk_fma_f32 v[6:7], v[6:7], v[8:9], v[84:85]
	v_pk_mul_f32 v[4:5], v[4:5], v[72:73]
	s_barrier
	ds_read2_b64 v[16:19], v183 offset1:1
	v_mov_b32_e32 v5, v7
	v_pk_mul_f32 v[6:7], v[4:5], v[78:79]
	v_pk_fma_f32 v[4:5], v[4:5], v[78:79], v[98:99]
	v_pk_mul_f32 v[6:7], v[6:7], v[76:77]
	v_mov_b32_e32 v8, v82
	v_mov_b32_e32 v4, v6
	v_mov_b32_e32 v9, v96
	v_pk_mul_f32 v[6:7], v[6:7], v[82:83]
	v_pk_fma_f32 v[4:5], v[4:5], v[8:9], v[96:97]
	v_pk_mul_f32 v[6:7], v[6:7], v[80:81]
	s_waitcnt lgkmcnt(0)
	v_mov_b32_e32 v115, v18
	v_mov_b32_e32 v7, v5
	v_pk_mul_f32 v[4:5], v[6:7], v[114:115]
	ds_read2_b64 v[20:23], v180 offset1:1
	ds_read2_b64 v[24:27], v182 offset1:1
	v_pk_mul_f32 v[4:5], v[4:5], v[112:113]
	v_pk_fma_f32 v[6:7], v[6:7], v[114:115], v[18:19]
	v_mov_b32_e32 v8, v122
	v_mov_b32_e32 v6, v4
	v_mov_b32_e32 v9, v16
	v_pk_mul_f32 v[4:5], v[4:5], v[122:123]
	v_pk_fma_f32 v[6:7], v[6:7], v[8:9], v[16:17]
	v_pk_mul_f32 v[4:5], v[4:5], v[120:121]
	s_waitcnt lgkmcnt(1)
	v_mov_b32_e32 v119, v22
	v_mov_b32_e32 v5, v7
	v_pk_mul_f32 v[6:7], v[4:5], v[118:119]
	v_pk_fma_f32 v[4:5], v[4:5], v[118:119], v[22:23]
	v_pk_mul_f32 v[6:7], v[6:7], v[116:117]
	v_mov_b32_e32 v8, v106
	v_mov_b32_e32 v4, v6
	v_mov_b32_e32 v9, v20
	v_pk_mul_f32 v[6:7], v[6:7], v[106:107]
	v_pk_fma_f32 v[4:5], v[4:5], v[8:9], v[20:21]
	v_pk_mul_f32 v[6:7], v[6:7], v[104:105]
	s_waitcnt lgkmcnt(0)
	v_mov_b32_e32 v95, v26
	v_mov_b32_e32 v7, v5
	v_pk_mul_f32 v[4:5], v[6:7], v[94:95]
	v_pk_fma_f32 v[6:7], v[6:7], v[94:95], v[26:27]
	v_pk_mul_f32 v[4:5], v[4:5], v[92:93]
	v_mov_b32_e32 v8, v90
	v_mov_b32_e32 v6, v4
	v_mov_b32_e32 v9, v24
	v_pk_mul_f32 v[4:5], v[4:5], v[90:91]
	v_ashrrev_i32_e32 v1, 31, v0
	v_pk_mul_f32 v[28:29], v[4:5], v[88:89]
	v_pk_fma_f32 v[4:5], v[6:7], v[8:9], v[24:25]
	v_lshl_add_u64 v[0:1], v[0:1], 3, s[0:1]
	v_mov_b32_e32 v29, v5
	ds_read2_b64 v[12:15], v181 offset1:1
	ds_read2_b64 v[8:11], v184 offset1:1
	ds_read2_b64 v[4:7], v186 offset1:1
	s_waitcnt lgkmcnt(2)
	v_mov_b32_e32 v87, v14
	v_pk_mul_f32 v[30:31], v[28:29], v[86:87]
	v_pk_fma_f32 v[28:29], v[28:29], v[86:87], v[14:15]
	v_pk_mul_f32 v[30:31], v[30:31], v[84:85]
	v_mov_b32_e32 v33, v12
	v_mov_b32_e32 v28, v30
	v_pk_mul_f32 v[30:31], v[30:31], v[98:99]
	v_pk_fma_f32 v[28:29], v[28:29], v[32:33], v[12:13]
	v_pk_mul_f32 v[30:31], v[30:31], v[96:97]
	s_waitcnt lgkmcnt(1)
	v_mov_b32_e32 v19, v10
	v_mov_b32_e32 v31, v29
	v_pk_mul_f32 v[28:29], v[30:31], v[18:19]
	v_pk_fma_f32 v[18:19], v[30:31], v[18:19], v[10:11]
	v_pk_mul_f32 v[16:17], v[28:29], v[16:17]
	v_mov_b32_e32 v28, v22
	v_mov_b32_e32 v18, v16
	v_mov_b32_e32 v29, v8
	v_pk_mul_f32 v[16:17], v[16:17], v[22:23]
	v_pk_fma_f32 v[18:19], v[18:19], v[28:29], v[8:9]
	v_pk_mul_f32 v[16:17], v[16:17], v[20:21]
	s_waitcnt lgkmcnt(0)
	v_mov_b32_e32 v27, v6
	v_mov_b32_e32 v17, v19
	v_pk_mul_f32 v[18:19], v[16:17], v[26:27]
	v_pk_fma_f32 v[20:21], v[16:17], v[26:27], v[6:7]
	v_pk_mul_f32 v[22:23], v[18:19], v[24:25]
	ds_read2_b64 v[16:19], v185 offset1:1
	ds_read2_b64 v[24:27], v171 offset1:1
	v_mov_b32_e32 v20, v22
	v_mov_b32_e32 v28, v14
	v_mov_b32_e32 v29, v4
	v_pk_mul_f32 v[14:15], v[22:23], v[14:15]
	s_waitcnt lgkmcnt(1)
	v_mov_b32_e32 v11, v18
	v_pk_mul_f32 v[12:13], v[14:15], v[12:13]
	v_pk_fma_f32 v[14:15], v[20:21], v[28:29], v[4:5]
	s_waitcnt lgkmcnt(0)
	v_mov_b32_e32 v13, v15
	v_pk_mul_f32 v[14:15], v[12:13], v[10:11]
	v_pk_fma_f32 v[10:11], v[12:13], v[10:11], v[18:19]
	v_pk_mul_f32 v[8:9], v[14:15], v[8:9]
	v_mov_b32_e32 v12, v6
	v_mov_b32_e32 v10, v8
	v_mov_b32_e32 v13, v16
	v_pk_mul_f32 v[6:7], v[8:9], v[6:7]
	v_mov_b32_e32 v19, v26
	v_pk_mul_f32 v[4:5], v[6:7], v[4:5]
	v_pk_fma_f32 v[6:7], v[10:11], v[12:13], v[16:17]
	v_mov_b32_e32 v8, v26
	v_mov_b32_e32 v5, v7
	v_pk_mul_f32 v[6:7], v[4:5], v[18:19]
	v_pk_fma_f32 v[4:5], v[4:5], v[18:19], v[26:27]
	v_pk_mul_f32 v[6:7], v[6:7], v[16:17]
	v_mov_b32_e32 v9, v24
	v_mov_b32_e32 v4, v6
	v_pk_mul_f32 v[6:7], v[6:7], v[26:27]
	v_pk_fma_f32 v[4:5], v[4:5], v[8:9], v[24:25]
	v_pk_mul_f32 v[6:7], v[6:7], v[24:25]
	s_barrier
	v_mov_b32_e32 v7, v5
	global_store_dwordx2 v[0:1], v[6:7], off

.LBB0_895:
	v_mov_b32_e32 v14, v222
	v_readlane_b32 s0, v252, 46
	v_ashrrev_i32_e32 v2, 6, v14
	v_bfe_u32 v16, v14, 4, 2
	v_add_u32_e32 v0, s0, v2
	v_readlane_b32 s0, v252, 47
	v_ashrrev_i32_e32 v1, 31, v0
	v_lshlrev_b64 v[0:1], 13, v[0:1]
	v_add_u32_e32 v4, s0, v2
	v_ashrrev_i32_e32 v5, 31, v4
	v_and_b32_e32 v15, 15, v14
	v_lshl_add_u64 v[0:1], s[84:85], 0, v[0:1]
	v_lshlrev_b64 v[4:5], 13, v[4:5]
	v_lshlrev_b32_e32 v2, 4, v16
	v_lshl_add_u64 v[4:5], s[84:85], 0, v[4:5]
	v_lshl_add_u64 v[0:1], v[0:1], 0, v[2:3]
	v_lshlrev_b32_e32 v6, 7, v15
	v_mov_b32_e32 v7, v3
	v_lshl_add_u64 v[4:5], v[4:5], 0, v[2:3]
	v_lshl_add_u64 v[8:9], v[0:1], 0, v[6:7]
	v_lshl_add_u64 v[10:11], v[4:5], 0, v[6:7]
	global_load_dwordx4 v[120:123], v[8:9], off
	global_load_dwordx4 v[116:119], v[10:11], off
	global_load_dwordx4 v[162:165], v[8:9], off offset:64
	global_load_dwordx4 v[124:127], v[10:11], off offset:64
	global_load_dwordx4 v[104:107], v[8:9], off offset:2048
	global_load_dwordx4 v[100:103], v[10:11], off offset:2048
	global_load_dwordx4 v[112:115], v[8:9], off offset:2112
	global_load_dwordx4 v[108:111], v[10:11], off offset:2112
	v_or_b32_e32 v8, 0x1000, v6
	v_mov_b32_e32 v9, v3
	v_lshl_add_u64 v[10:11], v[0:1], 0, v[8:9]
	v_lshl_add_u64 v[8:9], v[4:5], 0, v[8:9]
	global_load_dwordx4 v[88:91], v[10:11], off
	global_load_dwordx4 v[84:87], v[8:9], off
	global_load_dwordx4 v[96:99], v[10:11], off offset:64
	global_load_dwordx4 v[92:95], v[8:9], off offset:64
	v_or_b32_e32 v6, 0x1800, v6
	v_and_b32_e32 v8, 0xffffffc0, v14
	v_lshl_add_u64 v[0:1], v[0:1], 0, v[6:7]
	v_ashrrev_i32_e32 v9, 31, v8
	v_readlane_b32 s0, v252, 48
	v_lshl_add_u64 v[4:5], v[4:5], 0, v[6:7]
	global_load_dwordx4 v[72:75], v[0:1], off
	global_load_dwordx4 v[68:71], v[4:5], off
	global_load_dwordx4 v[80:83], v[0:1], off offset:64
	global_load_dwordx4 v[76:79], v[4:5], off offset:64
	v_lshlrev_b64 v[0:1], 2, v[8:9]
	v_readlane_b32 s1, v252, 49
	s_movk_i32 s6, 0x88
	v_lshl_or_b32 v33, v16, 2, v8
	v_lshl_add_u64 v[10:11], s[0:1], 0, v[0:1]
	v_readlane_b32 s0, v252, 50
	v_readlane_b32 s1, v252, 51
	v_lshlrev_b32_e32 v34, 3, v15
	v_lshlrev_b32_e32 v17, 3, v16
	v_lshl_add_u64 v[4:5], s[0:1], 0, v[0:1]
	v_lshl_add_u64 v[12:13], v[4:5], 0, v[2:3]
	v_readlane_b32 s0, v252, 52
	v_readlane_b32 s1, v252, 53
	s_mov_b32 s7, 0x1f000
	s_movk_i32 s22, 0xd000
	v_lshl_add_u64 v[0:1], s[0:1], 0, v[0:1]
	v_lshl_add_u64 v[170:171], v[0:1], 0, v[2:3]
	v_lshl_add_u64 v[0:1], v[10:11], 0, v[2:3]
	v_readlane_b32 s0, v252, 54
	s_movk_i32 s13, 0xb000
	s_movk_i32 s12, 0x9000
	s_mov_b32 s33, 0xffff6000
	s_mov_b32 s38, 0xffff4000
	s_mov_b32 s39, 0xffff2000
	s_mov_b32 s42, 0xffff1000
	s_mov_b32 s43, 0xfffef000
	s_mov_b32 s56, 0xfffed000
	s_mov_b32 s57, 0xfffeb000
	s_mov_b32 s58, 0xfffea000
	s_mov_b32 s59, 0xfffe6000
	s_waitcnt vmcnt(0)
	s_lshl_b32 s98, s16, 11
	s_add_u32 s98, s98, 0x8000
	s_add_u32 s98, s30, s98
	s_addc_u32 s99, s31, 0
	v_lshrrev_b32_e32 v187, 4, v222
	v_and_b32_e32 v186, 3, v187
	v_lshrrev_b32_e32 v187, 2, v187
	v_lshlrev_b32_e32 v186, 4, v186
	v_lshl_or_b32 v187, v187, 8, v186
	global_load_dword v172, v187, s[98:99]
	global_load_dword v173, v187, s[98:99] offset:4
	global_load_dword v174, v187, s[98:99] offset:8
	global_load_dword v175, v187, s[98:99] offset:12
	global_load_dword v176, v187, s[98:99] offset:64
	global_load_dword v177, v187, s[98:99] offset:68
	global_load_dword v179, v187, s[98:99] offset:72
	global_load_dword v181, v187, s[98:99] offset:76
	global_load_dword v178, v187, s[98:99] offset:128
	global_load_dword v180, v187, s[98:99] offset:132
	global_load_dword v182, v187, s[98:99] offset:136
	global_load_dword v183, v187, s[98:99] offset:140
	global_load_dword v184, v187, s[98:99] offset:192
	global_load_dword v185, v187, s[98:99] offset:196
	global_load_dword v186, v187, s[98:99] offset:200
	global_load_dword v187, v187, s[98:99] offset:204
	v_mul_lo_u32 v5, v14, s6
	v_add_u32_e32 v32, 32, v5
	v_mul_u32_u24_e32 v5, 0x220, v15
	v_add_u32_e32 v188, 0x8800, v32
	v_lshl_add_u32 v4, v8, 1, 32
	v_add3_u32 v166, v4, v5, v2
	ds_read_b128 v[4:7], v166
	ds_read_b128 v[8:11], v166 offset:64
	global_load_dwordx4 v[20:23], v[170:171], off
	global_load_dwordx4 v[24:27], v[0:1], off
	s_waitcnt lgkmcnt(1)
	v_mfma_f32_16x16x32_bf16 v[12:15], v[120:123], v[4:7], 0
	v_sub_u32_e32 v2, v166, v17
	ds_read_b64 v[28:29], v2
	s_waitcnt lgkmcnt(0)
	v_lshlrev_b32_e32 v31, 16, v28
	v_mfma_f32_16x16x32_bf16 v[16:19], v[162:165], v[8:11], v[12:15]
	v_and_b32_e32 v35, 0xffff0000, v28
	v_lshlrev_b32_e32 v36, 16, v29
	v_and_b32_e32 v29, 0xffff0000, v29
	v_mfma_f32_16x16x32_bf16 v[12:15], v[116:119], v[4:7], 0
	v_mfma_f32_16x16x32_bf16 v[12:15], v[124:127], v[8:11], v[12:15]
	s_waitcnt vmcnt(1)
	s_nop 1
	v_add_f32_e32 v16, v16, v20
	v_mul_f32_e32 v16, 0xbfb8aa3b, v16
	v_exp_f32_e32 v16, v16
	s_waitcnt vmcnt(0)
	s_nop 0
	v_add_f32_e32 v12, v12, v24
	v_mul_f32_e32 v12, 0xbfb8aa3b, v12
	v_exp_f32_e32 v12, v12
	v_add_f32_e32 v16, 1.0, v16
	v_rcp_f32_e32 v16, v16
	v_add_f32_e32 v13, v13, v25
	v_add_f32_e32 v12, 1.0, v12
	v_rcp_f32_e32 v12, v12
	v_mul_f32_e32 v16, 0xc1000000, v16
	s_waitcnt vmcnt(0)
	v_mul_f32_e32 v16, v16, v172
	v_mul_f32_e32 v16, 0x3fb8aa3b, v16
	v_exp_f32_e32 v30, v16
	v_mul_f32_e32 v13, 0xbfb8aa3b, v13
	v_exp_f32_e32 v13, v13
	v_add_f32_e32 v15, v15, v27
	v_sub_f32_e32 v16, 1.0, v30
	v_add_f32_e32 v20, 1.0, v30
	v_mul_f32_e32 v16, v16, v20
	v_max_f32_e32 v16, 0, v16
	v_sqrt_f32_e32 v16, v16
	v_add_f32_e32 v13, 1.0, v13
	v_rcp_f32_e32 v13, v13
	v_mul_f32_e32 v15, 0xbfb8aa3b, v15
	v_mul_f32_e32 v12, v12, v16
	v_mul_f32_e32 v31, v12, v31
	v_mul_lo_u32 v12, v33, s6
	v_add3_u32 v28, 32, v34, v12
	v_add_f32_e32 v12, v17, v21
	v_mul_f32_e32 v12, 0xbfb8aa3b, v12
	v_exp_f32_e32 v12, v12
	v_add_u32_e32 v190, 0x8800, v28
	v_exp_f32_e32 v15, v15
	v_add_u32_e32 v191, 0x9000, v28
	v_add_f32_e32 v12, 1.0, v12
	v_rcp_f32_e32 v12, v12
	v_add_f32_e32 v15, 1.0, v15
	v_rcp_f32_e32 v15, v15
	v_add_u32_e32 v192, 0x9800, v28
	v_mul_f32_e32 v12, 0xc1000000, v12
	v_mul_f32_e32 v12, v12, v173
	v_mul_f32_e32 v12, 0x3fb8aa3b, v12
	v_exp_f32_e32 v12, v12
	v_add_u32_e32 v189, 0xa000, v28
	v_sub_f32_e32 v16, 1.0, v12
	v_add_f32_e32 v17, 1.0, v12
	v_mul_f32_e32 v16, v16, v17
	v_max_f32_e32 v16, 0, v16
	v_sqrt_f32_e32 v16, v16
	s_nop 0
	v_mul_f32_e32 v13, v13, v16
	v_mul_f32_e32 v13, v13, v35
	ds_write2_b64 v190, v[30:31], v[12:13] offset1:17
	v_add_f32_e32 v12, v18, v22
	v_mul_f32_e32 v12, 0xbfb8aa3b, v12
	v_exp_f32_e32 v12, v12
	v_add_f32_e32 v13, v14, v26
	v_mul_f32_e32 v13, 0xbfb8aa3b, v13
	v_exp_f32_e32 v13, v13
	v_add_f32_e32 v12, 1.0, v12
	v_rcp_f32_e32 v12, v12
	v_add_f32_e32 v13, 1.0, v13
	v_rcp_f32_e32 v13, v13
	v_mul_f32_e32 v12, 0xc1000000, v12
	v_mul_f32_e32 v12, v12, v174
	v_mul_f32_e32 v12, 0x3fb8aa3b, v12
	v_exp_f32_e32 v12, v12
	s_nop 0
	v_sub_f32_e32 v14, 1.0, v12
	v_add_f32_e32 v16, 1.0, v12
	v_mul_f32_e32 v14, v14, v16
	v_max_f32_e32 v14, 0, v14
	v_sqrt_f32_e32 v14, v14
	s_nop 0
	v_mul_f32_e32 v13, v13, v14
	v_add_f32_e32 v14, v19, v23
	v_mul_f32_e32 v14, 0xbfb8aa3b, v14
	v_exp_f32_e32 v14, v14
	v_mul_f32_e32 v13, v13, v36
	v_add_f32_e32 v14, 1.0, v14
	v_rcp_f32_e32 v14, v14
	s_nop 0
	v_mul_f32_e32 v14, 0xc1000000, v14
	v_mul_f32_e32 v14, v14, v175
	v_mul_f32_e32 v14, 0x3fb8aa3b, v14
	v_exp_f32_e32 v14, v14
	s_nop 0
	v_sub_f32_e32 v16, 1.0, v14
	v_add_f32_e32 v17, 1.0, v14
	v_mul_f32_e32 v16, v16, v17
	v_max_f32_e32 v16, 0, v16
	v_sqrt_f32_e32 v16, v16
	s_nop 0
	v_mul_f32_e32 v15, v15, v16
	v_mul_f32_e32 v15, v15, v29
	ds_write2_b64 v190, v[12:13], v[14:15] offset0:34 offset1:51
	global_load_dwordx4 v[20:23], v[170:171], off offset:64
	global_load_dwordx4 v[24:27], v[0:1], off offset:64
	v_mfma_f32_16x16x32_bf16 v[12:15], v[104:107], v[4:7], 0
	ds_read_b64 v[30:31], v2 offset:32
	s_waitcnt lgkmcnt(0)
	v_lshlrev_b32_e32 v29, 16, v30
	v_mfma_f32_16x16x32_bf16 v[16:19], v[112:115], v[8:11], v[12:15]
	v_and_b32_e32 v33, 0xffff0000, v30
	v_lshlrev_b32_e32 v34, 16, v31
	v_and_b32_e32 v35, 0xffff0000, v31
	v_mfma_f32_16x16x32_bf16 v[12:15], v[100:103], v[4:7], 0
	v_mfma_f32_16x16x32_bf16 v[12:15], v[108:111], v[8:11], v[12:15]
	s_waitcnt vmcnt(1)
	s_nop 1
	v_add_f32_e32 v16, v16, v20
	v_mul_f32_e32 v16, 0xbfb8aa3b, v16
	v_exp_f32_e32 v16, v16
	s_waitcnt vmcnt(0)
	s_nop 0
	v_add_f32_e32 v12, v12, v24
	v_mul_f32_e32 v12, 0xbfb8aa3b, v12
	v_exp_f32_e32 v12, v12
	v_add_f32_e32 v16, 1.0, v16
	v_rcp_f32_e32 v16, v16
	v_add_f32_e32 v13, v13, v25
	v_add_f32_e32 v12, 1.0, v12
	v_rcp_f32_e32 v12, v12
	v_mul_f32_e32 v16, 0xc1000000, v16
	v_mul_f32_e32 v16, v16, v176
	v_mul_f32_e32 v16, 0x3fb8aa3b, v16
	v_exp_f32_e32 v30, v16
	v_mul_f32_e32 v13, 0xbfb8aa3b, v13
	v_exp_f32_e32 v13, v13
	v_add_f32_e32 v15, v15, v27
	v_sub_f32_e32 v16, 1.0, v30
	v_add_f32_e32 v20, 1.0, v30
	v_mul_f32_e32 v16, v16, v20
	v_max_f32_e32 v16, 0, v16
	v_sqrt_f32_e32 v16, v16
	v_add_f32_e32 v13, 1.0, v13
	v_rcp_f32_e32 v13, v13
	v_mul_f32_e32 v15, 0xbfb8aa3b, v15
	v_mul_f32_e32 v12, v12, v16
	v_mul_f32_e32 v31, v12, v29
	v_add_f32_e32 v12, v17, v21
	v_mul_f32_e32 v12, 0xbfb8aa3b, v12
	v_exp_f32_e32 v12, v12
	v_exp_f32_e32 v15, v15
	v_add_f32_e32 v12, 1.0, v12
	v_rcp_f32_e32 v12, v12
	v_add_f32_e32 v15, 1.0, v15
	v_rcp_f32_e32 v15, v15
	v_mul_f32_e32 v12, 0xc1000000, v12
	v_mul_f32_e32 v12, v12, v177
	v_mul_f32_e32 v12, 0x3fb8aa3b, v12
	v_exp_f32_e32 v12, v12
	s_nop 0
	v_sub_f32_e32 v16, 1.0, v12
	v_add_f32_e32 v17, 1.0, v12
	v_mul_f32_e32 v16, v16, v17
	v_max_f32_e32 v16, 0, v16
	v_sqrt_f32_e32 v16, v16
	s_nop 0
	v_mul_f32_e32 v13, v13, v16
	v_mul_f32_e32 v13, v13, v33
	ds_write2_b64 v191, v[30:31], v[12:13] offset0:16 offset1:33
	v_add_f32_e32 v12, v18, v22
	v_mul_f32_e32 v12, 0xbfb8aa3b, v12
	v_exp_f32_e32 v12, v12
	v_add_f32_e32 v13, v14, v26
	v_mul_f32_e32 v13, 0xbfb8aa3b, v13
	v_exp_f32_e32 v13, v13
	v_add_f32_e32 v12, 1.0, v12
	v_rcp_f32_e32 v12, v12
	v_add_f32_e32 v13, 1.0, v13
	v_rcp_f32_e32 v13, v13
	v_mul_f32_e32 v12, 0xc1000000, v12
	v_mul_f32_e32 v12, v12, v179
	v_mul_f32_e32 v12, 0x3fb8aa3b, v12
	v_exp_f32_e32 v12, v12
	s_nop 0
	v_sub_f32_e32 v14, 1.0, v12
	v_add_f32_e32 v16, 1.0, v12
	v_mul_f32_e32 v14, v14, v16
	v_max_f32_e32 v14, 0, v14
	v_sqrt_f32_e32 v14, v14
	s_nop 0
	v_mul_f32_e32 v13, v13, v14
	v_add_f32_e32 v14, v19, v23
	v_mul_f32_e32 v14, 0xbfb8aa3b, v14
	v_exp_f32_e32 v14, v14
	v_mul_f32_e32 v13, v13, v34
	v_add_f32_e32 v14, 1.0, v14
	v_rcp_f32_e32 v14, v14
	s_nop 0
	v_mul_f32_e32 v14, 0xc1000000, v14
	v_mul_f32_e32 v14, v14, v181
	v_mul_f32_e32 v14, 0x3fb8aa3b, v14
	v_exp_f32_e32 v14, v14
	s_nop 0
	v_sub_f32_e32 v16, 1.0, v14
	v_add_f32_e32 v17, 1.0, v14
	v_mul_f32_e32 v16, v16, v17
	v_max_f32_e32 v16, 0, v16
	v_sqrt_f32_e32 v16, v16
	s_nop 0
	v_mul_f32_e32 v15, v15, v16
	v_mul_f32_e32 v15, v15, v35
	ds_write2_b64 v191, v[12:13], v[14:15] offset0:50 offset1:67
	global_load_dwordx4 v[20:23], v[170:171], off offset:128
	global_load_dwordx4 v[24:27], v[0:1], off offset:128
	v_mfma_f32_16x16x32_bf16 v[12:15], v[88:91], v[4:7], 0
	ds_read_b64 v[30:31], v2 offset:64
	s_waitcnt lgkmcnt(0)
	v_lshlrev_b32_e32 v29, 16, v30
	v_mfma_f32_16x16x32_bf16 v[16:19], v[96:99], v[8:11], v[12:15]
	v_and_b32_e32 v33, 0xffff0000, v30
	v_lshlrev_b32_e32 v34, 16, v31
	v_and_b32_e32 v35, 0xffff0000, v31
	v_mfma_f32_16x16x32_bf16 v[12:15], v[84:87], v[4:7], 0
	v_mfma_f32_16x16x32_bf16 v[12:15], v[92:95], v[8:11], v[12:15]
	s_waitcnt vmcnt(1)
	s_nop 1
	v_add_f32_e32 v16, v16, v20
	v_mul_f32_e32 v16, 0xbfb8aa3b, v16
	v_exp_f32_e32 v16, v16
	s_waitcnt vmcnt(0)
	s_nop 0
	v_add_f32_e32 v12, v12, v24
	v_mul_f32_e32 v12, 0xbfb8aa3b, v12
	v_exp_f32_e32 v12, v12
	v_add_f32_e32 v16, 1.0, v16
	v_rcp_f32_e32 v16, v16
	v_add_f32_e32 v13, v13, v25
	v_add_f32_e32 v12, 1.0, v12
	v_rcp_f32_e32 v12, v12
	v_mul_f32_e32 v16, 0xc1000000, v16
	v_mul_f32_e32 v16, v16, v178
	v_mul_f32_e32 v16, 0x3fb8aa3b, v16
	v_exp_f32_e32 v30, v16
	v_mul_f32_e32 v13, 0xbfb8aa3b, v13
	v_exp_f32_e32 v13, v13
	v_add_f32_e32 v15, v15, v27
	v_sub_f32_e32 v16, 1.0, v30
	v_add_f32_e32 v20, 1.0, v30
	v_mul_f32_e32 v16, v16, v20
	v_max_f32_e32 v16, 0, v16
	v_sqrt_f32_e32 v16, v16
	v_add_f32_e32 v13, 1.0, v13
	v_rcp_f32_e32 v13, v13
	v_mul_f32_e32 v15, 0xbfb8aa3b, v15
	v_mul_f32_e32 v12, v12, v16
	v_mul_f32_e32 v31, v12, v29
	v_add_f32_e32 v12, v17, v21
	v_mul_f32_e32 v12, 0xbfb8aa3b, v12
	v_exp_f32_e32 v12, v12
	v_exp_f32_e32 v15, v15
	v_add_f32_e32 v12, 1.0, v12
	v_rcp_f32_e32 v12, v12
	v_add_f32_e32 v15, 1.0, v15
	v_rcp_f32_e32 v15, v15
	v_mul_f32_e32 v12, 0xc1000000, v12
	v_mul_f32_e32 v12, v12, v180
	v_mul_f32_e32 v12, 0x3fb8aa3b, v12
	v_exp_f32_e32 v12, v12
	s_nop 0
	v_sub_f32_e32 v16, 1.0, v12
	v_add_f32_e32 v17, 1.0, v12
	v_mul_f32_e32 v16, v16, v17
	v_max_f32_e32 v16, 0, v16
	v_sqrt_f32_e32 v16, v16
	s_nop 0
	v_mul_f32_e32 v13, v13, v16
	v_mul_f32_e32 v13, v13, v33
	ds_write2_b64 v192, v[30:31], v[12:13] offset0:32 offset1:49
	v_add_f32_e32 v12, v18, v22
	v_mul_f32_e32 v12, 0xbfb8aa3b, v12
	v_exp_f32_e32 v12, v12
	v_add_f32_e32 v13, v14, v26
	v_mul_f32_e32 v13, 0xbfb8aa3b, v13
	v_exp_f32_e32 v13, v13
	v_add_f32_e32 v12, 1.0, v12
	v_rcp_f32_e32 v12, v12
	v_add_f32_e32 v13, 1.0, v13
	v_rcp_f32_e32 v13, v13
	v_mul_f32_e32 v12, 0xc1000000, v12
	v_mul_f32_e32 v12, v12, v182
	v_mul_f32_e32 v12, 0x3fb8aa3b, v12
	v_exp_f32_e32 v12, v12
	s_nop 0
	v_sub_f32_e32 v14, 1.0, v12
	v_add_f32_e32 v16, 1.0, v12
	v_mul_f32_e32 v14, v14, v16
	v_max_f32_e32 v14, 0, v14
	v_sqrt_f32_e32 v14, v14
	s_nop 0
	v_mul_f32_e32 v13, v13, v14
	v_add_f32_e32 v14, v19, v23
	v_mul_f32_e32 v14, 0xbfb8aa3b, v14
	v_exp_f32_e32 v14, v14
	v_mul_f32_e32 v13, v13, v34
	v_add_f32_e32 v14, 1.0, v14
	v_rcp_f32_e32 v14, v14
	s_nop 0
	v_mul_f32_e32 v14, 0xc1000000, v14
	v_mul_f32_e32 v14, v14, v183
	v_mul_f32_e32 v14, 0x3fb8aa3b, v14
	v_exp_f32_e32 v14, v14
	s_nop 0
	v_sub_f32_e32 v16, 1.0, v14
	v_add_f32_e32 v17, 1.0, v14
	v_mul_f32_e32 v16, v16, v17
	v_max_f32_e32 v16, 0, v16
	v_sqrt_f32_e32 v16, v16
	s_nop 0
	v_mul_f32_e32 v15, v15, v16
	v_mul_f32_e32 v15, v15, v35
	ds_write2_b64 v192, v[12:13], v[14:15] offset0:66 offset1:83
	v_mfma_f32_16x16x32_bf16 v[12:15], v[72:75], v[4:7], 0
	v_mfma_f32_16x16x32_bf16 v[4:7], v[68:71], v[4:7], 0
	v_mfma_f32_16x16x32_bf16 v[12:15], v[80:83], v[8:11], v[12:15]
	v_mfma_f32_16x16x32_bf16 v[4:7], v[76:79], v[8:11], v[4:7]
	global_load_dwordx4 v[8:11], v[170:171], off offset:192
	global_load_dwordx4 v[16:19], v[0:1], off offset:192
	ds_read_b64 v[20:21], v2 offset:96
	s_waitcnt lgkmcnt(0)
	v_lshlrev_b32_e32 v22, 16, v20
	v_and_b32_e32 v23, 0xffff0000, v20
	v_lshlrev_b32_e32 v24, 16, v21
	v_and_b32_e32 v25, 0xffff0000, v21
	s_waitcnt vmcnt(1)
	v_add_f32_e32 v8, v12, v8
	v_mul_f32_e32 v8, 0xbfb8aa3b, v8
	v_exp_f32_e32 v8, v8
	s_waitcnt vmcnt(0)
	v_add_f32_e32 v4, v4, v16
	v_mul_f32_e32 v4, 0xbfb8aa3b, v4
	v_exp_f32_e32 v4, v4
	v_add_f32_e32 v8, 1.0, v8
	v_rcp_f32_e32 v8, v8
	v_add_f32_e32 v5, v5, v17
	v_add_f32_e32 v4, 1.0, v4
	v_rcp_f32_e32 v4, v4
	v_mul_f32_e32 v8, 0xc1000000, v8
	v_mul_f32_e32 v8, v184, v8
	v_mul_f32_e32 v8, 0x3fb8aa3b, v8
	v_exp_f32_e32 v20, v8
	v_mul_f32_e32 v5, 0xbfb8aa3b, v5
	v_exp_f32_e32 v5, v5
	v_add_f32_e32 v7, v7, v19
	v_sub_f32_e32 v8, 1.0, v20
	v_add_f32_e32 v12, 1.0, v20
	v_mul_f32_e32 v8, v8, v12
	v_max_f32_e32 v8, 0, v8
	v_sqrt_f32_e32 v8, v8
	v_add_f32_e32 v5, 1.0, v5
	v_rcp_f32_e32 v5, v5
	v_mul_f32_e32 v7, 0xbfb8aa3b, v7
	v_mul_f32_e32 v4, v4, v8
	v_mul_f32_e32 v21, v4, v22
	v_add_f32_e32 v4, v13, v9
	v_mul_f32_e32 v4, 0xbfb8aa3b, v4
	v_exp_f32_e32 v4, v4
	v_exp_f32_e32 v7, v7
	v_add_f32_e32 v4, 1.0, v4
	v_rcp_f32_e32 v4, v4
	v_add_f32_e32 v7, 1.0, v7
	v_rcp_f32_e32 v7, v7
	v_mul_f32_e32 v4, 0xc1000000, v4
	v_mul_f32_e32 v4, v185, v4
	v_mul_f32_e32 v4, 0x3fb8aa3b, v4
	v_exp_f32_e32 v4, v4
	s_nop 0
	v_sub_f32_e32 v8, 1.0, v4
	v_add_f32_e32 v9, 1.0, v4
	v_mul_f32_e32 v8, v8, v9
	v_max_f32_e32 v8, 0, v8
	v_sqrt_f32_e32 v8, v8
	s_nop 0
	v_mul_f32_e32 v5, v5, v8
	v_mul_f32_e32 v5, v5, v23
	ds_write2_b64 v189, v[20:21], v[4:5] offset0:48 offset1:65
	v_add_f32_e32 v4, v14, v10
	v_mul_f32_e32 v4, 0xbfb8aa3b, v4
	v_exp_f32_e32 v4, v4
	v_add_f32_e32 v5, v6, v18
	v_mul_f32_e32 v5, 0xbfb8aa3b, v5
	v_exp_f32_e32 v5, v5
	v_add_f32_e32 v4, 1.0, v4
	v_rcp_f32_e32 v4, v4
	v_add_f32_e32 v5, 1.0, v5
	v_rcp_f32_e32 v5, v5
	v_mul_f32_e32 v4, 0xc1000000, v4
	v_mul_f32_e32 v4, v186, v4
	v_mul_f32_e32 v4, 0x3fb8aa3b, v4
	v_exp_f32_e32 v4, v4
	s_nop 0
	v_sub_f32_e32 v6, 1.0, v4
	v_add_f32_e32 v8, 1.0, v4
	v_mul_f32_e32 v6, v6, v8
	v_max_f32_e32 v6, 0, v6
	v_sqrt_f32_e32 v6, v6
	s_nop 0
	v_mul_f32_e32 v5, v5, v6
	v_add_f32_e32 v6, v15, v11
	v_mul_f32_e32 v6, 0xbfb8aa3b, v6
	v_exp_f32_e32 v6, v6
	v_mul_f32_e32 v5, v5, v24
	v_add_f32_e32 v6, 1.0, v6
	v_rcp_f32_e32 v6, v6
	s_nop 0
	v_mul_f32_e32 v6, 0xc1000000, v6
	v_mul_f32_e32 v6, v187, v6
	v_mul_f32_e32 v6, 0x3fb8aa3b, v6
	v_exp_f32_e32 v6, v6
	s_nop 0
	v_sub_f32_e32 v8, 1.0, v6
	v_add_f32_e32 v9, 1.0, v6
	v_mul_f32_e32 v8, v8, v9
	v_max_f32_e32 v8, 0, v8
	v_sqrt_f32_e32 v8, v8
	s_nop 0
	v_mul_f32_e32 v7, v7, v8
	v_mul_f32_e32 v7, v7, v25
	ds_write2_b64 v189, v[4:5], v[6:7] offset0:82 offset1:99
	s_waitcnt lgkmcnt(0)
	s_barrier
	ds_read2_b64 v[4:7], v188 offset1:1
	s_waitcnt lgkmcnt(0)
	v_fma_f32 v220, v40, v4, v5
	v_add_u32_e32 v4, 0x8810, v32
	ds_read2_b64 v[8:11], v4 offset1:1
	v_add_u32_e32 v5, 0x8820, v32
	v_fmac_f32_e32 v7, v6, v220
	ds_read2_b64 v[12:15], v5 offset1:1
	s_waitcnt lgkmcnt(1)
	v_fma_f32 v6, v8, v7, v9
	v_add_u32_e32 v8, 0x8830, v32
	ds_read2_b64 v[16:19], v8 offset1:1
	v_fmac_f32_e32 v11, v10, v6
	s_waitcnt lgkmcnt(1)
	v_fma_f32 v10, v12, v11, v13
	v_fmac_f32_e32 v15, v14, v10
	v_add_u32_e32 v9, 0x8840, v32
	ds_read2_b64 v[20:23], v9 offset1:1
	s_waitcnt lgkmcnt(1)
	v_fma_f32 v14, v16, v15, v17
	v_add_u32_e32 v12, 0x8850, v32
	v_add_u32_e32 v13, 0x8860, v32
	v_add_u32_e32 v16, 0x8870, v32
	ds_read2_b64 v[24:27], v12 offset1:1
	ds_read2_b64 v[28:31], v13 offset1:1
	ds_read2_b64 v[32:35], v16 offset1:1
	s_waitcnt lgkmcnt(0)
	s_barrier
	ds_read_b128 v[36:39], v166 offset:8704
	ds_read_b128 v[40:43], v166 offset:8768
	global_load_dwordx4 v[52:55], v[170:171], off
	global_load_dwordx4 v[56:59], v[0:1], off
	s_waitcnt lgkmcnt(1)
	v_mfma_f32_16x16x32_bf16 v[44:47], v[120:123], v[36:39], 0
	v_fmac_f32_e32 v19, v18, v14
	v_fma_f32 v18, v20, v19, v21
	ds_read_b64 v[20:21], v2 offset:8704
	s_waitcnt lgkmcnt(1)
	v_mfma_f32_16x16x32_bf16 v[44:47], v[162:165], v[40:43], v[44:47]
	v_fmac_f32_e32 v23, v22, v18
	v_fma_f32 v22, v24, v23, v25
	v_fmac_f32_e32 v27, v26, v22
	s_waitcnt lgkmcnt(0)
	v_lshlrev_b32_e32 v17, 16, v20
	v_and_b32_e32 v25, 0xffff0000, v20
	v_mfma_f32_16x16x32_bf16 v[48:51], v[116:119], v[36:39], 0
	v_fma_f32 v26, v28, v27, v29
	v_fmac_f32_e32 v31, v30, v26
	v_lshlrev_b32_e32 v29, 16, v21
	v_mfma_f32_16x16x32_bf16 v[48:51], v[124:127], v[40:43], v[48:51]
	v_and_b32_e32 v30, 0xffff0000, v21
	v_fma_f32 v28, v32, v31, v33
	v_fmac_f32_e32 v35, v34, v28
	s_waitcnt vmcnt(1)
	v_add_f32_e32 v20, v44, v52
	v_mul_f32_e32 v20, 0xbfb8aa3b, v20
	v_exp_f32_e32 v20, v20
	s_waitcnt vmcnt(0)
	v_add_f32_e32 v21, v48, v56
	v_mul_f32_e32 v21, 0xbfb8aa3b, v21
	v_exp_f32_e32 v21, v21
	v_add_f32_e32 v20, 1.0, v20
	v_rcp_f32_e32 v20, v20
	v_add_f32_e32 v21, 1.0, v21
	v_rcp_f32_e32 v21, v21
	v_mul_f32_e32 v20, 0xc1000000, v20
	v_mul_f32_e32 v20, v172, v20
	v_mul_f32_e32 v20, 0x3fb8aa3b, v20
	v_exp_f32_e32 v20, v20
	s_nop 0
	v_sub_f32_e32 v24, 1.0, v20
	v_add_f32_e32 v32, 1.0, v20
	v_mul_f32_e32 v24, v24, v32
	v_max_f32_e32 v24, 0, v24
	v_sqrt_f32_e32 v24, v24
	s_nop 0
	v_mul_f32_e32 v21, v21, v24
	v_mul_f32_e32 v21, v21, v17
	v_add_f32_e32 v17, v45, v53
	v_mul_f32_e32 v17, 0xbfb8aa3b, v17
	v_exp_f32_e32 v17, v17
	v_add_f32_e32 v24, v49, v57
	v_mul_f32_e32 v24, 0xbfb8aa3b, v24
	v_exp_f32_e32 v24, v24
	v_add_f32_e32 v17, 1.0, v17
	v_rcp_f32_e32 v17, v17
	v_add_f32_e32 v24, 1.0, v24
	v_rcp_f32_e32 v32, v24
	v_mul_f32_e32 v17, 0xc1000000, v17
	v_mul_f32_e32 v17, v173, v17
	v_mul_f32_e32 v17, 0x3fb8aa3b, v17
	v_exp_f32_e32 v24, v17
	s_nop 0
	v_sub_f32_e32 v17, 1.0, v24
	v_add_f32_e32 v33, 1.0, v24
	v_mul_f32_e32 v17, v17, v33
	v_max_f32_e32 v17, 0, v17
	v_sqrt_f32_e32 v17, v17
	s_nop 0
	v_mul_f32_e32 v17, v32, v17
	v_mul_f32_e32 v25, v17, v25
	v_add_f32_e32 v17, v46, v54
	v_mul_f32_e32 v17, 0xbfb8aa3b, v17
	v_exp_f32_e32 v17, v17
	ds_write2_b64 v190, v[20:21], v[24:25] offset1:17
	v_add_f32_e32 v20, v50, v58
	v_mul_f32_e32 v20, 0xbfb8aa3b, v20
	v_add_f32_e32 v17, 1.0, v17
	v_rcp_f32_e32 v17, v17
	v_exp_f32_e32 v20, v20
	v_mul_f32_e32 v17, 0xc1000000, v17
	v_mul_f32_e32 v17, v174, v17
	v_add_f32_e32 v20, 1.0, v20
	v_mul_f32_e32 v17, 0x3fb8aa3b, v17
	v_rcp_f32_e32 v21, v20
	v_exp_f32_e32 v20, v17
	s_nop 0
	v_sub_f32_e32 v17, 1.0, v20
	v_add_f32_e32 v24, 1.0, v20
	v_mul_f32_e32 v17, v17, v24
	v_max_f32_e32 v17, 0, v17
	v_sqrt_f32_e32 v17, v17
	v_add_f32_e32 v24, v51, v59
	v_mul_f32_e32 v24, 0xbfb8aa3b, v24
	v_exp_f32_e32 v24, v24
	v_mul_f32_e32 v17, v21, v17
	v_mul_f32_e32 v21, v17, v29
	v_add_f32_e32 v17, v47, v55
	v_mul_f32_e32 v17, 0xbfb8aa3b, v17
	v_exp_f32_e32 v17, v17
	v_add_f32_e32 v24, 1.0, v24
	v_rcp_f32_e32 v25, v24
	v_mfma_f32_16x16x32_bf16 v[44:47], v[104:107], v[36:39], 0
	v_add_f32_e32 v17, 1.0, v17
	v_rcp_f32_e32 v17, v17
	v_mfma_f32_16x16x32_bf16 v[48:51], v[112:115], v[40:43], v[44:47]
	v_mul_f32_e32 v17, 0xc1000000, v17
	v_mul_f32_e32 v17, v175, v17
	v_mul_f32_e32 v17, 0x3fb8aa3b, v17
	v_exp_f32_e32 v24, v17
	v_mfma_f32_16x16x32_bf16 v[44:47], v[100:103], v[36:39], 0
	v_sub_f32_e32 v17, 1.0, v24
	v_add_f32_e32 v29, 1.0, v24
	v_mul_f32_e32 v17, v17, v29
	v_max_f32_e32 v17, 0, v17
	v_sqrt_f32_e32 v17, v17
	v_mfma_f32_16x16x32_bf16 v[44:47], v[108:111], v[40:43], v[44:47]
	v_mul_f32_e32 v17, v25, v17
	v_mul_f32_e32 v25, v17, v30
	ds_write2_b64 v190, v[20:21], v[24:25] offset0:34 offset1:51
	global_load_dwordx4 v[52:55], v[170:171], off offset:64
	global_load_dwordx4 v[56:59], v[0:1], off offset:64
	ds_read_b64 v[20:21], v2 offset:8736
	s_waitcnt lgkmcnt(0)
	v_lshlrev_b32_e32 v17, 16, v20
	v_and_b32_e32 v25, 0xffff0000, v20
	v_lshlrev_b32_e32 v29, 16, v21
	v_and_b32_e32 v30, 0xffff0000, v21
	s_waitcnt vmcnt(1)
	v_add_f32_e32 v20, v48, v52
	v_mul_f32_e32 v20, 0xbfb8aa3b, v20
	v_exp_f32_e32 v20, v20
	s_waitcnt vmcnt(0)
	v_add_f32_e32 v21, v44, v56
	v_mul_f32_e32 v21, 0xbfb8aa3b, v21
	v_exp_f32_e32 v21, v21
	v_add_f32_e32 v20, 1.0, v20
	v_rcp_f32_e32 v20, v20
	v_add_f32_e32 v21, 1.0, v21
	v_rcp_f32_e32 v21, v21
	v_mul_f32_e32 v20, 0xc1000000, v20
	v_mul_f32_e32 v20, v176, v20
	v_mul_f32_e32 v20, 0x3fb8aa3b, v20
	v_exp_f32_e32 v20, v20
	s_nop 0
	v_sub_f32_e32 v24, 1.0, v20
	v_add_f32_e32 v32, 1.0, v20
	v_mul_f32_e32 v24, v24, v32
	v_max_f32_e32 v24, 0, v24
	v_sqrt_f32_e32 v24, v24
	s_nop 0
	v_mul_f32_e32 v21, v21, v24
	v_mul_f32_e32 v21, v21, v17
	v_add_f32_e32 v17, v49, v53
	v_mul_f32_e32 v17, 0xbfb8aa3b, v17
	v_exp_f32_e32 v17, v17
	v_add_f32_e32 v24, v45, v57
	v_mul_f32_e32 v24, 0xbfb8aa3b, v24
	v_exp_f32_e32 v24, v24
	v_add_f32_e32 v17, 1.0, v17
	v_rcp_f32_e32 v17, v17
	v_add_f32_e32 v24, 1.0, v24
	v_rcp_f32_e32 v32, v24
	v_mul_f32_e32 v17, 0xc1000000, v17
	v_mul_f32_e32 v17, v177, v17
	v_mul_f32_e32 v17, 0x3fb8aa3b, v17
	v_exp_f32_e32 v24, v17
	s_nop 0
	v_sub_f32_e32 v17, 1.0, v24
	v_add_f32_e32 v33, 1.0, v24
	v_mul_f32_e32 v17, v17, v33
	v_max_f32_e32 v17, 0, v17
	v_sqrt_f32_e32 v17, v17
	s_nop 0
	v_mul_f32_e32 v17, v32, v17
	v_mul_f32_e32 v25, v17, v25
	v_add_f32_e32 v17, v50, v54
	v_mul_f32_e32 v17, 0xbfb8aa3b, v17
	v_exp_f32_e32 v17, v17
	ds_write2_b64 v191, v[20:21], v[24:25] offset0:16 offset1:33
	v_add_f32_e32 v20, v46, v58
	v_mul_f32_e32 v20, 0xbfb8aa3b, v20
	v_add_f32_e32 v17, 1.0, v17
	v_rcp_f32_e32 v17, v17
	v_exp_f32_e32 v20, v20
	v_mul_f32_e32 v17, 0xc1000000, v17
	v_mul_f32_e32 v17, v179, v17
	v_add_f32_e32 v20, 1.0, v20
	v_mul_f32_e32 v17, 0x3fb8aa3b, v17
	v_rcp_f32_e32 v21, v20
	v_exp_f32_e32 v20, v17
	s_nop 0
	v_sub_f32_e32 v17, 1.0, v20
	v_add_f32_e32 v24, 1.0, v20
	v_mul_f32_e32 v17, v17, v24
	v_max_f32_e32 v17, 0, v17
	v_sqrt_f32_e32 v17, v17
	v_add_f32_e32 v24, v47, v59
	v_mul_f32_e32 v24, 0xbfb8aa3b, v24
	v_exp_f32_e32 v24, v24
	v_mul_f32_e32 v17, v21, v17
	v_mul_f32_e32 v21, v17, v29
	v_add_f32_e32 v17, v51, v55
	v_mul_f32_e32 v17, 0xbfb8aa3b, v17
	v_exp_f32_e32 v17, v17
	v_add_f32_e32 v24, 1.0, v24
	v_rcp_f32_e32 v25, v24
	v_mfma_f32_16x16x32_bf16 v[44:47], v[88:91], v[36:39], 0
	v_add_f32_e32 v17, 1.0, v17
	v_rcp_f32_e32 v17, v17
	v_mfma_f32_16x16x32_bf16 v[48:51], v[96:99], v[40:43], v[44:47]
	v_mul_f32_e32 v17, 0xc1000000, v17
	v_mul_f32_e32 v17, v181, v17
	v_mul_f32_e32 v17, 0x3fb8aa3b, v17
	v_exp_f32_e32 v24, v17
	v_mfma_f32_16x16x32_bf16 v[44:47], v[84:87], v[36:39], 0
	v_sub_f32_e32 v17, 1.0, v24
	v_add_f32_e32 v29, 1.0, v24
	v_mul_f32_e32 v17, v17, v29
	v_max_f32_e32 v17, 0, v17
	v_sqrt_f32_e32 v17, v17
	v_mfma_f32_16x16x32_bf16 v[44:47], v[92:95], v[40:43], v[44:47]
	v_mul_f32_e32 v17, v25, v17
	v_mul_f32_e32 v25, v17, v30
	ds_write2_b64 v191, v[20:21], v[24:25] offset0:50 offset1:67
	global_load_dwordx4 v[52:55], v[170:171], off offset:128
	global_load_dwordx4 v[56:59], v[0:1], off offset:128
	ds_read_b64 v[20:21], v2 offset:8768
	s_waitcnt lgkmcnt(0)
	v_lshlrev_b32_e32 v17, 16, v20
	v_and_b32_e32 v25, 0xffff0000, v20
	v_lshlrev_b32_e32 v29, 16, v21
	v_and_b32_e32 v30, 0xffff0000, v21
	s_waitcnt vmcnt(1)
	v_add_f32_e32 v20, v48, v52
	v_mul_f32_e32 v20, 0xbfb8aa3b, v20
	v_exp_f32_e32 v20, v20
	s_waitcnt vmcnt(0)
	v_add_f32_e32 v21, v44, v56
	v_mul_f32_e32 v21, 0xbfb8aa3b, v21
	v_exp_f32_e32 v21, v21
	v_add_f32_e32 v20, 1.0, v20
	v_rcp_f32_e32 v20, v20
	v_add_f32_e32 v21, 1.0, v21
	v_rcp_f32_e32 v21, v21
	v_mul_f32_e32 v20, 0xc1000000, v20
	v_mul_f32_e32 v20, v178, v20
	v_mul_f32_e32 v20, 0x3fb8aa3b, v20
	v_exp_f32_e32 v20, v20
	s_nop 0
	v_sub_f32_e32 v24, 1.0, v20
	v_add_f32_e32 v32, 1.0, v20
	v_mul_f32_e32 v24, v24, v32
	v_max_f32_e32 v24, 0, v24
	v_sqrt_f32_e32 v24, v24
	s_nop 0
	v_mul_f32_e32 v21, v21, v24
	v_mul_f32_e32 v21, v21, v17
	v_add_f32_e32 v17, v49, v53
	v_mul_f32_e32 v17, 0xbfb8aa3b, v17
	v_exp_f32_e32 v17, v17
	v_add_f32_e32 v24, v45, v57
	v_mul_f32_e32 v24, 0xbfb8aa3b, v24
	v_exp_f32_e32 v24, v24
	v_add_f32_e32 v17, 1.0, v17
	v_rcp_f32_e32 v17, v17
	v_add_f32_e32 v24, 1.0, v24
	v_rcp_f32_e32 v32, v24
	v_mul_f32_e32 v17, 0xc1000000, v17
	v_mul_f32_e32 v17, v180, v17
	v_mul_f32_e32 v17, 0x3fb8aa3b, v17
	v_exp_f32_e32 v24, v17
	s_nop 0
	v_sub_f32_e32 v17, 1.0, v24
	v_add_f32_e32 v33, 1.0, v24
	v_mul_f32_e32 v17, v17, v33
	v_max_f32_e32 v17, 0, v17
	v_sqrt_f32_e32 v17, v17
	s_nop 0
	v_mul_f32_e32 v17, v32, v17
	v_mul_f32_e32 v25, v17, v25
	v_add_f32_e32 v17, v50, v54
	v_mul_f32_e32 v17, 0xbfb8aa3b, v17
	v_exp_f32_e32 v17, v17
	ds_write2_b64 v192, v[20:21], v[24:25] offset0:32 offset1:49
	v_add_f32_e32 v20, v46, v58
	v_mul_f32_e32 v20, 0xbfb8aa3b, v20
	v_add_f32_e32 v17, 1.0, v17
	v_rcp_f32_e32 v17, v17
	v_exp_f32_e32 v20, v20
	v_mul_f32_e32 v17, 0xc1000000, v17
	v_mul_f32_e32 v17, v182, v17
	v_add_f32_e32 v20, 1.0, v20
	v_mul_f32_e32 v17, 0x3fb8aa3b, v17
	v_rcp_f32_e32 v21, v20
	v_exp_f32_e32 v20, v17
	s_nop 0
	v_sub_f32_e32 v17, 1.0, v20
	v_add_f32_e32 v24, 1.0, v20
	v_mul_f32_e32 v17, v17, v24
	v_max_f32_e32 v17, 0, v17
	v_sqrt_f32_e32 v17, v17
	v_add_f32_e32 v24, v47, v59
	v_mul_f32_e32 v24, 0xbfb8aa3b, v24
	v_exp_f32_e32 v24, v24
	v_mul_f32_e32 v17, v21, v17
	v_mul_f32_e32 v21, v17, v29
	v_add_f32_e32 v17, v51, v55
	v_mul_f32_e32 v17, 0xbfb8aa3b, v17
	v_exp_f32_e32 v17, v17
	v_add_f32_e32 v24, 1.0, v24
	v_rcp_f32_e32 v25, v24
	v_mfma_f32_16x16x32_bf16 v[44:47], v[72:75], v[36:39], 0
	v_add_f32_e32 v17, 1.0, v17
	v_rcp_f32_e32 v17, v17
	v_mfma_f32_16x16x32_bf16 v[36:39], v[68:71], v[36:39], 0
	v_mul_f32_e32 v17, 0xc1000000, v17
	v_mul_f32_e32 v17, v183, v17
	v_mul_f32_e32 v17, 0x3fb8aa3b, v17
	v_exp_f32_e32 v24, v17
	v_mfma_f32_16x16x32_bf16 v[44:47], v[80:83], v[40:43], v[44:47]
	v_sub_f32_e32 v17, 1.0, v24
	v_add_f32_e32 v29, 1.0, v24
	v_mul_f32_e32 v17, v17, v29
	v_max_f32_e32 v17, 0, v17
	v_sqrt_f32_e32 v17, v17
	v_mfma_f32_16x16x32_bf16 v[36:39], v[76:79], v[40:43], v[36:39]
	v_mul_f32_e32 v17, v25, v17
	v_mul_f32_e32 v25, v17, v30
	ds_write2_b64 v192, v[20:21], v[24:25] offset0:66 offset1:83
	global_load_dwordx4 v[40:43], v[170:171], off offset:192
	global_load_dwordx4 v[48:51], v[0:1], off offset:192
	ds_read_b64 v[20:21], v2 offset:8800
	s_waitcnt lgkmcnt(0)
	v_lshlrev_b32_e32 v17, 16, v20
	v_and_b32_e32 v25, 0xffff0000, v20
	v_lshlrev_b32_e32 v29, 16, v21
	v_and_b32_e32 v30, 0xffff0000, v21
	s_waitcnt vmcnt(1)
	v_add_f32_e32 v20, v44, v40
	v_mul_f32_e32 v20, 0xbfb8aa3b, v20
	v_exp_f32_e32 v20, v20
	s_waitcnt vmcnt(0)
	v_add_f32_e32 v21, v36, v48
	v_mul_f32_e32 v21, 0xbfb8aa3b, v21
	v_exp_f32_e32 v21, v21
	v_add_f32_e32 v20, 1.0, v20
	v_rcp_f32_e32 v20, v20
	v_add_f32_e32 v21, 1.0, v21
	v_rcp_f32_e32 v21, v21
	v_mul_f32_e32 v20, 0xc1000000, v20
	v_mul_f32_e32 v20, v184, v20
	v_mul_f32_e32 v20, 0x3fb8aa3b, v20
	v_exp_f32_e32 v20, v20
	s_nop 0
	v_sub_f32_e32 v24, 1.0, v20
	v_add_f32_e32 v32, 1.0, v20
	v_mul_f32_e32 v24, v24, v32
	v_max_f32_e32 v24, 0, v24
	v_sqrt_f32_e32 v24, v24
	s_nop 0
	v_mul_f32_e32 v21, v21, v24
	v_mul_f32_e32 v21, v21, v17
	v_add_f32_e32 v17, v45, v41
	v_mul_f32_e32 v17, 0xbfb8aa3b, v17
	v_exp_f32_e32 v17, v17
	v_add_f32_e32 v24, v37, v49
	v_mul_f32_e32 v24, 0xbfb8aa3b, v24
	v_exp_f32_e32 v24, v24
	v_add_f32_e32 v17, 1.0, v17
	v_rcp_f32_e32 v17, v17
	v_add_f32_e32 v24, 1.0, v24
	v_rcp_f32_e32 v32, v24
	v_mul_f32_e32 v17, 0xc1000000, v17
	v_mul_f32_e32 v17, v185, v17
	v_mul_f32_e32 v17, 0x3fb8aa3b, v17
	v_exp_f32_e32 v24, v17
	s_nop 0
	v_sub_f32_e32 v17, 1.0, v24
	v_add_f32_e32 v33, 1.0, v24
	v_mul_f32_e32 v17, v17, v33
	v_max_f32_e32 v17, 0, v17
	v_sqrt_f32_e32 v17, v17
	s_nop 0
	v_mul_f32_e32 v17, v32, v17
	v_mul_f32_e32 v25, v17, v25
	v_add_f32_e32 v17, v46, v42
	v_mul_f32_e32 v17, 0xbfb8aa3b, v17
	v_exp_f32_e32 v17, v17
	ds_write2_b64 v189, v[20:21], v[24:25] offset0:48 offset1:65
	v_add_f32_e32 v20, v38, v50
	v_mul_f32_e32 v20, 0xbfb8aa3b, v20
	v_add_f32_e32 v17, 1.0, v17
	v_rcp_f32_e32 v17, v17
	v_exp_f32_e32 v20, v20
	v_mul_f32_e32 v17, 0xc1000000, v17
	v_mul_f32_e32 v17, v186, v17
	v_add_f32_e32 v20, 1.0, v20
	v_mul_f32_e32 v17, 0x3fb8aa3b, v17
	v_rcp_f32_e32 v21, v20
	v_exp_f32_e32 v20, v17
	s_nop 0
	v_sub_f32_e32 v17, 1.0, v20
	v_add_f32_e32 v24, 1.0, v20
	v_mul_f32_e32 v17, v17, v24
	v_max_f32_e32 v17, 0, v17
	v_sqrt_f32_e32 v17, v17
	v_add_f32_e32 v24, v39, v51
	v_mul_f32_e32 v24, 0xbfb8aa3b, v24
	v_exp_f32_e32 v24, v24
	v_mul_f32_e32 v17, v21, v17
	v_mul_f32_e32 v21, v17, v29
	v_add_f32_e32 v17, v47, v43
	v_mul_f32_e32 v17, 0xbfb8aa3b, v17
	v_exp_f32_e32 v17, v17
	v_add_f32_e32 v24, 1.0, v24
	v_rcp_f32_e32 v25, v24
	v_add_f32_e32 v17, 1.0, v17
	v_rcp_f32_e32 v17, v17
	s_nop 0
	v_mul_f32_e32 v17, 0xc1000000, v17
	v_mul_f32_e32 v17, v187, v17
	v_mul_f32_e32 v17, 0x3fb8aa3b, v17
	v_exp_f32_e32 v24, v17
	s_nop 0
	v_sub_f32_e32 v17, 1.0, v24
	v_add_f32_e32 v29, 1.0, v24
	v_mul_f32_e32 v17, v17, v29
	v_max_f32_e32 v17, 0, v17
	v_sqrt_f32_e32 v17, v17
	s_nop 0
	v_mul_f32_e32 v17, v25, v17
	v_mul_f32_e32 v25, v17, v30
	ds_write2_b64 v189, v[20:21], v[24:25] offset0:82 offset1:99
	s_waitcnt lgkmcnt(0)
	s_barrier
	ds_read2_b64 v[36:39], v188 offset1:1
	ds_read2_b64 v[64:67], v16 offset1:1
	ds_read2_b64 v[40:43], v4 offset1:1
	ds_read2_b64 v[44:47], v5 offset1:1
	ds_read2_b64 v[48:51], v8 offset1:1
	ds_read2_b64 v[52:55], v9 offset1:1
	ds_read2_b64 v[56:59], v12 offset1:1
	ds_read2_b64 v[60:63], v13 offset1:1
	s_waitcnt lgkmcnt(0)
	s_barrier
	ds_read_b128 v[128:131], v166 offset:17408
	ds_read_b128 v[132:135], v166 offset:17472
	global_load_dwordx4 v[144:147], v[170:171], off
	global_load_dwordx4 v[148:151], v[0:1], off
	s_waitcnt lgkmcnt(1)
	v_mfma_f32_16x16x32_bf16 v[136:139], v[120:123], v[128:131], 0
	ds_read_b64 v[20:21], v2 offset:17408
	v_fma_f32 v29, v35, v36, v37
	v_fmac_f32_e32 v39, v38, v29
	s_waitcnt lgkmcnt(1)
	v_mfma_f32_16x16x32_bf16 v[136:139], v[162:165], v[132:135], v[136:139]
	v_fma_f32 v30, v40, v39, v41
	s_waitcnt lgkmcnt(0)
	v_lshlrev_b32_e32 v17, 16, v20
	v_and_b32_e32 v25, 0xffff0000, v20
	v_mfma_f32_16x16x32_bf16 v[140:143], v[116:119], v[128:131], 0
	v_lshlrev_b32_e32 v40, 16, v21
	v_and_b32_e32 v41, 0xffff0000, v21
	v_fmac_f32_e32 v43, v42, v30
	v_mfma_f32_16x16x32_bf16 v[140:143], v[124:127], v[132:135], v[140:143]
	v_fma_f32 v32, v44, v43, v45
	v_fmac_f32_e32 v47, v46, v32
	v_fma_f32 v33, v48, v47, v49
	v_fmac_f32_e32 v51, v50, v33
	v_fma_f32 v34, v52, v51, v53
	v_fmac_f32_e32 v55, v54, v34
	v_fma_f32 v36, v56, v55, v57
	v_fmac_f32_e32 v59, v58, v36
	v_fma_f32 v37, v60, v59, v61
	v_fmac_f32_e32 v63, v62, v37
	v_fma_f32 v38, v64, v63, v65
	v_fmac_f32_e32 v67, v66, v38
	s_waitcnt vmcnt(1)
	v_add_f32_e32 v20, v136, v144
	v_mul_f32_e32 v20, 0xbfb8aa3b, v20
	v_exp_f32_e32 v20, v20
	s_waitcnt vmcnt(0)
	v_add_f32_e32 v21, v140, v148
	v_mul_f32_e32 v21, 0xbfb8aa3b, v21
	v_exp_f32_e32 v21, v21
	v_add_f32_e32 v20, 1.0, v20
	v_rcp_f32_e32 v20, v20
	v_add_f32_e32 v21, 1.0, v21
	v_rcp_f32_e32 v21, v21
	v_mul_f32_e32 v20, 0xc1000000, v20
	v_mul_f32_e32 v20, v172, v20
	v_mul_f32_e32 v20, 0x3fb8aa3b, v20
	v_exp_f32_e32 v20, v20
	s_nop 0
	v_sub_f32_e32 v24, 1.0, v20
	v_add_f32_e32 v42, 1.0, v20
	v_mul_f32_e32 v24, v24, v42
	v_max_f32_e32 v24, 0, v24
	v_sqrt_f32_e32 v24, v24
	s_nop 0
	v_mul_f32_e32 v21, v21, v24
	v_mul_f32_e32 v21, v21, v17
	v_add_f32_e32 v17, v137, v145
	v_mul_f32_e32 v17, 0xbfb8aa3b, v17
	v_exp_f32_e32 v17, v17
	v_add_f32_e32 v24, v141, v149
	v_mul_f32_e32 v24, 0xbfb8aa3b, v24
	v_exp_f32_e32 v24, v24
	v_add_f32_e32 v17, 1.0, v17
	v_rcp_f32_e32 v17, v17
	v_add_f32_e32 v24, 1.0, v24
	v_rcp_f32_e32 v42, v24
	v_mul_f32_e32 v17, 0xc1000000, v17
	v_mul_f32_e32 v17, v173, v17
	v_mul_f32_e32 v17, 0x3fb8aa3b, v17
	v_exp_f32_e32 v24, v17
	s_nop 0
	v_sub_f32_e32 v17, 1.0, v24
	v_add_f32_e32 v44, 1.0, v24
	v_mul_f32_e32 v17, v17, v44
	v_max_f32_e32 v17, 0, v17
	v_sqrt_f32_e32 v17, v17
	s_nop 0
	v_mul_f32_e32 v17, v42, v17
	v_mul_f32_e32 v25, v17, v25
	v_add_f32_e32 v17, v138, v146
	v_mul_f32_e32 v17, 0xbfb8aa3b, v17
	v_exp_f32_e32 v17, v17
	ds_write2_b64 v190, v[20:21], v[24:25] offset1:17
	v_add_f32_e32 v20, v142, v150
	v_mul_f32_e32 v20, 0xbfb8aa3b, v20
	v_add_f32_e32 v17, 1.0, v17
	v_rcp_f32_e32 v17, v17
	v_exp_f32_e32 v20, v20
	v_mul_f32_e32 v17, 0xc1000000, v17
	v_mul_f32_e32 v17, v174, v17
	v_add_f32_e32 v20, 1.0, v20
	v_mul_f32_e32 v17, 0x3fb8aa3b, v17
	v_rcp_f32_e32 v21, v20
	v_exp_f32_e32 v20, v17
	s_nop 0
	v_sub_f32_e32 v17, 1.0, v20
	v_add_f32_e32 v24, 1.0, v20
	v_mul_f32_e32 v17, v17, v24
	v_max_f32_e32 v17, 0, v17
	v_sqrt_f32_e32 v17, v17
	v_add_f32_e32 v24, v143, v151
	v_mul_f32_e32 v24, 0xbfb8aa3b, v24
	v_exp_f32_e32 v24, v24
	v_mul_f32_e32 v17, v21, v17
	v_mul_f32_e32 v21, v17, v40
	v_add_f32_e32 v17, v139, v147
	v_mul_f32_e32 v17, 0xbfb8aa3b, v17
	v_exp_f32_e32 v17, v17
	v_add_f32_e32 v24, 1.0, v24
	v_rcp_f32_e32 v25, v24
	v_mfma_f32_16x16x32_bf16 v[136:139], v[104:107], v[128:131], 0
	v_add_f32_e32 v17, 1.0, v17
	v_rcp_f32_e32 v17, v17
	v_mfma_f32_16x16x32_bf16 v[140:143], v[112:115], v[132:135], v[136:139]
	v_mul_f32_e32 v17, 0xc1000000, v17
	v_mul_f32_e32 v17, v175, v17
	v_mul_f32_e32 v17, 0x3fb8aa3b, v17
	v_exp_f32_e32 v24, v17
	v_mfma_f32_16x16x32_bf16 v[136:139], v[100:103], v[128:131], 0
	v_sub_f32_e32 v17, 1.0, v24
	v_add_f32_e32 v40, 1.0, v24
	v_mul_f32_e32 v17, v17, v40
	v_max_f32_e32 v17, 0, v17
	v_sqrt_f32_e32 v17, v17
	v_mfma_f32_16x16x32_bf16 v[136:139], v[108:111], v[132:135], v[136:139]
	v_mul_f32_e32 v17, v25, v17
	v_mul_f32_e32 v25, v17, v41
	ds_write2_b64 v190, v[20:21], v[24:25] offset0:34 offset1:51
	global_load_dwordx4 v[144:147], v[170:171], off offset:64
	global_load_dwordx4 v[148:151], v[0:1], off offset:64
	ds_read_b64 v[20:21], v2 offset:17440
	s_waitcnt lgkmcnt(0)
	v_lshlrev_b32_e32 v17, 16, v20
	v_and_b32_e32 v25, 0xffff0000, v20
	v_lshlrev_b32_e32 v40, 16, v21
	v_and_b32_e32 v41, 0xffff0000, v21
	s_waitcnt vmcnt(1)
	v_add_f32_e32 v20, v140, v144
	v_mul_f32_e32 v20, 0xbfb8aa3b, v20
	v_exp_f32_e32 v20, v20
	s_waitcnt vmcnt(0)
	v_add_f32_e32 v21, v136, v148
	v_mul_f32_e32 v21, 0xbfb8aa3b, v21
	v_exp_f32_e32 v21, v21
	v_add_f32_e32 v20, 1.0, v20
	v_rcp_f32_e32 v20, v20
	v_add_f32_e32 v21, 1.0, v21
	v_rcp_f32_e32 v21, v21
	v_mul_f32_e32 v20, 0xc1000000, v20
	v_mul_f32_e32 v20, v176, v20
	v_mul_f32_e32 v20, 0x3fb8aa3b, v20
	v_exp_f32_e32 v20, v20
	s_nop 0
	v_sub_f32_e32 v24, 1.0, v20
	v_add_f32_e32 v42, 1.0, v20
	v_mul_f32_e32 v24, v24, v42
	v_max_f32_e32 v24, 0, v24
	v_sqrt_f32_e32 v24, v24
	s_nop 0
	v_mul_f32_e32 v21, v21, v24
	v_mul_f32_e32 v21, v21, v17
	v_add_f32_e32 v17, v141, v145
	v_mul_f32_e32 v17, 0xbfb8aa3b, v17
	v_exp_f32_e32 v17, v17
	v_add_f32_e32 v24, v137, v149
	v_mul_f32_e32 v24, 0xbfb8aa3b, v24
	v_exp_f32_e32 v24, v24
	v_add_f32_e32 v17, 1.0, v17
	v_rcp_f32_e32 v17, v17
	v_add_f32_e32 v24, 1.0, v24
	v_rcp_f32_e32 v42, v24
	v_mul_f32_e32 v17, 0xc1000000, v17
	v_mul_f32_e32 v17, v177, v17
	v_mul_f32_e32 v17, 0x3fb8aa3b, v17
	v_exp_f32_e32 v24, v17
	s_nop 0
	v_sub_f32_e32 v17, 1.0, v24
	v_add_f32_e32 v44, 1.0, v24
	v_mul_f32_e32 v17, v17, v44
	v_max_f32_e32 v17, 0, v17
	v_sqrt_f32_e32 v17, v17
	s_nop 0
	v_mul_f32_e32 v17, v42, v17
	v_mul_f32_e32 v25, v17, v25
	v_add_f32_e32 v17, v142, v146
	v_mul_f32_e32 v17, 0xbfb8aa3b, v17
	v_exp_f32_e32 v17, v17
	ds_write2_b64 v191, v[20:21], v[24:25] offset0:16 offset1:33
	v_add_f32_e32 v20, v138, v150
	v_mul_f32_e32 v20, 0xbfb8aa3b, v20
	v_add_f32_e32 v17, 1.0, v17
	v_rcp_f32_e32 v17, v17
	v_exp_f32_e32 v20, v20
	v_mul_f32_e32 v17, 0xc1000000, v17
	v_mul_f32_e32 v17, v179, v17
	v_add_f32_e32 v20, 1.0, v20
	v_mul_f32_e32 v17, 0x3fb8aa3b, v17
	v_rcp_f32_e32 v21, v20
	v_exp_f32_e32 v20, v17
	s_nop 0
	v_sub_f32_e32 v17, 1.0, v20
	v_add_f32_e32 v24, 1.0, v20
	v_mul_f32_e32 v17, v17, v24
	v_max_f32_e32 v17, 0, v17
	v_sqrt_f32_e32 v17, v17
	v_add_f32_e32 v24, v139, v151
	v_mul_f32_e32 v24, 0xbfb8aa3b, v24
	v_exp_f32_e32 v24, v24
	v_mul_f32_e32 v17, v21, v17
	v_mul_f32_e32 v21, v17, v40
	v_add_f32_e32 v17, v143, v147
	v_mul_f32_e32 v17, 0xbfb8aa3b, v17
	v_exp_f32_e32 v17, v17
	v_add_f32_e32 v24, 1.0, v24
	v_rcp_f32_e32 v25, v24
	v_mfma_f32_16x16x32_bf16 v[136:139], v[88:91], v[128:131], 0
	v_add_f32_e32 v17, 1.0, v17
	v_rcp_f32_e32 v17, v17
	v_mfma_f32_16x16x32_bf16 v[140:143], v[96:99], v[132:135], v[136:139]
	v_mul_f32_e32 v17, 0xc1000000, v17
	v_mul_f32_e32 v17, v181, v17
	v_mul_f32_e32 v17, 0x3fb8aa3b, v17
	v_exp_f32_e32 v24, v17
	v_mfma_f32_16x16x32_bf16 v[136:139], v[84:87], v[128:131], 0
	v_sub_f32_e32 v17, 1.0, v24
	v_add_f32_e32 v40, 1.0, v24
	v_mul_f32_e32 v17, v17, v40
	v_max_f32_e32 v17, 0, v17
	v_sqrt_f32_e32 v17, v17
	v_mfma_f32_16x16x32_bf16 v[136:139], v[92:95], v[132:135], v[136:139]
	v_mul_f32_e32 v17, v25, v17
	v_mul_f32_e32 v25, v17, v41
	ds_write2_b64 v191, v[20:21], v[24:25] offset0:50 offset1:67
	global_load_dwordx4 v[144:147], v[170:171], off offset:128
	global_load_dwordx4 v[148:151], v[0:1], off offset:128
	ds_read_b64 v[20:21], v2 offset:17472
	s_waitcnt lgkmcnt(0)
	v_lshlrev_b32_e32 v17, 16, v20
	v_and_b32_e32 v25, 0xffff0000, v20
	v_lshlrev_b32_e32 v40, 16, v21
	v_and_b32_e32 v41, 0xffff0000, v21
	s_waitcnt vmcnt(1)
	v_add_f32_e32 v20, v140, v144
	v_mul_f32_e32 v20, 0xbfb8aa3b, v20
	v_exp_f32_e32 v20, v20
	s_waitcnt vmcnt(0)
	v_add_f32_e32 v21, v136, v148
	v_mul_f32_e32 v21, 0xbfb8aa3b, v21
	v_exp_f32_e32 v21, v21
	v_add_f32_e32 v20, 1.0, v20
	v_rcp_f32_e32 v20, v20
	v_add_f32_e32 v21, 1.0, v21
	v_rcp_f32_e32 v21, v21
	v_mul_f32_e32 v20, 0xc1000000, v20
	v_mul_f32_e32 v20, v178, v20
	v_mul_f32_e32 v20, 0x3fb8aa3b, v20
	v_exp_f32_e32 v20, v20
	s_nop 0
	v_sub_f32_e32 v24, 1.0, v20
	v_add_f32_e32 v42, 1.0, v20
	v_mul_f32_e32 v24, v24, v42
	v_max_f32_e32 v24, 0, v24
	v_sqrt_f32_e32 v24, v24
	s_nop 0
	v_mul_f32_e32 v21, v21, v24
	v_mul_f32_e32 v21, v21, v17
	v_add_f32_e32 v17, v141, v145
	v_mul_f32_e32 v17, 0xbfb8aa3b, v17
	v_exp_f32_e32 v17, v17
	v_add_f32_e32 v24, v137, v149
	v_mul_f32_e32 v24, 0xbfb8aa3b, v24
	v_exp_f32_e32 v24, v24
	v_add_f32_e32 v17, 1.0, v17
	v_rcp_f32_e32 v17, v17
	v_add_f32_e32 v24, 1.0, v24
	v_rcp_f32_e32 v42, v24
	v_mul_f32_e32 v17, 0xc1000000, v17
	v_mul_f32_e32 v17, v180, v17
	v_mul_f32_e32 v17, 0x3fb8aa3b, v17
	v_exp_f32_e32 v24, v17
	s_nop 0
	v_sub_f32_e32 v17, 1.0, v24
	v_add_f32_e32 v44, 1.0, v24
	v_mul_f32_e32 v17, v17, v44
	v_max_f32_e32 v17, 0, v17
	v_sqrt_f32_e32 v17, v17
	s_nop 0
	v_mul_f32_e32 v17, v42, v17
	v_mul_f32_e32 v25, v17, v25
	v_add_f32_e32 v17, v142, v146
	v_mul_f32_e32 v17, 0xbfb8aa3b, v17
	v_exp_f32_e32 v17, v17
	ds_write2_b64 v192, v[20:21], v[24:25] offset0:32 offset1:49
	v_add_f32_e32 v20, v138, v150
	v_mul_f32_e32 v20, 0xbfb8aa3b, v20
	v_add_f32_e32 v17, 1.0, v17
	v_rcp_f32_e32 v17, v17
	v_exp_f32_e32 v20, v20
	v_mul_f32_e32 v17, 0xc1000000, v17
	v_mul_f32_e32 v17, v182, v17
	v_add_f32_e32 v20, 1.0, v20
	v_mul_f32_e32 v17, 0x3fb8aa3b, v17
	v_rcp_f32_e32 v21, v20
	v_exp_f32_e32 v20, v17
	s_nop 0
	v_sub_f32_e32 v17, 1.0, v20
	v_add_f32_e32 v24, 1.0, v20
	v_mul_f32_e32 v17, v17, v24
	v_max_f32_e32 v17, 0, v17
	v_sqrt_f32_e32 v17, v17
	v_add_f32_e32 v24, v139, v151
	v_mul_f32_e32 v24, 0xbfb8aa3b, v24
	v_exp_f32_e32 v24, v24
	v_mul_f32_e32 v17, v21, v17
	v_mul_f32_e32 v21, v17, v40
	v_add_f32_e32 v17, v143, v147
	v_mul_f32_e32 v17, 0xbfb8aa3b, v17
	v_exp_f32_e32 v17, v17
	v_add_f32_e32 v24, 1.0, v24
	v_rcp_f32_e32 v25, v24
	v_mfma_f32_16x16x32_bf16 v[136:139], v[72:75], v[128:131], 0
	v_add_f32_e32 v17, 1.0, v17
	v_rcp_f32_e32 v17, v17
	v_mfma_f32_16x16x32_bf16 v[128:131], v[68:71], v[128:131], 0
	v_mul_f32_e32 v17, 0xc1000000, v17
	v_mul_f32_e32 v17, v183, v17
	v_mul_f32_e32 v17, 0x3fb8aa3b, v17
	v_exp_f32_e32 v24, v17
	v_mfma_f32_16x16x32_bf16 v[136:139], v[80:83], v[132:135], v[136:139]
	v_sub_f32_e32 v17, 1.0, v24
	v_add_f32_e32 v40, 1.0, v24
	v_mul_f32_e32 v17, v17, v40
	v_max_f32_e32 v17, 0, v17
	v_sqrt_f32_e32 v17, v17
	v_mfma_f32_16x16x32_bf16 v[128:131], v[76:79], v[132:135], v[128:131]
	v_mul_f32_e32 v17, v25, v17
	v_mul_f32_e32 v25, v17, v41
	ds_write2_b64 v192, v[20:21], v[24:25] offset0:66 offset1:83
	global_load_dwordx4 v[132:135], v[170:171], off offset:192
	global_load_dwordx4 v[140:143], v[0:1], off offset:192
	ds_read_b64 v[20:21], v2 offset:17504
	s_waitcnt lgkmcnt(0)
	v_lshlrev_b32_e32 v17, 16, v20
	v_and_b32_e32 v25, 0xffff0000, v20
	v_lshlrev_b32_e32 v40, 16, v21
	v_and_b32_e32 v41, 0xffff0000, v21
	s_waitcnt vmcnt(1)
	v_add_f32_e32 v20, v136, v132
	v_mul_f32_e32 v20, 0xbfb8aa3b, v20
	v_exp_f32_e32 v20, v20
	s_waitcnt vmcnt(0)
	v_add_f32_e32 v21, v128, v140
	v_mul_f32_e32 v21, 0xbfb8aa3b, v21
	v_exp_f32_e32 v21, v21
	v_add_f32_e32 v20, 1.0, v20
	v_rcp_f32_e32 v20, v20
	v_add_f32_e32 v21, 1.0, v21
	v_rcp_f32_e32 v21, v21
	v_mul_f32_e32 v20, 0xc1000000, v20
	v_mul_f32_e32 v20, v184, v20
	v_mul_f32_e32 v20, 0x3fb8aa3b, v20
	v_exp_f32_e32 v20, v20
	s_nop 0
	v_sub_f32_e32 v24, 1.0, v20
	v_add_f32_e32 v42, 1.0, v20
	v_mul_f32_e32 v24, v24, v42
	v_max_f32_e32 v24, 0, v24
	v_sqrt_f32_e32 v24, v24
	s_nop 0
	v_mul_f32_e32 v21, v21, v24
	v_mul_f32_e32 v21, v21, v17
	v_add_f32_e32 v17, v137, v133
	v_mul_f32_e32 v17, 0xbfb8aa3b, v17
	v_exp_f32_e32 v17, v17
	v_add_f32_e32 v24, v129, v141
	v_mul_f32_e32 v24, 0xbfb8aa3b, v24
	v_exp_f32_e32 v24, v24
	v_add_f32_e32 v17, 1.0, v17
	v_rcp_f32_e32 v17, v17
	v_add_f32_e32 v24, 1.0, v24
	v_rcp_f32_e32 v42, v24
	v_mul_f32_e32 v17, 0xc1000000, v17
	v_mul_f32_e32 v17, v185, v17
	v_mul_f32_e32 v17, 0x3fb8aa3b, v17
	v_exp_f32_e32 v24, v17
	s_nop 0
	v_sub_f32_e32 v17, 1.0, v24
	v_add_f32_e32 v44, 1.0, v24
	v_mul_f32_e32 v17, v17, v44
	v_max_f32_e32 v17, 0, v17
	v_sqrt_f32_e32 v17, v17
	s_nop 0
	v_mul_f32_e32 v17, v42, v17
	v_mul_f32_e32 v25, v17, v25
	v_add_f32_e32 v17, v138, v134
	v_mul_f32_e32 v17, 0xbfb8aa3b, v17
	v_exp_f32_e32 v17, v17
	ds_write2_b64 v189, v[20:21], v[24:25] offset0:48 offset1:65
	v_add_f32_e32 v20, v130, v142
	v_mul_f32_e32 v20, 0xbfb8aa3b, v20
	v_add_f32_e32 v17, 1.0, v17
	v_rcp_f32_e32 v17, v17
	v_exp_f32_e32 v20, v20
	v_mul_f32_e32 v17, 0xc1000000, v17
	v_mul_f32_e32 v17, v186, v17
	v_add_f32_e32 v20, 1.0, v20
	v_mul_f32_e32 v17, 0x3fb8aa3b, v17
	v_rcp_f32_e32 v21, v20
	v_exp_f32_e32 v20, v17
	s_nop 0
	v_sub_f32_e32 v17, 1.0, v20
	v_add_f32_e32 v24, 1.0, v20
	v_mul_f32_e32 v17, v17, v24
	v_max_f32_e32 v17, 0, v17
	v_sqrt_f32_e32 v17, v17
	v_add_f32_e32 v24, v131, v143
	v_mul_f32_e32 v24, 0xbfb8aa3b, v24
	v_exp_f32_e32 v24, v24
	v_mul_f32_e32 v17, v21, v17
	v_mul_f32_e32 v21, v17, v40
	v_add_f32_e32 v17, v139, v135
	v_mul_f32_e32 v17, 0xbfb8aa3b, v17
	v_exp_f32_e32 v17, v17
	v_add_f32_e32 v24, 1.0, v24
	v_rcp_f32_e32 v25, v24
	v_add_f32_e32 v17, 1.0, v17
	v_rcp_f32_e32 v17, v17
	s_nop 0
	v_mul_f32_e32 v17, 0xc1000000, v17
	v_mul_f32_e32 v17, v187, v17
	v_mul_f32_e32 v17, 0x3fb8aa3b, v17
	v_exp_f32_e32 v24, v17
	s_nop 0
	v_sub_f32_e32 v17, 1.0, v24
	v_add_f32_e32 v40, 1.0, v24
	v_mul_f32_e32 v17, v17, v40
	v_max_f32_e32 v17, 0, v17
	v_sqrt_f32_e32 v17, v17
	s_nop 0
	v_mul_f32_e32 v17, v25, v17
	v_mul_f32_e32 v25, v17, v41
	ds_write2_b64 v189, v[20:21], v[24:25] offset0:82 offset1:99
	s_waitcnt lgkmcnt(0)
	s_barrier
	ds_read2_b64 v[130:133], v188 offset1:1
	ds_read2_b64 v[158:161], v16 offset1:1
	ds_read2_b64 v[134:137], v4 offset1:1
	ds_read2_b64 v[138:141], v5 offset1:1
	ds_read2_b64 v[142:145], v8 offset1:1
	ds_read2_b64 v[146:149], v9 offset1:1
	s_waitcnt lgkmcnt(5)
	v_fma_f32 v40, v67, v130, v131
	ds_read2_b64 v[150:153], v12 offset1:1
	ds_read2_b64 v[154:157], v13 offset1:1
	s_waitcnt lgkmcnt(0)
	s_barrier
	ds_read_b128 v[128:131], v166 offset:26112
	ds_read_b128 v[166:169], v166 offset:26176
	s_waitcnt lgkmcnt(1)
	v_mfma_f32_16x16x32_bf16 v[120:123], v[120:123], v[128:131], 0
	v_fmac_f32_e32 v133, v132, v40
	v_fma_f32 v41, v134, v133, v135
	v_fmac_f32_e32 v137, v136, v41
	v_mfma_f32_16x16x32_bf16 v[116:119], v[116:119], v[128:131], 0
	v_fma_f32 v42, v138, v137, v139
	v_fmac_f32_e32 v141, v140, v42
	v_fma_f32 v44, v142, v141, v143
	s_waitcnt lgkmcnt(0)
	v_mfma_f32_16x16x32_bf16 v[120:123], v[162:165], v[166:169], v[120:123]
	v_fmac_f32_e32 v145, v144, v44
	v_fma_f32 v45, v146, v145, v147
	v_fmac_f32_e32 v149, v148, v45
	v_mfma_f32_16x16x32_bf16 v[116:119], v[124:127], v[166:169], v[116:119]
	global_load_dwordx4 v[124:127], v[170:171], off
	global_load_dwordx4 v[162:165], v[0:1], off
	ds_read_b64 v[20:21], v2 offset:26112
	v_fma_f32 v46, v150, v149, v151
	v_mfma_f32_16x16x32_bf16 v[104:107], v[104:107], v[128:131], 0
	v_fmac_f32_e32 v153, v152, v46
	v_fma_f32 v53, v154, v153, v155
	s_waitcnt lgkmcnt(0)
	v_lshlrev_b32_e32 v17, 16, v20
	v_and_b32_e32 v25, 0xffff0000, v20
	v_lshlrev_b32_e32 v48, 16, v21
	v_and_b32_e32 v49, 0xffff0000, v21
	v_mfma_f32_16x16x32_bf16 v[100:103], v[100:103], v[128:131], 0
	v_fmac_f32_e32 v157, v156, v53
	v_fma_f32 v54, v158, v157, v159
	v_fmac_f32_e32 v161, v160, v54
	v_mfma_f32_16x16x32_bf16 v[104:107], v[112:115], v[166:169], v[104:107]
	s_waitcnt vmcnt(1)
	v_add_f32_e32 v20, v120, v124
	v_mul_f32_e32 v20, 0xbfb8aa3b, v20
	v_exp_f32_e32 v20, v20
	s_waitcnt vmcnt(0)
	v_add_f32_e32 v21, v116, v162
	v_mul_f32_e32 v21, 0xbfb8aa3b, v21
	v_exp_f32_e32 v21, v21
	v_add_f32_e32 v20, 1.0, v20
	v_rcp_f32_e32 v20, v20
	v_mfma_f32_16x16x32_bf16 v[100:103], v[108:111], v[166:169], v[100:103]
	v_add_f32_e32 v21, 1.0, v21
	v_rcp_f32_e32 v21, v21
	v_mul_f32_e32 v20, 0xc1000000, v20
	v_mul_f32_e32 v20, v172, v20
	v_mul_f32_e32 v20, 0x3fb8aa3b, v20
	v_exp_f32_e32 v20, v20
	v_mfma_f32_16x16x32_bf16 v[88:91], v[88:91], v[128:131], 0
	v_sub_f32_e32 v24, 1.0, v20
	v_add_f32_e32 v50, 1.0, v20
	v_mul_f32_e32 v24, v24, v50
	v_max_f32_e32 v24, 0, v24
	v_sqrt_f32_e32 v24, v24
	v_mfma_f32_16x16x32_bf16 v[84:87], v[84:87], v[128:131], 0
	v_mul_f32_e32 v21, v21, v24
	v_mul_f32_e32 v21, v21, v17
	v_add_f32_e32 v17, v121, v125
	v_mul_f32_e32 v17, 0xbfb8aa3b, v17
	v_exp_f32_e32 v17, v17
	v_add_f32_e32 v24, v117, v163
	v_mul_f32_e32 v24, 0xbfb8aa3b, v24
	v_exp_f32_e32 v24, v24
	v_add_f32_e32 v17, 1.0, v17
	v_rcp_f32_e32 v17, v17
	v_mfma_f32_16x16x32_bf16 v[88:91], v[96:99], v[166:169], v[88:91]
	v_add_f32_e32 v24, 1.0, v24
	v_rcp_f32_e32 v50, v24
	v_mul_f32_e32 v17, 0xc1000000, v17
	v_mul_f32_e32 v17, v173, v17
	v_mul_f32_e32 v17, 0x3fb8aa3b, v17
	v_exp_f32_e32 v24, v17
	v_mfma_f32_16x16x32_bf16 v[84:87], v[92:95], v[166:169], v[84:87]
	v_sub_f32_e32 v17, 1.0, v24
	v_add_f32_e32 v52, 1.0, v24
	v_mul_f32_e32 v17, v17, v52
	v_max_f32_e32 v17, 0, v17
	v_sqrt_f32_e32 v17, v17
	v_mfma_f32_16x16x32_bf16 v[72:75], v[72:75], v[128:131], 0
	v_mul_f32_e32 v17, v50, v17
	v_mul_f32_e32 v25, v17, v25
	v_add_f32_e32 v17, v122, v126
	v_mul_f32_e32 v17, 0xbfb8aa3b, v17
	v_exp_f32_e32 v17, v17
	ds_write2_b64 v190, v[20:21], v[24:25] offset1:17
	v_add_f32_e32 v20, v118, v164
	v_mul_f32_e32 v20, 0xbfb8aa3b, v20
	v_add_f32_e32 v17, 1.0, v17
	v_rcp_f32_e32 v17, v17
	v_exp_f32_e32 v20, v20
	v_mfma_f32_16x16x32_bf16 v[68:71], v[68:71], v[128:131], 0
	v_mul_f32_e32 v17, 0xc1000000, v17
	v_mul_f32_e32 v17, v174, v17
	v_add_f32_e32 v20, 1.0, v20
	v_mul_f32_e32 v17, 0x3fb8aa3b, v17
	v_rcp_f32_e32 v21, v20
	v_exp_f32_e32 v20, v17
	v_mfma_f32_16x16x32_bf16 v[72:75], v[80:83], v[166:169], v[72:75]
	v_sub_f32_e32 v17, 1.0, v20
	v_add_f32_e32 v24, 1.0, v20
	v_mul_f32_e32 v17, v17, v24
	v_max_f32_e32 v17, 0, v17
	v_sqrt_f32_e32 v17, v17
	v_add_f32_e32 v24, v119, v165
	v_mul_f32_e32 v24, 0xbfb8aa3b, v24
	v_exp_f32_e32 v24, v24
	v_mul_f32_e32 v17, v21, v17
	v_mul_f32_e32 v21, v17, v48
	v_add_f32_e32 v17, v123, v127
	v_mul_f32_e32 v17, 0xbfb8aa3b, v17
	v_exp_f32_e32 v17, v17
	v_add_f32_e32 v24, 1.0, v24
	v_rcp_f32_e32 v25, v24
	v_mfma_f32_16x16x32_bf16 v[68:71], v[76:79], v[166:169], v[68:71]
	v_add_f32_e32 v17, 1.0, v17
	v_rcp_f32_e32 v17, v17
	s_nop 0
	v_mul_f32_e32 v17, 0xc1000000, v17
	v_mul_f32_e32 v17, v175, v17
	v_mul_f32_e32 v17, 0x3fb8aa3b, v17
	v_exp_f32_e32 v24, v17
	s_nop 0
	v_sub_f32_e32 v17, 1.0, v24
	v_add_f32_e32 v48, 1.0, v24
	v_mul_f32_e32 v17, v17, v48
	v_max_f32_e32 v17, 0, v17
	v_sqrt_f32_e32 v17, v17
	s_nop 0
	v_mul_f32_e32 v17, v25, v17
	v_mul_f32_e32 v25, v17, v49
	ds_write2_b64 v190, v[20:21], v[24:25] offset0:34 offset1:51
	global_load_dwordx4 v[108:111], v[170:171], off offset:64
	global_load_dwordx4 v[112:115], v[0:1], off offset:64
	ds_read_b64 v[20:21], v2 offset:26144
	s_waitcnt lgkmcnt(0)
	v_lshlrev_b32_e32 v17, 16, v20
	v_and_b32_e32 v25, 0xffff0000, v20
	v_lshlrev_b32_e32 v48, 16, v21
	v_and_b32_e32 v49, 0xffff0000, v21
	s_waitcnt vmcnt(1)
	v_add_f32_e32 v20, v104, v108
	v_mul_f32_e32 v20, 0xbfb8aa3b, v20
	v_exp_f32_e32 v20, v20
	s_waitcnt vmcnt(0)
	v_add_f32_e32 v21, v100, v112
	v_mul_f32_e32 v21, 0xbfb8aa3b, v21
	v_exp_f32_e32 v21, v21
	v_add_f32_e32 v20, 1.0, v20
	v_rcp_f32_e32 v20, v20
	v_add_f32_e32 v21, 1.0, v21
	v_rcp_f32_e32 v21, v21
	v_mul_f32_e32 v20, 0xc1000000, v20
	v_mul_f32_e32 v20, v176, v20
	v_mul_f32_e32 v20, 0x3fb8aa3b, v20
	v_exp_f32_e32 v20, v20
	s_nop 0
	v_sub_f32_e32 v24, 1.0, v20
	v_add_f32_e32 v50, 1.0, v20
	v_mul_f32_e32 v24, v24, v50
	v_max_f32_e32 v24, 0, v24
	v_sqrt_f32_e32 v24, v24
	s_nop 0
	v_mul_f32_e32 v21, v21, v24
	v_mul_f32_e32 v21, v21, v17
	v_add_f32_e32 v17, v105, v109
	v_mul_f32_e32 v17, 0xbfb8aa3b, v17
	v_exp_f32_e32 v17, v17
	v_add_f32_e32 v24, v101, v113
	v_mul_f32_e32 v24, 0xbfb8aa3b, v24
	v_exp_f32_e32 v24, v24
	v_add_f32_e32 v17, 1.0, v17
	v_rcp_f32_e32 v17, v17
	v_add_f32_e32 v24, 1.0, v24
	v_rcp_f32_e32 v50, v24
	v_mul_f32_e32 v17, 0xc1000000, v17
	v_mul_f32_e32 v17, v177, v17
	v_mul_f32_e32 v17, 0x3fb8aa3b, v17
	v_exp_f32_e32 v24, v17
	s_nop 0
	v_sub_f32_e32 v17, 1.0, v24
	v_add_f32_e32 v52, 1.0, v24
	v_mul_f32_e32 v17, v17, v52
	v_max_f32_e32 v17, 0, v17
	v_sqrt_f32_e32 v17, v17
	s_nop 0
	v_mul_f32_e32 v17, v50, v17
	v_mul_f32_e32 v25, v17, v25
	v_add_f32_e32 v17, v106, v110
	v_mul_f32_e32 v17, 0xbfb8aa3b, v17
	v_exp_f32_e32 v17, v17
	ds_write2_b64 v191, v[20:21], v[24:25] offset0:16 offset1:33
	v_add_f32_e32 v20, v102, v114
	v_mul_f32_e32 v20, 0xbfb8aa3b, v20
	v_add_f32_e32 v17, 1.0, v17
	v_rcp_f32_e32 v17, v17
	v_exp_f32_e32 v20, v20
	v_mul_f32_e32 v17, 0xc1000000, v17
	v_mul_f32_e32 v17, v179, v17
	v_add_f32_e32 v20, 1.0, v20
	v_mul_f32_e32 v17, 0x3fb8aa3b, v17
	v_rcp_f32_e32 v21, v20
	v_exp_f32_e32 v20, v17
	s_nop 0
	v_sub_f32_e32 v17, 1.0, v20
	v_add_f32_e32 v24, 1.0, v20
	v_mul_f32_e32 v17, v17, v24
	v_max_f32_e32 v17, 0, v17
	v_sqrt_f32_e32 v17, v17
	v_add_f32_e32 v24, v103, v115
	v_mul_f32_e32 v24, 0xbfb8aa3b, v24
	v_exp_f32_e32 v24, v24
	v_mul_f32_e32 v17, v21, v17
	v_mul_f32_e32 v21, v17, v48
	v_add_f32_e32 v17, v107, v111
	v_mul_f32_e32 v17, 0xbfb8aa3b, v17
	v_exp_f32_e32 v17, v17
	v_add_f32_e32 v24, 1.0, v24
	v_rcp_f32_e32 v25, v24
	v_add_f32_e32 v17, 1.0, v17
	v_rcp_f32_e32 v17, v17
	s_nop 0
	v_mul_f32_e32 v17, 0xc1000000, v17
	v_mul_f32_e32 v17, v181, v17
	v_mul_f32_e32 v17, 0x3fb8aa3b, v17
	v_exp_f32_e32 v24, v17
	s_nop 0
	v_sub_f32_e32 v17, 1.0, v24
	v_add_f32_e32 v48, 1.0, v24
	v_mul_f32_e32 v17, v17, v48
	v_max_f32_e32 v17, 0, v17
	v_sqrt_f32_e32 v17, v17
	s_nop 0
	v_mul_f32_e32 v17, v25, v17
	v_mul_f32_e32 v25, v17, v49
	ds_write2_b64 v191, v[20:21], v[24:25] offset0:50 offset1:67
	global_load_dwordx4 v[92:95], v[170:171], off offset:128
	global_load_dwordx4 v[96:99], v[0:1], off offset:128
	ds_read_b64 v[20:21], v2 offset:26176
	s_waitcnt lgkmcnt(0)
	v_lshlrev_b32_e32 v17, 16, v20
	v_and_b32_e32 v25, 0xffff0000, v20
	v_lshlrev_b32_e32 v48, 16, v21
	v_and_b32_e32 v49, 0xffff0000, v21
	s_waitcnt vmcnt(1)
	v_add_f32_e32 v20, v88, v92
	v_mul_f32_e32 v20, 0xbfb8aa3b, v20
	v_exp_f32_e32 v20, v20
	s_waitcnt vmcnt(0)
	v_add_f32_e32 v21, v84, v96
	v_mul_f32_e32 v21, 0xbfb8aa3b, v21
	v_exp_f32_e32 v21, v21
	v_add_f32_e32 v20, 1.0, v20
	v_rcp_f32_e32 v20, v20
	v_add_f32_e32 v21, 1.0, v21
	v_rcp_f32_e32 v21, v21
	v_mul_f32_e32 v20, 0xc1000000, v20
	v_mul_f32_e32 v20, v178, v20
	v_mul_f32_e32 v20, 0x3fb8aa3b, v20
	v_exp_f32_e32 v20, v20
	s_nop 0
	v_sub_f32_e32 v24, 1.0, v20
	v_add_f32_e32 v50, 1.0, v20
	v_mul_f32_e32 v24, v24, v50
	v_max_f32_e32 v24, 0, v24
	v_sqrt_f32_e32 v24, v24
	s_nop 0
	v_mul_f32_e32 v21, v21, v24
	v_mul_f32_e32 v21, v21, v17
	v_add_f32_e32 v17, v89, v93
	v_mul_f32_e32 v17, 0xbfb8aa3b, v17
	v_exp_f32_e32 v17, v17
	v_add_f32_e32 v24, v85, v97
	v_mul_f32_e32 v24, 0xbfb8aa3b, v24
	v_exp_f32_e32 v24, v24
	v_add_f32_e32 v17, 1.0, v17
	v_rcp_f32_e32 v17, v17
	v_add_f32_e32 v24, 1.0, v24
	v_rcp_f32_e32 v50, v24
	v_mul_f32_e32 v17, 0xc1000000, v17
	v_mul_f32_e32 v17, v180, v17
	v_mul_f32_e32 v17, 0x3fb8aa3b, v17
	v_exp_f32_e32 v24, v17
	s_nop 0
	v_sub_f32_e32 v17, 1.0, v24
	v_add_f32_e32 v52, 1.0, v24
	v_mul_f32_e32 v17, v17, v52
	v_max_f32_e32 v17, 0, v17
	v_sqrt_f32_e32 v17, v17
	s_nop 0
	v_mul_f32_e32 v17, v50, v17
	v_mul_f32_e32 v25, v17, v25
	v_add_f32_e32 v17, v90, v94
	v_mul_f32_e32 v17, 0xbfb8aa3b, v17
	v_exp_f32_e32 v17, v17
	ds_write2_b64 v192, v[20:21], v[24:25] offset0:32 offset1:49
	v_add_f32_e32 v20, v86, v98
	v_mul_f32_e32 v20, 0xbfb8aa3b, v20
	v_add_f32_e32 v17, 1.0, v17
	v_rcp_f32_e32 v17, v17
	v_exp_f32_e32 v20, v20
	v_mul_f32_e32 v17, 0xc1000000, v17
	v_mul_f32_e32 v17, v182, v17
	v_add_f32_e32 v20, 1.0, v20
	v_mul_f32_e32 v17, 0x3fb8aa3b, v17
	v_rcp_f32_e32 v21, v20
	v_exp_f32_e32 v20, v17
	s_nop 0
	v_sub_f32_e32 v17, 1.0, v20
	v_add_f32_e32 v24, 1.0, v20
	v_mul_f32_e32 v17, v17, v24
	v_max_f32_e32 v17, 0, v17
	v_sqrt_f32_e32 v17, v17
	v_add_f32_e32 v24, v87, v99
	v_mul_f32_e32 v24, 0xbfb8aa3b, v24
	v_exp_f32_e32 v24, v24
	v_mul_f32_e32 v17, v21, v17
	v_mul_f32_e32 v21, v17, v48
	v_add_f32_e32 v17, v91, v95
	v_mul_f32_e32 v17, 0xbfb8aa3b, v17
	v_exp_f32_e32 v17, v17
	v_add_f32_e32 v24, 1.0, v24
	v_rcp_f32_e32 v25, v24
	v_add_f32_e32 v17, 1.0, v17
	v_rcp_f32_e32 v17, v17
	s_nop 0
	v_mul_f32_e32 v17, 0xc1000000, v17
	v_mul_f32_e32 v17, v183, v17
	v_mul_f32_e32 v17, 0x3fb8aa3b, v17
	v_exp_f32_e32 v24, v17
	s_nop 0
	v_sub_f32_e32 v17, 1.0, v24
	v_add_f32_e32 v48, 1.0, v24
	v_mul_f32_e32 v17, v17, v48
	v_max_f32_e32 v17, 0, v17
	v_sqrt_f32_e32 v17, v17
	s_nop 0
	v_mul_f32_e32 v17, v25, v17
	v_mul_f32_e32 v25, v17, v49
	ds_write2_b64 v192, v[20:21], v[24:25] offset0:66 offset1:83
	global_load_dwordx4 v[76:79], v[170:171], off offset:192
	global_load_dwordx4 v[80:83], v[0:1], off offset:192
	ds_read_b64 v[0:1], v2 offset:26208
	s_waitcnt lgkmcnt(0)
	v_lshlrev_b32_e32 v2, 16, v0
	v_and_b32_e32 v17, 0xffff0000, v0
	v_lshlrev_b32_e32 v24, 16, v1
	v_and_b32_e32 v25, 0xffff0000, v1
	s_waitcnt vmcnt(1)
	v_add_f32_e32 v0, v72, v76
	v_mul_f32_e32 v0, 0xbfb8aa3b, v0
	v_exp_f32_e32 v0, v0
	s_waitcnt vmcnt(0)
	v_add_f32_e32 v1, v68, v80
	v_mul_f32_e32 v1, 0xbfb8aa3b, v1
	v_exp_f32_e32 v1, v1
	v_add_f32_e32 v0, 1.0, v0
	v_rcp_f32_e32 v0, v0
	v_add_f32_e32 v1, 1.0, v1
	v_rcp_f32_e32 v1, v1
	v_mul_f32_e32 v0, 0xc1000000, v0
	v_mul_f32_e32 v0, v184, v0
	v_mul_f32_e32 v0, 0x3fb8aa3b, v0
	v_exp_f32_e32 v0, v0
	s_nop 0
	v_sub_f32_e32 v20, 1.0, v0
	v_add_f32_e32 v21, 1.0, v0
	v_mul_f32_e32 v20, v20, v21
	v_max_f32_e32 v20, 0, v20
	v_sqrt_f32_e32 v20, v20
	s_nop 0
	v_mul_f32_e32 v1, v1, v20
	v_mul_f32_e32 v1, v1, v2
	v_add_f32_e32 v2, v73, v77
	v_mul_f32_e32 v2, 0xbfb8aa3b, v2
	v_exp_f32_e32 v2, v2
	v_add_f32_e32 v20, v69, v81
	v_mul_f32_e32 v20, 0xbfb8aa3b, v20
	v_exp_f32_e32 v20, v20
	v_add_f32_e32 v2, 1.0, v2
	v_rcp_f32_e32 v2, v2
	v_add_f32_e32 v20, 1.0, v20
	v_rcp_f32_e32 v21, v20
	v_mul_f32_e32 v2, 0xc1000000, v2
	v_mul_f32_e32 v2, v185, v2
	v_mul_f32_e32 v2, 0x3fb8aa3b, v2
	v_exp_f32_e32 v20, v2
	s_nop 0
	v_sub_f32_e32 v2, 1.0, v20
	v_add_f32_e32 v48, 1.0, v20
	v_mul_f32_e32 v2, v2, v48
	v_max_f32_e32 v2, 0, v2
	v_sqrt_f32_e32 v2, v2
	s_nop 0
	v_mul_f32_e32 v2, v21, v2
	v_mul_f32_e32 v21, v2, v17
	ds_write2_b64 v189, v[0:1], v[20:21] offset0:48 offset1:65
	v_add_f32_e32 v0, v74, v78
	v_mul_f32_e32 v0, 0xbfb8aa3b, v0
	v_exp_f32_e32 v0, v0
	v_add_f32_e32 v1, v70, v82
	v_mul_f32_e32 v1, 0xbfb8aa3b, v1
	v_exp_f32_e32 v1, v1
	v_add_f32_e32 v0, 1.0, v0
	v_rcp_f32_e32 v0, v0
	v_add_f32_e32 v1, 1.0, v1
	v_rcp_f32_e32 v1, v1
	v_mul_f32_e32 v0, 0xc1000000, v0
	v_mul_f32_e32 v0, v186, v0
	v_mul_f32_e32 v0, 0x3fb8aa3b, v0
	v_exp_f32_e32 v0, v0
	s_nop 0
	v_sub_f32_e32 v2, 1.0, v0
	v_add_f32_e32 v17, 1.0, v0
	v_mul_f32_e32 v2, v2, v17
	v_max_f32_e32 v2, 0, v2
	v_sqrt_f32_e32 v2, v2
	v_add_f32_e32 v17, v71, v83
	v_mul_f32_e32 v17, 0xbfb8aa3b, v17
	v_exp_f32_e32 v17, v17
	v_mul_f32_e32 v1, v1, v2
	v_add_f32_e32 v2, v75, v79
	v_mul_f32_e32 v2, 0xbfb8aa3b, v2
	v_exp_f32_e32 v2, v2
	v_add_f32_e32 v17, 1.0, v17
	v_rcp_f32_e32 v17, v17
	v_mul_f32_e32 v1, v1, v24
	v_add_f32_e32 v2, 1.0, v2
	v_rcp_f32_e32 v2, v2
	s_nop 0
	v_mul_f32_e32 v2, 0xc1000000, v2
	v_mul_f32_e32 v2, v187, v2
	v_mul_f32_e32 v2, 0x3fb8aa3b, v2
	v_exp_f32_e32 v20, v2
	s_nop 0
	v_sub_f32_e32 v2, 1.0, v20
	v_add_f32_e32 v21, 1.0, v20
	v_mul_f32_e32 v2, v2, v21
	v_max_f32_e32 v2, 0, v2
	v_sqrt_f32_e32 v2, v2
	s_nop 0
	v_mul_f32_e32 v2, v17, v2
	v_mul_f32_e32 v21, v2, v25
	ds_write2_b64 v189, v[0:1], v[20:21] offset0:82 offset1:99
	s_waitcnt lgkmcnt(0)
	s_barrier
	ds_read2_b64 v[182:185], v12 offset1:1
	ds_read2_b64 v[190:193], v16 offset1:1
	v_mov_b32_e32 v12, v222
	ds_read2_b64 v[162:165], v188 offset1:1
	ds_read2_b64 v[166:169], v4 offset1:1
	ds_read2_b64 v[170:173], v5 offset1:1
	ds_read2_b64 v[174:177], v8 offset1:1
	ds_read2_b64 v[178:181], v9 offset1:1
	ds_read2_b64 v[186:189], v13 offset1:1
	s_waitcnt lgkmcnt(0)
	s_barrier
	v_mov_b32_e32 v9, v3
	v_ashrrev_i32_e32 v2, 6, v12
	v_add_u32_e32 v0, s0, v2
	v_readlane_b32 s0, v252, 55
	v_ashrrev_i32_e32 v1, 31, v0
	v_bfe_u32 v13, v12, 4, 2
	v_add_u32_e32 v4, s0, v2
	v_lshlrev_b64 v[0:1], 13, v[0:1]
	v_ashrrev_i32_e32 v5, 31, v4
	v_and_b32_e32 v20, 15, v12
	v_lshl_add_u64 v[0:1], s[84:85], 0, v[0:1]
	v_lshlrev_b64 v[4:5], 13, v[4:5]
	v_lshlrev_b32_e32 v2, 4, v13
	v_lshl_add_u64 v[4:5], s[84:85], 0, v[4:5]
	v_lshl_add_u64 v[0:1], v[0:1], 0, v[2:3]
	v_lshlrev_b32_e32 v8, 7, v20
	v_lshl_add_u64 v[4:5], v[4:5], 0, v[2:3]
	v_lshl_add_u64 v[16:17], v[0:1], 0, v[8:9]
	v_lshl_add_u64 v[48:49], v[4:5], 0, v[8:9]
	global_load_dwordx4 v[120:123], v[16:17], off
	global_load_dwordx4 v[116:119], v[48:49], off
	global_load_dwordx4 v[128:131], v[16:17], off offset:64
	global_load_dwordx4 v[124:127], v[48:49], off offset:64
	global_load_dwordx4 v[104:107], v[16:17], off offset:2048
	global_load_dwordx4 v[100:103], v[48:49], off offset:2048
	global_load_dwordx4 v[112:115], v[16:17], off offset:2112
	global_load_dwordx4 v[108:111], v[48:49], off offset:2112
	v_or_b32_e32 v16, 0x1000, v8
	v_mov_b32_e32 v17, v3
	v_or_b32_e32 v8, 0x1800, v8
	v_lshl_add_u64 v[48:49], v[0:1], 0, v[16:17]
	v_lshl_add_u64 v[16:17], v[4:5], 0, v[16:17]
	v_lshl_add_u64 v[0:1], v[0:1], 0, v[8:9]
	v_lshl_add_u64 v[4:5], v[4:5], 0, v[8:9]
	v_and_b32_e32 v8, 0xffffffc0, v12
	v_ashrrev_i32_e32 v9, 31, v8
	v_readlane_b32 s0, v252, 56
	global_load_dwordx4 v[88:91], v[48:49], off
	global_load_dwordx4 v[84:87], v[16:17], off
	global_load_dwordx4 v[96:99], v[48:49], off offset:64
	global_load_dwordx4 v[92:95], v[16:17], off offset:64
	global_load_dwordx4 v[72:75], v[0:1], off
	global_load_dwordx4 v[68:71], v[4:5], off
	global_load_dwordx4 v[80:83], v[0:1], off offset:64
	global_load_dwordx4 v[76:79], v[4:5], off offset:64
	v_lshlrev_b64 v[0:1], 2, v[8:9]
	v_readlane_b32 s1, v252, 57
	v_fma_f32 v24, v161, v162, v163
	v_fmac_f32_e32 v165, v164, v24
	v_lshl_add_u64 v[16:17], s[0:1], 0, v[0:1]
	v_readlane_b32 s0, v252, 58
	v_readlane_b32 s1, v252, 59
	v_fma_f32 v25, v166, v165, v167
	v_fmac_f32_e32 v169, v168, v25
	v_lshl_add_u64 v[4:5], s[0:1], 0, v[0:1]
	v_lshl_add_u64 v[4:5], v[4:5], 0, v[2:3]
	v_fma_f32 v58, v170, v169, v171
	v_fmac_f32_e32 v173, v172, v58
	v_fma_f32 v60, v174, v173, v175
	v_fmac_f32_e32 v177, v176, v60
	v_fma_f32 v61, v178, v177, v179
	v_fmac_f32_e32 v181, v180, v61
	v_fma_f32 v134, v182, v181, v183
	v_fmac_f32_e32 v185, v184, v134
	v_fma_f32 v135, v186, v185, v187
	v_readlane_b32 s0, v252, 60
	v_readlane_b32 s1, v252, 61
	v_lshlrev_b32_e32 v21, 3, v13
	v_fmac_f32_e32 v189, v188, v135
	v_lshl_add_u64 v[0:1], s[0:1], 0, v[0:1]
	v_fma_f32 v136, v190, v189, v191
	v_fmac_f32_e32 v193, v192, v136
	s_ashr_i32 s1, s8, 31
	s_add_u32 s0, s4, s8
	s_addc_u32 s1, s5, s1
	v_readlane_b32 s4, v252, 17
	v_readlane_b32 s5, v252, 18
	s_waitcnt vmcnt(0)
	s_lshl_b32 s98, s16, 11
	s_add_u32 s98, s98, 0x8400
	s_add_u32 s98, s30, s98
	s_addc_u32 s99, s31, 0
	v_lshrrev_b32_e32 v66, 4, v222
	v_and_b32_e32 v65, 3, v66
	v_lshrrev_b32_e32 v66, 2, v66
	v_lshlrev_b32_e32 v65, 4, v65
	v_lshl_or_b32 v66, v66, 8, v65
	global_load_dword v48, v66, s[98:99]
	global_load_dword v49, v66, s[98:99] offset:4
	global_load_dword v50, v66, s[98:99] offset:8
	global_load_dword v52, v66, s[98:99] offset:12
	global_load_dword v182, v66, s[98:99] offset:64
	global_load_dword v184, v66, s[98:99] offset:68
	global_load_dword v186, v66, s[98:99] offset:72
	global_load_dword v187, v66, s[98:99] offset:76
	global_load_dword v132, v66, s[98:99] offset:128
	global_load_dword v160, v66, s[98:99] offset:132
	global_load_dword v180, v66, s[98:99] offset:136
	global_load_dword v183, v66, s[98:99] offset:140
	global_load_dword v62, v66, s[98:99] offset:192
	global_load_dword v64, v66, s[98:99] offset:196
	global_load_dword v65, v66, s[98:99] offset:200
	global_load_dword v66, v66, s[98:99] offset:204
	v_lshlrev_b32_e32 v140, 3, v20
	v_lshl_or_b32 v139, v13, 2, v8
	v_ashrrev_i32_e32 v13, 31, v12
	v_lshl_add_u32 v56, v8, 1, 32
	v_lshl_add_u64 v[4:5], v[0:1], 0, v[2:3]
	v_lshl_add_u64 v[0:1], v[16:17], 0, v[2:3]
	v_lshlrev_b64 v[16:17], 1, v[12:13]
	v_mul_lo_u32 v12, v12, s6
	v_add_u32_e32 v138, 32, v12
	v_mul_u32_u24_e32 v12, 0x220, v20
	v_add3_u32 v57, v56, v12, v2
	ds_read_b128 v[194:197], v57 offset:26112
	ds_read_b128 v[198:201], v57 offset:26176
	global_load_dwordx4 v[210:213], v[4:5], off
	global_load_dwordx4 v[214:217], v[0:1], off
	s_waitcnt lgkmcnt(1)
	v_mfma_f32_16x16x32_bf16 v[202:205], v[120:123], v[194:197], 0
	v_sub_u32_e32 v2, v57, v21
	ds_read_b64 v[12:13], v2 offset:26112
	v_lshl_add_u64 v[8:9], s[4:5], 0, v[16:17]
	s_waitcnt lgkmcnt(1)
	v_mfma_f32_16x16x32_bf16 v[202:205], v[128:131], v[198:201], v[202:205]
	v_lshl_add_u64 v[16:17], s[20:21], 0, v[16:17]
	v_add_u32_e32 v188, 0x8800, v138
	s_waitcnt lgkmcnt(0)
	v_lshlrev_b32_e32 v21, 16, v12
	v_mfma_f32_16x16x32_bf16 v[206:209], v[116:119], v[194:197], 0
	v_and_b32_e32 v56, 0xffff0000, v12
	v_lshlrev_b32_e32 v144, 16, v13
	v_and_b32_e32 v13, 0xffff0000, v13
	v_mfma_f32_16x16x32_bf16 v[206:209], v[124:127], v[198:201], v[206:209]
	s_waitcnt vmcnt(1)
	v_add_f32_e32 v12, v202, v210
	v_mul_f32_e32 v12, 0xbfb8aa3b, v12
	v_exp_f32_e32 v12, v12
	s_waitcnt vmcnt(0)
	s_nop 2
	v_add_f32_e32 v20, v206, v214
	v_mul_f32_e32 v20, 0xbfb8aa3b, v20
	v_exp_f32_e32 v20, v20
	v_add_f32_e32 v12, 1.0, v12
	v_rcp_f32_e32 v12, v12
	v_add_f32_e32 v20, 1.0, v20
	v_rcp_f32_e32 v142, v20
	v_mul_f32_e32 v12, 0xc1000000, v12
	s_waitcnt vmcnt(0)
	v_mul_f32_e32 v12, v12, v48
	v_mul_f32_e32 v12, 0x3fb8aa3b, v12
	v_exp_f32_e32 v20, v12
	s_nop 0
	v_sub_f32_e32 v12, 1.0, v20
	v_add_f32_e32 v143, 1.0, v20
	v_mul_f32_e32 v12, v12, v143
	v_max_f32_e32 v12, 0, v12
	v_sqrt_f32_e32 v12, v12
	s_nop 0
	v_mul_f32_e32 v12, v142, v12
	v_mul_f32_e32 v21, v12, v21
	v_mul_lo_u32 v12, v139, s6
	v_add_f32_e32 v139, v203, v211
	v_mul_f32_e32 v139, 0xbfb8aa3b, v139
	v_exp_f32_e32 v139, v139
	v_add3_u32 v12, 32, v140, v12
	v_add_f32_e32 v140, v207, v215
	v_mul_f32_e32 v140, 0xbfb8aa3b, v140
	v_add_f32_e32 v139, 1.0, v139
	v_rcp_f32_e32 v139, v139
	v_exp_f32_e32 v140, v140
	v_add_u32_e32 v192, 0x9000, v12
	v_add_u32_e32 v191, 0x9800, v12
	v_mul_f32_e32 v139, 0xc1000000, v139
	v_mul_f32_e32 v139, v139, v49
	v_mul_f32_e32 v139, 0x3fb8aa3b, v139
	v_exp_f32_e32 v142, v139
	v_add_f32_e32 v140, 1.0, v140
	v_rcp_f32_e32 v140, v140
	v_add_u32_e32 v190, 0xa000, v12
	v_sub_f32_e32 v139, 1.0, v142
	v_add_f32_e32 v143, 1.0, v142
	v_mul_f32_e32 v139, v139, v143
	v_max_f32_e32 v139, 0, v139
	v_sqrt_f32_e32 v139, v139
	s_mul_i32 s6, s1, 0x1c00
	v_mul_f32_e32 v139, v140, v139
	v_mul_f32_e32 v143, v139, v56
	v_add_u32_e32 v56, 0x8800, v12
	ds_write2_b64 v56, v[20:21], v[142:143] offset1:17
	v_add_f32_e32 v20, v204, v212
	v_mul_f32_e32 v20, 0xbfb8aa3b, v20
	v_exp_f32_e32 v20, v20
	v_add_f32_e32 v21, v208, v216
	v_mul_f32_e32 v21, 0xbfb8aa3b, v21
	v_exp_f32_e32 v21, v21
	v_add_f32_e32 v20, 1.0, v20
	v_rcp_f32_e32 v20, v20
	v_add_f32_e32 v21, 1.0, v21
	v_rcp_f32_e32 v21, v21
	v_mul_f32_e32 v20, 0xc1000000, v20
	v_mul_f32_e32 v20, v20, v50
	v_mul_f32_e32 v20, 0x3fb8aa3b, v20
	v_exp_f32_e32 v20, v20
	s_nop 0
	v_sub_f32_e32 v139, 1.0, v20
	v_add_f32_e32 v140, 1.0, v20
	v_mul_f32_e32 v139, v139, v140
	v_max_f32_e32 v139, 0, v139
	v_sqrt_f32_e32 v139, v139
	v_add_f32_e32 v140, v209, v217
	v_mul_f32_e32 v140, 0xbfb8aa3b, v140
	v_exp_f32_e32 v140, v140
	v_mul_f32_e32 v21, v21, v139
	v_add_f32_e32 v139, v205, v213
	v_mul_f32_e32 v139, 0xbfb8aa3b, v139
	v_exp_f32_e32 v139, v139
	v_add_f32_e32 v140, 1.0, v140
	v_rcp_f32_e32 v140, v140
	v_mul_f32_e32 v21, v21, v144
	v_add_f32_e32 v139, 1.0, v139
	v_rcp_f32_e32 v139, v139
	v_mfma_f32_16x16x32_bf16 v[202:205], v[104:107], v[194:197], 0
	v_mul_f32_e32 v139, 0xc1000000, v139
	v_mul_f32_e32 v139, v139, v52
	v_mul_f32_e32 v139, 0x3fb8aa3b, v139
	v_exp_f32_e32 v142, v139
	v_mfma_f32_16x16x32_bf16 v[206:209], v[112:115], v[198:201], v[202:205]
	v_sub_f32_e32 v139, 1.0, v142
	v_add_f32_e32 v143, 1.0, v142
	v_mul_f32_e32 v139, v139, v143
	v_max_f32_e32 v139, 0, v139
	v_sqrt_f32_e32 v139, v139
	v_mfma_f32_16x16x32_bf16 v[202:205], v[100:103], v[194:197], 0
	v_mul_f32_e32 v139, v140, v139
	v_mul_f32_e32 v143, v139, v13
	ds_write2_b64 v56, v[20:21], v[142:143] offset0:34 offset1:51
	global_load_dwordx4 v[210:213], v[4:5], off offset:64
	global_load_dwordx4 v[214:217], v[0:1], off offset:64
	ds_read_b64 v[20:21], v2 offset:26144
	v_mfma_f32_16x16x32_bf16 v[202:205], v[108:111], v[198:201], v[202:205]
	s_waitcnt lgkmcnt(0)
	v_lshlrev_b32_e32 v13, 16, v20
	v_and_b32_e32 v139, 0xffff0000, v20
	v_lshlrev_b32_e32 v140, 16, v21
	v_and_b32_e32 v144, 0xffff0000, v21
	s_waitcnt vmcnt(1)
	v_add_f32_e32 v20, v206, v210
	v_mul_f32_e32 v20, 0xbfb8aa3b, v20
	v_exp_f32_e32 v20, v20
	s_waitcnt vmcnt(0)
	v_add_f32_e32 v21, v202, v214
	v_mul_f32_e32 v21, 0xbfb8aa3b, v21
	v_exp_f32_e32 v21, v21
	v_add_f32_e32 v20, 1.0, v20
	v_rcp_f32_e32 v20, v20
	v_add_f32_e32 v21, 1.0, v21
	v_rcp_f32_e32 v21, v21
	v_mul_f32_e32 v20, 0xc1000000, v20
	v_mul_f32_e32 v20, v20, v182
	v_mul_f32_e32 v20, 0x3fb8aa3b, v20
	v_exp_f32_e32 v20, v20
	s_nop 0
	v_sub_f32_e32 v142, 1.0, v20
	v_add_f32_e32 v143, 1.0, v20
	v_mul_f32_e32 v142, v142, v143
	v_max_f32_e32 v142, 0, v142
	v_sqrt_f32_e32 v142, v142
	s_nop 0
	v_mul_f32_e32 v21, v21, v142
	v_mul_f32_e32 v21, v21, v13
	v_add_f32_e32 v13, v207, v211
	v_mul_f32_e32 v13, 0xbfb8aa3b, v13
	v_exp_f32_e32 v13, v13
	v_add_f32_e32 v142, v203, v215
	v_mul_f32_e32 v142, 0xbfb8aa3b, v142
	v_exp_f32_e32 v142, v142
	v_add_f32_e32 v13, 1.0, v13
	v_rcp_f32_e32 v13, v13
	v_add_f32_e32 v142, 1.0, v142
	v_rcp_f32_e32 v143, v142
	v_mul_f32_e32 v13, 0xc1000000, v13
	v_mul_f32_e32 v13, v13, v184
	v_mul_f32_e32 v13, 0x3fb8aa3b, v13
	v_exp_f32_e32 v142, v13
	s_nop 0
	v_sub_f32_e32 v13, 1.0, v142
	v_add_f32_e32 v146, 1.0, v142
	v_mul_f32_e32 v13, v13, v146
	v_max_f32_e32 v13, 0, v13
	v_sqrt_f32_e32 v13, v13
	s_nop 0
	v_mul_f32_e32 v13, v143, v13
	v_mul_f32_e32 v143, v13, v139
	v_add_f32_e32 v13, v208, v212
	v_mul_f32_e32 v13, 0xbfb8aa3b, v13
	v_exp_f32_e32 v13, v13
	ds_write2_b64 v192, v[20:21], v[142:143] offset0:16 offset1:33
	v_add_f32_e32 v20, v204, v216
	v_mul_f32_e32 v20, 0xbfb8aa3b, v20
	v_add_f32_e32 v13, 1.0, v13
	v_rcp_f32_e32 v13, v13
	v_exp_f32_e32 v20, v20
	v_mul_f32_e32 v13, 0xc1000000, v13
	v_mul_f32_e32 v13, v13, v186
	v_add_f32_e32 v20, 1.0, v20
	v_mul_f32_e32 v13, 0x3fb8aa3b, v13
	v_rcp_f32_e32 v21, v20
	v_exp_f32_e32 v20, v13
	s_nop 0
	v_sub_f32_e32 v13, 1.0, v20
	v_add_f32_e32 v139, 1.0, v20
	v_mul_f32_e32 v13, v13, v139
	v_max_f32_e32 v13, 0, v13
	v_sqrt_f32_e32 v13, v13
	v_add_f32_e32 v139, v205, v217
	v_mul_f32_e32 v139, 0xbfb8aa3b, v139
	v_exp_f32_e32 v139, v139
	v_mul_f32_e32 v13, v21, v13
	v_mul_f32_e32 v21, v13, v140
	v_add_f32_e32 v13, v209, v213
	v_mul_f32_e32 v13, 0xbfb8aa3b, v13
	v_exp_f32_e32 v13, v13
	v_add_f32_e32 v139, 1.0, v139
	v_rcp_f32_e32 v139, v139
	v_mfma_f32_16x16x32_bf16 v[202:205], v[88:91], v[194:197], 0
	v_add_f32_e32 v13, 1.0, v13
	v_rcp_f32_e32 v13, v13
	v_mfma_f32_16x16x32_bf16 v[202:205], v[96:99], v[198:201], v[202:205]
	v_mul_f32_e32 v13, 0xc1000000, v13
	v_mul_f32_e32 v13, v13, v187
	v_mul_f32_e32 v13, 0x3fb8aa3b, v13
	v_exp_f32_e32 v142, v13
	v_mfma_f32_16x16x32_bf16 v[206:209], v[84:87], v[194:197], 0
	v_sub_f32_e32 v13, 1.0, v142
	v_add_f32_e32 v140, 1.0, v142
	v_mul_f32_e32 v13, v13, v140
	v_max_f32_e32 v13, 0, v13
	v_sqrt_f32_e32 v13, v13
	v_mfma_f32_16x16x32_bf16 v[206:209], v[92:95], v[198:201], v[206:209]
	v_mul_f32_e32 v13, v139, v13
	v_mul_f32_e32 v143, v13, v144
	ds_write2_b64 v192, v[20:21], v[142:143] offset0:50 offset1:67
	global_load_dwordx4 v[210:213], v[4:5], off offset:128
	global_load_dwordx4 v[214:217], v[0:1], off offset:128
	ds_read_b64 v[20:21], v2 offset:26176
	s_waitcnt lgkmcnt(0)
	v_lshlrev_b32_e32 v13, 16, v20
	v_and_b32_e32 v139, 0xffff0000, v20
	v_lshlrev_b32_e32 v140, 16, v21
	v_and_b32_e32 v144, 0xffff0000, v21
	s_waitcnt vmcnt(1)
	v_add_f32_e32 v20, v202, v210
	v_mul_f32_e32 v20, 0xbfb8aa3b, v20
	v_exp_f32_e32 v20, v20
	s_waitcnt vmcnt(0)
	v_add_f32_e32 v21, v206, v214
	v_mul_f32_e32 v21, 0xbfb8aa3b, v21
	v_exp_f32_e32 v21, v21
	v_add_f32_e32 v20, 1.0, v20
	v_rcp_f32_e32 v20, v20
	v_add_f32_e32 v21, 1.0, v21
	v_rcp_f32_e32 v21, v21
	v_mul_f32_e32 v20, 0xc1000000, v20
	v_mul_f32_e32 v20, v20, v132
	v_mul_f32_e32 v20, 0x3fb8aa3b, v20
	v_exp_f32_e32 v20, v20
	s_nop 0
	v_sub_f32_e32 v142, 1.0, v20
	v_add_f32_e32 v143, 1.0, v20
	v_mul_f32_e32 v142, v142, v143
	v_max_f32_e32 v142, 0, v142
	v_sqrt_f32_e32 v142, v142
	s_nop 0
	v_mul_f32_e32 v21, v21, v142
	v_mul_f32_e32 v21, v21, v13
	v_add_f32_e32 v13, v203, v211
	v_mul_f32_e32 v13, 0xbfb8aa3b, v13
	v_exp_f32_e32 v13, v13
	v_add_f32_e32 v142, v207, v215
	v_mul_f32_e32 v142, 0xbfb8aa3b, v142
	v_exp_f32_e32 v142, v142
	v_add_f32_e32 v13, 1.0, v13
	v_rcp_f32_e32 v13, v13
	v_add_f32_e32 v142, 1.0, v142
	v_rcp_f32_e32 v143, v142
	v_mul_f32_e32 v13, 0xc1000000, v13
	v_mul_f32_e32 v13, v13, v160
	v_mul_f32_e32 v13, 0x3fb8aa3b, v13
	v_exp_f32_e32 v142, v13
	s_nop 0
	v_sub_f32_e32 v13, 1.0, v142
	v_add_f32_e32 v146, 1.0, v142
	v_mul_f32_e32 v13, v13, v146
	v_max_f32_e32 v13, 0, v13
	v_sqrt_f32_e32 v13, v13
	s_nop 0
	v_mul_f32_e32 v13, v143, v13
	v_mul_f32_e32 v143, v13, v139
	v_add_f32_e32 v13, v204, v212
	v_mul_f32_e32 v13, 0xbfb8aa3b, v13
	v_exp_f32_e32 v13, v13
	ds_write2_b64 v191, v[20:21], v[142:143] offset0:32 offset1:49
	v_add_f32_e32 v20, v208, v216
	v_mul_f32_e32 v20, 0xbfb8aa3b, v20
	v_add_f32_e32 v13, 1.0, v13
	v_rcp_f32_e32 v13, v13
	v_exp_f32_e32 v20, v20
	v_mul_f32_e32 v13, 0xc1000000, v13
	v_mul_f32_e32 v13, v13, v180
	v_add_f32_e32 v20, 1.0, v20
	v_mul_f32_e32 v13, 0x3fb8aa3b, v13
	v_rcp_f32_e32 v21, v20
	v_exp_f32_e32 v20, v13
	s_nop 0
	v_sub_f32_e32 v13, 1.0, v20
	v_add_f32_e32 v139, 1.0, v20
	v_mul_f32_e32 v13, v13, v139
	v_max_f32_e32 v13, 0, v13
	v_sqrt_f32_e32 v13, v13
	v_add_f32_e32 v139, v209, v217
	v_mul_f32_e32 v139, 0xbfb8aa3b, v139
	v_exp_f32_e32 v139, v139
	v_mul_f32_e32 v13, v21, v13
	v_mul_f32_e32 v21, v13, v140
	v_add_f32_e32 v13, v205, v213
	v_mul_f32_e32 v13, 0xbfb8aa3b, v13
	v_exp_f32_e32 v13, v13
	v_add_f32_e32 v139, 1.0, v139
	v_rcp_f32_e32 v139, v139
	v_mfma_f32_16x16x32_bf16 v[202:205], v[72:75], v[194:197], 0
	v_add_f32_e32 v13, 1.0, v13
	v_rcp_f32_e32 v13, v13
	v_mfma_f32_16x16x32_bf16 v[194:197], v[68:71], v[194:197], 0
	v_mul_f32_e32 v13, 0xc1000000, v13
	v_mul_f32_e32 v13, v13, v183
	v_mul_f32_e32 v13, 0x3fb8aa3b, v13
	v_exp_f32_e32 v142, v13
	v_mfma_f32_16x16x32_bf16 v[202:205], v[80:83], v[198:201], v[202:205]
	v_sub_f32_e32 v13, 1.0, v142
	v_add_f32_e32 v140, 1.0, v142
	v_mul_f32_e32 v13, v13, v140
	v_max_f32_e32 v13, 0, v13
	v_sqrt_f32_e32 v13, v13
	v_mfma_f32_16x16x32_bf16 v[194:197], v[76:79], v[198:201], v[194:197]
	v_mul_f32_e32 v13, v139, v13
	v_mul_f32_e32 v143, v13, v144
	ds_write2_b64 v191, v[20:21], v[142:143] offset0:66 offset1:83
	global_load_dwordx4 v[206:209], v[4:5], off offset:192
	global_load_dwordx4 v[198:201], v[0:1], off offset:192
	ds_read_b64 v[20:21], v2 offset:26208
	s_waitcnt lgkmcnt(0)
	v_lshlrev_b32_e32 v13, 16, v20
	v_and_b32_e32 v139, 0xffff0000, v20
	v_lshlrev_b32_e32 v140, 16, v21
	v_and_b32_e32 v20, 0xffff0000, v21
	s_waitcnt vmcnt(1)
	v_add_f32_e32 v21, v202, v206
	v_mul_f32_e32 v21, 0xbfb8aa3b, v21
	v_exp_f32_e32 v21, v21
	s_waitcnt vmcnt(0)
	v_add_f32_e32 v142, v194, v198
	v_mul_f32_e32 v142, 0xbfb8aa3b, v142
	v_exp_f32_e32 v142, v142
	v_add_f32_e32 v21, 1.0, v21
	v_rcp_f32_e32 v21, v21
	v_add_f32_e32 v12, v204, v208
	v_add_f32_e32 v142, 1.0, v142
	v_rcp_f32_e32 v143, v142
	v_mul_f32_e32 v21, 0xc1000000, v21
	v_mul_f32_e32 v21, v62, v21
	v_mul_f32_e32 v21, 0x3fb8aa3b, v21
	v_exp_f32_e32 v142, v21
	v_mul_f32_e32 v12, 0xbfb8aa3b, v12
	v_exp_f32_e32 v12, v12
	v_add_u32_e32 v194, 0x8850, v138
	v_sub_f32_e32 v21, 1.0, v142
	v_add_f32_e32 v144, 1.0, v142
	v_mul_f32_e32 v21, v21, v144
	v_max_f32_e32 v21, 0, v21
	v_sqrt_f32_e32 v21, v21
	v_add_f32_e32 v12, 1.0, v12
	v_rcp_f32_e32 v12, v12
	v_mul_f32_e32 v21, v143, v21
	v_mul_f32_e32 v143, v21, v13
	v_add_f32_e32 v13, v203, v207
	v_mul_f32_e32 v13, 0xbfb8aa3b, v13
	v_exp_f32_e32 v13, v13
	v_add_f32_e32 v21, v195, v199
	v_mul_f32_e32 v21, 0xbfb8aa3b, v21
	v_exp_f32_e32 v21, v21
	v_add_f32_e32 v13, 1.0, v13
	v_rcp_f32_e32 v13, v13
	v_mul_f32_e32 v12, 0xc1000000, v12
	v_add_f32_e32 v21, 1.0, v21
	v_rcp_f32_e32 v21, v21
	v_mul_f32_e32 v13, 0xc1000000, v13
	v_mul_f32_e32 v13, v64, v13
	v_mul_f32_e32 v13, 0x3fb8aa3b, v13
	v_exp_f32_e32 v146, v13
	v_mul_f32_e32 v12, v65, v12
	v_mul_f32_e32 v12, 0x3fb8aa3b, v12
	v_exp_f32_e32 v12, v12
	v_sub_f32_e32 v13, 1.0, v146
	v_add_f32_e32 v144, 1.0, v146
	v_mul_f32_e32 v13, v13, v144
	v_max_f32_e32 v13, 0, v13
	v_sqrt_f32_e32 v13, v13
	v_add_u32_e32 v195, 0x8860, v138
	v_mul_f32_e32 v13, v21, v13
	v_mul_f32_e32 v147, v13, v139
	v_add_f32_e32 v13, v196, v200
	v_mul_f32_e32 v13, 0xbfb8aa3b, v13
	v_exp_f32_e32 v13, v13
	v_sub_f32_e32 v21, 1.0, v12
	v_add_f32_e32 v139, 1.0, v12
	v_mul_f32_e32 v21, v21, v139
	v_add_f32_e32 v13, 1.0, v13
	v_max_f32_e32 v21, 0, v21
	v_rcp_f32_e32 v13, v13
	v_sqrt_f32_e32 v21, v21
	ds_write2_b64 v190, v[142:143], v[146:147] offset0:48 offset1:65
	v_add_f32_e32 v139, v197, v201
	v_mul_f32_e32 v139, 0xbfb8aa3b, v139
	v_mul_f32_e32 v13, v13, v21
	v_add_f32_e32 v21, v205, v209
	v_mul_f32_e32 v21, 0xbfb8aa3b, v21
	v_exp_f32_e32 v21, v21
	v_exp_f32_e32 v139, v139
	v_mul_f32_e32 v13, v13, v140
	v_add_u32_e32 v196, 0x8870, v138
	v_add_f32_e32 v21, 1.0, v21
	v_rcp_f32_e32 v21, v21
	v_add_f32_e32 v139, 1.0, v139
	v_rcp_f32_e32 v139, v139
	v_mul_f32_e32 v21, 0xc1000000, v21
	v_mul_f32_e32 v21, v66, v21
	v_mul_f32_e32 v21, 0x3fb8aa3b, v21
	v_exp_f32_e32 v142, v21
	s_nop 0
	v_sub_f32_e32 v21, 1.0, v142
	v_add_f32_e32 v140, 1.0, v142
	v_mul_f32_e32 v21, v21, v140
	v_max_f32_e32 v21, 0, v21
	v_sqrt_f32_e32 v21, v21
	s_nop 0
	v_mul_f32_e32 v21, v139, v21
	v_mul_f32_e32 v143, v21, v20
	ds_write2_b64 v190, v[12:13], v[142:143] offset0:82 offset1:99
	v_mad_u64_u32 v[12:13], s[4:5], s0, v233, v[8:9]
	s_mov_b32 s4, 0x6e000
	v_add_u32_e32 v13, s6, v13
	v_add_co_u32_e32 v20, vcc, s4, v12
	s_waitcnt lgkmcnt(0)
	s_nop 0
	v_addc_co_u32_e32 v21, vcc, 0, v13, vcc
	s_barrier
	global_load_ushort v20, v[20:21], off offset:1024
	ds_read2_b64 v[198:201], v196 offset1:1
	s_lshl_b64 s[4:5], s[0:1], 11
	s_or_b32 s8, s4, 0x18000
	s_mov_b32 s9, s5
	s_waitcnt lgkmcnt(0)
	v_fma_f32 v144, v221, v200, v201
	v_add_f32_e32 v139, v193, v144
	ds_read2_b64 v[200:203], v195 offset1:1
	v_fmac_f32_e32 v199, v144, v198
	v_add_f32_e32 v136, v136, v199
	v_add_u32_e32 v193, 0x8840, v138
	s_waitcnt vmcnt(0)
	v_lshlrev_b32_e32 v20, 16, v20
	v_mul_f32_e32 v20, v139, v20
	v_cvt_pk_bf16_f32 v148, v20, s0
	v_lshl_add_u64 v[20:21], v[16:17], 0, s[4:5]
	v_add_co_u32_e32 v142, vcc, s7, v20
	s_mov_b32 s7, 0x6c000
	s_nop 0
	v_addc_co_u32_e32 v143, vcc, 0, v21, vcc
	v_add_co_u32_e32 v146, vcc, s7, v12
	s_mov_b32 s7, 0x6a000
	s_nop 0
	v_addc_co_u32_e32 v147, vcc, 0, v13, vcc
	global_load_ushort v150, v[146:147], off offset:2048
	v_add_co_u32_e32 v146, vcc, s7, v12
	s_mov_b32 s7, 0x69000
	s_nop 0
	v_addc_co_u32_e32 v147, vcc, 0, v13, vcc
	global_load_ushort v151, v[146:147], off offset:3072
	v_add_co_u32_e32 v146, vcc, s7, v12
	s_mov_b32 s7, 0x67000
	s_nop 0
	v_addc_co_u32_e32 v147, vcc, 0, v13, vcc
	global_load_ushort v152, v[146:147], off
	v_add_co_u32_e32 v146, vcc, s7, v12
	s_mov_b32 s7, 0x65000
	s_nop 0
	v_addc_co_u32_e32 v147, vcc, 0, v13, vcc
	global_load_ushort v154, v[146:147], off offset:1024
	v_add_co_u32_e32 v146, vcc, s7, v12
	s_mov_b32 s7, 0x63000
	s_nop 0
	v_addc_co_u32_e32 v147, vcc, 0, v13, vcc
	global_load_ushort v155, v[146:147], off offset:2048
	v_add_co_u32_e32 v146, vcc, s7, v12
	s_mov_b32 s7, 0x62000
	s_nop 0
	v_addc_co_u32_e32 v147, vcc, 0, v13, vcc
	global_load_ushort v156, v[146:147], off offset:3072
	v_add_co_u32_e32 v146, vcc, s7, v12
	s_mov_b32 s7, 0x60000
	s_nop 0
	v_addc_co_u32_e32 v147, vcc, 0, v13, vcc
	global_load_ushort v158, v[146:147], off
	v_add_co_u32_e32 v146, vcc, s7, v12
	s_mov_b32 s7, 0x5e000
	s_nop 0
	v_addc_co_u32_e32 v147, vcc, 0, v13, vcc
	global_load_ushort v159, v[146:147], off offset:1024
	v_add_co_u32_e32 v146, vcc, s7, v12
	s_mov_b32 s7, 0x5c000
	s_nop 0
	v_addc_co_u32_e32 v147, vcc, 0, v13, vcc
	global_load_ushort v162, v[146:147], off offset:2048
	v_add_co_u32_e32 v146, vcc, s7, v12
	s_mov_b32 s7, 0x5b000
	s_nop 0
	v_addc_co_u32_e32 v147, vcc, 0, v13, vcc
	global_load_ushort v163, v[146:147], off offset:3072
	v_add_co_u32_e32 v146, vcc, s7, v12
	s_mov_b32 s7, 0x59000
	s_nop 0
	v_addc_co_u32_e32 v147, vcc, 0, v13, vcc
	global_load_ushort v164, v[146:147], off
	v_add_co_u32_e32 v146, vcc, s7, v12
	s_mov_b32 s7, 0x57000
	s_nop 0
	v_addc_co_u32_e32 v147, vcc, 0, v13, vcc
	global_load_ushort v166, v[146:147], off offset:1024
	v_add_co_u32_e32 v146, vcc, s7, v12
	s_mov_b32 s7, 0x55000
	s_nop 0
	v_addc_co_u32_e32 v147, vcc, 0, v13, vcc
	global_load_ushort v167, v[146:147], off offset:2048
	v_add_co_u32_e32 v146, vcc, s7, v12
	s_mov_b32 s7, 0x54000
	s_nop 0
	v_addc_co_u32_e32 v147, vcc, 0, v13, vcc
	global_load_ushort v140, v[146:147], off offset:3072
	v_add_co_u32_e32 v146, vcc, s7, v12
	s_waitcnt vmcnt(13)
	v_lshlrev_b32_e32 v144, 16, v150
	v_addc_co_u32_e32 v147, vcc, 0, v13, vcc
	global_load_ushort v139, v[146:147], off
	v_mul_f32_e32 v136, v136, v144
	v_cvt_pk_bf16_f32 v136, v136, s0
	global_store_short v[142:143], v136, off
	s_waitcnt lgkmcnt(0)
	v_fma_f32 v136, v199, v202, v203
	ds_read2_b64 v[202:205], v194 offset1:1
	global_store_short v[142:143], v148, off offset:2048
	v_add_f32_e32 v142, v189, v136
	s_waitcnt vmcnt(15)
	v_lshlrev_b32_e32 v143, 16, v151
	v_fmac_f32_e32 v201, v136, v200
	v_mul_f32_e32 v142, v142, v143
	s_mov_b32 s7, 0x1e000
	v_add_f32_e32 v135, v135, v201
	s_waitcnt vmcnt(14)
	v_lshlrev_b32_e32 v136, 16, v152
	v_cvt_pk_bf16_f32 v144, v142, s0
	v_add_co_u32_e32 v142, vcc, s7, v20
	v_mul_f32_e32 v135, v135, v136
	s_nop 0
	v_addc_co_u32_e32 v143, vcc, 0, v21, vcc
	v_cvt_pk_bf16_f32 v135, v135, s0
	global_store_short v[142:143], v135, off
	s_waitcnt lgkmcnt(0)
	v_fma_f32 v135, v201, v204, v205
	ds_read2_b64 v[198:201], v193 offset1:1
	global_store_short v[142:143], v144, off offset:2048
	v_add_f32_e32 v136, v185, v135
	s_waitcnt vmcnt(15)
	v_lshlrev_b32_e32 v142, 16, v154
	s_mov_b32 s7, 0x1d000
	v_fmac_f32_e32 v203, v135, v202
	v_mul_f32_e32 v136, v136, v142
	v_add_co_u32_e32 v142, vcc, s7, v20
	v_add_f32_e32 v134, v134, v203
	s_waitcnt vmcnt(14)
	v_lshlrev_b32_e32 v135, 16, v155
	v_cvt_pk_bf16_f32 v136, v136, s0
	v_addc_co_u32_e32 v143, vcc, 0, v21, vcc
	v_mul_f32_e32 v134, v134, v135
	v_add_u32_e32 v189, 0x8830, v138
	global_store_short v[142:143], v136, off offset:2048
	v_cvt_pk_bf16_f32 v134, v134, s0
	s_waitcnt lgkmcnt(0)
	v_fma_f32 v136, v203, v200, v201
	ds_read2_b64 v[200:203], v189 offset1:1
	global_store_short v[142:143], v134, off
	v_add_f32_e32 v134, v181, v136
	s_waitcnt vmcnt(15)
	v_lshlrev_b32_e32 v135, 16, v156
	v_fmac_f32_e32 v199, v136, v198
	v_mul_f32_e32 v134, v134, v135
	s_mov_b32 s7, 0x1c000
	v_add_f32_e32 v61, v61, v199
	s_waitcnt vmcnt(14)
	v_lshlrev_b32_e32 v136, 16, v158
	v_cvt_pk_bf16_f32 v142, v134, s0
	v_add_co_u32_e32 v134, vcc, s7, v20
	v_mul_f32_e32 v61, v61, v136
	s_nop 0
	v_addc_co_u32_e32 v135, vcc, 0, v21, vcc
	v_cvt_pk_bf16_f32 v61, v61, s0
	global_store_short v[134:135], v61, off
	s_waitcnt lgkmcnt(0)
	v_fma_f32 v61, v199, v202, v203
	v_add_u32_e32 v185, 0x8820, v138
	global_store_short v[134:135], v142, off offset:2048
	v_add_f32_e32 v134, v177, v61
	ds_read2_b64 v[174:177], v185 offset1:1
	s_waitcnt vmcnt(15)
	v_lshlrev_b32_e32 v135, 16, v159
	v_fmac_f32_e32 v201, v61, v200
	v_mul_f32_e32 v134, v134, v135
	s_mov_b32 s7, 0x1b000
	v_add_f32_e32 v60, v60, v201
	s_waitcnt vmcnt(14)
	v_lshlrev_b32_e32 v61, 16, v162
	v_cvt_pk_bf16_f32 v136, v134, s0
	v_add_co_u32_e32 v134, vcc, s7, v20
	v_mul_f32_e32 v60, v60, v61
	s_nop 0
	v_addc_co_u32_e32 v135, vcc, 0, v21, vcc
	v_cvt_pk_bf16_f32 v60, v60, s0
	global_store_short v[134:135], v136, off offset:2048
	global_store_short v[134:135], v60, off
	s_waitcnt lgkmcnt(0)
	v_fma_f32 v134, v201, v176, v177
	v_add_u32_e32 v181, 0x8810, v138
	v_add_f32_e32 v60, v173, v134
	ds_read2_b64 v[170:173], v181 offset1:1
	s_waitcnt vmcnt(15)
	v_lshlrev_b32_e32 v61, 16, v163
	v_fmac_f32_e32 v175, v134, v174
	v_mul_f32_e32 v60, v60, v61
	s_mov_b32 s7, 0x1a000
	v_add_f32_e32 v58, v58, v175
	s_waitcnt vmcnt(14)
	v_lshlrev_b32_e32 v134, 16, v164
	v_cvt_pk_bf16_f32 v135, v60, s0
	v_add_co_u32_e32 v60, vcc, s7, v20
	v_mul_f32_e32 v58, v58, v134
	s_nop 0
	v_addc_co_u32_e32 v61, vcc, 0, v21, vcc
	v_cvt_pk_bf16_f32 v58, v58, s0
	global_store_short v[60:61], v58, off
	s_waitcnt lgkmcnt(0)
	v_fma_f32 v58, v175, v172, v173
	global_store_short v[60:61], v135, off offset:2048
	v_add_f32_e32 v60, v169, v58
	s_waitcnt vmcnt(15)
	v_lshlrev_b32_e32 v61, 16, v166
	v_fmac_f32_e32 v171, v58, v170
	s_waitcnt vmcnt(14)
	v_lshlrev_b32_e32 v58, 16, v167
	ds_read2_b64 v[166:169], v188 offset1:1
	v_mul_f32_e32 v60, v60, v61
	s_mov_b32 s7, 0x19000
	v_add_f32_e32 v25, v25, v171
	v_cvt_pk_bf16_f32 v134, v60, s0
	v_add_co_u32_e32 v60, vcc, s7, v20
	v_mul_f32_e32 v25, v25, v58
	s_nop 0
	v_addc_co_u32_e32 v61, vcc, 0, v21, vcc
	v_cvt_pk_bf16_f32 v25, v25, s0
	global_store_short v[60:61], v25, off
	s_waitcnt lgkmcnt(0)
	v_fma_f32 v25, v171, v168, v169
	global_store_short v[60:61], v134, off offset:2048
	v_add_f32_e32 v58, v165, v25
	s_waitcnt vmcnt(15)
	v_lshlrev_b32_e32 v60, 16, v140
	s_mov_b32 s7, 0x18000
	v_fmac_f32_e32 v167, v25, v166
	v_mul_f32_e32 v58, v58, v60
	v_add_co_u32_e32 v60, vcc, s7, v20
	v_add_f32_e32 v24, v24, v167
	s_waitcnt vmcnt(14)
	v_lshlrev_b32_e32 v25, 16, v139
	v_cvt_pk_bf16_f32 v58, v58, s0
	v_addc_co_u32_e32 v61, vcc, 0, v21, vcc
	v_mul_f32_e32 v24, v24, v25
	global_store_short v[60:61], v58, off offset:2048
	v_cvt_pk_bf16_f32 v58, v24, s0
	v_lshl_add_u64 v[24:25], v[16:17], 0, s[8:9]
	global_store_short v[24:25], v58, off
	s_barrier
	ds_read_b128 v[162:165], v57 offset:17408
	ds_read_b128 v[168:171], v57 offset:17472
	global_load_dwordx4 v[198:201], v[4:5], off
	global_load_dwordx4 v[202:205], v[0:1], off
	s_waitcnt lgkmcnt(1)
	v_mfma_f32_16x16x32_bf16 v[172:175], v[120:123], v[162:165], 0
	ds_read_b64 v[24:25], v2 offset:17408
	s_or_b32 s8, s0, 47
	s_mov_b32 s7, 0xfffe8000
	s_waitcnt lgkmcnt(1)
	v_mfma_f32_16x16x32_bf16 v[172:175], v[128:131], v[168:171], v[172:175]
	s_mov_b32 s9, s1
	s_waitcnt lgkmcnt(0)
	v_lshlrev_b32_e32 v58, 16, v24
	v_and_b32_e32 v61, 0xffff0000, v24
	v_mfma_f32_16x16x32_bf16 v[176:179], v[116:119], v[162:165], 0
	v_lshlrev_b32_e32 v134, 16, v25
	v_and_b32_e32 v135, 0xffff0000, v25
	s_waitcnt vmcnt(1)
	v_add_f32_e32 v24, v172, v198
	v_mul_f32_e32 v24, 0xbfb8aa3b, v24
	v_exp_f32_e32 v24, v24
	v_mfma_f32_16x16x32_bf16 v[176:179], v[124:127], v[168:171], v[176:179]
	v_add_f32_e32 v24, 1.0, v24
	v_rcp_f32_e32 v24, v24
	s_nop 0
	v_mul_f32_e32 v24, 0xc1000000, v24
	v_mul_f32_e32 v24, v48, v24
	v_mul_f32_e32 v24, 0x3fb8aa3b, v24
	s_waitcnt vmcnt(0)
	s_nop 0
	v_add_f32_e32 v25, v176, v202
	v_exp_f32_e32 v24, v24
	v_mul_f32_e32 v25, 0xbfb8aa3b, v25
	v_exp_f32_e32 v25, v25
	v_sub_f32_e32 v60, 1.0, v24
	v_add_f32_e32 v136, 1.0, v24
	v_mul_f32_e32 v60, v60, v136
	v_add_f32_e32 v25, 1.0, v25
	v_max_f32_e32 v60, 0, v60
	v_rcp_f32_e32 v25, v25
	v_sqrt_f32_e32 v60, v60
	s_nop 0
	v_mul_f32_e32 v25, v25, v60
	v_mul_f32_e32 v25, v25, v58
	v_add_f32_e32 v58, v173, v199
	v_mul_f32_e32 v58, 0xbfb8aa3b, v58
	v_exp_f32_e32 v58, v58
	v_add_f32_e32 v60, v177, v203
	v_mul_f32_e32 v60, 0xbfb8aa3b, v60
	v_exp_f32_e32 v60, v60
	v_add_f32_e32 v58, 1.0, v58
	v_rcp_f32_e32 v58, v58
	v_add_f32_e32 v60, 1.0, v60
	v_rcp_f32_e32 v136, v60
	v_mul_f32_e32 v58, 0xc1000000, v58
	v_mul_f32_e32 v58, v49, v58
	v_mul_f32_e32 v58, 0x3fb8aa3b, v58
	v_exp_f32_e32 v60, v58
	s_nop 0
	v_sub_f32_e32 v58, 1.0, v60
	v_add_f32_e32 v138, 1.0, v60
	v_mul_f32_e32 v58, v58, v138
	v_max_f32_e32 v58, 0, v58
	v_sqrt_f32_e32 v58, v58
	s_nop 0
	v_mul_f32_e32 v58, v136, v58
	v_mul_f32_e32 v61, v58, v61
	ds_write2_b64 v56, v[24:25], v[60:61] offset1:17
	v_add_f32_e32 v24, v174, v200
	v_mul_f32_e32 v24, 0xbfb8aa3b, v24
	v_exp_f32_e32 v24, v24
	v_add_f32_e32 v25, v178, v204
	v_mul_f32_e32 v25, 0xbfb8aa3b, v25
	v_exp_f32_e32 v25, v25
	v_add_f32_e32 v24, 1.0, v24
	v_rcp_f32_e32 v24, v24
	v_add_f32_e32 v25, 1.0, v25
	v_rcp_f32_e32 v25, v25
	v_mul_f32_e32 v24, 0xc1000000, v24
	v_mul_f32_e32 v24, v50, v24
	v_mul_f32_e32 v24, 0x3fb8aa3b, v24
	v_exp_f32_e32 v24, v24
	s_nop 0
	v_sub_f32_e32 v58, 1.0, v24
	v_add_f32_e32 v60, 1.0, v24
	v_mul_f32_e32 v58, v58, v60
	v_max_f32_e32 v58, 0, v58
	v_sqrt_f32_e32 v58, v58
	v_add_f32_e32 v60, v179, v205
	v_mul_f32_e32 v60, 0xbfb8aa3b, v60
	v_exp_f32_e32 v60, v60
	v_mul_f32_e32 v25, v25, v58
	v_add_f32_e32 v58, v175, v201
	v_mul_f32_e32 v58, 0xbfb8aa3b, v58
	v_exp_f32_e32 v58, v58
	v_add_f32_e32 v60, 1.0, v60
	v_rcp_f32_e32 v61, v60
	v_mul_f32_e32 v25, v25, v134
	v_add_f32_e32 v58, 1.0, v58
	v_rcp_f32_e32 v58, v58
	v_mfma_f32_16x16x32_bf16 v[172:175], v[104:107], v[162:165], 0
	v_mul_f32_e32 v58, 0xc1000000, v58
	v_mul_f32_e32 v58, v52, v58
	v_mul_f32_e32 v58, 0x3fb8aa3b, v58
	v_exp_f32_e32 v60, v58
	v_mfma_f32_16x16x32_bf16 v[172:175], v[112:115], v[168:171], v[172:175]
	v_sub_f32_e32 v58, 1.0, v60
	v_add_f32_e32 v134, 1.0, v60
	v_mul_f32_e32 v58, v58, v134
	v_max_f32_e32 v58, 0, v58
	v_sqrt_f32_e32 v58, v58
	v_mfma_f32_16x16x32_bf16 v[176:179], v[100:103], v[162:165], 0
	v_mul_f32_e32 v58, v61, v58
	v_mul_f32_e32 v61, v58, v135
	ds_write2_b64 v56, v[24:25], v[60:61] offset0:34 offset1:51
	global_load_dwordx4 v[198:201], v[4:5], off offset:64
	global_load_dwordx4 v[202:205], v[0:1], off offset:64
	ds_read_b64 v[24:25], v2 offset:17440
	v_mfma_f32_16x16x32_bf16 v[176:179], v[108:111], v[168:171], v[176:179]
	s_waitcnt lgkmcnt(0)
	v_lshlrev_b32_e32 v58, 16, v24
	v_and_b32_e32 v61, 0xffff0000, v24
	v_lshlrev_b32_e32 v134, 16, v25
	v_and_b32_e32 v135, 0xffff0000, v25
	s_waitcnt vmcnt(1)
	v_add_f32_e32 v24, v172, v198
	v_mul_f32_e32 v24, 0xbfb8aa3b, v24
	v_exp_f32_e32 v24, v24
	s_waitcnt vmcnt(0)
	v_add_f32_e32 v25, v176, v202
	v_mul_f32_e32 v25, 0xbfb8aa3b, v25
	v_exp_f32_e32 v25, v25
	v_add_f32_e32 v24, 1.0, v24
	v_rcp_f32_e32 v24, v24
	v_add_f32_e32 v25, 1.0, v25
	v_rcp_f32_e32 v25, v25
	v_mul_f32_e32 v24, 0xc1000000, v24
	v_mul_f32_e32 v24, v182, v24
	v_mul_f32_e32 v24, 0x3fb8aa3b, v24
	v_exp_f32_e32 v24, v24
	s_nop 0
	v_sub_f32_e32 v60, 1.0, v24
	v_add_f32_e32 v136, 1.0, v24
	v_mul_f32_e32 v60, v60, v136
	v_max_f32_e32 v60, 0, v60
	v_sqrt_f32_e32 v60, v60
	s_nop 0
	v_mul_f32_e32 v25, v25, v60
	v_mul_f32_e32 v25, v25, v58
	v_add_f32_e32 v58, v173, v199
	v_mul_f32_e32 v58, 0xbfb8aa3b, v58
	v_exp_f32_e32 v58, v58
	v_add_f32_e32 v60, v177, v203
	v_mul_f32_e32 v60, 0xbfb8aa3b, v60
	v_exp_f32_e32 v60, v60
	v_add_f32_e32 v58, 1.0, v58
	v_rcp_f32_e32 v58, v58
	v_add_f32_e32 v60, 1.0, v60
	v_rcp_f32_e32 v136, v60
	v_mul_f32_e32 v58, 0xc1000000, v58
	v_mul_f32_e32 v58, v184, v58
	v_mul_f32_e32 v58, 0x3fb8aa3b, v58
	v_exp_f32_e32 v60, v58
	s_nop 0
	v_sub_f32_e32 v58, 1.0, v60
	v_add_f32_e32 v138, 1.0, v60
	v_mul_f32_e32 v58, v58, v138
	v_max_f32_e32 v58, 0, v58
	v_sqrt_f32_e32 v58, v58
	s_nop 0
	v_mul_f32_e32 v58, v136, v58
	v_mul_f32_e32 v61, v58, v61
	ds_write2_b64 v192, v[24:25], v[60:61] offset0:16 offset1:33
	v_add_f32_e32 v24, v174, v200
	v_mul_f32_e32 v24, 0xbfb8aa3b, v24
	v_exp_f32_e32 v24, v24
	v_add_f32_e32 v25, v178, v204
	v_mul_f32_e32 v25, 0xbfb8aa3b, v25
	v_exp_f32_e32 v25, v25
	v_add_f32_e32 v24, 1.0, v24
	v_rcp_f32_e32 v24, v24
	v_add_f32_e32 v25, 1.0, v25
	v_rcp_f32_e32 v25, v25
	v_mul_f32_e32 v24, 0xc1000000, v24
	v_mul_f32_e32 v24, v186, v24
	v_mul_f32_e32 v24, 0x3fb8aa3b, v24
	v_exp_f32_e32 v24, v24
	s_nop 0
	v_sub_f32_e32 v58, 1.0, v24
	v_add_f32_e32 v60, 1.0, v24
	v_mul_f32_e32 v58, v58, v60
	v_max_f32_e32 v58, 0, v58
	v_sqrt_f32_e32 v58, v58
	v_add_f32_e32 v60, v179, v205
	v_mul_f32_e32 v60, 0xbfb8aa3b, v60
	v_exp_f32_e32 v60, v60
	v_mul_f32_e32 v25, v25, v58
	v_add_f32_e32 v58, v175, v201
	v_mul_f32_e32 v58, 0xbfb8aa3b, v58
	v_exp_f32_e32 v58, v58
	v_add_f32_e32 v60, 1.0, v60
	v_rcp_f32_e32 v61, v60
	v_mul_f32_e32 v25, v25, v134
	v_add_f32_e32 v58, 1.0, v58
	v_rcp_f32_e32 v58, v58
	v_mfma_f32_16x16x32_bf16 v[172:175], v[88:91], v[162:165], 0
	v_mul_f32_e32 v58, 0xc1000000, v58
	v_mul_f32_e32 v58, v187, v58
	v_mul_f32_e32 v58, 0x3fb8aa3b, v58
	v_exp_f32_e32 v60, v58
	v_mfma_f32_16x16x32_bf16 v[172:175], v[96:99], v[168:171], v[172:175]
	v_sub_f32_e32 v58, 1.0, v60
	v_add_f32_e32 v134, 1.0, v60
	v_mul_f32_e32 v58, v58, v134
	v_max_f32_e32 v58, 0, v58
	v_sqrt_f32_e32 v58, v58
	v_mfma_f32_16x16x32_bf16 v[176:179], v[84:87], v[162:165], 0
	v_mul_f32_e32 v58, v61, v58
	v_mul_f32_e32 v61, v58, v135
	ds_write2_b64 v192, v[24:25], v[60:61] offset0:50 offset1:67
	global_load_dwordx4 v[198:201], v[4:5], off offset:128
	global_load_dwordx4 v[202:205], v[0:1], off offset:128
	ds_read_b64 v[24:25], v2 offset:17472
	v_mfma_f32_16x16x32_bf16 v[176:179], v[92:95], v[168:171], v[176:179]
	s_waitcnt lgkmcnt(0)
	v_lshlrev_b32_e32 v58, 16, v24
	v_and_b32_e32 v61, 0xffff0000, v24
	v_lshlrev_b32_e32 v134, 16, v25
	v_and_b32_e32 v135, 0xffff0000, v25
	s_waitcnt vmcnt(1)
	v_add_f32_e32 v24, v172, v198
	v_mul_f32_e32 v24, 0xbfb8aa3b, v24
	v_exp_f32_e32 v24, v24
	s_waitcnt vmcnt(0)
	v_add_f32_e32 v25, v176, v202
	v_mul_f32_e32 v25, 0xbfb8aa3b, v25
	v_exp_f32_e32 v25, v25
	v_add_f32_e32 v24, 1.0, v24
	v_rcp_f32_e32 v24, v24
	v_add_f32_e32 v25, 1.0, v25
	v_rcp_f32_e32 v25, v25
	v_mul_f32_e32 v24, 0xc1000000, v24
	v_mul_f32_e32 v24, v132, v24
	v_mul_f32_e32 v24, 0x3fb8aa3b, v24
	v_exp_f32_e32 v24, v24
	s_nop 0
	v_sub_f32_e32 v60, 1.0, v24
	v_add_f32_e32 v136, 1.0, v24
	v_mul_f32_e32 v60, v60, v136
	v_max_f32_e32 v60, 0, v60
	v_sqrt_f32_e32 v60, v60
	s_nop 0
	v_mul_f32_e32 v25, v25, v60
	v_mul_f32_e32 v25, v25, v58
	v_add_f32_e32 v58, v173, v199
	v_mul_f32_e32 v58, 0xbfb8aa3b, v58
	v_exp_f32_e32 v58, v58
	v_add_f32_e32 v60, v177, v203
	v_mul_f32_e32 v60, 0xbfb8aa3b, v60
	v_exp_f32_e32 v60, v60
	v_add_f32_e32 v58, 1.0, v58
	v_rcp_f32_e32 v58, v58
	v_add_f32_e32 v60, 1.0, v60
	v_rcp_f32_e32 v136, v60
	v_mul_f32_e32 v58, 0xc1000000, v58
	v_mul_f32_e32 v58, v160, v58
	v_mul_f32_e32 v58, 0x3fb8aa3b, v58
	v_exp_f32_e32 v60, v58
	s_nop 0
	v_sub_f32_e32 v58, 1.0, v60
	v_add_f32_e32 v138, 1.0, v60
	v_mul_f32_e32 v58, v58, v138
	v_max_f32_e32 v58, 0, v58
	v_sqrt_f32_e32 v58, v58
	s_nop 0
	v_mul_f32_e32 v58, v136, v58
	v_mul_f32_e32 v61, v58, v61
	ds_write2_b64 v191, v[24:25], v[60:61] offset0:32 offset1:49
	v_add_f32_e32 v24, v174, v200
	v_mul_f32_e32 v24, 0xbfb8aa3b, v24
	v_exp_f32_e32 v24, v24
	v_add_f32_e32 v25, v178, v204
	v_mul_f32_e32 v25, 0xbfb8aa3b, v25
	v_exp_f32_e32 v25, v25
	v_add_f32_e32 v24, 1.0, v24
	v_rcp_f32_e32 v24, v24
	v_add_f32_e32 v25, 1.0, v25
	v_rcp_f32_e32 v25, v25
	v_mul_f32_e32 v24, 0xc1000000, v24
	v_mul_f32_e32 v24, v180, v24
	v_mul_f32_e32 v24, 0x3fb8aa3b, v24
	v_exp_f32_e32 v24, v24
	s_nop 0
	v_sub_f32_e32 v58, 1.0, v24
	v_add_f32_e32 v60, 1.0, v24
	v_mul_f32_e32 v58, v58, v60
	v_max_f32_e32 v58, 0, v58
	v_sqrt_f32_e32 v58, v58
	v_add_f32_e32 v60, v179, v205
	v_mul_f32_e32 v60, 0xbfb8aa3b, v60
	v_exp_f32_e32 v60, v60
	v_mul_f32_e32 v25, v25, v58
	v_add_f32_e32 v58, v175, v201
	v_mul_f32_e32 v58, 0xbfb8aa3b, v58
	v_exp_f32_e32 v58, v58
	v_add_f32_e32 v60, 1.0, v60
	v_rcp_f32_e32 v61, v60
	v_mul_f32_e32 v25, v25, v134
	v_add_f32_e32 v58, 1.0, v58
	v_rcp_f32_e32 v58, v58
	v_mfma_f32_16x16x32_bf16 v[172:175], v[72:75], v[162:165], 0
	v_mul_f32_e32 v58, 0xc1000000, v58
	v_mul_f32_e32 v58, v183, v58
	v_mul_f32_e32 v58, 0x3fb8aa3b, v58
	v_exp_f32_e32 v60, v58
	v_mfma_f32_16x16x32_bf16 v[162:165], v[68:71], v[162:165], 0
	v_sub_f32_e32 v58, 1.0, v60
	v_add_f32_e32 v134, 1.0, v60
	v_mul_f32_e32 v58, v58, v134
	v_max_f32_e32 v58, 0, v58
	v_sqrt_f32_e32 v58, v58
	v_mfma_f32_16x16x32_bf16 v[172:175], v[80:83], v[168:171], v[172:175]
	v_mul_f32_e32 v58, v61, v58
	v_mul_f32_e32 v61, v58, v135
	ds_write2_b64 v191, v[24:25], v[60:61] offset0:66 offset1:83
	v_mfma_f32_16x16x32_bf16 v[162:165], v[76:79], v[168:171], v[162:165]
	global_load_dwordx4 v[176:179], v[4:5], off offset:192
	global_load_dwordx4 v[168:171], v[0:1], off offset:192
	ds_read_b64 v[24:25], v2 offset:17504
	s_waitcnt lgkmcnt(0)
	v_lshlrev_b32_e32 v60, 16, v24
	v_and_b32_e32 v61, 0xffff0000, v24
	v_lshlrev_b32_e32 v134, 16, v25
	v_and_b32_e32 v58, 0xffff0000, v25
	s_waitcnt vmcnt(1)
	v_add_f32_e32 v24, v172, v176
	v_mul_f32_e32 v24, 0xbfb8aa3b, v24
	v_exp_f32_e32 v24, v24
	s_waitcnt vmcnt(0)
	v_add_f32_e32 v25, v162, v168
	v_mul_f32_e32 v25, 0xbfb8aa3b, v25
	v_exp_f32_e32 v25, v25
	v_add_f32_e32 v24, 1.0, v24
	v_rcp_f32_e32 v24, v24
	v_add_f32_e32 v25, 1.0, v25
	v_rcp_f32_e32 v25, v25
	v_mul_f32_e32 v24, 0xc1000000, v24
	v_mul_f32_e32 v24, v62, v24
	v_mul_f32_e32 v24, 0x3fb8aa3b, v24
	v_exp_f32_e32 v24, v24
	s_nop 0
	v_sub_f32_e32 v135, 1.0, v24
	v_add_f32_e32 v136, 1.0, v24
	v_mul_f32_e32 v135, v135, v136
	v_max_f32_e32 v135, 0, v135
	v_sqrt_f32_e32 v135, v135
	s_nop 0
	v_mul_f32_e32 v25, v25, v135
	v_mul_f32_e32 v25, v25, v60
	v_add_f32_e32 v60, v173, v177
	v_mul_f32_e32 v60, 0xbfb8aa3b, v60
	v_exp_f32_e32 v60, v60
	v_add_f32_e32 v135, v163, v169
	v_mul_f32_e32 v135, 0xbfb8aa3b, v135
	v_exp_f32_e32 v135, v135
	v_add_f32_e32 v60, 1.0, v60
	v_rcp_f32_e32 v60, v60
	v_add_f32_e32 v135, 1.0, v135
	v_rcp_f32_e32 v135, v135
	v_mul_f32_e32 v60, 0xc1000000, v60
	v_mul_f32_e32 v60, v64, v60
	v_mul_f32_e32 v60, 0x3fb8aa3b, v60
	v_exp_f32_e32 v60, v60
	s_nop 0
	v_sub_f32_e32 v136, 1.0, v60
	v_add_f32_e32 v138, 1.0, v60
	v_mul_f32_e32 v136, v136, v138
	v_max_f32_e32 v136, 0, v136
	v_sqrt_f32_e32 v136, v136
	s_nop 0
	v_mul_f32_e32 v135, v135, v136
	v_mul_f32_e32 v61, v135, v61
	ds_write2_b64 v190, v[24:25], v[60:61] offset0:48 offset1:65
	v_add_f32_e32 v24, v174, v178
	v_mul_f32_e32 v24, 0xbfb8aa3b, v24
	v_exp_f32_e32 v24, v24
	v_add_f32_e32 v25, v164, v170
	v_mul_f32_e32 v25, 0xbfb8aa3b, v25
	v_exp_f32_e32 v25, v25
	v_add_f32_e32 v24, 1.0, v24
	v_rcp_f32_e32 v24, v24
	v_add_f32_e32 v25, 1.0, v25
	v_rcp_f32_e32 v25, v25
	v_mul_f32_e32 v24, 0xc1000000, v24
	v_mul_f32_e32 v24, v65, v24
	v_mul_f32_e32 v24, 0x3fb8aa3b, v24
	v_exp_f32_e32 v24, v24
	s_nop 0
	v_sub_f32_e32 v60, 1.0, v24
	v_add_f32_e32 v61, 1.0, v24
	v_mul_f32_e32 v60, v60, v61
	v_max_f32_e32 v60, 0, v60
	v_sqrt_f32_e32 v60, v60
	v_add_f32_e32 v61, v165, v171
	v_mul_f32_e32 v61, 0xbfb8aa3b, v61
	v_exp_f32_e32 v61, v61
	v_mul_f32_e32 v25, v25, v60
	v_add_f32_e32 v60, v175, v179
	v_mul_f32_e32 v60, 0xbfb8aa3b, v60
	v_exp_f32_e32 v60, v60
	v_mul_f32_e32 v25, v25, v134
	v_add_f32_e32 v61, 1.0, v61
	v_rcp_f32_e32 v61, v61
	v_add_f32_e32 v60, 1.0, v60
	v_rcp_f32_e32 v60, v60
	s_nop 0
	v_mul_f32_e32 v60, 0xc1000000, v60
	v_mul_f32_e32 v60, v66, v60
	v_mul_f32_e32 v60, 0x3fb8aa3b, v60
	v_exp_f32_e32 v60, v60
	s_nop 0
	v_sub_f32_e32 v134, 1.0, v60
	v_add_f32_e32 v135, 1.0, v60
	v_mul_f32_e32 v134, v134, v135
	v_max_f32_e32 v134, 0, v134
	v_sqrt_f32_e32 v134, v134
	s_nop 0
	v_mul_f32_e32 v61, v61, v134
	v_mul_f32_e32 v61, v61, v58
	ds_write2_b64 v190, v[24:25], v[60:61] offset0:82 offset1:99
	v_mad_u64_u32 v[60:61], s[10:11], s8, v233, v[8:9]
	v_add_u32_e32 v61, s6, v61
	s_waitcnt lgkmcnt(0)
	s_barrier
	global_load_ushort v25, v[60:61], off
	ds_read2_b64 v[162:165], v196 offset1:1
	s_movk_i32 s11, 0xf000
	s_movk_i32 s10, 0x8000
	s_lshl_b64 s[8:9], s[8:9], 11
	v_lshl_add_u64 v[134:135], v[16:17], 0, s[8:9]
	s_waitcnt lgkmcnt(0)
	v_fma_f32 v58, v167, v164, v165
	v_add_f32_e32 v24, v161, v58
	ds_read2_b64 v[164:167], v195 offset1:1
	v_fmac_f32_e32 v163, v58, v162
	v_add_f32_e32 v54, v54, v163
	s_or_b32 s8, s4, 0x17000
	s_mov_b32 s9, s5
	s_waitcnt vmcnt(0)
	v_lshlrev_b32_e32 v25, 16, v25
	v_mul_f32_e32 v24, v24, v25
	v_cvt_pk_bf16_f32 v136, v24, s0
	v_add_co_u32_e32 v24, vcc, s11, v60
	s_nop 1
	v_addc_co_u32_e32 v25, vcc, -1, v61, vcc
	global_load_ushort v138, v[24:25], off offset:-3072
	v_add_co_u32_e32 v24, vcc, s22, v60
	s_nop 1
	v_addc_co_u32_e32 v25, vcc, -1, v61, vcc
	global_load_ushort v139, v[24:25], off offset:-2048
	v_add_co_u32_e32 v24, vcc, s13, v60
	s_nop 1
	v_addc_co_u32_e32 v25, vcc, -1, v61, vcc
	global_load_ushort v140, v[24:25], off offset:-1024
	v_add_co_u32_e32 v24, vcc, s12, v60
	s_nop 1
	v_addc_co_u32_e32 v25, vcc, -1, v61, vcc
	global_load_ushort v142, v[24:25], off
	v_add_co_u32_e32 v24, vcc, s10, v60
	s_nop 1
	v_addc_co_u32_e32 v25, vcc, -1, v61, vcc
	global_load_ushort v143, v[24:25], off offset:-3072
	v_add_co_u32_e32 v24, vcc, s33, v60
	s_nop 1
	v_addc_co_u32_e32 v25, vcc, -1, v61, vcc
	global_load_ushort v144, v[24:25], off offset:-2048
	v_add_co_u32_e32 v24, vcc, s38, v60
	s_nop 1
	v_addc_co_u32_e32 v25, vcc, -1, v61, vcc
	global_load_ushort v146, v[24:25], off offset:-1024
	v_add_co_u32_e32 v24, vcc, s39, v60
	s_nop 1
	v_addc_co_u32_e32 v25, vcc, -1, v61, vcc
	global_load_ushort v158, v[24:25], off
	v_add_co_u32_e32 v24, vcc, s42, v60
	s_nop 1
	v_addc_co_u32_e32 v25, vcc, -1, v61, vcc
	global_load_ushort v159, v[24:25], off offset:-3072
	v_add_co_u32_e32 v24, vcc, s43, v60
	s_nop 1
	v_addc_co_u32_e32 v25, vcc, -1, v61, vcc
	global_load_ushort v161, v[24:25], off offset:-2048
	v_add_co_u32_e32 v24, vcc, s56, v60
	s_nop 1
	v_addc_co_u32_e32 v25, vcc, -1, v61, vcc
	global_load_ushort v168, v[24:25], off offset:-1024
	v_add_co_u32_e32 v24, vcc, s57, v60
	s_nop 1
	v_addc_co_u32_e32 v25, vcc, -1, v61, vcc
	global_load_ushort v169, v[24:25], off
	v_add_co_u32_e32 v24, vcc, s58, v60
	s_nop 1
	v_addc_co_u32_e32 v25, vcc, -1, v61, vcc
	global_load_ushort v170, v[24:25], off offset:-3072
	v_add_co_u32_e32 v24, vcc, s7, v60
	s_waitcnt vmcnt(12)
	v_lshlrev_b32_e32 v58, 16, v138
	v_addc_co_u32_e32 v25, vcc, -1, v61, vcc
	global_load_ushort v25, v[24:25], off offset:-2048
	v_add_co_u32_e32 v60, vcc, s59, v60
	v_mul_f32_e32 v54, v54, v58
	s_nop 0
	v_addc_co_u32_e32 v61, vcc, -1, v61, vcc
	global_load_ushort v24, v[60:61], off offset:-1024
	v_cvt_pk_bf16_f32 v54, v54, s0
	v_lshl_add_u64 v[60:61], v[16:17], 0, s[8:9]
	global_store_short v[60:61], v54, off
	s_waitcnt lgkmcnt(0)
	v_fma_f32 v54, v163, v166, v167
	v_add_f32_e32 v58, v157, v54
	ds_read2_b64 v[154:157], v194 offset1:1
	s_waitcnt vmcnt(14)
	v_lshlrev_b32_e32 v60, 16, v139
	v_fmac_f32_e32 v165, v54, v164
	v_mul_f32_e32 v58, v58, v60
	s_or_b32 s8, s4, 0x16800
	v_add_f32_e32 v53, v53, v165
	s_waitcnt vmcnt(13)
	v_lshlrev_b32_e32 v54, 16, v140
	v_cvt_pk_bf16_f32 v58, v58, s0
	v_lshl_add_u64 v[60:61], v[16:17], 0, s[8:9]
	v_mul_f32_e32 v53, v53, v54
	s_or_b32 s8, s4, 0x16000
	global_store_short v[60:61], v58, off
	v_cvt_pk_bf16_f32 v53, v53, s0
	v_lshl_add_u64 v[60:61], v[16:17], 0, s[8:9]
	global_store_short v[60:61], v53, off
	s_waitcnt lgkmcnt(0)
	v_fma_f32 v53, v165, v156, v157
	v_add_f32_e32 v54, v153, v53
	ds_read2_b64 v[150:153], v193 offset1:1
	s_waitcnt vmcnt(14)
	v_lshlrev_b32_e32 v58, 16, v142
	v_fmac_f32_e32 v155, v53, v154
	v_mul_f32_e32 v54, v54, v58
	s_or_b32 s8, s4, 0x15800
	v_add_f32_e32 v46, v46, v155
	s_waitcnt vmcnt(13)
	v_lshlrev_b32_e32 v53, 16, v143
	v_cvt_pk_bf16_f32 v54, v54, s0
	v_lshl_add_u64 v[60:61], v[16:17], 0, s[8:9]
	v_mul_f32_e32 v46, v46, v53
	s_or_b32 s8, s4, 0x15000
	global_store_short v[60:61], v54, off
	v_cvt_pk_bf16_f32 v46, v46, s0
	v_lshl_add_u64 v[60:61], v[16:17], 0, s[8:9]
	global_store_short v[60:61], v46, off
	s_waitcnt lgkmcnt(0)
	v_fma_f32 v46, v155, v152, v153
	v_add_f32_e32 v53, v149, v46
	v_fmac_f32_e32 v151, v46, v150
	s_waitcnt vmcnt(13)
	v_lshlrev_b32_e32 v46, 16, v146
	ds_read2_b64 v[146:149], v189 offset1:1
	v_lshlrev_b32_e32 v54, 16, v144
	v_mul_f32_e32 v53, v53, v54
	s_or_b32 s8, s4, 0x14800
	v_add_f32_e32 v45, v45, v151
	v_cvt_pk_bf16_f32 v53, v53, s0
	v_lshl_add_u64 v[60:61], v[16:17], 0, s[8:9]
	v_mul_f32_e32 v45, v45, v46
	s_or_b32 s8, s4, 0x14000
	global_store_short v[60:61], v53, off
	v_cvt_pk_bf16_f32 v45, v45, s0
	v_lshl_add_u64 v[60:61], v[16:17], 0, s[8:9]
	global_store_short v[60:61], v45, off
	s_waitcnt lgkmcnt(0)
	v_fma_f32 v45, v151, v148, v149
	v_add_f32_e32 v46, v145, v45
	ds_read2_b64 v[142:145], v185 offset1:1
	s_waitcnt vmcnt(14)
	v_lshlrev_b32_e32 v53, 16, v158
	v_fmac_f32_e32 v147, v45, v146
	v_mul_f32_e32 v46, v46, v53
	s_or_b32 s8, s4, 0x13800
	v_add_f32_e32 v44, v44, v147
	s_waitcnt vmcnt(13)
	v_lshlrev_b32_e32 v45, 16, v159
	v_cvt_pk_bf16_f32 v46, v46, s0
	v_lshl_add_u64 v[60:61], v[16:17], 0, s[8:9]
	v_mul_f32_e32 v44, v44, v45
	s_or_b32 s8, s4, 0x13000
	global_store_short v[60:61], v46, off
	v_cvt_pk_bf16_f32 v46, v44, s0
	v_lshl_add_u64 v[44:45], v[16:17], 0, s[8:9]
	global_store_short v[44:45], v46, off
	s_waitcnt lgkmcnt(0)
	v_fma_f32 v46, v147, v144, v145
	v_add_f32_e32 v44, v141, v46
	s_waitcnt vmcnt(14)
	v_lshlrev_b32_e32 v45, 16, v161
	v_mul_f32_e32 v44, v44, v45
	s_or_b32 s8, s4, 0x12800
	ds_read2_b64 v[138:141], v181 offset1:1
	v_cvt_pk_bf16_f32 v53, v44, s0
	v_lshl_add_u64 v[44:45], v[16:17], 0, s[8:9]
	v_fmac_f32_e32 v143, v46, v142
	global_store_short v[44:45], v53, off
	v_add_f32_e32 v42, v42, v143
	s_waitcnt vmcnt(14)
	v_lshlrev_b32_e32 v44, 16, v168
	v_mul_f32_e32 v42, v42, v44
	s_or_b32 s8, s4, 0x12000
	v_cvt_pk_bf16_f32 v42, v42, s0
	v_lshl_add_u64 v[44:45], v[16:17], 0, s[8:9]
	global_store_short v[44:45], v42, off
	s_waitcnt lgkmcnt(0)
	v_fma_f32 v42, v143, v140, v141
	global_store_short v[134:135], v136, off
	v_add_f32_e32 v44, v137, v42
	ds_read2_b64 v[134:137], v188 offset1:1
	s_waitcnt vmcnt(15)
	v_lshlrev_b32_e32 v45, 16, v169
	v_fmac_f32_e32 v139, v42, v138
	v_mul_f32_e32 v44, v44, v45
	s_or_b32 s8, s4, 0x11800
	v_add_f32_e32 v41, v41, v139
	s_waitcnt vmcnt(14)
	v_lshlrev_b32_e32 v42, 16, v170
	v_cvt_pk_bf16_f32 v46, v44, s0
	v_lshl_add_u64 v[44:45], v[16:17], 0, s[8:9]
	v_mul_f32_e32 v41, v41, v42
	s_or_b32 s8, s4, 0x11000
	global_store_short v[44:45], v46, off
	v_cvt_pk_bf16_f32 v41, v41, s0
	v_lshl_add_u64 v[44:45], v[16:17], 0, s[8:9]
	global_store_short v[44:45], v41, off
	s_waitcnt lgkmcnt(0)
	v_fma_f32 v41, v139, v136, v137
	v_add_f32_e32 v42, v133, v41
	s_waitcnt vmcnt(15)
	v_lshlrev_b32_e32 v25, 16, v25
	v_mul_f32_e32 v25, v42, v25
	s_or_b32 s8, s4, 0x10800
	v_cvt_pk_bf16_f32 v25, v25, s0
	v_lshl_add_u64 v[44:45], v[16:17], 0, s[8:9]
	v_fmac_f32_e32 v135, v41, v134
	global_store_short v[44:45], v25, off
	v_add_f32_e32 v25, v40, v135
	s_waitcnt vmcnt(15)
	v_lshlrev_b32_e32 v24, 16, v24
	v_mul_f32_e32 v24, v25, v24
	s_or_b32 s8, s4, 0x10000
	v_cvt_pk_bf16_f32 v40, v24, s0
	v_lshl_add_u64 v[24:25], v[16:17], 0, s[8:9]
	global_store_short v[24:25], v40, off
	s_barrier
	ds_read_b128 v[136:139], v57 offset:8704
	ds_read_b128 v[144:147], v57 offset:8768
	global_load_dwordx4 v[152:155], v[4:5], off
	global_load_dwordx4 v[156:159], v[0:1], off
	s_waitcnt lgkmcnt(1)
	v_mfma_f32_16x16x32_bf16 v[140:143], v[120:123], v[136:139], 0
	ds_read_b64 v[24:25], v2 offset:8704
	s_or_b32 s0, s0, 31
	v_mad_u64_u32 v[8:9], s[8:9], s0, v233, v[8:9]
	s_waitcnt lgkmcnt(1)
	v_mfma_f32_16x16x32_bf16 v[140:143], v[128:131], v[144:147], v[140:143]
	s_waitcnt lgkmcnt(0)
	v_lshlrev_b32_e32 v40, 16, v24
	v_and_b32_e32 v41, 0xffff0000, v24
	v_lshlrev_b32_e32 v42, 16, v25
	v_mfma_f32_16x16x32_bf16 v[148:151], v[116:119], v[136:139], 0
	v_and_b32_e32 v44, 0xffff0000, v25
	v_add_u32_e32 v9, s6, v9
	s_waitcnt vmcnt(1)
	v_add_f32_e32 v24, v140, v152
	v_mul_f32_e32 v24, 0xbfb8aa3b, v24
	v_exp_f32_e32 v24, v24
	v_mfma_f32_16x16x32_bf16 v[148:151], v[124:127], v[144:147], v[148:151]
	v_add_f32_e32 v24, 1.0, v24
	v_rcp_f32_e32 v24, v24
	s_nop 0
	v_mul_f32_e32 v24, 0xc1000000, v24
	v_mul_f32_e32 v24, v48, v24
	v_mul_f32_e32 v24, 0x3fb8aa3b, v24
	s_waitcnt vmcnt(0)
	s_nop 0
	v_add_f32_e32 v25, v148, v156
	v_exp_f32_e32 v24, v24
	v_mul_f32_e32 v25, 0xbfb8aa3b, v25
	v_exp_f32_e32 v25, v25
	v_sub_f32_e32 v45, 1.0, v24
	v_add_f32_e32 v46, 1.0, v24
	v_mul_f32_e32 v45, v45, v46
	v_add_f32_e32 v25, 1.0, v25
	v_max_f32_e32 v45, 0, v45
	v_rcp_f32_e32 v25, v25
	v_sqrt_f32_e32 v45, v45
	s_nop 0
	v_mul_f32_e32 v25, v25, v45
	v_mul_f32_e32 v25, v25, v40
	v_add_f32_e32 v40, v141, v153
	v_mul_f32_e32 v40, 0xbfb8aa3b, v40
	v_exp_f32_e32 v40, v40
	v_add_f32_e32 v45, v149, v157
	v_mul_f32_e32 v45, 0xbfb8aa3b, v45
	v_exp_f32_e32 v45, v45
	v_add_f32_e32 v40, 1.0, v40
	v_rcp_f32_e32 v40, v40
	v_add_f32_e32 v45, 1.0, v45
	v_rcp_f32_e32 v45, v45
	v_mul_f32_e32 v40, 0xc1000000, v40
	v_mul_f32_e32 v40, v49, v40
	v_mul_f32_e32 v40, 0x3fb8aa3b, v40
	v_exp_f32_e32 v40, v40
	s_nop 0
	v_sub_f32_e32 v46, 1.0, v40
	v_add_f32_e32 v53, 1.0, v40
	v_mul_f32_e32 v46, v46, v53
	v_max_f32_e32 v46, 0, v46
	v_sqrt_f32_e32 v46, v46
	s_nop 0
	v_mul_f32_e32 v45, v45, v46
	v_mul_f32_e32 v41, v45, v41
	ds_write2_b64 v56, v[24:25], v[40:41] offset1:17
	v_add_f32_e32 v24, v142, v154
	v_mul_f32_e32 v24, 0xbfb8aa3b, v24
	v_exp_f32_e32 v24, v24
	v_add_f32_e32 v25, v150, v158
	v_mul_f32_e32 v25, 0xbfb8aa3b, v25
	v_exp_f32_e32 v25, v25
	v_add_f32_e32 v24, 1.0, v24
	v_rcp_f32_e32 v24, v24
	v_add_f32_e32 v25, 1.0, v25
	v_rcp_f32_e32 v25, v25
	v_mul_f32_e32 v24, 0xc1000000, v24
	v_mul_f32_e32 v24, v50, v24
	v_mul_f32_e32 v24, 0x3fb8aa3b, v24
	v_exp_f32_e32 v24, v24
	s_nop 0
	v_sub_f32_e32 v40, 1.0, v24
	v_add_f32_e32 v41, 1.0, v24
	v_mul_f32_e32 v40, v40, v41
	v_max_f32_e32 v40, 0, v40
	v_sqrt_f32_e32 v40, v40
	v_add_f32_e32 v41, v151, v159
	v_mul_f32_e32 v41, 0xbfb8aa3b, v41
	v_exp_f32_e32 v41, v41
	v_mul_f32_e32 v25, v25, v40
	v_add_f32_e32 v40, v143, v155
	v_mul_f32_e32 v40, 0xbfb8aa3b, v40
	v_exp_f32_e32 v40, v40
	v_mul_f32_e32 v25, v25, v42
	v_add_f32_e32 v41, 1.0, v41
	v_rcp_f32_e32 v41, v41
	v_add_f32_e32 v40, 1.0, v40
	v_rcp_f32_e32 v40, v40
	v_mfma_f32_16x16x32_bf16 v[140:143], v[104:107], v[136:139], 0
	v_mul_f32_e32 v40, 0xc1000000, v40
	v_mul_f32_e32 v40, v52, v40
	v_mul_f32_e32 v40, 0x3fb8aa3b, v40
	v_exp_f32_e32 v40, v40
	v_mfma_f32_16x16x32_bf16 v[148:151], v[112:115], v[144:147], v[140:143]
	v_sub_f32_e32 v42, 1.0, v40
	v_add_f32_e32 v45, 1.0, v40
	v_mul_f32_e32 v42, v42, v45
	v_max_f32_e32 v42, 0, v42
	v_sqrt_f32_e32 v42, v42
	v_mfma_f32_16x16x32_bf16 v[140:143], v[100:103], v[136:139], 0
	v_mul_f32_e32 v41, v41, v42
	v_mul_f32_e32 v41, v41, v44
	ds_write2_b64 v56, v[24:25], v[40:41] offset0:34 offset1:51
	global_load_dwordx4 v[152:155], v[4:5], off offset:64
	global_load_dwordx4 v[156:159], v[0:1], off offset:64
	ds_read_b64 v[24:25], v2 offset:8736
	v_mfma_f32_16x16x32_bf16 v[140:143], v[108:111], v[144:147], v[140:143]
	s_waitcnt lgkmcnt(0)
	v_lshlrev_b32_e32 v40, 16, v24
	v_and_b32_e32 v41, 0xffff0000, v24
	v_lshlrev_b32_e32 v42, 16, v25
	v_and_b32_e32 v44, 0xffff0000, v25
	s_waitcnt vmcnt(1)
	v_add_f32_e32 v24, v148, v152
	v_mul_f32_e32 v24, 0xbfb8aa3b, v24
	v_exp_f32_e32 v24, v24
	s_waitcnt vmcnt(0)
	v_add_f32_e32 v25, v140, v156
	v_mul_f32_e32 v25, 0xbfb8aa3b, v25
	v_exp_f32_e32 v25, v25
	v_add_f32_e32 v24, 1.0, v24
	v_rcp_f32_e32 v24, v24
	v_add_f32_e32 v25, 1.0, v25
	v_rcp_f32_e32 v25, v25
	v_mul_f32_e32 v24, 0xc1000000, v24
	v_mul_f32_e32 v24, v182, v24
	v_mul_f32_e32 v24, 0x3fb8aa3b, v24
	v_exp_f32_e32 v24, v24
	s_nop 0
	v_sub_f32_e32 v45, 1.0, v24
	v_add_f32_e32 v46, 1.0, v24
	v_mul_f32_e32 v45, v45, v46
	v_max_f32_e32 v45, 0, v45
	v_sqrt_f32_e32 v45, v45
	s_nop 0
	v_mul_f32_e32 v25, v25, v45
	v_mul_f32_e32 v25, v25, v40
	v_add_f32_e32 v40, v149, v153
	v_mul_f32_e32 v40, 0xbfb8aa3b, v40
	v_exp_f32_e32 v40, v40
	v_add_f32_e32 v45, v141, v157
	v_mul_f32_e32 v45, 0xbfb8aa3b, v45
	v_exp_f32_e32 v45, v45
	v_add_f32_e32 v40, 1.0, v40
	v_rcp_f32_e32 v40, v40
	v_add_f32_e32 v45, 1.0, v45
	v_rcp_f32_e32 v45, v45
	v_mul_f32_e32 v40, 0xc1000000, v40
	v_mul_f32_e32 v40, v184, v40
	v_mul_f32_e32 v40, 0x3fb8aa3b, v40
	v_exp_f32_e32 v40, v40
	s_nop 0
	v_sub_f32_e32 v46, 1.0, v40
	v_add_f32_e32 v53, 1.0, v40
	v_mul_f32_e32 v46, v46, v53
	v_max_f32_e32 v46, 0, v46
	v_sqrt_f32_e32 v46, v46
	s_nop 0
	v_mul_f32_e32 v45, v45, v46
	v_mul_f32_e32 v41, v45, v41
	ds_write2_b64 v192, v[24:25], v[40:41] offset0:16 offset1:33
	v_add_f32_e32 v24, v150, v154
	v_mul_f32_e32 v24, 0xbfb8aa3b, v24
	v_exp_f32_e32 v24, v24
	v_add_f32_e32 v25, v142, v158
	v_mul_f32_e32 v25, 0xbfb8aa3b, v25
	v_exp_f32_e32 v25, v25
	v_add_f32_e32 v24, 1.0, v24
	v_rcp_f32_e32 v24, v24
	v_add_f32_e32 v25, 1.0, v25
	v_rcp_f32_e32 v25, v25
	v_mul_f32_e32 v24, 0xc1000000, v24
	v_mul_f32_e32 v24, v186, v24
	v_mul_f32_e32 v24, 0x3fb8aa3b, v24
	v_exp_f32_e32 v24, v24
	s_nop 0
	v_sub_f32_e32 v40, 1.0, v24
	v_add_f32_e32 v41, 1.0, v24
	v_mul_f32_e32 v40, v40, v41
	v_max_f32_e32 v40, 0, v40
	v_sqrt_f32_e32 v40, v40
	v_add_f32_e32 v41, v143, v159
	v_mul_f32_e32 v41, 0xbfb8aa3b, v41
	v_exp_f32_e32 v41, v41
	v_mul_f32_e32 v25, v25, v40
	v_add_f32_e32 v40, v151, v155
	v_mul_f32_e32 v40, 0xbfb8aa3b, v40
	v_exp_f32_e32 v40, v40
	v_mul_f32_e32 v25, v25, v42
	v_add_f32_e32 v41, 1.0, v41
	v_rcp_f32_e32 v41, v41
	v_add_f32_e32 v40, 1.0, v40
	v_rcp_f32_e32 v40, v40
	v_mfma_f32_16x16x32_bf16 v[140:143], v[88:91], v[136:139], 0
	v_mul_f32_e32 v40, 0xc1000000, v40
	v_mul_f32_e32 v40, v187, v40
	v_mul_f32_e32 v40, 0x3fb8aa3b, v40
	v_exp_f32_e32 v40, v40
	v_mfma_f32_16x16x32_bf16 v[140:143], v[96:99], v[144:147], v[140:143]
	v_sub_f32_e32 v42, 1.0, v40
	v_add_f32_e32 v45, 1.0, v40
	v_mul_f32_e32 v42, v42, v45
	v_max_f32_e32 v42, 0, v42
	v_sqrt_f32_e32 v42, v42
	v_mfma_f32_16x16x32_bf16 v[148:151], v[84:87], v[136:139], 0
	v_mul_f32_e32 v41, v41, v42
	v_mul_f32_e32 v41, v41, v44
	ds_write2_b64 v192, v[24:25], v[40:41] offset0:50 offset1:67
	global_load_dwordx4 v[152:155], v[4:5], off offset:128
	global_load_dwordx4 v[156:159], v[0:1], off offset:128
	ds_read_b64 v[24:25], v2 offset:8768
	v_mfma_f32_16x16x32_bf16 v[148:151], v[92:95], v[144:147], v[148:151]
	s_waitcnt lgkmcnt(0)
	v_lshlrev_b32_e32 v40, 16, v24
	v_and_b32_e32 v41, 0xffff0000, v24
	v_lshlrev_b32_e32 v42, 16, v25
	v_and_b32_e32 v44, 0xffff0000, v25
	s_waitcnt vmcnt(1)
	v_add_f32_e32 v24, v140, v152
	v_mul_f32_e32 v24, 0xbfb8aa3b, v24
	v_exp_f32_e32 v24, v24
	s_waitcnt vmcnt(0)
	v_add_f32_e32 v25, v148, v156
	v_mul_f32_e32 v25, 0xbfb8aa3b, v25
	v_exp_f32_e32 v25, v25
	v_add_f32_e32 v24, 1.0, v24
	v_rcp_f32_e32 v24, v24
	v_add_f32_e32 v25, 1.0, v25
	v_rcp_f32_e32 v25, v25
	v_mul_f32_e32 v24, 0xc1000000, v24
	v_mul_f32_e32 v24, v132, v24
	v_mul_f32_e32 v24, 0x3fb8aa3b, v24
	v_exp_f32_e32 v24, v24
	s_nop 0
	v_sub_f32_e32 v45, 1.0, v24
	v_add_f32_e32 v46, 1.0, v24
	v_mul_f32_e32 v45, v45, v46
	v_max_f32_e32 v45, 0, v45
	v_sqrt_f32_e32 v45, v45
	s_nop 0
	v_mul_f32_e32 v25, v25, v45
	v_mul_f32_e32 v25, v25, v40
	v_add_f32_e32 v40, v141, v153
	v_mul_f32_e32 v40, 0xbfb8aa3b, v40
	v_exp_f32_e32 v40, v40
	v_add_f32_e32 v45, v149, v157
	v_mul_f32_e32 v45, 0xbfb8aa3b, v45
	v_exp_f32_e32 v45, v45
	v_add_f32_e32 v40, 1.0, v40
	v_rcp_f32_e32 v40, v40
	v_add_f32_e32 v45, 1.0, v45
	v_rcp_f32_e32 v45, v45
	v_mul_f32_e32 v40, 0xc1000000, v40
	v_mul_f32_e32 v40, v160, v40
	v_mul_f32_e32 v40, 0x3fb8aa3b, v40
	v_exp_f32_e32 v40, v40
	s_nop 0
	v_sub_f32_e32 v46, 1.0, v40
	v_add_f32_e32 v53, 1.0, v40
	v_mul_f32_e32 v46, v46, v53
	v_max_f32_e32 v46, 0, v46
	v_sqrt_f32_e32 v46, v46
	s_nop 0
	v_mul_f32_e32 v45, v45, v46
	v_mul_f32_e32 v41, v45, v41
	ds_write2_b64 v191, v[24:25], v[40:41] offset0:32 offset1:49
	v_add_f32_e32 v24, v142, v154
	v_mul_f32_e32 v24, 0xbfb8aa3b, v24
	v_exp_f32_e32 v24, v24
	v_add_f32_e32 v25, v150, v158
	v_mul_f32_e32 v25, 0xbfb8aa3b, v25
	v_exp_f32_e32 v25, v25
	v_add_f32_e32 v24, 1.0, v24
	v_rcp_f32_e32 v24, v24
	v_add_f32_e32 v25, 1.0, v25
	v_rcp_f32_e32 v25, v25
	v_mul_f32_e32 v24, 0xc1000000, v24
	v_mul_f32_e32 v24, v180, v24
	v_mul_f32_e32 v24, 0x3fb8aa3b, v24
	v_exp_f32_e32 v24, v24
	s_nop 0
	v_sub_f32_e32 v40, 1.0, v24
	v_add_f32_e32 v41, 1.0, v24
	v_mul_f32_e32 v40, v40, v41
	v_max_f32_e32 v40, 0, v40
	v_sqrt_f32_e32 v40, v40
	v_add_f32_e32 v41, v151, v159
	v_mul_f32_e32 v41, 0xbfb8aa3b, v41
	v_exp_f32_e32 v41, v41
	v_mul_f32_e32 v25, v25, v40
	v_add_f32_e32 v40, v143, v155
	v_mul_f32_e32 v40, 0xbfb8aa3b, v40
	v_exp_f32_e32 v40, v40
	v_mul_f32_e32 v25, v25, v42
	v_add_f32_e32 v41, 1.0, v41
	v_rcp_f32_e32 v41, v41
	v_add_f32_e32 v40, 1.0, v40
	v_rcp_f32_e32 v40, v40
	v_mfma_f32_16x16x32_bf16 v[140:143], v[72:75], v[136:139], 0
	v_mul_f32_e32 v40, 0xc1000000, v40
	v_mul_f32_e32 v40, v183, v40
	v_mul_f32_e32 v40, 0x3fb8aa3b, v40
	v_exp_f32_e32 v40, v40
	v_mfma_f32_16x16x32_bf16 v[136:139], v[68:71], v[136:139], 0
	v_sub_f32_e32 v42, 1.0, v40
	v_add_f32_e32 v45, 1.0, v40
	v_mul_f32_e32 v42, v42, v45
	v_max_f32_e32 v42, 0, v42
	v_sqrt_f32_e32 v42, v42
	v_mfma_f32_16x16x32_bf16 v[140:143], v[80:83], v[144:147], v[140:143]
	v_mul_f32_e32 v41, v41, v42
	v_mul_f32_e32 v41, v41, v44
	ds_write2_b64 v191, v[24:25], v[40:41] offset0:66 offset1:83
	v_mfma_f32_16x16x32_bf16 v[136:139], v[76:79], v[144:147], v[136:139]
	global_load_dwordx4 v[148:151], v[4:5], off offset:192
	global_load_dwordx4 v[144:147], v[0:1], off offset:192
	ds_read_b64 v[24:25], v2 offset:8800
	s_waitcnt lgkmcnt(0)
	v_lshlrev_b32_e32 v41, 16, v24
	v_and_b32_e32 v42, 0xffff0000, v24
	v_lshlrev_b32_e32 v46, 16, v25
	v_and_b32_e32 v40, 0xffff0000, v25
	s_waitcnt vmcnt(1)
	v_add_f32_e32 v24, v140, v148
	v_mul_f32_e32 v24, 0xbfb8aa3b, v24
	v_exp_f32_e32 v24, v24
	s_waitcnt vmcnt(0)
	v_add_f32_e32 v25, v136, v144
	v_mul_f32_e32 v25, 0xbfb8aa3b, v25
	v_exp_f32_e32 v25, v25
	v_add_f32_e32 v24, 1.0, v24
	v_rcp_f32_e32 v24, v24
	v_add_f32_e32 v25, 1.0, v25
	v_rcp_f32_e32 v25, v25
	v_mul_f32_e32 v24, 0xc1000000, v24
	v_mul_f32_e32 v24, v62, v24
	v_mul_f32_e32 v24, 0x3fb8aa3b, v24
	v_exp_f32_e32 v24, v24
	s_nop 0
	v_sub_f32_e32 v44, 1.0, v24
	v_add_f32_e32 v45, 1.0, v24
	v_mul_f32_e32 v44, v44, v45
	v_max_f32_e32 v44, 0, v44
	v_sqrt_f32_e32 v44, v44
	s_nop 0
	v_mul_f32_e32 v25, v25, v44
	v_mul_f32_e32 v25, v25, v41
	v_add_f32_e32 v41, v141, v149
	v_mul_f32_e32 v41, 0xbfb8aa3b, v41
	v_exp_f32_e32 v41, v41
	v_add_f32_e32 v44, v137, v145
	v_mul_f32_e32 v44, 0xbfb8aa3b, v44
	v_exp_f32_e32 v44, v44
	v_add_f32_e32 v41, 1.0, v41
	v_rcp_f32_e32 v41, v41
	v_add_f32_e32 v44, 1.0, v44
	v_rcp_f32_e32 v45, v44
	v_mul_f32_e32 v41, 0xc1000000, v41
	v_mul_f32_e32 v41, v64, v41
	v_mul_f32_e32 v41, 0x3fb8aa3b, v41
	v_exp_f32_e32 v44, v41
	s_nop 0
	v_sub_f32_e32 v41, 1.0, v44
	v_add_f32_e32 v53, 1.0, v44
	v_mul_f32_e32 v41, v41, v53
	v_max_f32_e32 v41, 0, v41
	v_sqrt_f32_e32 v41, v41
	s_nop 0
	v_mul_f32_e32 v41, v45, v41
	v_mul_f32_e32 v45, v41, v42
	ds_write2_b64 v190, v[24:25], v[44:45] offset0:48 offset1:65
	v_add_f32_e32 v24, v142, v150
	v_mul_f32_e32 v24, 0xbfb8aa3b, v24
	v_exp_f32_e32 v24, v24
	v_add_f32_e32 v25, v138, v146
	v_mul_f32_e32 v25, 0xbfb8aa3b, v25
	v_exp_f32_e32 v25, v25
	v_add_f32_e32 v24, 1.0, v24
	v_rcp_f32_e32 v24, v24
	v_add_f32_e32 v25, 1.0, v25
	v_rcp_f32_e32 v25, v25
	v_mul_f32_e32 v24, 0xc1000000, v24
	v_mul_f32_e32 v24, v65, v24
	v_mul_f32_e32 v24, 0x3fb8aa3b, v24
	v_exp_f32_e32 v24, v24
	s_nop 0
	v_sub_f32_e32 v41, 1.0, v24
	v_add_f32_e32 v42, 1.0, v24
	v_mul_f32_e32 v41, v41, v42
	v_max_f32_e32 v41, 0, v41
	v_sqrt_f32_e32 v41, v41
	v_add_f32_e32 v42, v139, v147
	v_mul_f32_e32 v42, 0xbfb8aa3b, v42
	v_exp_f32_e32 v42, v42
	v_mul_f32_e32 v25, v25, v41
	v_add_f32_e32 v41, v143, v151
	v_mul_f32_e32 v41, 0xbfb8aa3b, v41
	v_exp_f32_e32 v41, v41
	v_add_f32_e32 v42, 1.0, v42
	v_rcp_f32_e32 v42, v42
	v_mul_f32_e32 v25, v25, v46
	v_add_f32_e32 v41, 1.0, v41
	v_rcp_f32_e32 v41, v41
	s_nop 0
	v_mul_f32_e32 v41, 0xc1000000, v41
	v_mul_f32_e32 v41, v66, v41
	v_mul_f32_e32 v41, 0x3fb8aa3b, v41
	v_exp_f32_e32 v44, v41
	s_nop 0
	v_sub_f32_e32 v41, 1.0, v44
	v_add_f32_e32 v45, 1.0, v44
	v_mul_f32_e32 v41, v41, v45
	v_max_f32_e32 v41, 0, v41
	v_sqrt_f32_e32 v41, v41
	s_nop 0
	v_mul_f32_e32 v41, v42, v41
	v_mul_f32_e32 v45, v41, v40
	ds_write2_b64 v190, v[24:25], v[44:45] offset0:82 offset1:99
	s_waitcnt lgkmcnt(0)
	s_barrier
	global_load_ushort v25, v[8:9], off
	ds_read2_b64 v[136:139], v196 offset1:1
	s_waitcnt lgkmcnt(0)
	v_fma_f32 v42, v135, v138, v139
	v_add_f32_e32 v24, v67, v42
	v_fmac_f32_e32 v137, v42, v136
	ds_read2_b64 v[138:141], v195 offset1:1
	v_add_f32_e32 v38, v38, v137
	s_waitcnt vmcnt(0)
	v_lshlrev_b32_e32 v25, 16, v25
	v_mul_f32_e32 v24, v24, v25
	v_cvt_pk_bf16_f32 v46, v24, s0
	v_add_co_u32_e32 v24, vcc, s11, v8
	s_lshl_b64 s[0:1], s[0:1], 11
	s_nop 0
	v_addc_co_u32_e32 v25, vcc, -1, v9, vcc
	global_load_ushort v53, v[24:25], off offset:-3072
	v_add_co_u32_e32 v24, vcc, s22, v8
	v_lshl_add_u64 v[40:41], v[16:17], 0, s[0:1]
	s_nop 0
	v_addc_co_u32_e32 v25, vcc, -1, v9, vcc
	global_load_ushort v54, v[24:25], off offset:-2048
	v_add_co_u32_e32 v24, vcc, s13, v8
	s_mov_b32 s1, s5
	s_nop 0
	v_addc_co_u32_e32 v25, vcc, -1, v9, vcc
	global_load_ushort v58, v[24:25], off offset:-1024
	v_add_co_u32_e32 v24, vcc, s12, v8
	s_nop 1
	v_addc_co_u32_e32 v25, vcc, -1, v9, vcc
	global_load_ushort v60, v[24:25], off
	v_add_co_u32_e32 v24, vcc, s10, v8
	s_nop 1
	v_addc_co_u32_e32 v25, vcc, -1, v9, vcc
	global_load_ushort v61, v[24:25], off offset:-3072
	v_add_co_u32_e32 v24, vcc, s33, v8
	s_nop 1
	v_addc_co_u32_e32 v25, vcc, -1, v9, vcc
	global_load_ushort v67, v[24:25], off offset:-2048
	v_add_co_u32_e32 v24, vcc, s38, v8
	s_nop 1
	v_addc_co_u32_e32 v25, vcc, -1, v9, vcc
	global_load_ushort v133, v[24:25], off offset:-1024
	v_add_co_u32_e32 v24, vcc, s39, v8
	s_nop 1
	v_addc_co_u32_e32 v25, vcc, -1, v9, vcc
	global_load_ushort v142, v[24:25], off
	v_add_co_u32_e32 v24, vcc, s42, v8
	s_nop 1
	v_addc_co_u32_e32 v25, vcc, -1, v9, vcc
	global_load_ushort v143, v[24:25], off offset:-3072
	v_add_co_u32_e32 v24, vcc, s43, v8
	s_nop 1
	v_addc_co_u32_e32 v25, vcc, -1, v9, vcc
	global_load_ushort v144, v[24:25], off offset:-2048
	v_add_co_u32_e32 v24, vcc, s56, v8
	s_nop 1
	v_addc_co_u32_e32 v25, vcc, -1, v9, vcc
	global_load_ushort v145, v[24:25], off offset:-1024
	v_add_co_u32_e32 v24, vcc, s57, v8
	s_nop 1
	v_addc_co_u32_e32 v25, vcc, -1, v9, vcc
	global_load_ushort v146, v[24:25], off
	v_add_co_u32_e32 v24, vcc, s58, v8
	s_nop 1
	v_addc_co_u32_e32 v25, vcc, -1, v9, vcc
	global_load_ushort v147, v[24:25], off offset:-3072
	v_add_co_u32_e32 v24, vcc, s7, v8
	s_nop 1
	v_addc_co_u32_e32 v25, vcc, -1, v9, vcc
	global_load_ushort v25, v[24:25], off offset:-2048
	v_add_co_u32_e32 v44, vcc, s59, v8
	s_waitcnt vmcnt(0)
	v_lshlrev_b32_e32 v25, 16, v25
	v_addc_co_u32_e32 v45, vcc, -1, v9, vcc
	global_load_ushort v24, v[44:45], off offset:-1024
	s_waitcnt vmcnt(0)
	v_lshlrev_b32_e32 v24, 16, v24
	global_store_short v[40:41], v46, off
	v_lshlrev_b32_e32 v40, 16, v53
	v_mul_f32_e32 v38, v38, v40
	v_cvt_pk_bf16_f32 v38, v38, s0
	s_or_b32 s0, s4, 0xf000
	v_lshl_add_u64 v[40:41], v[16:17], 0, s[0:1]
	global_store_short v[40:41], v38, off
	s_waitcnt lgkmcnt(0)
	v_fma_f32 v38, v137, v140, v141
	v_add_f32_e32 v40, v63, v38
	v_lshlrev_b32_e32 v41, 16, v54
	v_fmac_f32_e32 v139, v38, v138
	ds_read2_b64 v[134:137], v194 offset1:1
	v_mul_f32_e32 v40, v40, v41
	v_add_f32_e32 v37, v37, v139
	v_lshlrev_b32_e32 v38, 16, v58
	v_cvt_pk_bf16_f32 v42, v40, s0
	s_or_b32 s0, s4, 0xe800
	v_mul_f32_e32 v37, v37, v38
	v_lshl_add_u64 v[40:41], v[16:17], 0, s[0:1]
	v_cvt_pk_bf16_f32 v37, v37, s0
	s_or_b32 s0, s4, 0xe000
	global_store_short v[40:41], v42, off
	v_lshl_add_u64 v[40:41], v[16:17], 0, s[0:1]
	global_store_short v[40:41], v37, off
	s_waitcnt lgkmcnt(0)
	v_fma_f32 v37, v139, v136, v137
	v_add_f32_e32 v38, v59, v37
	v_lshlrev_b32_e32 v40, 16, v60
	v_mul_f32_e32 v38, v38, v40
	v_fmac_f32_e32 v135, v37, v134
	v_lshlrev_b32_e32 v37, 16, v61
	ds_read2_b64 v[58:61], v193 offset1:1
	v_cvt_pk_bf16_f32 v38, v38, s0
	s_or_b32 s0, s4, 0xd800
	v_add_f32_e32 v36, v36, v135
	v_lshl_add_u64 v[40:41], v[16:17], 0, s[0:1]
	v_mul_f32_e32 v36, v36, v37
	global_store_short v[40:41], v38, off
	v_cvt_pk_bf16_f32 v38, v36, s0
	s_or_b32 s0, s4, 0xd000
	v_lshl_add_u64 v[36:37], v[16:17], 0, s[0:1]
	global_store_short v[36:37], v38, off
	s_waitcnt lgkmcnt(0)
	v_fma_f32 v38, v135, v60, v61
	v_add_f32_e32 v36, v55, v38
	v_lshlrev_b32_e32 v37, 16, v67
	v_mul_f32_e32 v36, v36, v37
	v_cvt_pk_bf16_f32 v40, v36, s0
	s_or_b32 s0, s4, 0xc800
	v_lshl_add_u64 v[36:37], v[16:17], 0, s[0:1]
	v_fmac_f32_e32 v59, v38, v58
	ds_read2_b64 v[134:137], v189 offset1:1
	global_store_short v[36:37], v40, off
	v_add_f32_e32 v34, v34, v59
	v_lshlrev_b32_e32 v36, 16, v133
	v_mul_f32_e32 v34, v34, v36
	v_cvt_pk_bf16_f32 v34, v34, s0
	s_or_b32 s0, s4, 0xc000
	v_lshl_add_u64 v[36:37], v[16:17], 0, s[0:1]
	global_store_short v[36:37], v34, off
	s_waitcnt lgkmcnt(0)
	v_fma_f32 v34, v59, v136, v137
	v_add_f32_e32 v36, v51, v34
	v_lshlrev_b32_e32 v37, 16, v142
	v_fmac_f32_e32 v135, v34, v134
	ds_read2_b64 v[58:61], v185 offset1:1
	v_mul_f32_e32 v36, v36, v37
	v_add_f32_e32 v33, v33, v135
	v_lshlrev_b32_e32 v34, 16, v143
	v_cvt_pk_bf16_f32 v38, v36, s0
	s_or_b32 s0, s4, 0xb800
	v_mul_f32_e32 v33, v33, v34
	v_lshl_add_u64 v[36:37], v[16:17], 0, s[0:1]
	v_cvt_pk_bf16_f32 v33, v33, s0
	s_or_b32 s0, s4, 0xb000
	global_store_short v[36:37], v38, off
	v_lshl_add_u64 v[36:37], v[16:17], 0, s[0:1]
	global_store_short v[36:37], v33, off
	s_waitcnt lgkmcnt(0)
	v_fma_f32 v33, v135, v60, v61
	v_add_f32_e32 v34, v47, v33
	v_lshlrev_b32_e32 v36, 16, v144
	v_mul_f32_e32 v34, v34, v36
	v_fmac_f32_e32 v59, v33, v58
	ds_read2_b64 v[44:47], v181 offset1:1
	v_cvt_pk_bf16_f32 v34, v34, s0
	s_or_b32 s0, s4, 0xa800
	v_add_f32_e32 v32, v32, v59
	v_lshlrev_b32_e32 v33, 16, v145
	v_lshl_add_u64 v[36:37], v[16:17], 0, s[0:1]
	v_mul_f32_e32 v32, v32, v33
	global_store_short v[36:37], v34, off
	v_cvt_pk_bf16_f32 v34, v32, s0
	s_or_b32 s0, s4, 0xa000
	v_lshl_add_u64 v[32:33], v[16:17], 0, s[0:1]
	global_store_short v[32:33], v34, off
	s_waitcnt lgkmcnt(0)
	v_fma_f32 v34, v59, v46, v47
	v_add_f32_e32 v32, v43, v34
	v_lshlrev_b32_e32 v33, 16, v146
	v_mul_f32_e32 v32, v32, v33
	v_cvt_pk_bf16_f32 v36, v32, s0
	s_or_b32 s0, s4, 0x9800
	v_lshl_add_u64 v[32:33], v[16:17], 0, s[0:1]
	v_fmac_f32_e32 v45, v34, v44
	ds_read2_b64 v[40:43], v188 offset1:1
	global_store_short v[32:33], v36, off
	v_add_f32_e32 v30, v30, v45
	v_lshlrev_b32_e32 v32, 16, v147
	v_mul_f32_e32 v30, v30, v32
	v_cvt_pk_bf16_f32 v30, v30, s0
	s_or_b32 s0, s4, 0x9000
	v_lshl_add_u64 v[32:33], v[16:17], 0, s[0:1]
	global_store_short v[32:33], v30, off
	s_waitcnt lgkmcnt(0)
	v_fma_f32 v30, v45, v42, v43
	v_add_f32_e32 v32, v39, v30
	v_mul_f32_e32 v25, v32, v25
	v_cvt_pk_bf16_f32 v25, v25, s0
	s_or_b32 s0, s4, 0x8800
	v_lshl_add_u64 v[32:33], v[16:17], 0, s[0:1]
	v_fmac_f32_e32 v41, v30, v40
	global_store_short v[32:33], v25, off
	v_add_f32_e32 v25, v29, v41
	v_mul_f32_e32 v24, v25, v24
	v_cvt_pk_bf16_f32 v29, v24, s0
	s_or_b32 s0, s4, 0x8000
	v_lshl_add_u64 v[24:25], v[16:17], 0, s[0:1]
	global_store_short v[24:25], v29, off
	s_barrier
	ds_read_b128 v[36:39], v57
	ds_read_b128 v[42:45], v57 offset:64
	s_waitcnt lgkmcnt(1)
	v_mfma_f32_16x16x32_bf16 v[116:119], v[116:119], v[36:39], 0
	s_mov_b32 s0, 0xfffe4000
	v_mfma_f32_16x16x32_bf16 v[58:61], v[120:123], v[36:39], 0
	s_waitcnt lgkmcnt(0)
	v_mfma_f32_16x16x32_bf16 v[116:119], v[124:127], v[42:45], v[116:119]
	global_load_dwordx4 v[120:123], v[4:5], off
	global_load_dwordx4 v[124:127], v[0:1], off
	ds_read_b64 v[24:25], v2
	s_waitcnt lgkmcnt(0)
	v_lshlrev_b32_e32 v29, 16, v24
	v_mfma_f32_16x16x32_bf16 v[58:61], v[128:131], v[42:45], v[58:61]
	v_and_b32_e32 v30, 0xffff0000, v24
	v_lshlrev_b32_e32 v34, 16, v25
	v_and_b32_e32 v40, 0xffff0000, v25
	s_waitcnt vmcnt(0)
	v_add_f32_e32 v25, v116, v124
	s_nop 2
	v_add_f32_e32 v24, v58, v120
	v_mul_f32_e32 v24, 0xbfb8aa3b, v24
	v_exp_f32_e32 v24, v24
	v_mul_f32_e32 v25, 0xbfb8aa3b, v25
	v_exp_f32_e32 v25, v25
	v_add_f32_e32 v24, 1.0, v24
	v_rcp_f32_e32 v24, v24
	v_add_f32_e32 v25, 1.0, v25
	v_rcp_f32_e32 v25, v25
	v_mul_f32_e32 v24, 0xc1000000, v24
	v_mul_f32_e32 v24, v48, v24
	v_mul_f32_e32 v24, 0x3fb8aa3b, v24
	v_exp_f32_e32 v24, v24
	s_nop 0
	v_sub_f32_e32 v32, 1.0, v24
	v_add_f32_e32 v33, 1.0, v24
	v_mul_f32_e32 v32, v32, v33
	v_max_f32_e32 v32, 0, v32
	v_sqrt_f32_e32 v32, v32
	s_nop 0
	v_mul_f32_e32 v25, v25, v32
	v_mul_f32_e32 v25, v25, v29
	v_add_f32_e32 v29, v59, v121
	v_mul_f32_e32 v29, 0xbfb8aa3b, v29
	v_exp_f32_e32 v29, v29
	v_add_f32_e32 v32, v117, v125
	v_mul_f32_e32 v32, 0xbfb8aa3b, v32
	v_exp_f32_e32 v32, v32
	v_add_f32_e32 v29, 1.0, v29
	v_rcp_f32_e32 v29, v29
	v_add_f32_e32 v32, 1.0, v32
	v_rcp_f32_e32 v33, v32
	v_mul_f32_e32 v29, 0xc1000000, v29
	v_mul_f32_e32 v29, v49, v29
	v_mul_f32_e32 v29, 0x3fb8aa3b, v29
	v_exp_f32_e32 v32, v29
	s_nop 0
	v_sub_f32_e32 v29, 1.0, v32
	v_add_f32_e32 v46, 1.0, v32
	v_mul_f32_e32 v29, v29, v46
	v_max_f32_e32 v29, 0, v29
	v_sqrt_f32_e32 v29, v29
	v_mfma_f32_16x16x32_bf16 v[46:49], v[104:107], v[36:39], 0
	v_mul_f32_e32 v29, v33, v29
	v_mul_f32_e32 v33, v29, v30
	ds_write2_b64 v56, v[24:25], v[32:33] offset1:17
	v_add_f32_e32 v24, v60, v122
	v_mul_f32_e32 v24, 0xbfb8aa3b, v24
	v_exp_f32_e32 v24, v24
	v_add_f32_e32 v25, v118, v126
	v_mul_f32_e32 v25, 0xbfb8aa3b, v25
	v_exp_f32_e32 v25, v25
	v_add_f32_e32 v24, 1.0, v24
	v_rcp_f32_e32 v24, v24
	v_add_f32_e32 v25, 1.0, v25
	v_rcp_f32_e32 v25, v25
	v_mul_f32_e32 v24, 0xc1000000, v24
	v_mul_f32_e32 v24, v50, v24
	v_mul_f32_e32 v24, 0x3fb8aa3b, v24
	v_exp_f32_e32 v24, v24
	s_nop 0
	v_sub_f32_e32 v29, 1.0, v24
	v_add_f32_e32 v30, 1.0, v24
	v_mul_f32_e32 v29, v29, v30
	v_max_f32_e32 v29, 0, v29
	v_sqrt_f32_e32 v29, v29
	v_add_f32_e32 v30, v119, v127
	v_mul_f32_e32 v30, 0xbfb8aa3b, v30
	v_exp_f32_e32 v30, v30
	v_mul_f32_e32 v25, v25, v29
	v_add_f32_e32 v29, v61, v123
	v_mul_f32_e32 v29, 0xbfb8aa3b, v29
	v_exp_f32_e32 v29, v29
	v_add_f32_e32 v30, 1.0, v30
	v_rcp_f32_e32 v30, v30
	v_mul_f32_e32 v25, v25, v34
	v_add_f32_e32 v29, 1.0, v29
	v_rcp_f32_e32 v29, v29
	s_nop 0
	v_mul_f32_e32 v29, 0xc1000000, v29
	v_mul_f32_e32 v29, v52, v29
	v_mul_f32_e32 v29, 0x3fb8aa3b, v29
	v_exp_f32_e32 v32, v29
	v_mfma_f32_16x16x32_bf16 v[50:53], v[112:115], v[42:45], v[46:49]
	v_sub_f32_e32 v29, 1.0, v32
	v_add_f32_e32 v33, 1.0, v32
	v_mul_f32_e32 v29, v29, v33
	v_max_f32_e32 v29, 0, v29
	v_sqrt_f32_e32 v29, v29
	v_mfma_f32_16x16x32_bf16 v[46:49], v[100:103], v[36:39], 0
	v_mul_f32_e32 v29, v30, v29
	v_mul_f32_e32 v33, v29, v40
	ds_write2_b64 v56, v[24:25], v[32:33] offset0:34 offset1:51
	global_load_dwordx4 v[54:57], v[4:5], off offset:64
	global_load_dwordx4 v[58:61], v[0:1], off offset:64
	ds_read_b64 v[24:25], v2 offset:32
	v_mfma_f32_16x16x32_bf16 v[46:49], v[108:111], v[42:45], v[46:49]
	s_waitcnt lgkmcnt(0)
	v_lshlrev_b32_e32 v29, 16, v24
	v_and_b32_e32 v30, 0xffff0000, v24
	v_lshlrev_b32_e32 v34, 16, v25
	v_and_b32_e32 v40, 0xffff0000, v25
	s_waitcnt vmcnt(1)
	v_add_f32_e32 v24, v50, v54
	v_mul_f32_e32 v24, 0xbfb8aa3b, v24
	v_exp_f32_e32 v24, v24
	s_waitcnt vmcnt(0)
	v_add_f32_e32 v25, v46, v58
	v_mul_f32_e32 v25, 0xbfb8aa3b, v25
	v_exp_f32_e32 v25, v25
	v_add_f32_e32 v24, 1.0, v24
	v_rcp_f32_e32 v24, v24
	v_add_f32_e32 v25, 1.0, v25
	v_rcp_f32_e32 v25, v25
	v_mul_f32_e32 v24, 0xc1000000, v24
	v_mul_f32_e32 v24, v182, v24
	v_mul_f32_e32 v24, 0x3fb8aa3b, v24
	v_exp_f32_e32 v24, v24
	s_nop 0
	v_sub_f32_e32 v32, 1.0, v24
	v_add_f32_e32 v33, 1.0, v24
	v_mul_f32_e32 v32, v32, v33
	v_max_f32_e32 v32, 0, v32
	v_sqrt_f32_e32 v32, v32
	s_nop 0
	v_mul_f32_e32 v25, v25, v32
	v_mul_f32_e32 v25, v25, v29
	v_add_f32_e32 v29, v51, v55
	v_mul_f32_e32 v29, 0xbfb8aa3b, v29
	v_exp_f32_e32 v29, v29
	v_add_f32_e32 v32, v47, v59
	v_mul_f32_e32 v32, 0xbfb8aa3b, v32
	v_exp_f32_e32 v32, v32
	v_add_f32_e32 v29, 1.0, v29
	v_rcp_f32_e32 v29, v29
	v_add_f32_e32 v32, 1.0, v32
	v_rcp_f32_e32 v33, v32
	v_mul_f32_e32 v29, 0xc1000000, v29
	v_mul_f32_e32 v29, v184, v29
	v_mul_f32_e32 v29, 0x3fb8aa3b, v29
	v_exp_f32_e32 v32, v29
	s_nop 0
	v_sub_f32_e32 v29, 1.0, v32
	v_add_f32_e32 v46, 1.0, v32
	v_mul_f32_e32 v29, v29, v46
	v_max_f32_e32 v29, 0, v29
	v_sqrt_f32_e32 v29, v29
	s_nop 0
	v_mul_f32_e32 v29, v33, v29
	v_mul_f32_e32 v33, v29, v30
	ds_write2_b64 v192, v[24:25], v[32:33] offset0:16 offset1:33
	v_add_f32_e32 v24, v52, v56
	v_mul_f32_e32 v24, 0xbfb8aa3b, v24
	v_exp_f32_e32 v24, v24
	v_add_f32_e32 v25, v48, v60
	v_mul_f32_e32 v25, 0xbfb8aa3b, v25
	v_exp_f32_e32 v25, v25
	v_add_f32_e32 v24, 1.0, v24
	v_rcp_f32_e32 v24, v24
	v_add_f32_e32 v25, 1.0, v25
	v_rcp_f32_e32 v25, v25
	v_mul_f32_e32 v24, 0xc1000000, v24
	v_mul_f32_e32 v24, v186, v24
	v_mul_f32_e32 v24, 0x3fb8aa3b, v24
	v_exp_f32_e32 v24, v24
	s_nop 0
	v_sub_f32_e32 v29, 1.0, v24
	v_add_f32_e32 v30, 1.0, v24
	v_mul_f32_e32 v29, v29, v30
	v_max_f32_e32 v29, 0, v29
	v_sqrt_f32_e32 v29, v29
	v_add_f32_e32 v30, v49, v61
	v_mul_f32_e32 v30, 0xbfb8aa3b, v30
	v_exp_f32_e32 v30, v30
	v_mul_f32_e32 v25, v25, v29
	v_add_f32_e32 v29, v53, v57
	v_mul_f32_e32 v29, 0xbfb8aa3b, v29
	v_exp_f32_e32 v29, v29
	v_add_f32_e32 v30, 1.0, v30
	v_rcp_f32_e32 v30, v30
	v_mul_f32_e32 v25, v25, v34
	v_add_f32_e32 v29, 1.0, v29
	v_rcp_f32_e32 v29, v29
	v_mfma_f32_16x16x32_bf16 v[46:49], v[88:91], v[36:39], 0
	v_mul_f32_e32 v29, 0xc1000000, v29
	v_mul_f32_e32 v29, v187, v29
	v_mul_f32_e32 v29, 0x3fb8aa3b, v29
	v_exp_f32_e32 v32, v29
	v_mfma_f32_16x16x32_bf16 v[50:53], v[96:99], v[42:45], v[46:49]
	v_sub_f32_e32 v29, 1.0, v32
	v_add_f32_e32 v33, 1.0, v32
	v_mul_f32_e32 v29, v29, v33
	v_max_f32_e32 v29, 0, v29
	v_sqrt_f32_e32 v29, v29
	v_mfma_f32_16x16x32_bf16 v[46:49], v[84:87], v[36:39], 0
	v_mul_f32_e32 v29, v30, v29
	v_mul_f32_e32 v33, v29, v40
	ds_write2_b64 v192, v[24:25], v[32:33] offset0:50 offset1:67
	global_load_dwordx4 v[54:57], v[4:5], off offset:128
	global_load_dwordx4 v[58:61], v[0:1], off offset:128
	ds_read_b64 v[24:25], v2 offset:64
	v_mfma_f32_16x16x32_bf16 v[46:49], v[92:95], v[42:45], v[46:49]
	s_waitcnt lgkmcnt(0)
	v_lshlrev_b32_e32 v29, 16, v24
	v_and_b32_e32 v30, 0xffff0000, v24
	v_lshlrev_b32_e32 v34, 16, v25
	v_and_b32_e32 v40, 0xffff0000, v25
	s_waitcnt vmcnt(1)
	v_add_f32_e32 v24, v50, v54
	v_mul_f32_e32 v24, 0xbfb8aa3b, v24
	v_exp_f32_e32 v24, v24
	s_waitcnt vmcnt(0)
	v_add_f32_e32 v25, v46, v58
	v_mul_f32_e32 v25, 0xbfb8aa3b, v25
	v_exp_f32_e32 v25, v25
	v_add_f32_e32 v24, 1.0, v24
	v_rcp_f32_e32 v24, v24
	v_add_f32_e32 v25, 1.0, v25
	v_rcp_f32_e32 v25, v25
	v_mul_f32_e32 v24, 0xc1000000, v24
	v_mul_f32_e32 v24, v132, v24
	v_mul_f32_e32 v24, 0x3fb8aa3b, v24
	v_exp_f32_e32 v24, v24
	s_nop 0
	v_sub_f32_e32 v32, 1.0, v24
	v_add_f32_e32 v33, 1.0, v24
	v_mul_f32_e32 v32, v32, v33
	v_max_f32_e32 v32, 0, v32
	v_sqrt_f32_e32 v32, v32
	s_nop 0
	v_mul_f32_e32 v25, v25, v32
	v_mul_f32_e32 v25, v25, v29
	v_add_f32_e32 v29, v51, v55
	v_mul_f32_e32 v29, 0xbfb8aa3b, v29
	v_exp_f32_e32 v29, v29
	v_add_f32_e32 v32, v47, v59
	v_mul_f32_e32 v32, 0xbfb8aa3b, v32
	v_exp_f32_e32 v32, v32
	v_add_f32_e32 v29, 1.0, v29
	v_rcp_f32_e32 v29, v29
	v_add_f32_e32 v32, 1.0, v32
	v_rcp_f32_e32 v33, v32
	v_mul_f32_e32 v29, 0xc1000000, v29
	v_mul_f32_e32 v29, v160, v29
	v_mul_f32_e32 v29, 0x3fb8aa3b, v29
	v_exp_f32_e32 v32, v29
	s_nop 0
	v_sub_f32_e32 v29, 1.0, v32
	v_add_f32_e32 v46, 1.0, v32
	v_mul_f32_e32 v29, v29, v46
	v_max_f32_e32 v29, 0, v29
	v_sqrt_f32_e32 v29, v29
	s_nop 0
	v_mul_f32_e32 v29, v33, v29
	v_mul_f32_e32 v33, v29, v30
	ds_write2_b64 v191, v[24:25], v[32:33] offset0:32 offset1:49
	v_add_f32_e32 v24, v52, v56
	v_mul_f32_e32 v24, 0xbfb8aa3b, v24
	v_exp_f32_e32 v24, v24
	v_add_f32_e32 v25, v48, v60
	v_mul_f32_e32 v25, 0xbfb8aa3b, v25
	v_exp_f32_e32 v25, v25
	v_add_f32_e32 v24, 1.0, v24
	v_rcp_f32_e32 v24, v24
	v_add_f32_e32 v25, 1.0, v25
	v_rcp_f32_e32 v25, v25
	v_mul_f32_e32 v24, 0xc1000000, v24
	v_mul_f32_e32 v24, v180, v24
	v_mul_f32_e32 v24, 0x3fb8aa3b, v24
	v_exp_f32_e32 v24, v24
	s_nop 0
	v_sub_f32_e32 v29, 1.0, v24
	v_add_f32_e32 v30, 1.0, v24
	v_mul_f32_e32 v29, v29, v30
	v_max_f32_e32 v29, 0, v29
	v_sqrt_f32_e32 v29, v29
	v_add_f32_e32 v30, v49, v61
	v_mul_f32_e32 v30, 0xbfb8aa3b, v30
	v_exp_f32_e32 v30, v30
	v_mul_f32_e32 v25, v25, v29
	v_add_f32_e32 v29, v53, v57
	v_mul_f32_e32 v29, 0xbfb8aa3b, v29
	v_exp_f32_e32 v29, v29
	v_add_f32_e32 v30, 1.0, v30
	v_rcp_f32_e32 v30, v30
	v_mfma_f32_16x16x32_bf16 v[46:49], v[72:75], v[36:39], 0
	v_add_f32_e32 v29, 1.0, v29
	v_rcp_f32_e32 v29, v29
	v_mul_f32_e32 v25, v25, v34
	v_mfma_f32_16x16x32_bf16 v[36:39], v[68:71], v[36:39], 0
	v_mul_f32_e32 v29, 0xc1000000, v29
	v_mul_f32_e32 v29, v183, v29
	v_mul_f32_e32 v29, 0x3fb8aa3b, v29
	v_exp_f32_e32 v32, v29
	v_mfma_f32_16x16x32_bf16 v[46:49], v[80:83], v[42:45], v[46:49]
	v_sub_f32_e32 v29, 1.0, v32
	v_add_f32_e32 v33, 1.0, v32
	v_mul_f32_e32 v29, v29, v33
	v_max_f32_e32 v29, 0, v29
	v_sqrt_f32_e32 v29, v29
	v_mfma_f32_16x16x32_bf16 v[36:39], v[76:79], v[42:45], v[36:39]
	v_mul_f32_e32 v29, v30, v29
	v_mul_f32_e32 v33, v29, v40
	ds_write2_b64 v191, v[24:25], v[32:33] offset0:66 offset1:83
	global_load_dwordx4 v[42:45], v[4:5], off offset:192
	global_load_dwordx4 v[50:53], v[0:1], off offset:192
	ds_read_b64 v[0:1], v2 offset:96
	s_waitcnt lgkmcnt(0)
	v_lshlrev_b32_e32 v2, 16, v0
	v_and_b32_e32 v5, 0xffff0000, v0
	v_lshlrev_b32_e32 v24, 16, v1
	v_and_b32_e32 v25, 0xffff0000, v1
	s_waitcnt vmcnt(1)
	v_add_f32_e32 v0, v46, v42
	v_mul_f32_e32 v0, 0xbfb8aa3b, v0
	v_exp_f32_e32 v0, v0
	s_waitcnt vmcnt(0)
	v_add_f32_e32 v1, v36, v50
	v_mul_f32_e32 v1, 0xbfb8aa3b, v1
	v_exp_f32_e32 v1, v1
	v_add_f32_e32 v0, 1.0, v0
	v_rcp_f32_e32 v0, v0
	v_add_f32_e32 v1, 1.0, v1
	v_rcp_f32_e32 v1, v1
	v_mul_f32_e32 v0, 0xc1000000, v0
	v_mul_f32_e32 v0, v62, v0
	v_mul_f32_e32 v0, 0x3fb8aa3b, v0
	v_exp_f32_e32 v0, v0
	s_nop 0
	v_sub_f32_e32 v4, 1.0, v0
	v_add_f32_e32 v29, 1.0, v0
	v_mul_f32_e32 v4, v4, v29
	v_max_f32_e32 v4, 0, v4
	v_sqrt_f32_e32 v4, v4
	s_nop 0
	v_mul_f32_e32 v1, v1, v4
	v_mul_f32_e32 v1, v1, v2
	v_add_f32_e32 v2, v47, v43
	v_mul_f32_e32 v2, 0xbfb8aa3b, v2
	v_exp_f32_e32 v2, v2
	v_add_f32_e32 v4, v37, v51
	v_mul_f32_e32 v4, 0xbfb8aa3b, v4
	v_exp_f32_e32 v4, v4
	v_add_f32_e32 v2, 1.0, v2
	v_rcp_f32_e32 v2, v2
	v_add_f32_e32 v4, 1.0, v4
	v_rcp_f32_e32 v29, v4
	v_mul_f32_e32 v2, 0xc1000000, v2
	v_mul_f32_e32 v2, v64, v2
	v_mul_f32_e32 v2, 0x3fb8aa3b, v2
	v_exp_f32_e32 v4, v2
	s_nop 0
	v_sub_f32_e32 v2, 1.0, v4
	v_add_f32_e32 v30, 1.0, v4
	v_mul_f32_e32 v2, v2, v30
	v_max_f32_e32 v2, 0, v2
	v_sqrt_f32_e32 v2, v2
	s_nop 0
	v_mul_f32_e32 v2, v29, v2
	v_mul_f32_e32 v5, v2, v5
	ds_write2_b64 v190, v[0:1], v[4:5] offset0:48 offset1:65
	v_add_f32_e32 v0, v48, v44
	v_mul_f32_e32 v0, 0xbfb8aa3b, v0
	v_exp_f32_e32 v0, v0
	v_add_f32_e32 v1, v38, v52
	v_mul_f32_e32 v1, 0xbfb8aa3b, v1
	v_exp_f32_e32 v1, v1
	v_add_f32_e32 v0, 1.0, v0
	v_rcp_f32_e32 v0, v0
	v_add_f32_e32 v1, 1.0, v1
	v_rcp_f32_e32 v1, v1
	v_mul_f32_e32 v0, 0xc1000000, v0
	v_mul_f32_e32 v0, v65, v0
	v_mul_f32_e32 v0, 0x3fb8aa3b, v0
	v_exp_f32_e32 v0, v0
	s_nop 0
	v_sub_f32_e32 v2, 1.0, v0
	v_add_f32_e32 v4, 1.0, v0
	v_mul_f32_e32 v2, v2, v4
	v_max_f32_e32 v2, 0, v2
	v_sqrt_f32_e32 v2, v2
	v_add_f32_e32 v4, v39, v53
	v_mul_f32_e32 v4, 0xbfb8aa3b, v4
	v_exp_f32_e32 v4, v4
	v_mul_f32_e32 v1, v1, v2
	v_add_f32_e32 v2, v49, v45
	v_mul_f32_e32 v2, 0xbfb8aa3b, v2
	v_exp_f32_e32 v2, v2
	v_add_f32_e32 v4, 1.0, v4
	v_rcp_f32_e32 v5, v4
	v_mul_f32_e32 v1, v1, v24
	v_add_f32_e32 v2, 1.0, v2
	v_rcp_f32_e32 v2, v2
	s_nop 0
	v_mul_f32_e32 v2, 0xc1000000, v2
	v_mul_f32_e32 v2, v66, v2
	v_mul_f32_e32 v2, 0x3fb8aa3b, v2
	v_exp_f32_e32 v4, v2
	s_nop 0
	v_sub_f32_e32 v2, 1.0, v4
	v_add_f32_e32 v24, 1.0, v4
	v_mul_f32_e32 v2, v2, v24
	v_max_f32_e32 v2, 0, v2
	v_sqrt_f32_e32 v2, v2
	s_nop 0
	v_mul_f32_e32 v2, v5, v2
	v_mul_f32_e32 v5, v2, v25
	ds_write2_b64 v190, v[0:1], v[4:5] offset0:82 offset1:99
	v_add_co_u32_e32 v0, vcc, s0, v8
	s_waitcnt lgkmcnt(0)
	s_nop 0
	v_addc_co_u32_e32 v1, vcc, -1, v9, vcc
	s_barrier
	global_load_ushort v0, v[0:1], off
	ds_read2_b64 v[36:39], v196 offset1:1
	s_waitcnt lgkmcnt(0)
	v_fma_f32 v2, v41, v38, v39
	v_add_f32_e32 v4, v35, v2
	v_fmac_f32_e32 v37, v2, v36
	v_add_f32_e32 v2, v28, v37
	s_waitcnt vmcnt(0)
	v_lshlrev_b32_e32 v0, 16, v0
	v_mul_f32_e32 v0, v4, v0
	v_cvt_pk_bf16_f32 v24, v0, s0
	s_or_b32 s0, s4, 0x7800
	v_lshl_add_u64 v[4:5], v[16:17], 0, s[0:1]
	s_mov_b32 s0, 0xfffe3000
	v_add_co_u32_e32 v0, vcc, s0, v8
	s_mov_b32 s0, 0xfffe1000
	s_nop 0
	v_addc_co_u32_e32 v1, vcc, -1, v9, vcc
	global_load_ushort v25, v[0:1], off offset:-3072
	v_add_co_u32_e32 v0, vcc, s0, v8
	s_mov_b32 s0, 0xfffdf000
	s_nop 0
	v_addc_co_u32_e32 v1, vcc, -1, v9, vcc
	global_load_ushort v29, v[0:1], off offset:-2048
	v_add_co_u32_e32 v0, vcc, s0, v8
	s_mov_b32 s0, 0xfffdd000
	s_nop 0
	v_addc_co_u32_e32 v1, vcc, -1, v9, vcc
	global_load_ushort v30, v[0:1], off offset:-1024
	v_add_co_u32_e32 v0, vcc, s0, v8
	s_mov_b32 s0, 0xfffdc000
	s_nop 0
	v_addc_co_u32_e32 v1, vcc, -1, v9, vcc
	global_load_ushort v38, v[0:1], off
	v_add_co_u32_e32 v0, vcc, s0, v8
	s_mov_b32 s0, 0xfffda000
	s_nop 0
	v_addc_co_u32_e32 v1, vcc, -1, v9, vcc
	global_load_ushort v39, v[0:1], off offset:-3072
	v_add_co_u32_e32 v0, vcc, s0, v8
	s_mov_b32 s0, 0xfffd8000
	s_nop 0
	v_addc_co_u32_e32 v1, vcc, -1, v9, vcc
	global_load_ushort v40, v[0:1], off offset:-2048
	v_add_co_u32_e32 v0, vcc, s0, v8
	s_mov_b32 s0, 0xfffd6000
	s_nop 0
	v_addc_co_u32_e32 v1, vcc, -1, v9, vcc
	global_load_ushort v41, v[0:1], off offset:-1024
	v_add_co_u32_e32 v0, vcc, s0, v8
	s_mov_b32 s0, 0xfffd5000
	s_nop 0
	v_addc_co_u32_e32 v1, vcc, -1, v9, vcc
	global_load_ushort v42, v[0:1], off
	v_add_co_u32_e32 v0, vcc, s0, v8
	s_mov_b32 s0, 0xfffd3000
	s_nop 0
	v_addc_co_u32_e32 v1, vcc, -1, v9, vcc
	global_load_ushort v43, v[0:1], off offset:-3072
	v_add_co_u32_e32 v0, vcc, s0, v8
	s_mov_b32 s0, 0xfffd1000
	s_nop 0
	v_addc_co_u32_e32 v1, vcc, -1, v9, vcc
	global_load_ushort v44, v[0:1], off offset:-2048
	v_add_co_u32_e32 v0, vcc, s0, v8
	s_mov_b32 s0, 0xfffcf000
	s_nop 0
	v_addc_co_u32_e32 v1, vcc, -1, v9, vcc
	global_load_ushort v45, v[0:1], off offset:-1024
	v_add_co_u32_e32 v0, vcc, s0, v8
	s_mov_b32 s0, 0xfffce000
	s_nop 0
	v_addc_co_u32_e32 v1, vcc, -1, v9, vcc
	global_load_ushort v46, v[0:1], off
	v_add_co_u32_e32 v0, vcc, s0, v8
	s_mov_b32 s0, 0xfffcc000
	s_nop 0
	v_addc_co_u32_e32 v1, vcc, -1, v9, vcc
	global_load_ushort v47, v[0:1], off offset:-3072
	v_add_co_u32_e32 v0, vcc, s0, v8
	s_nop 1
	v_addc_co_u32_e32 v1, vcc, -1, v9, vcc
	global_load_ushort v1, v[0:1], off offset:-2048
	s_nop 0
	global_load_ushort v0, v[12:13], off
	ds_read2_b64 v[32:35], v195 offset1:1
	global_store_short v[4:5], v24, off
	s_waitcnt vmcnt(15)
	v_lshlrev_b32_e32 v4, 16, v25
	v_mul_f32_e32 v2, v2, v4
	v_cvt_pk_bf16_f32 v2, v2, s0
	s_or_b32 s0, s4, 0x7000
	v_lshl_add_u64 v[4:5], v[16:17], 0, s[0:1]
	global_store_short v[4:5], v2, off
	s_waitcnt lgkmcnt(0)
	v_fma_f32 v2, v37, v34, v35
	v_add_f32_e32 v4, v31, v2
	s_waitcnt vmcnt(15)
	v_lshlrev_b32_e32 v5, 16, v29
	v_mul_f32_e32 v4, v4, v5
	v_cvt_pk_bf16_f32 v8, v4, s0
	s_or_b32 s0, s4, 0x6800
	v_lshl_add_u64 v[4:5], v[16:17], 0, s[0:1]
	global_store_short v[4:5], v8, off
	v_fmac_f32_e32 v33, v2, v32
	s_waitcnt vmcnt(15)
	v_lshlrev_b32_e32 v4, 16, v30
	ds_read2_b64 v[28:31], v194 offset1:1
	v_add_f32_e32 v2, v26, v33
	v_mul_f32_e32 v2, v2, v4
	v_cvt_pk_bf16_f32 v2, v2, s0
	s_or_b32 s0, s4, 0x6000
	v_lshl_add_u64 v[4:5], v[16:17], 0, s[0:1]
	global_store_short v[4:5], v2, off
	s_waitcnt lgkmcnt(0)
	v_fma_f32 v2, v33, v30, v31
	v_add_f32_e32 v4, v27, v2
	s_waitcnt vmcnt(15)
	v_lshlrev_b32_e32 v5, 16, v38
	v_mul_f32_e32 v4, v4, v5
	v_cvt_pk_bf16_f32 v8, v4, s0
	s_or_b32 s0, s4, 0x5800
	v_lshl_add_u64 v[4:5], v[16:17], 0, s[0:1]
	v_fmac_f32_e32 v29, v2, v28
	ds_read2_b64 v[24:27], v193 offset1:1
	global_store_short v[4:5], v8, off
	v_add_f32_e32 v2, v22, v29
	s_waitcnt vmcnt(15)
	v_lshlrev_b32_e32 v4, 16, v39
	v_mul_f32_e32 v2, v2, v4
	v_cvt_pk_bf16_f32 v2, v2, s0
	s_or_b32 s0, s4, 0x5000
	v_lshl_add_u64 v[4:5], v[16:17], 0, s[0:1]
	global_store_short v[4:5], v2, off
	s_waitcnt lgkmcnt(0)
	v_fma_f32 v2, v29, v26, v27
	v_add_f32_e32 v4, v23, v2
	s_waitcnt vmcnt(15)
	v_lshlrev_b32_e32 v5, 16, v40
	v_mul_f32_e32 v4, v4, v5
	v_cvt_pk_bf16_f32 v8, v4, s0
	s_or_b32 s0, s4, 0x4800
	v_lshl_add_u64 v[4:5], v[16:17], 0, s[0:1]
	v_fmac_f32_e32 v25, v2, v24
	ds_read2_b64 v[26:29], v189 offset1:1
	global_store_short v[4:5], v8, off
	v_add_f32_e32 v2, v18, v25
	s_waitcnt vmcnt(15)
	v_lshlrev_b32_e32 v4, 16, v41
	v_mul_f32_e32 v2, v2, v4
	v_cvt_pk_bf16_f32 v2, v2, s0
	s_or_b32 s0, s4, 0x4000
	v_lshl_add_u64 v[4:5], v[16:17], 0, s[0:1]
	global_store_short v[4:5], v2, off
	s_waitcnt lgkmcnt(0)
	v_fma_f32 v2, v25, v28, v29
	v_add_f32_e32 v4, v19, v2
	s_waitcnt vmcnt(15)
	v_lshlrev_b32_e32 v5, 16, v42
	v_mul_f32_e32 v4, v4, v5
	v_cvt_pk_bf16_f32 v8, v4, s0
	s_or_b32 s0, s4, 0x3800
	v_lshl_add_u64 v[4:5], v[16:17], 0, s[0:1]
	v_fmac_f32_e32 v27, v2, v26
	ds_read2_b64 v[22:25], v185 offset1:1
	global_store_short v[4:5], v8, off
	v_add_f32_e32 v2, v14, v27
	s_waitcnt vmcnt(15)
	v_lshlrev_b32_e32 v4, 16, v43
	v_mul_f32_e32 v2, v2, v4
	v_cvt_pk_bf16_f32 v2, v2, s0
	s_or_b32 s0, s4, 0x3000
	v_lshl_add_u64 v[4:5], v[16:17], 0, s[0:1]
	global_store_short v[4:5], v2, off
	s_waitcnt lgkmcnt(0)
	v_fma_f32 v2, v27, v24, v25
	v_add_f32_e32 v4, v15, v2
	s_waitcnt vmcnt(15)
	v_lshlrev_b32_e32 v5, 16, v44
	v_mul_f32_e32 v4, v4, v5
	v_cvt_pk_bf16_f32 v8, v4, s0
	s_or_b32 s0, s4, 0x2800
	v_lshl_add_u64 v[4:5], v[16:17], 0, s[0:1]
	v_fmac_f32_e32 v23, v2, v22
	ds_read2_b64 v[12:15], v181 offset1:1
	global_store_short v[4:5], v8, off
	v_add_f32_e32 v2, v10, v23
	s_waitcnt vmcnt(15)
	v_lshlrev_b32_e32 v4, 16, v45
	v_mul_f32_e32 v2, v2, v4
	v_cvt_pk_bf16_f32 v2, v2, s0
	s_or_b32 s0, s4, 0x2000
	v_lshl_add_u64 v[4:5], v[16:17], 0, s[0:1]
	global_store_short v[4:5], v2, off
	s_waitcnt lgkmcnt(0)
	v_fma_f32 v2, v23, v14, v15
	v_add_f32_e32 v4, v11, v2
	s_waitcnt vmcnt(15)
	v_lshlrev_b32_e32 v5, 16, v46
	v_mul_f32_e32 v4, v4, v5
	v_cvt_pk_bf16_f32 v8, v4, s0
	s_or_b32 s0, s4, 0x1800
	v_lshl_add_u64 v[4:5], v[16:17], 0, s[0:1]
	global_store_short v[4:5], v8, off
	v_fmac_f32_e32 v13, v2, v12
	ds_read2_b64 v[8:11], v188 offset1:1
	v_add_f32_e32 v2, v6, v13
	s_waitcnt vmcnt(15)
	v_lshlrev_b32_e32 v4, 16, v47
	v_mul_f32_e32 v2, v2, v4
	v_cvt_pk_bf16_f32 v2, v2, s0
	s_or_b32 s0, s4, 0x1000
	v_lshl_add_u64 v[4:5], v[16:17], 0, s[0:1]
	global_store_short v[4:5], v2, off
	s_waitcnt lgkmcnt(0)
	v_fma_f32 v2, v13, v10, v11
	v_add_f32_e32 v4, v7, v2
	s_waitcnt vmcnt(15)
	v_lshlrev_b32_e32 v1, 16, v1
	v_mul_f32_e32 v1, v4, v1
	s_bitset1_b32 s4, 11
	v_cvt_pk_bf16_f32 v1, v1, s0
	v_lshl_add_u64 v[4:5], v[16:17], 0, s[4:5]
	v_fmac_f32_e32 v9, v2, v8
	global_store_short v[4:5], v1, off
	v_add_f32_e32 v1, v220, v9
	s_waitcnt vmcnt(15)
	v_lshlrev_b32_e32 v0, 16, v0
	v_mul_f32_e32 v0, v1, v0
	v_cvt_pk_bf16_f32 v0, v0, s0
	global_store_short v[20:21], v0, off
	s_barrier
